# nt cache hint on once-read streams (P in F/G, fp32 weights in conversion, finish/LN1/LN2 row loads) + G/L epilogue load hoisting + D2 store-aware waits
# speedup vs baseline: 1.0286x; 1.0286x over previous
; __device__ __forceinline__ void transpose_item8(const float* W, int N, unsigned char* WT, int ldt, int item, int lane, int mode, int aux) {
;     const int nblk = (N + 63) >> 6, kb = item / nblk, nb = item - kb * nblk, k0 = 64 * kb, n0 = 64 * nb;
;     const int ncol = n0 + lane;
;     const float* wp = W + (size_t)k0 * N + ncol;
;     float v[64];
; #pragma unroll
;     for (int i = 0; i < 64; ++i) v[i] = wp[(size_t)i * N];
; __device__ __forceinline__ void convert_rest(const Args& a, LAS unsigned char* lds, int wave, int lane, int gw, int ngw, int l, int it0, int it1) {
;     ...
;     for (int it = it0 + gw; it < it1; it += ngw) {
;         int r = it;
;         if (r < WI_G) { const int g = r >> 8; transpose_item8(a.in[I_WGATE] + (size_t)(l * 4 + g) * 1024 * 1024, 1024, ws + WS_WG, 1024, r & 255, lane, 2, g); continue; } r -= WI_G;
;         if (r < WI_BR) { const int g = r >> 6; transpose_item(a.in[I_WBR] + (size_t)(l * 4 + g) * 256 * 1024, 1024, (bf16*)(ws + WS_WBR) + (size_t)g * 1024 * 256, 256, scr, r & 63, lane, 0, 0); continue; } r -= WI_BR;
;         if (r < WI_OUT) { transpose_item(a.in[I_WOUT] + (size_t)l * 1024 * 1024, 1024, (bf16*)(ws + WS_WOUT), 1024, scr, r, lane, 0, 0); continue; } r -= WI_OUT;
;         if (r < WI_FF) { const int e = r >> 8; transpose_item8(a.in[I_WFFG] + (size_t)(l * 16 + e) * 1024 * 1024, 1024, ws + WS_WGU + (size_t)e * 2048 * 1024, 1024, r & 255, lane, 3, 0); continue; } r -= WI_FF;
;         if (r < WI_FF) { const int e = r >> 8; transpose_item8(a.in[I_WFFU] + (size_t)(l * 16 + e) * 1024 * 1024, 1024, ws + WS_WGU + (size_t)e * 2048 * 1024, 1024, r & 255, lane, 4, 0); continue; } r -= WI_FF;
;         { const int e = r >> 8; transpose_item8(a.in[I_WFFD] + (size_t)(l * 16 + e) * 1024 * 1024, 1024, ws + WS_WDN + (size_t)e * 1024 * 1024, 1024, r & 255, lane, 0, 0); }
.LBB0_1072:
	s_add_i32 s17, s9, 0x2600
	s_cmpk_gt_i32 s17, 0x3ff
	s_mov_b64 s[0:1], -1
	s_cbranch_scc0 .LBB0_1136
	s_cmpk_gt_u32 s17, 0x4ff
	s_cbranch_scc0 .LBB0_1133
	s_cmpk_gt_u32 s17, 0x5ff
	s_cbranch_scc0 .LBB0_1084
	s_cmpk_gt_u32 s17, 0x15ff
	s_cbranch_scc0 .LBB0_1081
	s_cmpk_gt_u32 s17, 0x25ff
	s_cbranch_scc0 .LBB0_1078
	s_lshr_b32 s0, s9, 8
	v_readlane_b32 s22, v254, 32
	v_readlane_b32 s23, v254, 33
	s_add_i32 s22, s0, s5
	v_readlane_b32 s56, v252, 41
	s_lshl_b64 s[2:3], s[22:23], 22
	v_readlane_b32 s64, v252, 49
	v_readlane_b32 s65, v252, 50
	s_add_u32 s2, s64, s2
	s_mov_b32 s1, s23
	s_addc_u32 s3, s65, s3
	s_lshl_b64 s[0:1], s[0:1], 20
	v_readlane_b32 s21, v253, 59
	s_add_u32 s0, s21, s0
	v_readlane_b32 s21, v253, 60
	s_addc_u32 s1, s21, s1
	s_lshl_b32 s21, s17, 2
	s_and_b32 s22, s21, 0x3c0
	s_lshl_b32 s21, s17, 6
	s_and_b32 s21, s21, 0x3c0
	v_or_b32_e32 v17, s21, v20
	s_lshl_b32 s21, s22, 12
	s_add_u32 s2, s2, s21
	s_addc_u32 s3, s3, 0
	v_lshlrev_b32_e32 v50, 2, v17
	v_lshl_add_u64 v[2:3], s[2:3], 0, v[50:51]
	global_load_dword v18, v50, s[2:3] nt
	s_movk_i32 s2, 0x2000
	v_readlane_b32 s70, v252, 55
	v_add_co_u32_e32 v4, vcc, s2, v2
	s_movk_i32 s70, 0x4000
	s_nop 0
	v_addc_co_u32_e32 v5, vcc, 0, v3, vcc
	global_load_dword v19, v[4:5], off offset:-4096 nt
	global_load_dword v41, v[4:5], off nt
	v_add_co_u32_e32 v4, vcc, s70, v2
	s_movk_i32 s2, 0x6000
	s_nop 0
	v_addc_co_u32_e32 v5, vcc, 0, v3, vcc
	global_load_dword v42, v[4:5], off offset:-4096 nt
	global_load_dword v43, v[4:5], off nt
	v_add_co_u32_e32 v4, vcc, s2, v2
	s_mov_b32 s2, 0x8000
	s_nop 0
	v_addc_co_u32_e32 v5, vcc, 0, v3, vcc
	global_load_dword v44, v[4:5], off offset:-4096 nt
	global_load_dword v45, v[4:5], off nt
	v_add_co_u32_e32 v4, vcc, s2, v2
	s_mov_b32 s2, 0xa000
	s_nop 0
	v_addc_co_u32_e32 v5, vcc, 0, v3, vcc
	global_load_dword v46, v[4:5], off offset:-4096 nt
	global_load_dword v47, v[4:5], off nt
	v_add_co_u32_e32 v4, vcc, s2, v2
	s_mov_b32 s2, 0xc000
	s_nop 0
	v_addc_co_u32_e32 v5, vcc, 0, v3, vcc
	global_load_dword v48, v[4:5], off offset:-4096 nt
	global_load_dword v49, v[4:5], off nt
	v_add_co_u32_e32 v4, vcc, s2, v2
	s_mov_b32 s2, 0xe000
	s_nop 0
	v_addc_co_u32_e32 v5, vcc, 0, v3, vcc
	global_load_dword v50, v[4:5], off offset:-4096 nt
	global_load_dword v52, v[4:5], off nt
	v_add_co_u32_e32 v4, vcc, s2, v2
	s_mov_b32 s2, 0x10000
	s_nop 0
	v_addc_co_u32_e32 v5, vcc, 0, v3, vcc
	global_load_dword v53, v[4:5], off offset:-4096 nt
	global_load_dword v54, v[4:5], off nt
	v_add_co_u32_e32 v4, vcc, s2, v2
	s_mov_b32 s2, 0x12000
	s_nop 0
	v_addc_co_u32_e32 v5, vcc, 0, v3, vcc
	global_load_dword v55, v[4:5], off offset:-4096 nt
	global_load_dword v10, v[4:5], off nt
	v_add_co_u32_e32 v4, vcc, s2, v2
	s_mov_b32 s2, 0x14000
	s_nop 0
	v_addc_co_u32_e32 v5, vcc, 0, v3, vcc
	global_load_dword v56, v[4:5], off offset:-4096 nt
	global_load_dword v57, v[4:5], off nt
	v_add_co_u32_e32 v4, vcc, s2, v2
	s_mov_b32 s2, 0x16000
	s_nop 0
	v_addc_co_u32_e32 v5, vcc, 0, v3, vcc
	global_load_dword v58, v[4:5], off offset:-4096 nt
	global_load_dword v11, v[4:5], off nt
	v_add_co_u32_e32 v4, vcc, s2, v2
	s_mov_b32 s2, 0x18000
	s_nop 0
	v_addc_co_u32_e32 v5, vcc, 0, v3, vcc
	global_load_dword v59, v[4:5], off offset:-4096 nt
	global_load_dword v60, v[4:5], off nt
	v_add_co_u32_e32 v4, vcc, s2, v2
	s_mov_b32 s2, 0x1a000
	s_nop 0
	v_addc_co_u32_e32 v5, vcc, 0, v3, vcc
	global_load_dword v61, v[4:5], off offset:-4096 nt
	global_load_dword v12, v[4:5], off nt
	v_add_co_u32_e32 v4, vcc, s2, v2
	s_mov_b32 s2, 0x1c000
	s_nop 0
	v_addc_co_u32_e32 v5, vcc, 0, v3, vcc
	global_load_dword v62, v[4:5], off offset:-4096 nt
	global_load_dword v63, v[4:5], off nt
	v_add_co_u32_e32 v4, vcc, s2, v2
	s_mov_b32 s2, 0x1e000
	s_nop 0
	v_addc_co_u32_e32 v5, vcc, 0, v3, vcc
	global_load_dword v64, v[4:5], off offset:-4096 nt
	global_load_dword v13, v[4:5], off nt
	v_add_co_u32_e32 v4, vcc, s2, v2
	s_mov_b32 s2, 0x20000
	s_nop 0
	v_addc_co_u32_e32 v5, vcc, 0, v3, vcc
	global_load_dword v65, v[4:5], off offset:-4096 nt
	global_load_dword v66, v[4:5], off nt
	v_add_co_u32_e32 v4, vcc, s2, v2
	s_mov_b32 s2, 0x22000
	s_nop 0
	v_addc_co_u32_e32 v5, vcc, 0, v3, vcc
	global_load_dword v67, v[4:5], off offset:-4096 nt
	global_load_dword v6, v[4:5], off nt
	v_add_co_u32_e32 v4, vcc, s2, v2
	s_mov_b32 s2, 0x24000
	s_nop 0
	v_addc_co_u32_e32 v5, vcc, 0, v3, vcc
	global_load_dword v68, v[4:5], off offset:-4096 nt
	global_load_dword v69, v[4:5], off nt
	v_add_co_u32_e32 v4, vcc, s2, v2
	s_mov_b32 s2, 0x26000
	s_nop 0
	v_addc_co_u32_e32 v5, vcc, 0, v3, vcc
	global_load_dword v70, v[4:5], off offset:-4096 nt
	global_load_dword v7, v[4:5], off nt
	v_add_co_u32_e32 v4, vcc, s2, v2
	s_mov_b32 s2, 0x28000
	s_nop 0
	v_addc_co_u32_e32 v5, vcc, 0, v3, vcc
	global_load_dword v71, v[4:5], off offset:-4096 nt
	global_load_dword v72, v[4:5], off nt
	v_add_co_u32_e32 v4, vcc, s2, v2
	s_mov_b32 s2, 0x2a000
	s_nop 0
	v_addc_co_u32_e32 v5, vcc, 0, v3, vcc
	global_load_dword v73, v[4:5], off offset:-4096 nt
	global_load_dword v8, v[4:5], off nt
	v_add_co_u32_e32 v4, vcc, s2, v2
	s_mov_b32 s2, 0x2c000
	s_nop 0
	v_addc_co_u32_e32 v5, vcc, 0, v3, vcc
	global_load_dword v74, v[4:5], off offset:-4096 nt
	global_load_dword v75, v[4:5], off nt
	v_add_co_u32_e32 v4, vcc, s2, v2
	s_mov_b32 s2, 0x2e000
	s_nop 0
	v_addc_co_u32_e32 v5, vcc, 0, v3, vcc
	global_load_dword v76, v[4:5], off offset:-4096 nt
	global_load_dword v9, v[4:5], off nt
	v_add_co_u32_e32 v4, vcc, s2, v2
	s_mov_b32 s2, 0x30000
	s_nop 0
	v_addc_co_u32_e32 v5, vcc, 0, v3, vcc
	global_load_dword v77, v[4:5], off offset:-4096 nt
	global_load_dword v78, v[4:5], off nt
; __device__ __forceinline__ unsigned pk4_fp8(float a, float b, float c, float d) { int w = 0; w = __builtin_amdgcn_cvt_pk_fp8_f32(a, b, w, false); w = __builtin_amdgcn_cvt_pk_fp8_f32(c, d, w, true); return (unsigned)w; }
; __device__ __forceinline__ void transpose_item8(const float* W, int N, unsigned char* WT, int ldt, int item, int lane, int mode, int aux) {
;     ...
;     for (int i = 0; i < 64; ++i) v[i] = wp[(size_t)i * N];
;     unsigned o[16];
; #pragma unroll
;     for (int q = 0; q < 16; ++q) o[q] = pk4_fp8(fminf(fmaxf(v[4 * q] * 64.f, -448.f), 448.f), fminf(fmaxf(v[4 * q + 1] * 64.f, -448.f), 448.f), fminf(fmaxf(v[4 * q + 2] * 64.f, -448.f), 448.f), fminf(fmaxf(v[4 * q + 3] * 64.f, -448.f), 448.f));
	v_add_co_u32_e32 v4, vcc, s2, v2
	s_mov_b32 s2, 0x32000
	s_nop 0
	v_addc_co_u32_e32 v5, vcc, 0, v3, vcc
	global_load_dword v79, v[4:5], off offset:-4096 nt
	global_load_dword v80, v[4:5], off nt
	v_add_co_u32_e32 v4, vcc, s2, v2
	s_mov_b32 s2, 0x34000
	s_nop 0
	v_addc_co_u32_e32 v5, vcc, 0, v3, vcc
	global_load_dword v81, v[4:5], off offset:-4096 nt
	global_load_dword v82, v[4:5], off nt
	v_add_co_u32_e32 v4, vcc, s2, v2
	s_mov_b32 s2, 0x36000
	s_nop 0
	v_addc_co_u32_e32 v5, vcc, 0, v3, vcc
	global_load_dword v83, v[4:5], off offset:-4096 nt
	global_load_dword v84, v[4:5], off nt
	v_add_co_u32_e32 v4, vcc, s2, v2
	s_mov_b32 s2, 0x38000
	s_nop 0
	v_addc_co_u32_e32 v5, vcc, 0, v3, vcc
	global_load_dword v85, v[4:5], off offset:-4096 nt
	global_load_dword v86, v[4:5], off nt
	v_add_co_u32_e32 v4, vcc, s2, v2
	s_mov_b32 s2, 0x3a000
	s_nop 0
	v_addc_co_u32_e32 v5, vcc, 0, v3, vcc
	global_load_dword v87, v[4:5], off offset:-4096 nt
	global_load_dword v88, v[4:5], off nt
	v_add_co_u32_e32 v4, vcc, s2, v2
	s_mov_b32 s2, 0x3c000
	s_nop 0
	v_addc_co_u32_e32 v5, vcc, 0, v3, vcc
	global_load_dword v89, v[4:5], off offset:-4096 nt
	global_load_dword v90, v[4:5], off nt
	v_add_co_u32_e32 v4, vcc, s2, v2
	s_mov_b32 s2, 0x3e000
	s_nop 0
	v_addc_co_u32_e32 v5, vcc, 0, v3, vcc
	global_load_dword v91, v[4:5], off offset:-4096 nt
	global_load_dword v92, v[4:5], off nt
	v_add_co_u32_e32 v4, vcc, s2, v2
	s_mov_b32 s2, 0x3f000
	s_nop 0
	v_addc_co_u32_e32 v5, vcc, 0, v3, vcc
	global_load_dword v93, v[4:5], off offset:-4096 nt
	s_nop 0
	global_load_dword v4, v[4:5], off nt
	v_add_co_u32_e32 v2, vcc, s2, v2
	s_mov_b32 s2, 0xc3e00000
	s_nop 0
	v_addc_co_u32_e32 v3, vcc, 0, v3, vcc
	global_load_dword v2, v[2:3], off nt
	s_waitcnt vmcnt(27)
	v_mul_f32_e32 v7, 0x42800000, v7
	v_mul_f32_e32 v6, 0x42800000, v6
	v_mul_f32_e32 v13, 0x42800000, v13
	v_mul_f32_e32 v12, 0x42800000, v12
	v_mul_f32_e32 v11, 0x42800000, v11
	v_mul_f32_e32 v10, 0x42800000, v10
	v_mul_f32_e32 v55, 0x42800000, v55
	s_waitcnt vmcnt(23)
	v_mul_f32_e32 v8, 0x42800000, v8
	v_mul_f32_e32 v52, 0x42800000, v52
	v_mul_f32_e32 v53, 0x42800000, v53
	v_med3_f32 v52, v52, s2, v236
	v_med3_f32 v53, v53, s2, v236
	v_mul_f32_e32 v54, 0x42800000, v54
	v_med3_f32 v54, v54, s2, v236
	v_mul_f32_e32 v47, 0x42800000, v47
	v_mul_f32_e32 v48, 0x42800000, v48
	v_mul_f32_e32 v43, 0x42800000, v43
	v_mul_f32_e32 v44, 0x42800000, v44
	v_mul_f32_e32 v18, 0x42800000, v18
	s_waitcnt vmcnt(19)
	v_mul_f32_e32 v9, 0x42800000, v9
	v_mul_f32_e32 v19, 0x42800000, v19
	v_med3_f32 v47, v47, s2, v236
	v_med3_f32 v48, v48, s2, v236
	v_med3_f32 v43, v43, s2, v236
	v_med3_f32 v44, v44, s2, v236
	v_med3_f32 v18, v18, s2, v236
	v_med3_f32 v19, v19, s2, v236
	v_mul_f32_e32 v49, 0x42800000, v49
	v_mul_f32_e32 v50, 0x42800000, v50
	v_mul_f32_e32 v45, 0x42800000, v45
	v_mul_f32_e32 v46, 0x42800000, v46
	v_mul_f32_e32 v41, 0x42800000, v41
	v_mul_f32_e32 v42, 0x42800000, v42
	v_mul_f32_e32 v66, 0x42800000, v66
	v_mul_f32_e32 v67, 0x42800000, v67
	v_mul_f32_e32 v63, 0x42800000, v63
	v_mul_f32_e32 v64, 0x42800000, v64
	v_mul_f32_e32 v60, 0x42800000, v60
	v_mul_f32_e32 v61, 0x42800000, v61
	v_mul_f32_e32 v57, 0x42800000, v57
	v_mul_f32_e32 v58, 0x42800000, v58
	v_med3_f32 v49, v49, s2, v236
	v_med3_f32 v50, v50, s2, v236
	v_med3_f32 v45, v45, s2, v236
	v_med3_f32 v46, v46, s2, v236
	v_med3_f32 v41, v41, s2, v236
	v_med3_f32 v42, v42, s2, v236
	s_waitcnt vmcnt(17)
	v_mul_f32_e32 v78, 0x42800000, v78
	s_waitcnt vmcnt(16)
	v_mul_f32_e32 v79, 0x42800000, v79
	v_mul_f32_e32 v75, 0x42800000, v75
	v_mul_f32_e32 v76, 0x42800000, v76
	v_mul_f32_e32 v72, 0x42800000, v72
	v_mul_f32_e32 v73, 0x42800000, v73
	v_mul_f32_e32 v69, 0x42800000, v69
	v_mul_f32_e32 v70, 0x42800000, v70
	v_med3_f32 v66, v66, s2, v236
	v_med3_f32 v67, v67, s2, v236
	v_med3_f32 v63, v63, s2, v236
	v_med3_f32 v64, v64, s2, v236
	v_med3_f32 v60, v60, s2, v236
	v_med3_f32 v61, v61, s2, v236
	v_med3_f32 v57, v57, s2, v236
	v_med3_f32 v58, v58, s2, v236
	v_med3_f32 v78, v78, s2, v236
	v_med3_f32 v79, v79, s2, v236
	v_med3_f32 v75, v75, s2, v236
	v_med3_f32 v76, v76, s2, v236
	v_med3_f32 v72, v72, s2, v236
	v_med3_f32 v73, v73, s2, v236
	v_med3_f32 v69, v69, s2, v236
	v_med3_f32 v70, v70, s2, v236
	v_readlane_b32 s58, v252, 43
	s_waitcnt vmcnt(2)
	v_mul_f32_e32 v5, 0x42800000, v93
	s_waitcnt vmcnt(1)
	v_mul_f32_e32 v3, 0x42800000, v4
	v_mul_f32_e32 v4, 0x42800000, v92
	v_med3_f32 v4, v4, s2, v236
	v_med3_f32 v92, v5, s2, v236
	v_mov_b32_e32 v5, v51
	v_cvt_pk_fp8_f32 v5, v4, v92
	v_mul_f32_e32 v4, 0x42800000, v88
	v_med3_f32 v88, v4, s2, v236
	v_mul_f32_e32 v4, 0x42800000, v89
	v_med3_f32 v89, v4, s2, v236
	v_mov_b32_e32 v4, v51
	s_waitcnt vmcnt(0)
; __device__ __forceinline__ unsigned pk4_fp8(float a, float b, float c, float d) { int w = 0; w = __builtin_amdgcn_cvt_pk_fp8_f32(a, b, w, false); w = __builtin_amdgcn_cvt_pk_fp8_f32(c, d, w, true); return (unsigned)w; }
; __device__ __forceinline__ void transpose_item8(const float* W, int N, unsigned char* WT, int ldt, int item, int lane, int mode, int aux) {
;     ...
;     for (int q = 0; q < 16; ++q) o[q] = pk4_fp8(fminf(fmaxf(v[4 * q] * 64.f, -448.f), 448.f), fminf(fmaxf(v[4 * q + 1] * 64.f, -448.f), 448.f), fminf(fmaxf(v[4 * q + 2] * 64.f, -448.f), 448.f), fminf(fmaxf(v[4 * q + 3] * 64.f, -448.f), 448.f));
;     v4u* dst = (v4u*)(WT + (size_t)rowmap(mode, aux, ncol) * ldt + k0);
; #pragma unroll
;     for (int q = 0; q < 4; ++q) dst[q] = (v4u){o[4 * q], o[4 * q + 1], o[4 * q + 2], o[4 * q + 3]};
; __device__ __forceinline__ void convert_rest(const Args& a, LAS unsigned char* lds, int wave, int lane, int gw, int ngw, int l, int it0, int it1) {
;     ...
;         if (r < WI_FF) { const int e = r >> 8; transpose_item8(a.in[I_WFFG] + (size_t)(l * 16 + e) * 1024 * 1024, 1024, ws + WS_WGU + (size_t)e * 2048 * 1024, 1024, r & 255, lane, 3, 0); continue; } r -= WI_FF;
;         if (r < WI_FF) { const int e = r >> 8; transpose_item8(a.in[I_WFFU] + (size_t)(l * 16 + e) * 1024 * 1024, 1024, ws + WS_WGU + (size_t)e * 2048 * 1024, 1024, r & 255, lane, 4, 0); continue; } r -= WI_FF;
	v_mul_f32_e32 v2, 0x42800000, v2
	v_cvt_pk_fp8_f32 v4, v88, v89
	v_med3_f32 v3, v3, s2, v236
	v_med3_f32 v2, v2, s2, v236
	v_cvt_pk_fp8_f32 v5, v3, v2 op_sel:[0,0,1]
	v_mul_f32_e32 v2, 0x42800000, v90
	v_mul_f32_e32 v3, 0x42800000, v91
	v_med3_f32 v2, v2, s2, v236
	v_med3_f32 v3, v3, s2, v236
	v_cvt_pk_fp8_f32 v4, v2, v3 op_sel:[0,0,1]
	v_mul_f32_e32 v3, 0x42800000, v87
	v_mul_f32_e32 v2, 0x42800000, v86
	v_med3_f32 v86, v3, s2, v236
	v_mul_f32_e32 v3, 0x42800000, v84
	v_med3_f32 v84, v3, s2, v236
	v_mul_f32_e32 v3, 0x42800000, v85
	v_med3_f32 v85, v3, s2, v236
	v_mov_b32_e32 v3, v51
	v_cvt_pk_fp8_f32 v3, v84, v85
	v_med3_f32 v2, v2, s2, v236
	v_readlane_b32 s59, v252, 44
	v_readlane_b32 s60, v252, 45
	v_cvt_pk_fp8_f32 v3, v2, v86 op_sel:[0,0,1]
	v_mul_f32_e32 v2, 0x42800000, v82
	v_med3_f32 v82, v2, s2, v236
	v_mul_f32_e32 v2, 0x42800000, v83
	v_med3_f32 v83, v2, s2, v236
	v_mul_f32_e32 v2, 0x42800000, v80
	v_med3_f32 v80, v2, s2, v236
	v_mul_f32_e32 v2, 0x42800000, v81
	v_med3_f32 v81, v2, s2, v236
	v_mov_b32_e32 v2, v51
	v_cvt_pk_fp8_f32 v2, v80, v81
	v_med3_f32 v80, v9, s2, v236
	v_mul_f32_e32 v9, 0x42800000, v77
	v_med3_f32 v77, v9, s2, v236
	v_mov_b32_e32 v9, v51
	v_cvt_pk_fp8_f32 v9, v80, v77
	v_med3_f32 v77, v8, s2, v236
	v_mul_f32_e32 v8, 0x42800000, v74
	v_med3_f32 v74, v8, s2, v236
	v_mov_b32_e32 v8, v51
	v_cvt_pk_fp8_f32 v8, v77, v74
	v_med3_f32 v74, v7, s2, v236
	v_mul_f32_e32 v7, 0x42800000, v71
	v_med3_f32 v71, v7, s2, v236
	v_mov_b32_e32 v7, v51
	v_cvt_pk_fp8_f32 v7, v74, v71
	v_med3_f32 v71, v6, s2, v236
	v_mul_f32_e32 v6, 0x42800000, v68
	v_med3_f32 v68, v6, s2, v236
	v_mov_b32_e32 v6, v51
	v_cvt_pk_fp8_f32 v6, v71, v68
	v_med3_f32 v68, v13, s2, v236
	v_mul_f32_e32 v13, 0x42800000, v65
	v_med3_f32 v65, v13, s2, v236
	v_mov_b32_e32 v13, v51
	v_cvt_pk_fp8_f32 v13, v68, v65
	v_med3_f32 v65, v12, s2, v236
	v_mul_f32_e32 v12, 0x42800000, v62
	v_med3_f32 v62, v12, s2, v236
	v_mov_b32_e32 v12, v51
	v_cvt_pk_fp8_f32 v12, v65, v62
	v_med3_f32 v62, v11, s2, v236
	v_mul_f32_e32 v11, 0x42800000, v59
	v_med3_f32 v59, v11, s2, v236
	v_mov_b32_e32 v11, v51
	v_cvt_pk_fp8_f32 v11, v62, v59
	v_med3_f32 v59, v10, s2, v236
	v_mul_f32_e32 v10, 0x42800000, v56
	v_med3_f32 v56, v10, s2, v236
	v_mov_b32_e32 v10, v51
	v_cvt_pk_fp8_f32 v10, v59, v56
	v_med3_f32 v56, v55, s2, v236
	v_mov_b32_e32 v55, v51
	v_cvt_pk_fp8_f32 v55, v52, v53
	v_mov_b32_e32 v53, v51
	v_mov_b32_e32 v52, v51
	v_cvt_pk_fp8_f32 v53, v43, v44
	v_cvt_pk_fp8_f32 v55, v54, v56 op_sel:[0,0,1]
	v_mov_b32_e32 v54, v51
	v_cvt_pk_fp8_f32 v54, v47, v48
	v_cvt_pk_fp8_f32 v52, v18, v19
	v_cvt_pk_fp8_f32 v53, v45, v46 op_sel:[0,0,1]
	v_cvt_pk_fp8_f32 v13, v66, v67 op_sel:[0,0,1]
	v_cvt_pk_fp8_f32 v54, v49, v50 op_sel:[0,0,1]
	v_cvt_pk_fp8_f32 v52, v41, v42 op_sel:[0,0,1]
	v_cvt_pk_fp8_f32 v12, v63, v64 op_sel:[0,0,1]
	v_cvt_pk_fp8_f32 v11, v60, v61 op_sel:[0,0,1]
	v_cvt_pk_fp8_f32 v10, v57, v58 op_sel:[0,0,1]
	v_lshlrev_b32_e32 v50, 10, v17
	v_readlane_b32 s61, v252, 46
	v_cvt_pk_fp8_f32 v9, v78, v79 op_sel:[0,0,1]
	v_cvt_pk_fp8_f32 v8, v75, v76 op_sel:[0,0,1]
	v_cvt_pk_fp8_f32 v7, v72, v73 op_sel:[0,0,1]
	v_cvt_pk_fp8_f32 v6, v69, v70 op_sel:[0,0,1]
	v_lshl_add_u64 v[18:19], s[0:1], 0, v[50:51]
	s_mov_b32 s1, s23
	v_readlane_b32 s62, v252, 47
	v_readlane_b32 s63, v252, 48
	v_readlane_b32 s68, v252, 53
	v_readlane_b32 s69, v252, 54
	v_readlane_b32 s71, v252, 56
	s_mov_b32 s58, 0x3f6c835e
	v_readlane_b32 s60, v255, 2
	v_cvt_pk_fp8_f32 v2, v82, v83 op_sel:[0,0,1]
	v_writelane_b32 v254, s0, 32
	v_lshl_add_u64 v[18:19], v[18:19], 0, s[22:23]
	v_readlane_b32 s57, v252, 42
	v_readlane_b32 s66, v252, 51
	v_readlane_b32 s67, v252, 52
	s_mov_b32 s63, 0xbf6c835e
	v_readlane_b32 s62, v255, 4
	s_movk_i32 s68, 0x2200
	s_movk_i32 s71, 0x1ff
	s_mov_b32 s69, 0x7f800000
	s_mov_b32 s59, 0xbec3ef15
	v_readlane_b32 s61, v255, 3
	s_movk_i32 s64, 0x440
	v_writelane_b32 v254, s1, 33
	global_store_dwordx4 v[18:19], v[52:55], off
	global_store_dwordx4 v[18:19], v[10:13], off offset:16
	global_store_dwordx4 v[18:19], v[6:9], off offset:32
	global_store_dwordx4 v[18:19], v[2:5], off offset:48
	s_mov_b64 s[0:1], 0
.LBB0_1078:
	s_andn2_b64 vcc, exec, s[0:1]
	s_cbranch_vccnz .LBB0_1080
	s_add_i32 s0, s9, 0x1000
	s_lshr_b32 s0, s0, 8
	v_readlane_b32 s26, v254, 32
	v_readlane_b32 s27, v254, 33
	s_add_i32 s26, s0, s5
	v_readlane_b32 s56, v252, 41
	s_lshl_b64 s[2:3], s[26:27], 22
	v_readlane_b32 s62, v252, 47
	v_readlane_b32 s63, v252, 48
	s_add_u32 s21, s62, s2
	s_mov_b32 s1, s27
	s_addc_u32 s3, s63, s3
	s_lshl_b64 s[0:1], s[0:1], 21
	v_readlane_b32 s2, v253, 61
	s_add_u32 s0, s2, s0
	v_readlane_b32 s2, v253, 62
	s_addc_u32 s1, s2, s1
	s_and_b32 s26, s10, 0x3c0
	s_add_i32 s2, s12, 0x90000
	s_and_b32 s2, s2, 0x3c0
	s_lshl_b32 s22, s26, 12
	v_or_b32_e32 v2, s2, v20
	s_add_u32 s24, s21, s22
	s_addc_u32 s25, s3, 0
	v_lshlrev_b32_e32 v50, 2, v2
	v_lshl_add_u64 v[2:3], s[24:25], 0, v[50:51]
	s_movk_i32 s3, 0x2000
	v_readlane_b32 s70, v252, 55
	v_add_co_u32_e32 v4, vcc, s3, v2
	s_movk_i32 s70, 0x4000
	s_nop 0
	v_addc_co_u32_e32 v5, vcc, 0, v3, vcc
	global_load_dword v17, v50, s[24:25] nt
	global_load_dword v18, v[4:5], off offset:-4096 nt
	global_load_dword v19, v[4:5], off nt
	v_add_co_u32_e32 v4, vcc, s70, v2
	s_movk_i32 s3, 0x6000
	s_nop 0
	v_addc_co_u32_e32 v5, vcc, 0, v3, vcc
	global_load_dword v41, v[4:5], off offset:-4096 nt
	global_load_dword v42, v[4:5], off nt
	v_add_co_u32_e32 v4, vcc, s3, v2
	s_mov_b32 s3, 0x8000
	s_nop 0
	v_addc_co_u32_e32 v5, vcc, 0, v3, vcc
	global_load_dword v43, v[4:5], off offset:-4096 nt
	global_load_dword v44, v[4:5], off nt
	v_add_co_u32_e32 v4, vcc, s3, v2
	s_mov_b32 s3, 0xa000
	s_nop 0
; __device__ __forceinline__ void transpose_item8(const float* W, int N, unsigned char* WT, int ldt, int item, int lane, int mode, int aux) {
;     const int nblk = (N + 63) >> 6, kb = item / nblk, nb = item - kb * nblk, k0 = 64 * kb, n0 = 64 * nb;
;     const int ncol = n0 + lane;
;     const float* wp = W + (size_t)k0 * N + ncol;
;     float v[64];
; #pragma unroll
;     for (int i = 0; i < 64; ++i) v[i] = wp[(size_t)i * N];
	v_addc_co_u32_e32 v5, vcc, 0, v3, vcc
	global_load_dword v45, v[4:5], off offset:-4096 nt
	global_load_dword v46, v[4:5], off nt
	v_add_co_u32_e32 v4, vcc, s3, v2
	s_mov_b32 s3, 0xc000
	s_nop 0
	v_addc_co_u32_e32 v5, vcc, 0, v3, vcc
	global_load_dword v47, v[4:5], off offset:-4096 nt
	global_load_dword v48, v[4:5], off nt
	v_add_co_u32_e32 v4, vcc, s3, v2
	s_mov_b32 s3, 0xe000
	s_nop 0
	v_addc_co_u32_e32 v5, vcc, 0, v3, vcc
	global_load_dword v49, v[4:5], off offset:-4096 nt
	global_load_dword v50, v[4:5], off nt
	v_add_co_u32_e32 v4, vcc, s3, v2
	s_mov_b32 s3, 0x10000
	s_nop 0
	v_addc_co_u32_e32 v5, vcc, 0, v3, vcc
	global_load_dword v52, v[4:5], off offset:-4096 nt
	global_load_dword v53, v[4:5], off nt
	v_add_co_u32_e32 v4, vcc, s3, v2
	s_mov_b32 s3, 0x12000
	s_nop 0
	v_addc_co_u32_e32 v5, vcc, 0, v3, vcc
	global_load_dword v54, v[4:5], off offset:-4096 nt
	global_load_dword v10, v[4:5], off nt
	v_add_co_u32_e32 v4, vcc, s3, v2
	s_mov_b32 s3, 0x14000
	s_nop 0
	v_addc_co_u32_e32 v5, vcc, 0, v3, vcc
	global_load_dword v55, v[4:5], off offset:-4096 nt
	global_load_dword v56, v[4:5], off nt
	v_add_co_u32_e32 v4, vcc, s3, v2
	s_mov_b32 s3, 0x16000
	s_nop 0
	v_addc_co_u32_e32 v5, vcc, 0, v3, vcc
	global_load_dword v57, v[4:5], off offset:-4096 nt
	global_load_dword v11, v[4:5], off nt
	v_add_co_u32_e32 v4, vcc, s3, v2
	s_mov_b32 s3, 0x18000
	s_nop 0
	v_addc_co_u32_e32 v5, vcc, 0, v3, vcc
	global_load_dword v58, v[4:5], off offset:-4096 nt
	global_load_dword v59, v[4:5], off nt
	v_add_co_u32_e32 v4, vcc, s3, v2
	s_mov_b32 s3, 0x1a000
	s_nop 0
	v_addc_co_u32_e32 v5, vcc, 0, v3, vcc
	global_load_dword v60, v[4:5], off offset:-4096 nt
	global_load_dword v12, v[4:5], off nt
	v_add_co_u32_e32 v4, vcc, s3, v2
	s_mov_b32 s3, 0x1c000
	s_nop 0
	v_addc_co_u32_e32 v5, vcc, 0, v3, vcc
	global_load_dword v61, v[4:5], off offset:-4096 nt
	global_load_dword v62, v[4:5], off nt
	v_add_co_u32_e32 v4, vcc, s3, v2
	s_mov_b32 s3, 0x1e000
	s_nop 0
	v_addc_co_u32_e32 v5, vcc, 0, v3, vcc
	global_load_dword v63, v[4:5], off offset:-4096 nt
	global_load_dword v13, v[4:5], off nt
	v_add_co_u32_e32 v4, vcc, s3, v2
	s_mov_b32 s3, 0x20000
	s_nop 0
	v_addc_co_u32_e32 v5, vcc, 0, v3, vcc
	global_load_dword v64, v[4:5], off offset:-4096 nt
	global_load_dword v65, v[4:5], off nt
	v_add_co_u32_e32 v4, vcc, s3, v2
	s_mov_b32 s3, 0x22000
	s_nop 0
	v_addc_co_u32_e32 v5, vcc, 0, v3, vcc
	global_load_dword v66, v[4:5], off offset:-4096 nt
	global_load_dword v6, v[4:5], off nt
	v_add_co_u32_e32 v4, vcc, s3, v2
	s_mov_b32 s3, 0x24000
	s_nop 0
	v_addc_co_u32_e32 v5, vcc, 0, v3, vcc
	global_load_dword v67, v[4:5], off offset:-4096 nt
	global_load_dword v68, v[4:5], off nt
	v_add_co_u32_e32 v4, vcc, s3, v2
	s_mov_b32 s3, 0x26000
	s_nop 0
	v_addc_co_u32_e32 v5, vcc, 0, v3, vcc
	global_load_dword v69, v[4:5], off offset:-4096 nt
	global_load_dword v7, v[4:5], off nt
	v_add_co_u32_e32 v4, vcc, s3, v2
	s_mov_b32 s3, 0x28000
	s_nop 0
	v_addc_co_u32_e32 v5, vcc, 0, v3, vcc
	global_load_dword v70, v[4:5], off offset:-4096 nt
	global_load_dword v71, v[4:5], off nt
	v_add_co_u32_e32 v4, vcc, s3, v2
	s_mov_b32 s3, 0x2a000
	s_nop 0
	v_addc_co_u32_e32 v5, vcc, 0, v3, vcc
	global_load_dword v72, v[4:5], off offset:-4096 nt
	global_load_dword v8, v[4:5], off nt
	v_add_co_u32_e32 v4, vcc, s3, v2
	s_mov_b32 s3, 0x2c000
	s_nop 0
	v_addc_co_u32_e32 v5, vcc, 0, v3, vcc
	global_load_dword v73, v[4:5], off offset:-4096 nt
	global_load_dword v74, v[4:5], off nt
	v_add_co_u32_e32 v4, vcc, s3, v2
	s_mov_b32 s3, 0x2e000
	s_nop 0
	v_addc_co_u32_e32 v5, vcc, 0, v3, vcc
	global_load_dword v75, v[4:5], off offset:-4096 nt
	global_load_dword v9, v[4:5], off nt
	v_add_co_u32_e32 v4, vcc, s3, v2
	s_mov_b32 s3, 0x30000
	s_nop 0
	v_addc_co_u32_e32 v5, vcc, 0, v3, vcc
	global_load_dword v76, v[4:5], off offset:-4096 nt
	global_load_dword v77, v[4:5], off nt
	v_add_co_u32_e32 v4, vcc, s3, v2
	s_mov_b32 s3, 0x32000
	s_nop 0
	v_addc_co_u32_e32 v5, vcc, 0, v3, vcc
	global_load_dword v79, v[4:5], off offset:-4096 nt
	global_load_dword v80, v[4:5], off nt
	v_add_co_u32_e32 v4, vcc, s3, v2
	s_mov_b32 s3, 0x34000
	s_nop 0
	v_addc_co_u32_e32 v5, vcc, 0, v3, vcc
	global_load_dword v81, v[4:5], off offset:-4096 nt
	global_load_dword v82, v[4:5], off nt
	v_add_co_u32_e32 v4, vcc, s3, v2
	s_mov_b32 s3, 0x36000
	s_nop 0
	v_addc_co_u32_e32 v5, vcc, 0, v3, vcc
	global_load_dword v83, v[4:5], off offset:-4096 nt
	global_load_dword v84, v[4:5], off nt
	v_add_co_u32_e32 v4, vcc, s3, v2
	s_mov_b32 s3, 0x38000
	s_nop 0
	v_addc_co_u32_e32 v5, vcc, 0, v3, vcc
	global_load_dword v85, v[4:5], off offset:-4096 nt
	global_load_dword v86, v[4:5], off nt
	v_add_co_u32_e32 v4, vcc, s3, v2
	s_mov_b32 s3, 0x3a000
	s_nop 0
	v_addc_co_u32_e32 v5, vcc, 0, v3, vcc
	global_load_dword v87, v[4:5], off offset:-4096 nt
	global_load_dword v88, v[4:5], off nt
	v_add_co_u32_e32 v4, vcc, s3, v2
	s_mov_b32 s3, 0x3c000
	s_nop 0
	v_addc_co_u32_e32 v5, vcc, 0, v3, vcc
	global_load_dword v89, v[4:5], off offset:-4096 nt
	global_load_dword v90, v[4:5], off nt
	v_add_co_u32_e32 v4, vcc, s3, v2
	s_mov_b32 s3, 0x3e000
	s_nop 0
	v_addc_co_u32_e32 v5, vcc, 0, v3, vcc
	global_load_dword v91, v[4:5], off offset:-4096 nt
	global_load_dword v92, v[4:5], off nt
	v_add_co_u32_e32 v4, vcc, s3, v2
	s_mov_b32 s3, 0x3f000
	s_nop 0
	v_addc_co_u32_e32 v5, vcc, 0, v3, vcc
	global_load_dword v93, v[4:5], off offset:-4096 nt
	s_nop 0
	global_load_dword v4, v[4:5], off nt
	v_add_co_u32_e32 v2, vcc, s3, v2
	s_and_b32 s3, s16, 0x700
	s_nop 0
	v_addc_co_u32_e32 v3, vcc, 0, v3, vcc
	global_load_dword v2, v[2:3], off nt
	v_bitop3_b32 v3, s2, v237, v20 bitop3:0xc8
	v_or_b32_e32 v78, s3, v3
	s_mov_b32 s2, 0xc3e00000
	s_waitcnt vmcnt(27)
; __device__ __forceinline__ unsigned pk4_fp8(float a, float b, float c, float d) { int w = 0; w = __builtin_amdgcn_cvt_pk_fp8_f32(a, b, w, false); w = __builtin_amdgcn_cvt_pk_fp8_f32(c, d, w, true); return (unsigned)w; }
; __device__ __forceinline__ void transpose_item8(const float* W, int N, unsigned char* WT, int ldt, int item, int lane, int mode, int aux) {
;     ...
;     for (int q = 0; q < 16; ++q) o[q] = pk4_fp8(fminf(fmaxf(v[4 * q] * 64.f, -448.f), 448.f), fminf(fmaxf(v[4 * q + 1] * 64.f, -448.f), 448.f), fminf(fmaxf(v[4 * q + 2] * 64.f, -448.f), 448.f), fminf(fmaxf(v[4 * q + 3] * 64.f, -448.f), 448.f));
	v_mul_f32_e32 v7, 0x42800000, v7
	v_mul_f32_e32 v6, 0x42800000, v6
	v_mul_f32_e32 v13, 0x42800000, v13
	v_mul_f32_e32 v12, 0x42800000, v12
	s_waitcnt vmcnt(23)
	v_mul_f32_e32 v8, 0x42800000, v8
	v_mul_f32_e32 v11, 0x42800000, v11
	v_mul_f32_e32 v10, 0x42800000, v10
	v_mul_f32_e32 v50, 0x42800000, v50
	v_mul_f32_e32 v52, 0x42800000, v52
	v_med3_f32 v50, v50, s2, v236
	v_med3_f32 v52, v52, s2, v236
	v_mul_f32_e32 v53, 0x42800000, v53
	v_mul_f32_e32 v54, 0x42800000, v54
	v_mul_f32_e32 v17, 0x42800000, v17
	v_mul_f32_e32 v18, 0x42800000, v18
	v_med3_f32 v53, v53, s2, v236
	s_waitcnt vmcnt(19)
	v_mul_f32_e32 v9, 0x42800000, v9
	v_med3_f32 v54, v54, s2, v236
	v_mul_f32_e32 v46, 0x42800000, v46
	v_mul_f32_e32 v47, 0x42800000, v47
	v_mul_f32_e32 v42, 0x42800000, v42
	v_mul_f32_e32 v43, 0x42800000, v43
	v_med3_f32 v17, v17, s2, v236
	v_med3_f32 v18, v18, s2, v236
	v_med3_f32 v46, v46, s2, v236
	v_med3_f32 v47, v47, s2, v236
	v_med3_f32 v42, v42, s2, v236
	v_med3_f32 v43, v43, s2, v236
	v_mul_f32_e32 v19, 0x42800000, v19
	v_mul_f32_e32 v41, 0x42800000, v41
	v_mul_f32_e32 v48, 0x42800000, v48
	v_mul_f32_e32 v49, 0x42800000, v49
	v_mul_f32_e32 v44, 0x42800000, v44
	v_mul_f32_e32 v45, 0x42800000, v45
	v_med3_f32 v19, v19, s2, v236
	v_med3_f32 v41, v41, s2, v236
	v_mul_f32_e32 v65, 0x42800000, v65
	v_mul_f32_e32 v66, 0x42800000, v66
	v_mul_f32_e32 v62, 0x42800000, v62
	v_mul_f32_e32 v63, 0x42800000, v63
	v_mul_f32_e32 v59, 0x42800000, v59
	v_mul_f32_e32 v60, 0x42800000, v60
	v_mul_f32_e32 v56, 0x42800000, v56
	v_mul_f32_e32 v57, 0x42800000, v57
	v_med3_f32 v48, v48, s2, v236
	v_med3_f32 v49, v49, s2, v236
	v_med3_f32 v44, v44, s2, v236
	v_med3_f32 v45, v45, s2, v236
	s_waitcnt vmcnt(17)
	v_mul_f32_e32 v77, 0x42800000, v77
	s_waitcnt vmcnt(16)
	v_mul_f32_e32 v79, 0x42800000, v79
	v_mul_f32_e32 v74, 0x42800000, v74
	v_mul_f32_e32 v75, 0x42800000, v75
	v_mul_f32_e32 v71, 0x42800000, v71
	v_mul_f32_e32 v72, 0x42800000, v72
	v_mul_f32_e32 v68, 0x42800000, v68
	v_mul_f32_e32 v69, 0x42800000, v69
	v_med3_f32 v65, v65, s2, v236
	v_med3_f32 v66, v66, s2, v236
	v_med3_f32 v62, v62, s2, v236
	v_med3_f32 v63, v63, s2, v236
	v_med3_f32 v59, v59, s2, v236
	v_med3_f32 v60, v60, s2, v236
	v_med3_f32 v56, v56, s2, v236
	v_med3_f32 v57, v57, s2, v236
	v_readlane_b32 s58, v252, 43
	v_readlane_b32 s59, v252, 44
	v_readlane_b32 s60, v252, 45
	v_readlane_b32 s61, v252, 46
	v_med3_f32 v77, v77, s2, v236
	s_waitcnt vmcnt(2)
	v_mul_f32_e32 v5, 0x42800000, v93
	s_waitcnt vmcnt(1)
	v_mul_f32_e32 v3, 0x42800000, v4
	v_mul_f32_e32 v4, 0x42800000, v92
	v_med3_f32 v4, v4, s2, v236
	v_med3_f32 v92, v5, s2, v236
	v_mov_b32_e32 v5, v51
	v_cvt_pk_fp8_f32 v5, v4, v92
	v_mul_f32_e32 v4, 0x42800000, v88
	v_med3_f32 v88, v4, s2, v236
	v_mul_f32_e32 v4, 0x42800000, v89
	v_med3_f32 v89, v4, s2, v236
	v_mov_b32_e32 v4, v51
	s_waitcnt vmcnt(0)
; __device__ __forceinline__ unsigned pk4_fp8(float a, float b, float c, float d) { int w = 0; w = __builtin_amdgcn_cvt_pk_fp8_f32(a, b, w, false); w = __builtin_amdgcn_cvt_pk_fp8_f32(c, d, w, true); return (unsigned)w; }
; __device__ __forceinline__ void transpose_item8(const float* W, int N, unsigned char* WT, int ldt, int item, int lane, int mode, int aux) {
;     ...
;     for (int q = 0; q < 16; ++q) o[q] = pk4_fp8(fminf(fmaxf(v[4 * q] * 64.f, -448.f), 448.f), fminf(fmaxf(v[4 * q + 1] * 64.f, -448.f), 448.f), fminf(fmaxf(v[4 * q + 2] * 64.f, -448.f), 448.f), fminf(fmaxf(v[4 * q + 3] * 64.f, -448.f), 448.f));
;     v4u* dst = (v4u*)(WT + (size_t)rowmap(mode, aux, ncol) * ldt + k0);
; #pragma unroll
;     for (int q = 0; q < 4; ++q) dst[q] = (v4u){o[4 * q], o[4 * q + 1], o[4 * q + 2], o[4 * q + 3]};
	v_mul_f32_e32 v2, 0x42800000, v2
	v_cvt_pk_fp8_f32 v4, v88, v89
	v_med3_f32 v3, v3, s2, v236
	v_med3_f32 v2, v2, s2, v236
	v_cvt_pk_fp8_f32 v5, v3, v2 op_sel:[0,0,1]
	v_mul_f32_e32 v2, 0x42800000, v90
	v_mul_f32_e32 v3, 0x42800000, v91
	v_med3_f32 v2, v2, s2, v236
	v_med3_f32 v3, v3, s2, v236
	v_cvt_pk_fp8_f32 v4, v2, v3 op_sel:[0,0,1]
	v_mul_f32_e32 v3, 0x42800000, v87
	v_mul_f32_e32 v2, 0x42800000, v86
	v_med3_f32 v86, v3, s2, v236
	v_mul_f32_e32 v3, 0x42800000, v84
	v_med3_f32 v84, v3, s2, v236
	v_mul_f32_e32 v3, 0x42800000, v85
	v_med3_f32 v85, v3, s2, v236
	v_mov_b32_e32 v3, v51
	v_cvt_pk_fp8_f32 v3, v84, v85
	v_med3_f32 v2, v2, s2, v236
	v_med3_f32 v79, v79, s2, v236
	v_med3_f32 v74, v74, s2, v236
	v_cvt_pk_fp8_f32 v3, v2, v86 op_sel:[0,0,1]
	v_mul_f32_e32 v2, 0x42800000, v82
	v_med3_f32 v82, v2, s2, v236
	v_mul_f32_e32 v2, 0x42800000, v83
	v_med3_f32 v83, v2, s2, v236
	v_mul_f32_e32 v2, 0x42800000, v80
	v_med3_f32 v80, v2, s2, v236
	v_mul_f32_e32 v2, 0x42800000, v81
	v_med3_f32 v81, v2, s2, v236
	v_mov_b32_e32 v2, v51
	v_cvt_pk_fp8_f32 v2, v80, v81
	v_med3_f32 v80, v9, s2, v236
	v_mul_f32_e32 v9, 0x42800000, v76
	v_med3_f32 v76, v9, s2, v236
	v_mov_b32_e32 v9, v51
	v_cvt_pk_fp8_f32 v9, v80, v76
	v_med3_f32 v76, v8, s2, v236
	v_mul_f32_e32 v8, 0x42800000, v73
	v_med3_f32 v73, v8, s2, v236
	v_mov_b32_e32 v8, v51
	v_cvt_pk_fp8_f32 v8, v76, v73
	v_med3_f32 v73, v7, s2, v236
	v_mul_f32_e32 v7, 0x42800000, v70
	v_med3_f32 v70, v7, s2, v236
	v_mov_b32_e32 v7, v51
	v_cvt_pk_fp8_f32 v7, v73, v70
	v_med3_f32 v70, v6, s2, v236
	v_mul_f32_e32 v6, 0x42800000, v67
	v_med3_f32 v67, v6, s2, v236
	v_mov_b32_e32 v6, v51
	v_cvt_pk_fp8_f32 v6, v70, v67
	v_med3_f32 v67, v13, s2, v236
	v_mul_f32_e32 v13, 0x42800000, v64
	v_med3_f32 v64, v13, s2, v236
	v_mov_b32_e32 v13, v51
	v_cvt_pk_fp8_f32 v13, v67, v64
	v_med3_f32 v64, v12, s2, v236
	v_mul_f32_e32 v12, 0x42800000, v61
	v_med3_f32 v61, v12, s2, v236
	v_mov_b32_e32 v12, v51
	v_cvt_pk_fp8_f32 v12, v64, v61
	v_med3_f32 v61, v11, s2, v236
	v_mul_f32_e32 v11, 0x42800000, v58
	v_med3_f32 v58, v11, s2, v236
	v_mov_b32_e32 v11, v51
	v_cvt_pk_fp8_f32 v11, v61, v58
	v_med3_f32 v58, v10, s2, v236
	v_mul_f32_e32 v10, 0x42800000, v55
	v_med3_f32 v55, v10, s2, v236
	v_mov_b32_e32 v10, v51
	v_cvt_pk_fp8_f32 v10, v58, v55
	v_mov_b32_e32 v55, v51
	v_cvt_pk_fp8_f32 v55, v50, v52
	v_mov_b32_e32 v52, v51
	v_cvt_pk_fp8_f32 v52, v17, v18
	v_lshlrev_b32_e32 v50, 10, v78
	v_cvt_pk_fp8_f32 v55, v53, v54 op_sel:[0,0,1]
	v_mov_b32_e32 v54, v51
	v_mov_b32_e32 v53, v51
	v_cvt_pk_fp8_f32 v54, v46, v47
	v_cvt_pk_fp8_f32 v53, v42, v43
	v_cvt_pk_fp8_f32 v52, v19, v41 op_sel:[0,0,1]
	v_lshl_add_u64 v[18:19], s[0:1], 0, v[50:51]
	s_mov_b32 s1, s27
	v_cvt_pk_fp8_f32 v54, v48, v49 op_sel:[0,0,1]
	v_cvt_pk_fp8_f32 v53, v44, v45 op_sel:[0,0,1]
	v_writelane_b32 v254, s0, 32
	v_med3_f32 v75, v75, s2, v236
	v_med3_f32 v71, v71, s2, v236
	v_med3_f32 v72, v72, s2, v236
	v_med3_f32 v68, v68, s2, v236
	v_med3_f32 v69, v69, s2, v236
	v_cvt_pk_fp8_f32 v13, v65, v66 op_sel:[0,0,1]
	v_cvt_pk_fp8_f32 v12, v62, v63 op_sel:[0,0,1]
	v_cvt_pk_fp8_f32 v11, v59, v60 op_sel:[0,0,1]
	v_cvt_pk_fp8_f32 v10, v56, v57 op_sel:[0,0,1]
	v_writelane_b32 v254, s1, 33
	v_lshl_add_u64 v[18:19], v[18:19], 0, s[26:27]
	s_mov_b64 s[0:1], 0x20000
	v_readlane_b32 s64, v252, 49
	v_readlane_b32 s68, v252, 53
	v_readlane_b32 s69, v252, 54
	v_readlane_b32 s71, v252, 56
	s_mov_b32 s58, 0x3f6c835e
	v_readlane_b32 s60, v255, 2
	v_cvt_pk_fp8_f32 v9, v77, v79 op_sel:[0,0,1]
	v_cvt_pk_fp8_f32 v8, v74, v75 op_sel:[0,0,1]
	v_cvt_pk_fp8_f32 v7, v71, v72 op_sel:[0,0,1]
	v_cvt_pk_fp8_f32 v6, v68, v69 op_sel:[0,0,1]
	v_lshl_add_u64 v[42:43], v[18:19], 0, s[0:1]
	v_add_co_u32_e32 v18, vcc, 0x20000, v18
	s_movk_i32 s64, 0x440
	s_movk_i32 s68, 0x2200
	s_movk_i32 s71, 0x1ff
	s_mov_b32 s69, 0x7f800000
	s_mov_b32 s59, 0xbec3ef15
	v_readlane_b32 s61, v255, 3
	v_readlane_b32 s62, v255, 4
	s_mov_b32 s63, 0xbf6c835e
	v_cvt_pk_fp8_f32 v2, v82, v83 op_sel:[0,0,1]
	v_addc_co_u32_e32 v19, vcc, 0, v19, vcc
	v_readlane_b32 s57, v252, 42
	v_readlane_b32 s65, v252, 50
	v_readlane_b32 s66, v252, 51
	v_readlane_b32 s67, v252, 52
	global_store_dwordx4 v[18:19], v[52:55], off
	global_store_dwordx4 v[42:43], v[10:13], off offset:16
	global_store_dwordx4 v[42:43], v[6:9], off offset:32
	global_store_dwordx4 v[42:43], v[2:5], off offset:48

; __device__ __forceinline__ void transpose_item8(const float* W, int N, unsigned char* WT, int ldt, int item, int lane, int mode, int aux) {
;     const int nblk = (N + 63) >> 6, kb = item / nblk, nb = item - kb * nblk, k0 = 64 * kb, n0 = 64 * nb;
;     const int ncol = n0 + lane;
;     const float* wp = W + (size_t)k0 * N + ncol;
;     float v[64];
; #pragma unroll
;     for (int i = 0; i < 64; ++i) v[i] = wp[(size_t)i * N];
; __device__ __forceinline__ void convert_rest(const Args& a, LAS unsigned char* lds, int wave, int lane, int gw, int ngw, int l, int it0, int it1) {
;     ...
;         if (r < WI_FF) { const int e = r >> 8; transpose_item8(a.in[I_WFFG] + (size_t)(l * 16 + e) * 1024 * 1024, 1024, ws + WS_WGU + (size_t)e * 2048 * 1024, 1024, r & 255, lane, 3, 0); continue; } r -= WI_FF;
.LBB0_1081:
	s_andn2_b64 vcc, exec, s[0:1]
	s_cbranch_vccnz .LBB0_1083
	s_add_i32 s0, s9, 0x2000
	s_lshr_b32 s0, s0, 8
	v_readlane_b32 s26, v254, 32
	v_readlane_b32 s27, v254, 33
	s_add_i32 s26, s0, s5
	v_readlane_b32 s56, v252, 41
	s_lshl_b64 s[2:3], s[26:27], 22
	v_readlane_b32 s60, v252, 45
	v_readlane_b32 s61, v252, 46
	s_add_u32 s21, s60, s2
	s_mov_b32 s1, s27
	s_addc_u32 s3, s61, s3
	s_lshl_b64 s[0:1], s[0:1], 21
	v_readlane_b32 s2, v253, 61
	s_add_u32 s0, s2, s0
	v_readlane_b32 s2, v253, 62
	s_addc_u32 s1, s2, s1
	s_and_b32 s26, s10, 0x3c0
	s_add_i32 s2, s12, 0x90000
	s_and_b32 s2, s2, 0x3c0
	s_lshl_b32 s22, s26, 12
	v_or_b32_e32 v2, s2, v20
	s_add_u32 s24, s21, s22
	s_addc_u32 s25, s3, 0
	v_lshlrev_b32_e32 v50, 2, v2
	v_lshl_add_u64 v[2:3], s[24:25], 0, v[50:51]
	s_movk_i32 s3, 0x2000
	v_readlane_b32 s70, v252, 55
	v_add_co_u32_e32 v4, vcc, s3, v2
	s_movk_i32 s70, 0x4000
	s_nop 0
	v_addc_co_u32_e32 v5, vcc, 0, v3, vcc
	global_load_dword v17, v50, s[24:25] nt
	global_load_dword v18, v[4:5], off offset:-4096 nt
	global_load_dword v19, v[4:5], off nt
	v_add_co_u32_e32 v4, vcc, s70, v2
	s_movk_i32 s3, 0x6000
	s_nop 0
	v_addc_co_u32_e32 v5, vcc, 0, v3, vcc
	global_load_dword v41, v[4:5], off offset:-4096 nt
	global_load_dword v42, v[4:5], off nt
	v_add_co_u32_e32 v4, vcc, s3, v2
	s_mov_b32 s3, 0x8000
	s_nop 0
	v_addc_co_u32_e32 v5, vcc, 0, v3, vcc
	global_load_dword v43, v[4:5], off offset:-4096 nt
	global_load_dword v44, v[4:5], off nt
	v_add_co_u32_e32 v4, vcc, s3, v2
	s_mov_b32 s3, 0xa000
	s_nop 0
	v_addc_co_u32_e32 v5, vcc, 0, v3, vcc
	global_load_dword v45, v[4:5], off offset:-4096 nt
	global_load_dword v46, v[4:5], off nt
	v_add_co_u32_e32 v4, vcc, s3, v2
	s_mov_b32 s3, 0xc000
	s_nop 0
	v_addc_co_u32_e32 v5, vcc, 0, v3, vcc
	global_load_dword v47, v[4:5], off offset:-4096 nt
	global_load_dword v48, v[4:5], off nt
	v_add_co_u32_e32 v4, vcc, s3, v2
	s_mov_b32 s3, 0xe000
	s_nop 0
	v_addc_co_u32_e32 v5, vcc, 0, v3, vcc
	global_load_dword v49, v[4:5], off offset:-4096 nt
	global_load_dword v50, v[4:5], off nt
	v_add_co_u32_e32 v4, vcc, s3, v2
	s_mov_b32 s3, 0x10000
	s_nop 0
	v_addc_co_u32_e32 v5, vcc, 0, v3, vcc
	global_load_dword v52, v[4:5], off offset:-4096 nt
	global_load_dword v53, v[4:5], off nt
	v_add_co_u32_e32 v4, vcc, s3, v2
	s_mov_b32 s3, 0x12000
	s_nop 0
	v_addc_co_u32_e32 v5, vcc, 0, v3, vcc
	global_load_dword v54, v[4:5], off offset:-4096 nt
	global_load_dword v10, v[4:5], off nt
	v_add_co_u32_e32 v4, vcc, s3, v2
	s_mov_b32 s3, 0x14000
	s_nop 0
	v_addc_co_u32_e32 v5, vcc, 0, v3, vcc
	global_load_dword v55, v[4:5], off offset:-4096 nt
	global_load_dword v56, v[4:5], off nt
	v_add_co_u32_e32 v4, vcc, s3, v2
	s_mov_b32 s3, 0x16000
	s_nop 0
	v_addc_co_u32_e32 v5, vcc, 0, v3, vcc
	global_load_dword v57, v[4:5], off offset:-4096 nt
	global_load_dword v11, v[4:5], off nt
	v_add_co_u32_e32 v4, vcc, s3, v2
	s_mov_b32 s3, 0x18000
	s_nop 0
	v_addc_co_u32_e32 v5, vcc, 0, v3, vcc
	global_load_dword v58, v[4:5], off offset:-4096 nt
	global_load_dword v59, v[4:5], off nt
	v_add_co_u32_e32 v4, vcc, s3, v2
	s_mov_b32 s3, 0x1a000
	s_nop 0
	v_addc_co_u32_e32 v5, vcc, 0, v3, vcc
	global_load_dword v60, v[4:5], off offset:-4096 nt
	global_load_dword v12, v[4:5], off nt
	v_add_co_u32_e32 v4, vcc, s3, v2
	s_mov_b32 s3, 0x1c000
	s_nop 0
	v_addc_co_u32_e32 v5, vcc, 0, v3, vcc
	global_load_dword v61, v[4:5], off offset:-4096 nt
	global_load_dword v62, v[4:5], off nt
	v_add_co_u32_e32 v4, vcc, s3, v2
	s_mov_b32 s3, 0x1e000
	s_nop 0
	v_addc_co_u32_e32 v5, vcc, 0, v3, vcc
	global_load_dword v63, v[4:5], off offset:-4096 nt
	global_load_dword v13, v[4:5], off nt
	v_add_co_u32_e32 v4, vcc, s3, v2
	s_mov_b32 s3, 0x20000
	s_nop 0
	v_addc_co_u32_e32 v5, vcc, 0, v3, vcc
	global_load_dword v64, v[4:5], off offset:-4096 nt
	global_load_dword v65, v[4:5], off nt
	v_add_co_u32_e32 v4, vcc, s3, v2
	s_mov_b32 s3, 0x22000
	s_nop 0
	v_addc_co_u32_e32 v5, vcc, 0, v3, vcc
	global_load_dword v66, v[4:5], off offset:-4096 nt
	global_load_dword v6, v[4:5], off nt
	v_add_co_u32_e32 v4, vcc, s3, v2
	s_mov_b32 s3, 0x24000
	s_nop 0
	v_addc_co_u32_e32 v5, vcc, 0, v3, vcc
	global_load_dword v67, v[4:5], off offset:-4096 nt
	global_load_dword v68, v[4:5], off nt
	v_add_co_u32_e32 v4, vcc, s3, v2
	s_mov_b32 s3, 0x26000
	s_nop 0
	v_addc_co_u32_e32 v5, vcc, 0, v3, vcc
	global_load_dword v69, v[4:5], off offset:-4096 nt
	global_load_dword v7, v[4:5], off nt
	v_add_co_u32_e32 v4, vcc, s3, v2
	s_mov_b32 s3, 0x28000
	s_nop 0
	v_addc_co_u32_e32 v5, vcc, 0, v3, vcc
	global_load_dword v70, v[4:5], off offset:-4096 nt
	global_load_dword v71, v[4:5], off nt
	v_add_co_u32_e32 v4, vcc, s3, v2
	s_mov_b32 s3, 0x2a000
	s_nop 0
	v_addc_co_u32_e32 v5, vcc, 0, v3, vcc
	global_load_dword v72, v[4:5], off offset:-4096 nt
	global_load_dword v8, v[4:5], off nt
	v_add_co_u32_e32 v4, vcc, s3, v2
	s_mov_b32 s3, 0x2c000
	s_nop 0
	v_addc_co_u32_e32 v5, vcc, 0, v3, vcc
	global_load_dword v73, v[4:5], off offset:-4096 nt
	global_load_dword v74, v[4:5], off nt
	v_add_co_u32_e32 v4, vcc, s3, v2
	s_mov_b32 s3, 0x2e000
	s_nop 0
	v_addc_co_u32_e32 v5, vcc, 0, v3, vcc
	global_load_dword v75, v[4:5], off offset:-4096 nt
	global_load_dword v9, v[4:5], off nt
	v_add_co_u32_e32 v4, vcc, s3, v2
	s_mov_b32 s3, 0x30000
	s_nop 0
	v_addc_co_u32_e32 v5, vcc, 0, v3, vcc
	global_load_dword v76, v[4:5], off offset:-4096 nt
	global_load_dword v77, v[4:5], off nt
	v_add_co_u32_e32 v4, vcc, s3, v2
	s_mov_b32 s3, 0x32000
	s_nop 0
	v_addc_co_u32_e32 v5, vcc, 0, v3, vcc
	global_load_dword v79, v[4:5], off offset:-4096 nt
	global_load_dword v80, v[4:5], off nt
	v_add_co_u32_e32 v4, vcc, s3, v2
	s_mov_b32 s3, 0x34000
	s_nop 0
; __device__ __forceinline__ unsigned pk4_fp8(float a, float b, float c, float d) { int w = 0; w = __builtin_amdgcn_cvt_pk_fp8_f32(a, b, w, false); w = __builtin_amdgcn_cvt_pk_fp8_f32(c, d, w, true); return (unsigned)w; }
; __device__ __forceinline__ void transpose_item8(const float* W, int N, unsigned char* WT, int ldt, int item, int lane, int mode, int aux) {
;     ...
;     for (int i = 0; i < 64; ++i) v[i] = wp[(size_t)i * N];
;     unsigned o[16];
; #pragma unroll
;     for (int q = 0; q < 16; ++q) o[q] = pk4_fp8(fminf(fmaxf(v[4 * q] * 64.f, -448.f), 448.f), fminf(fmaxf(v[4 * q + 1] * 64.f, -448.f), 448.f), fminf(fmaxf(v[4 * q + 2] * 64.f, -448.f), 448.f), fminf(fmaxf(v[4 * q + 3] * 64.f, -448.f), 448.f));
	v_addc_co_u32_e32 v5, vcc, 0, v3, vcc
	global_load_dword v81, v[4:5], off offset:-4096 nt
	global_load_dword v82, v[4:5], off nt
	v_add_co_u32_e32 v4, vcc, s3, v2
	s_mov_b32 s3, 0x36000
	s_nop 0
	v_addc_co_u32_e32 v5, vcc, 0, v3, vcc
	global_load_dword v83, v[4:5], off offset:-4096 nt
	global_load_dword v84, v[4:5], off nt
	v_add_co_u32_e32 v4, vcc, s3, v2
	s_mov_b32 s3, 0x38000
	s_nop 0
	v_addc_co_u32_e32 v5, vcc, 0, v3, vcc
	global_load_dword v85, v[4:5], off offset:-4096 nt
	global_load_dword v86, v[4:5], off nt
	v_add_co_u32_e32 v4, vcc, s3, v2
	s_mov_b32 s3, 0x3a000
	s_nop 0
	v_addc_co_u32_e32 v5, vcc, 0, v3, vcc
	global_load_dword v87, v[4:5], off offset:-4096 nt
	global_load_dword v88, v[4:5], off nt
	v_add_co_u32_e32 v4, vcc, s3, v2
	s_mov_b32 s3, 0x3c000
	s_nop 0
	v_addc_co_u32_e32 v5, vcc, 0, v3, vcc
	global_load_dword v89, v[4:5], off offset:-4096 nt
	global_load_dword v90, v[4:5], off nt
	v_add_co_u32_e32 v4, vcc, s3, v2
	s_mov_b32 s3, 0x3e000
	s_nop 0
	v_addc_co_u32_e32 v5, vcc, 0, v3, vcc
	global_load_dword v91, v[4:5], off offset:-4096 nt
	global_load_dword v92, v[4:5], off nt
	v_add_co_u32_e32 v4, vcc, s3, v2
	s_mov_b32 s3, 0x3f000
	s_nop 0
	v_addc_co_u32_e32 v5, vcc, 0, v3, vcc
	global_load_dword v93, v[4:5], off offset:-4096 nt
	s_nop 0
	global_load_dword v4, v[4:5], off nt
	v_add_co_u32_e32 v2, vcc, s3, v2
	s_and_b32 s3, s16, 0x700
	s_nop 0
	v_addc_co_u32_e32 v3, vcc, 0, v3, vcc
	global_load_dword v2, v[2:3], off nt
	v_bitop3_b32 v3, s2, v237, v20 bitop3:0xc8
	v_or_b32_e32 v78, s3, v3
	s_mov_b32 s2, 0xc3e00000
	s_waitcnt vmcnt(27)
	v_mul_f32_e32 v7, 0x42800000, v7
	v_mul_f32_e32 v6, 0x42800000, v6
	v_mul_f32_e32 v13, 0x42800000, v13
	v_mul_f32_e32 v12, 0x42800000, v12
	s_waitcnt vmcnt(23)
	v_mul_f32_e32 v8, 0x42800000, v8
	v_mul_f32_e32 v11, 0x42800000, v11
	v_mul_f32_e32 v10, 0x42800000, v10
	v_mul_f32_e32 v50, 0x42800000, v50
	v_mul_f32_e32 v52, 0x42800000, v52
	v_med3_f32 v50, v50, s2, v236
	v_med3_f32 v52, v52, s2, v236
	v_mul_f32_e32 v53, 0x42800000, v53
	v_mul_f32_e32 v54, 0x42800000, v54
	v_med3_f32 v53, v53, s2, v236
	v_med3_f32 v54, v54, s2, v236
	v_mul_f32_e32 v46, 0x42800000, v46
	s_waitcnt vmcnt(19)
	v_mul_f32_e32 v9, 0x42800000, v9
	v_mul_f32_e32 v47, 0x42800000, v47
	v_mul_f32_e32 v42, 0x42800000, v42
	v_mul_f32_e32 v43, 0x42800000, v43
	v_mul_f32_e32 v17, 0x42800000, v17
	v_mul_f32_e32 v18, 0x42800000, v18
	v_med3_f32 v46, v46, s2, v236
	v_med3_f32 v47, v47, s2, v236
	v_med3_f32 v42, v42, s2, v236
	v_med3_f32 v43, v43, s2, v236
	v_med3_f32 v17, v17, s2, v236
	v_med3_f32 v18, v18, s2, v236
	v_mul_f32_e32 v48, 0x42800000, v48
	v_mul_f32_e32 v49, 0x42800000, v49
	v_mul_f32_e32 v44, 0x42800000, v44
	v_mul_f32_e32 v45, 0x42800000, v45
	v_mul_f32_e32 v19, 0x42800000, v19
	v_mul_f32_e32 v41, 0x42800000, v41
	v_mul_f32_e32 v65, 0x42800000, v65
	v_mul_f32_e32 v66, 0x42800000, v66
	v_mul_f32_e32 v62, 0x42800000, v62
	v_mul_f32_e32 v63, 0x42800000, v63
	v_mul_f32_e32 v59, 0x42800000, v59
	v_mul_f32_e32 v60, 0x42800000, v60
	v_mul_f32_e32 v56, 0x42800000, v56
	v_mul_f32_e32 v57, 0x42800000, v57
	v_med3_f32 v48, v48, s2, v236
	v_med3_f32 v49, v49, s2, v236
	v_med3_f32 v44, v44, s2, v236
	v_med3_f32 v45, v45, s2, v236
	v_med3_f32 v19, v19, s2, v236
	v_med3_f32 v41, v41, s2, v236
	s_waitcnt vmcnt(17)
	v_mul_f32_e32 v77, 0x42800000, v77
	s_waitcnt vmcnt(16)
	v_mul_f32_e32 v79, 0x42800000, v79
	v_mul_f32_e32 v74, 0x42800000, v74
	v_mul_f32_e32 v75, 0x42800000, v75
	v_mul_f32_e32 v71, 0x42800000, v71
	v_mul_f32_e32 v72, 0x42800000, v72
	v_mul_f32_e32 v68, 0x42800000, v68
	v_mul_f32_e32 v69, 0x42800000, v69
	v_med3_f32 v65, v65, s2, v236
	v_med3_f32 v66, v66, s2, v236
	v_med3_f32 v62, v62, s2, v236
	v_med3_f32 v63, v63, s2, v236
	v_med3_f32 v59, v59, s2, v236
	v_med3_f32 v60, v60, s2, v236
	v_med3_f32 v56, v56, s2, v236
	v_med3_f32 v57, v57, s2, v236
	v_readlane_b32 s58, v252, 43
	v_readlane_b32 s59, v252, 44
	v_med3_f32 v77, v77, s2, v236
	v_med3_f32 v79, v79, s2, v236
	v_med3_f32 v74, v74, s2, v236
	s_waitcnt vmcnt(2)
	v_mul_f32_e32 v5, 0x42800000, v93
	s_waitcnt vmcnt(1)
	v_mul_f32_e32 v3, 0x42800000, v4
	v_mul_f32_e32 v4, 0x42800000, v92
	v_med3_f32 v4, v4, s2, v236
	v_med3_f32 v92, v5, s2, v236
	v_mov_b32_e32 v5, v51
	v_cvt_pk_fp8_f32 v5, v4, v92
	v_mul_f32_e32 v4, 0x42800000, v88
	v_med3_f32 v88, v4, s2, v236
	v_mul_f32_e32 v4, 0x42800000, v89
	v_med3_f32 v89, v4, s2, v236
	v_mov_b32_e32 v4, v51
	s_waitcnt vmcnt(0)
; __device__ __forceinline__ unsigned pk4_fp8(float a, float b, float c, float d) { int w = 0; w = __builtin_amdgcn_cvt_pk_fp8_f32(a, b, w, false); w = __builtin_amdgcn_cvt_pk_fp8_f32(c, d, w, true); return (unsigned)w; }
; __device__ __forceinline__ void transpose_item8(const float* W, int N, unsigned char* WT, int ldt, int item, int lane, int mode, int aux) {
;     ...
;     for (int q = 0; q < 16; ++q) o[q] = pk4_fp8(fminf(fmaxf(v[4 * q] * 64.f, -448.f), 448.f), fminf(fmaxf(v[4 * q + 1] * 64.f, -448.f), 448.f), fminf(fmaxf(v[4 * q + 2] * 64.f, -448.f), 448.f), fminf(fmaxf(v[4 * q + 3] * 64.f, -448.f), 448.f));
;     v4u* dst = (v4u*)(WT + (size_t)rowmap(mode, aux, ncol) * ldt + k0);
; #pragma unroll
;     for (int q = 0; q < 4; ++q) dst[q] = (v4u){o[4 * q], o[4 * q + 1], o[4 * q + 2], o[4 * q + 3]};
	v_mul_f32_e32 v2, 0x42800000, v2
	v_cvt_pk_fp8_f32 v4, v88, v89
	v_med3_f32 v3, v3, s2, v236
	v_med3_f32 v2, v2, s2, v236
	v_cvt_pk_fp8_f32 v5, v3, v2 op_sel:[0,0,1]
	v_mul_f32_e32 v2, 0x42800000, v90
	v_mul_f32_e32 v3, 0x42800000, v91
	v_med3_f32 v2, v2, s2, v236
	v_med3_f32 v3, v3, s2, v236
	v_cvt_pk_fp8_f32 v4, v2, v3 op_sel:[0,0,1]
	v_mul_f32_e32 v3, 0x42800000, v87
	v_mul_f32_e32 v2, 0x42800000, v86
	v_med3_f32 v86, v3, s2, v236
	v_mul_f32_e32 v3, 0x42800000, v84
	v_med3_f32 v84, v3, s2, v236
	v_mul_f32_e32 v3, 0x42800000, v85
	v_med3_f32 v85, v3, s2, v236
	v_mov_b32_e32 v3, v51
	v_cvt_pk_fp8_f32 v3, v84, v85
	v_med3_f32 v2, v2, s2, v236
	v_med3_f32 v75, v75, s2, v236
	v_med3_f32 v71, v71, s2, v236
	v_cvt_pk_fp8_f32 v3, v2, v86 op_sel:[0,0,1]
	v_mul_f32_e32 v2, 0x42800000, v82
	v_med3_f32 v82, v2, s2, v236
	v_mul_f32_e32 v2, 0x42800000, v83
	v_med3_f32 v83, v2, s2, v236
	v_mul_f32_e32 v2, 0x42800000, v80
	v_med3_f32 v80, v2, s2, v236
	v_mul_f32_e32 v2, 0x42800000, v81
	v_med3_f32 v81, v2, s2, v236
	v_mov_b32_e32 v2, v51
	v_cvt_pk_fp8_f32 v2, v80, v81
	v_med3_f32 v80, v9, s2, v236
	v_mul_f32_e32 v9, 0x42800000, v76
	v_med3_f32 v76, v9, s2, v236
	v_mov_b32_e32 v9, v51
	v_cvt_pk_fp8_f32 v9, v80, v76
	v_med3_f32 v76, v8, s2, v236
	v_mul_f32_e32 v8, 0x42800000, v73
	v_med3_f32 v73, v8, s2, v236
	v_mov_b32_e32 v8, v51
	v_cvt_pk_fp8_f32 v8, v76, v73
	v_med3_f32 v73, v7, s2, v236
	v_mul_f32_e32 v7, 0x42800000, v70
	v_med3_f32 v70, v7, s2, v236
	v_mov_b32_e32 v7, v51
	v_cvt_pk_fp8_f32 v7, v73, v70
	v_med3_f32 v70, v6, s2, v236
	v_mul_f32_e32 v6, 0x42800000, v67
	v_med3_f32 v67, v6, s2, v236
	v_mov_b32_e32 v6, v51
	v_cvt_pk_fp8_f32 v6, v70, v67
	v_med3_f32 v67, v13, s2, v236
	v_mul_f32_e32 v13, 0x42800000, v64
	v_med3_f32 v64, v13, s2, v236
	v_mov_b32_e32 v13, v51
	v_cvt_pk_fp8_f32 v13, v67, v64
	v_med3_f32 v64, v12, s2, v236
	v_mul_f32_e32 v12, 0x42800000, v61
	v_med3_f32 v61, v12, s2, v236
	v_mov_b32_e32 v12, v51
	v_cvt_pk_fp8_f32 v12, v64, v61
	v_med3_f32 v61, v11, s2, v236
	v_mul_f32_e32 v11, 0x42800000, v58
	v_med3_f32 v58, v11, s2, v236
	v_mov_b32_e32 v11, v51
	v_cvt_pk_fp8_f32 v11, v61, v58
	v_med3_f32 v58, v10, s2, v236
	v_mul_f32_e32 v10, 0x42800000, v55
	v_med3_f32 v55, v10, s2, v236
	v_mov_b32_e32 v10, v51
	v_cvt_pk_fp8_f32 v10, v58, v55
	v_mov_b32_e32 v55, v51
	v_cvt_pk_fp8_f32 v55, v50, v52
	v_mov_b32_e32 v52, v51
	v_cvt_pk_fp8_f32 v52, v17, v18
	v_lshlrev_b32_e32 v50, 10, v78
	v_cvt_pk_fp8_f32 v55, v53, v54 op_sel:[0,0,1]
	v_mov_b32_e32 v54, v51
	v_mov_b32_e32 v53, v51
	v_cvt_pk_fp8_f32 v54, v46, v47
	v_cvt_pk_fp8_f32 v53, v42, v43
	v_cvt_pk_fp8_f32 v52, v19, v41 op_sel:[0,0,1]
	v_med3_f32 v72, v72, s2, v236
	v_cvt_pk_fp8_f32 v54, v48, v49 op_sel:[0,0,1]
	v_cvt_pk_fp8_f32 v53, v44, v45 op_sel:[0,0,1]
	v_med3_f32 v68, v68, s2, v236
	v_med3_f32 v69, v69, s2, v236
	v_cvt_pk_fp8_f32 v13, v65, v66 op_sel:[0,0,1]
	v_cvt_pk_fp8_f32 v12, v62, v63 op_sel:[0,0,1]
	v_cvt_pk_fp8_f32 v11, v59, v60 op_sel:[0,0,1]
	v_cvt_pk_fp8_f32 v10, v56, v57 op_sel:[0,0,1]
	v_lshl_add_u64 v[18:19], s[0:1], 0, v[50:51]
	s_mov_b32 s1, s27
	v_readlane_b32 s62, v252, 47
	v_readlane_b32 s63, v252, 48
	v_readlane_b32 s64, v252, 49
	v_readlane_b32 s68, v252, 53
	v_readlane_b32 s69, v252, 54
	v_readlane_b32 s71, v252, 56
	s_mov_b32 s58, 0x3f6c835e
	v_readlane_b32 s60, v255, 2
	v_cvt_pk_fp8_f32 v9, v77, v79 op_sel:[0,0,1]
	v_cvt_pk_fp8_f32 v8, v74, v75 op_sel:[0,0,1]
	v_cvt_pk_fp8_f32 v7, v71, v72 op_sel:[0,0,1]
	v_cvt_pk_fp8_f32 v6, v68, v69 op_sel:[0,0,1]
	v_writelane_b32 v254, s0, 32
	s_movk_i32 s64, 0x440
	s_mov_b32 s63, 0xbf6c835e
	v_readlane_b32 s62, v255, 4
	s_movk_i32 s68, 0x2200
	s_movk_i32 s71, 0x1ff
	s_mov_b32 s69, 0x7f800000
	s_mov_b32 s59, 0xbec3ef15
	v_readlane_b32 s61, v255, 3
	v_cvt_pk_fp8_f32 v2, v82, v83 op_sel:[0,0,1]
	v_writelane_b32 v254, s1, 33
	v_lshl_add_u64 v[18:19], v[18:19], 0, s[26:27]
	v_readlane_b32 s57, v252, 42
	v_readlane_b32 s65, v252, 50
	v_readlane_b32 s66, v252, 51
	v_readlane_b32 s67, v252, 52
	global_store_dwordx4 v[18:19], v[52:55], off
	global_store_dwordx4 v[18:19], v[10:13], off offset:16
	global_store_dwordx4 v[18:19], v[6:9], off offset:32
	global_store_dwordx4 v[18:19], v[2:5], off offset:48

; #define LAS __attribute__((address_space(3)))
; __device__ __forceinline__ unsigned pk2(float lo, float hi) { return f2bf(lo) | (f2bf(hi) << 16); }
; __device__ __forceinline__ void transpose_item(const float* W, int N, bf16* WT, int ldt, LAS unsigned* scr, int item, int lane, int mode, int aux) {
;     const int nblk = (N + 63) >> 6, kb = item / nblk, nb = item - kb * nblk, k0 = 64 * kb, n0 = 64 * nb;
;     const int ncol = n0 + lane; const bool okc = ncol < N;
;     const float* wp = W + (size_t)k0 * N + (okc ? ncol : 0);
;     float v[64];
; #pragma unroll
;     for (int i = 0; i < 64; ++i) v[i] = wp[(size_t)i * N];
; #pragma unroll
;     for (int i = 0; i < 32; ++i) scr[i * 65 + lane] = okc ? pk2(v[2 * i], v[2 * i + 1]) : 0u;
.LBB0_1084:
	s_andn2_b64 vcc, exec, s[0:1]
	s_cbranch_vccnz .LBB0_1132
	s_lshl_b32 s0, s4, 6
	s_and_b32 s21, s0, 0x3c00
	s_bfe_u32 s23, s17, 0x40004
	s_sub_i32 s0, s12, s21
	v_add_u32_e32 v81, s0, v40
	s_lshl_b32 s0, s23, 18
	s_add_u32 s2, s7, s0
	s_movk_i32 s0, 0x400
	v_cmp_gt_i32_e64 s[0:1], s0, v81
	s_addc_u32 s3, s8, 0
	s_nop 0
	v_cndmask_b32_e64 v2, 0, v81, s[0:1]
	v_ashrrev_i32_e32 v3, 31, v2
	v_lshl_add_u64 v[2:3], v[2:3], 2, s[2:3]
	s_mov_b32 s2, 0xd000
	v_add_co_u32_e32 v4, vcc, s2, v2
	s_mov_b32 s2, 0xf000
	s_nop 0
	v_addc_co_u32_e32 v5, vcc, 0, v3, vcc
	v_add_co_u32_e32 v6, vcc, s2, v2
	s_mov_b32 s2, 0x11000
	s_nop 0
	v_addc_co_u32_e32 v7, vcc, 0, v3, vcc
	v_add_co_u32_e32 v8, vcc, s2, v2
	s_mov_b32 s2, 0x13000
	s_nop 0
	v_addc_co_u32_e32 v9, vcc, 0, v3, vcc
	v_add_co_u32_e32 v10, vcc, s2, v2
	s_mov_b32 s2, 0x15000
	s_nop 0
	v_addc_co_u32_e32 v11, vcc, 0, v3, vcc
	v_add_co_u32_e32 v12, vcc, s2, v2
	s_mov_b32 s2, 0x17000
	s_nop 0
	v_addc_co_u32_e32 v13, vcc, 0, v3, vcc
	v_add_co_u32_e32 v18, vcc, s2, v2
	s_mov_b32 s2, 0x19000
	s_nop 0
	v_addc_co_u32_e32 v19, vcc, 0, v3, vcc
	global_load_dword v76, v[8:9], off offset:-4096 nt
	global_load_dword v75, v[8:9], off nt
	global_load_dword v74, v[10:11], off offset:-4096 nt
	global_load_dword v73, v[10:11], off nt
	global_load_dword v68, v[12:13], off offset:-4096 nt
	global_load_dword v66, v[12:13], off nt
	global_load_dword v67, v[18:19], off offset:-4096 nt
	global_load_dword v65, v[18:19], off nt
	v_add_co_u32_e32 v8, vcc, s2, v2
	s_mov_b32 s2, 0x1b000
	s_nop 0
	v_addc_co_u32_e32 v9, vcc, 0, v3, vcc
	v_add_co_u32_e32 v10, vcc, s2, v2
	s_mov_b32 s2, 0x1d000
	s_nop 0
	v_addc_co_u32_e32 v11, vcc, 0, v3, vcc
	v_add_co_u32_e32 v12, vcc, s2, v2
	s_mov_b32 s2, 0x1f000
	s_nop 0
	v_addc_co_u32_e32 v13, vcc, 0, v3, vcc
	v_add_co_u32_e32 v18, vcc, s2, v2
	s_mov_b32 s2, 0x21000
	s_nop 0
	v_addc_co_u32_e32 v19, vcc, 0, v3, vcc
	global_load_dword v72, v[8:9], off offset:-4096 nt
	global_load_dword v71, v[8:9], off nt
	global_load_dword v70, v[10:11], off offset:-4096 nt
	global_load_dword v69, v[10:11], off nt
	global_load_dword v60, v[12:13], off offset:-4096 nt
	global_load_dword v58, v[12:13], off nt
	global_load_dword v59, v[18:19], off offset:-4096 nt
	global_load_dword v57, v[18:19], off nt
	v_add_co_u32_e32 v8, vcc, s2, v2
	s_mov_b32 s2, 0x23000
	s_nop 0
	v_addc_co_u32_e32 v9, vcc, 0, v3, vcc
	v_add_co_u32_e32 v10, vcc, s2, v2
	s_mov_b32 s2, 0x25000
	s_nop 0
	v_addc_co_u32_e32 v11, vcc, 0, v3, vcc
	v_add_co_u32_e32 v12, vcc, s2, v2
	s_mov_b32 s2, 0x27000
	s_nop 0
	v_addc_co_u32_e32 v13, vcc, 0, v3, vcc
	v_add_co_u32_e32 v18, vcc, s2, v2
	s_mov_b32 s2, 0x29000
	s_nop 0
	v_addc_co_u32_e32 v19, vcc, 0, v3, vcc
	global_load_dword v64, v[8:9], off offset:-4096 nt
	global_load_dword v63, v[8:9], off nt
	global_load_dword v62, v[10:11], off offset:-4096 nt
	global_load_dword v61, v[10:11], off nt
	global_load_dword v52, v[12:13], off offset:-4096 nt
	global_load_dword v49, v[12:13], off nt
	global_load_dword v50, v[18:19], off offset:-4096 nt
	global_load_dword v48, v[18:19], off nt
	v_add_co_u32_e32 v8, vcc, s2, v2
	s_mov_b32 s2, 0x2b000
	s_nop 0
	v_addc_co_u32_e32 v9, vcc, 0, v3, vcc
	v_add_co_u32_e32 v10, vcc, s2, v2
	s_mov_b32 s2, 0x2d000
	s_nop 0
	v_addc_co_u32_e32 v11, vcc, 0, v3, vcc
	v_add_co_u32_e32 v12, vcc, s2, v2
	s_mov_b32 s2, 0x2f000
	s_nop 0
	v_addc_co_u32_e32 v13, vcc, 0, v3, vcc
	v_add_co_u32_e32 v18, vcc, s2, v2
	s_mov_b32 s2, 0x31000
	s_nop 0
	v_addc_co_u32_e32 v19, vcc, 0, v3, vcc
	global_load_dword v56, v[8:9], off offset:-4096 nt
	global_load_dword v55, v[8:9], off nt
	global_load_dword v54, v[10:11], off offset:-4096 nt
	global_load_dword v53, v[10:11], off nt
	global_load_dword v43, v[12:13], off offset:-4096 nt
	global_load_dword v41, v[12:13], off nt
	global_load_dword v42, v[18:19], off offset:-4096 nt
	s_nop 0
	global_load_dword v19, v[18:19], off nt
	v_add_co_u32_e32 v8, vcc, s2, v2
	s_mov_b32 s2, 0x33000
	s_nop 0
	v_addc_co_u32_e32 v9, vcc, 0, v3, vcc
	v_add_co_u32_e32 v10, vcc, s2, v2
	s_mov_b32 s2, 0x35000
	s_nop 0
	v_addc_co_u32_e32 v11, vcc, 0, v3, vcc
	v_add_co_u32_e32 v12, vcc, s2, v2
	s_mov_b32 s2, 0x37000
	s_nop 0
	v_addc_co_u32_e32 v13, vcc, 0, v3, vcc
	v_add_co_u32_e32 v78, vcc, s2, v2
	s_mov_b32 s2, 0x39000
	s_nop 0
	v_addc_co_u32_e32 v79, vcc, 0, v3, vcc
	global_load_dword v47, v[8:9], off offset:-4096 nt
	global_load_dword v46, v[8:9], off nt
	global_load_dword v45, v[10:11], off offset:-4096 nt
	global_load_dword v44, v[10:11], off nt
	s_nop 0
	global_load_dword v11, v[12:13], off offset:-4096 nt
	global_load_dword v9, v[12:13], off nt
	global_load_dword v10, v[78:79], off offset:-4096 nt
	global_load_dword v8, v[78:79], off nt
	v_add_co_u32_e32 v12, vcc, s2, v2
	s_mov_b32 s2, 0x3b000
	s_nop 0
	v_addc_co_u32_e32 v13, vcc, 0, v3, vcc
	v_add_co_u32_e32 v78, vcc, s2, v2
	s_mov_b32 s2, 0x3c000
	s_nop 0
	v_addc_co_u32_e32 v79, vcc, 0, v3, vcc
	v_add_co_u32_e32 v82, vcc, s2, v2
	global_load_dword v17, v[12:13], off offset:-4096 nt
	s_nop 0
	global_load_dword v13, v[12:13], off nt
	s_nop 0
	global_load_dword v18, v[78:79], off offset:-4096 nt
	global_load_dword v12, v[78:79], off nt
	v_addc_co_u32_e32 v83, vcc, 0, v3, vcc
	v_add_co_u32_e32 v84, vcc, 0x3d000, v2
	s_movk_i32 s2, 0x3ff
	s_nop 0
	v_addc_co_u32_e32 v85, vcc, 0, v3, vcc
	v_add_co_u32_e32 v86, vcc, 0x3e000, v2
	v_cmp_lt_i32_e64 s[36:37], s2, v81
	s_nop 0
	v_addc_co_u32_e32 v87, vcc, 0, v3, vcc
	v_add_co_u32_e32 v88, vcc, 0x3f000, v2
	s_nop 1
	v_addc_co_u32_e32 v89, vcc, 0, v3, vcc
	global_load_dword v80, v[4:5], off offset:-4096 nt
	global_load_dword v79, v[4:5], off nt
	global_load_dword v78, v[6:7], off offset:-4096 nt
	global_load_dword v77, v[6:7], off nt
	s_nop 0
	global_load_dword v7, v[82:83], off nt
	global_load_dword v6, v[84:85], off nt
	global_load_dword v5, v[86:87], off nt
	global_load_dword v4, v[88:89], off nt
	s_and_saveexec_b64 s[2:3], s[36:37]
	s_xor_b64 s[2:3], exec, s[2:3]
	s_cbranch_execz .LBB0_1087
	ds_write2_b32 v21, v51, v51 offset1:65
	ds_write2_b32 v21, v51, v51 offset0:130 offset1:195
; __device__ __forceinline__ unsigned pk2(float lo, float hi) { return f2bf(lo) | (f2bf(hi) << 16); }
; __device__ __forceinline__ void transpose_item(const float* W, int N, bf16* WT, int ldt, LAS unsigned* scr, int item, int lane, int mode, int aux) {
;     ...
;     const float* wp = W + (size_t)k0 * N + (okc ? ncol : 0);
;     float v[64];
; #pragma unroll
;     for (int i = 0; i < 64; ++i) v[i] = wp[(size_t)i * N];
; #pragma unroll
;     for (int i = 0; i < 32; ++i) scr[i * 65 + lane] = okc ? pk2(v[2 * i], v[2 * i + 1]) : 0u;
.LBB0_1087:
	s_or_saveexec_b64 s[2:3], s[2:3]
	v_mov_b32_e32 v81, 0
	v_mov_b32_e32 v82, 0
	s_xor_b64 exec, exec, s[2:3]
	s_cbranch_execz .LBB0_1089
	v_add_co_u32_e32 v82, vcc, 0xb000, v2
	s_movk_i32 s22, 0x6000
	s_nop 0
	v_addc_co_u32_e32 v83, vcc, 0, v3, vcc
	global_load_dword v84, v[82:83], off nt
	v_add_co_u32_e32 v82, vcc, 0xa000, v2
	s_movk_i32 s24, 0x7fff
	s_nop 0
	v_addc_co_u32_e32 v83, vcc, 0, v3, vcc
	global_load_dword v85, v[82:83], off nt
	v_add_co_u32_e32 v82, vcc, 0x9000, v2
	s_nop 1
	v_addc_co_u32_e32 v83, vcc, 0, v3, vcc
	global_load_dword v81, v[82:83], off nt
	v_add_co_u32_e32 v82, vcc, 0x8000, v2
	s_nop 1
	v_addc_co_u32_e32 v83, vcc, 0, v3, vcc
	global_load_dword v86, v[82:83], off nt
	v_add_co_u32_e32 v82, vcc, 0x7000, v2
	s_nop 1
	v_addc_co_u32_e32 v83, vcc, 0, v3, vcc
	global_load_dword v87, v[82:83], off nt
	v_add_co_u32_e32 v82, vcc, s22, v2
	s_movk_i32 s22, 0x3000
	s_nop 0
	v_addc_co_u32_e32 v83, vcc, 0, v3, vcc
	global_load_dword v88, v[82:83], off nt
	v_add_co_u32_e32 v82, vcc, 0x5000, v2
	s_nop 1
	v_addc_co_u32_e32 v83, vcc, 0, v3, vcc
	global_load_dword v89, v[82:83], off nt
	v_add_co_u32_e32 v82, vcc, s70, v2
	s_nop 1
	v_addc_co_u32_e32 v83, vcc, 0, v3, vcc
	global_load_dword v90, v[82:83], off nt
	v_add_co_u32_e32 v82, vcc, s22, v2
	s_movk_i32 s22, 0x2000
	s_nop 0
	v_addc_co_u32_e32 v83, vcc, 0, v3, vcc
	global_load_dword v91, v[82:83], off nt
	v_add_co_u32_e32 v82, vcc, s22, v2
	s_movk_i32 s22, 0x1000
	s_nop 0
	v_addc_co_u32_e32 v83, vcc, 0, v3, vcc
	global_load_dword v92, v[82:83], off nt
	v_add_co_u32_e32 v82, vcc, s22, v2
	s_mov_b32 s22, 0xffff0000
	s_nop 0
	v_addc_co_u32_e32 v83, vcc, 0, v3, vcc
	global_load_dword v82, v[82:83], off nt
	s_nop 0
	global_load_dword v2, v[2:3], off nt
	s_waitcnt vmcnt(5)
	v_bfe_u32 v83, v89, 16, 1
	v_add3_u32 v83, v89, v83, s24
	s_waitcnt vmcnt(0)
	v_bfe_u32 v3, v2, 16, 1
	v_add3_u32 v2, v2, v3, s24
	v_bfe_u32 v3, v82, 16, 1
	v_lshrrev_b32_e32 v2, 16, v2
	v_add3_u32 v3, v82, v3, s24
	v_and_or_b32 v2, v3, s22, v2
	v_bfe_u32 v3, v92, 16, 1
	v_add3_u32 v3, v92, v3, s24
	v_bfe_u32 v82, v91, 16, 1
	v_lshrrev_b32_e32 v3, 16, v3
	v_add3_u32 v82, v91, v82, s24
	v_and_or_b32 v3, v82, s22, v3
	v_bfe_u32 v82, v90, 16, 1
	v_add3_u32 v82, v90, v82, s24
	v_lshrrev_b32_e32 v82, 16, v82
	v_and_or_b32 v82, v83, s22, v82
	v_bfe_u32 v83, v88, 16, 1
	v_add3_u32 v83, v88, v83, s24
	v_bfe_u32 v88, v87, 16, 1
	v_lshrrev_b32_e32 v83, 16, v83
	v_add3_u32 v87, v87, v88, s24
	v_and_or_b32 v83, v87, s22, v83
	ds_write2_b32 v21, v2, v3 offset1:65
	ds_write2_b32 v21, v82, v83 offset0:130 offset1:195
	v_bfe_u32 v2, v86, 16, 1
	v_add3_u32 v2, v86, v2, s24
	v_bfe_u32 v3, v81, 16, 1
	v_lshrrev_b32_e32 v2, 16, v2
	v_add3_u32 v3, v81, v3, s24
	v_and_or_b32 v81, v3, s22, v2
	v_bfe_u32 v2, v85, 16, 1
	v_add3_u32 v2, v85, v2, s24
	v_bfe_u32 v3, v84, 16, 1
	v_lshrrev_b32_e32 v2, 16, v2
	v_add3_u32 v3, v84, v3, s24
	v_and_or_b32 v82, v3, s22, v2

; #define LAS __attribute__((address_space(3)))
; __device__ __forceinline__ unsigned pk2(float lo, float hi) { return f2bf(lo) | (f2bf(hi) << 16); }
; __device__ __forceinline__ void transpose_item(const float* W, int N, bf16* WT, int ldt, LAS unsigned* scr, int item, int lane, int mode, int aux) {
;     const int nblk = (N + 63) >> 6, kb = item / nblk, nb = item - kb * nblk, k0 = 64 * kb, n0 = 64 * nb;
;     const int ncol = n0 + lane; const bool okc = ncol < N;
;     const float* wp = W + (size_t)k0 * N + (okc ? ncol : 0);
;     float v[64];
; #pragma unroll
;     for (int i = 0; i < 64; ++i) v[i] = wp[(size_t)i * N];
; #pragma unroll
;     for (int i = 0; i < 32; ++i) scr[i * 65 + lane] = okc ? pk2(v[2 * i], v[2 * i + 1]) : 0u;
.LBB0_1133:
	s_andn2_b64 vcc, exec, s[0:1]
	s_cbranch_vccnz .LBB0_1135
	v_readlane_b32 s2, v254, 32
	s_add_i32 s0, s9, 0x2200
	v_readlane_b32 s3, v254, 33
	s_lshr_b32 s0, s0, 6
	s_mov_b32 s23, s3
	s_add_i32 s22, s0, s6
	s_mov_b32 s1, s23
	s_lshl_b64 s[2:3], s[22:23], 20
	v_writelane_b32 v254, s0, 32
	s_add_u32 s22, s82, s2
	s_addc_u32 s24, s83, s3
	v_writelane_b32 v254, s1, 33
	s_mov_b32 s1, s23
	s_lshl_b64 s[0:1], s[0:1], 19
	v_readlane_b32 s2, v254, 1
	s_add_u32 s3, s2, s0
	v_readlane_b32 s0, v254, 2
	s_addc_u32 s21, s0, s1
	s_and_b32 s23, s10, 0xc0
	s_add_i32 s0, s12, 0x90000
	s_and_b32 s2, s0, 0x3c0
	s_lshl_b32 s0, s23, 12
	v_or_b32_e32 v2, s2, v20
	s_add_u32 s0, s22, s0
	s_addc_u32 s1, s24, 0
	v_lshlrev_b32_e32 v50, 2, v2
	v_lshl_add_u64 v[2:3], s[0:1], 0, v[50:51]
	s_mov_b32 s22, 0x9000
	v_add_co_u32_e32 v6, vcc, s22, v2
	s_mov_b32 s22, 0xb000
	s_nop 0
	v_addc_co_u32_e32 v7, vcc, 0, v3, vcc
	v_add_co_u32_e32 v8, vcc, s22, v2
	s_mov_b32 s22, 0xd000
	s_nop 0
	v_addc_co_u32_e32 v9, vcc, 0, v3, vcc
	v_add_co_u32_e32 v10, vcc, s22, v2
	s_mov_b32 s22, 0xf000
	s_nop 0
	v_addc_co_u32_e32 v11, vcc, 0, v3, vcc
	global_load_dword v5, v[6:7], off offset:-4096 nt
	global_load_dword v4, v[6:7], off nt
	s_nop 0
	global_load_dword v7, v[8:9], off offset:-4096 nt
	global_load_dword v6, v[8:9], off nt
	s_nop 0
	global_load_dword v9, v[10:11], off offset:-4096 nt
	global_load_dword v8, v[10:11], off nt
	v_add_co_u32_e32 v10, vcc, s22, v2
	s_mov_b32 s22, 0x11000
	s_nop 0
	v_addc_co_u32_e32 v11, vcc, 0, v3, vcc
	v_add_co_u32_e32 v18, vcc, s22, v2
	s_mov_b32 s22, 0x13000
	s_nop 0
	v_addc_co_u32_e32 v19, vcc, 0, v3, vcc
	v_add_co_u32_e32 v42, vcc, s22, v2
	s_mov_b32 s22, 0x15000
	s_nop 0
	v_addc_co_u32_e32 v43, vcc, 0, v3, vcc
	global_load_dword v13, v[10:11], off offset:-4096 nt
	s_nop 0
	global_load_dword v11, v[10:11], off nt
	s_nop 0
	global_load_dword v12, v[18:19], off offset:-4096 nt
	global_load_dword v10, v[18:19], off nt
	s_nop 0
	global_load_dword v18, v[42:43], off offset:-4096 nt
	global_load_dword v17, v[42:43], off nt
	v_add_co_u32_e32 v42, vcc, s22, v2
	s_mov_b32 s22, 0x17000
	s_nop 0
	v_addc_co_u32_e32 v43, vcc, 0, v3, vcc
	global_load_dword v41, v[42:43], off offset:-4096 nt
	global_load_dword v19, v[42:43], off nt
	v_add_co_u32_e32 v42, vcc, s22, v2
	s_mov_b32 s22, 0x19000
	s_nop 0
	v_addc_co_u32_e32 v43, vcc, 0, v3, vcc
	v_add_co_u32_e32 v46, vcc, s22, v2
	s_mov_b32 s22, 0x1b000
	s_nop 0
	v_addc_co_u32_e32 v47, vcc, 0, v3, vcc
	v_add_co_u32_e32 v48, vcc, s22, v2
	s_mov_b32 s22, 0x1d000
	s_nop 0
	v_addc_co_u32_e32 v49, vcc, 0, v3, vcc
	v_add_co_u32_e32 v52, vcc, s22, v2
	s_mov_b32 s22, 0x1f000
	s_nop 0
	v_addc_co_u32_e32 v53, vcc, 0, v3, vcc
	global_load_dword v45, v[42:43], off offset:-4096 nt
	s_nop 0
	global_load_dword v43, v[42:43], off nt
	s_nop 0
	global_load_dword v44, v[46:47], off offset:-4096 nt
	global_load_dword v42, v[46:47], off nt
	s_nop 0
	global_load_dword v47, v[48:49], off offset:-4096 nt
	global_load_dword v46, v[48:49], off nt
	s_nop 0
	global_load_dword v49, v[52:53], off offset:-4096 nt
	global_load_dword v48, v[52:53], off nt
	v_add_co_u32_e32 v52, vcc, s22, v2
	s_mov_b32 s22, 0x21000
	s_nop 0
	v_addc_co_u32_e32 v53, vcc, 0, v3, vcc
	global_load_dword v61, v[52:53], off offset:-4096 nt
	global_load_dword v57, v[52:53], off nt
	v_add_co_u32_e32 v52, vcc, s22, v2
	s_mov_b32 s22, 0x23000
	s_nop 0
	v_addc_co_u32_e32 v53, vcc, 0, v3, vcc
	global_load_dword v58, v[52:53], off offset:-4096 nt
	global_load_dword v54, v[52:53], off nt
	v_add_co_u32_e32 v52, vcc, s22, v2
	s_mov_b32 s22, 0x25000
	s_nop 0
	v_addc_co_u32_e32 v53, vcc, 0, v3, vcc
	global_load_dword v69, v[52:53], off offset:-4096 nt
	global_load_dword v66, v[52:53], off nt
	v_add_co_u32_e32 v52, vcc, s22, v2
	s_mov_b32 s22, 0x27000
	s_nop 0
	v_addc_co_u32_e32 v53, vcc, 0, v3, vcc
	global_load_dword v77, v[52:53], off offset:-4096 nt
	global_load_dword v73, v[52:53], off nt
	v_add_co_u32_e32 v52, vcc, s22, v2
	s_mov_b32 s22, 0x29000
	s_nop 0
	v_addc_co_u32_e32 v53, vcc, 0, v3, vcc
	global_load_dword v85, v[52:53], off offset:-4096 nt
	global_load_dword v83, v[52:53], off nt
	v_add_co_u32_e32 v52, vcc, s22, v2
	s_mov_b32 s22, 0x2b000
	s_nop 0
	v_addc_co_u32_e32 v53, vcc, 0, v3, vcc
	global_load_dword v84, v[52:53], off offset:-4096 nt
	global_load_dword v81, v[52:53], off nt
	v_add_co_u32_e32 v52, vcc, s22, v2
	s_mov_b32 s22, 0x2d000
	s_nop 0
	v_addc_co_u32_e32 v53, vcc, 0, v3, vcc
	global_load_dword v82, v[52:53], off offset:-4096 nt
	global_load_dword v80, v[52:53], off nt
	v_add_co_u32_e32 v52, vcc, s22, v2
	s_mov_b32 s22, 0x2f000
	s_nop 0
	v_addc_co_u32_e32 v53, vcc, 0, v3, vcc
	global_load_dword v79, v[52:53], off offset:-4096 nt
	global_load_dword v76, v[52:53], off nt
	v_add_co_u32_e32 v52, vcc, s22, v2
	s_mov_b32 s22, 0x31000
	s_nop 0
	v_addc_co_u32_e32 v53, vcc, 0, v3, vcc
	global_load_dword v78, v[52:53], off offset:-4096 nt
	global_load_dword v74, v[52:53], off nt
	v_add_co_u32_e32 v52, vcc, s22, v2
	s_mov_b32 s22, 0x33000
	s_nop 0
	v_addc_co_u32_e32 v53, vcc, 0, v3, vcc
	global_load_dword v75, v[52:53], off offset:-4096 nt
	global_load_dword v71, v[52:53], off nt
	v_add_co_u32_e32 v52, vcc, s22, v2
	s_mov_b32 s22, 0x35000
	s_nop 0
	v_addc_co_u32_e32 v53, vcc, 0, v3, vcc
	global_load_dword v72, v[52:53], off offset:-4096 nt
	global_load_dword v70, v[52:53], off nt
	v_add_co_u32_e32 v52, vcc, s22, v2
	s_mov_b32 s22, 0x37000
	s_nop 0
	v_addc_co_u32_e32 v53, vcc, 0, v3, vcc
	global_load_dword v68, v[52:53], off offset:-4096 nt
	global_load_dword v65, v[52:53], off nt
	v_add_co_u32_e32 v52, vcc, s22, v2
	s_mov_b32 s22, 0x39000
	s_nop 0
; __device__ __forceinline__ unsigned pk2(float lo, float hi) { return f2bf(lo) | (f2bf(hi) << 16); }
; #define LDS_WAIT() asm volatile("s_waitcnt lgkmcnt(0)" ::: "memory")
; __device__ __forceinline__ void transpose_item(const float* W, int N, bf16* WT, int ldt, LAS unsigned* scr, int item, int lane, int mode, int aux) {
;     ...
;     const float* wp = W + (size_t)k0 * N + (okc ? ncol : 0);
;     float v[64];
; #pragma unroll
;     for (int i = 0; i < 64; ++i) v[i] = wp[(size_t)i * N];
; #pragma unroll
;     for (int i = 0; i < 32; ++i) scr[i * 65 + lane] = okc ? pk2(v[2 * i], v[2 * i + 1]) : 0u;
;     LDS_WAIT();
;     const int c = lane & 7;
; #pragma unroll
;     for (int j = 0; j < 8; ++j) { const int nn = (lane >> 3) + 8 * j, n = n0 + nn;
;         v4u o; o.x = scr[(4 * c + 0) * 65 + nn]; o.y = scr[(4 * c + 1) * 65 + nn]; o.z = scr[(4 * c + 2) * 65 + nn]; o.w = scr[(4 * c + 3) * 65 + nn];
	v_addc_co_u32_e32 v53, vcc, 0, v3, vcc
	global_load_dword v67, v[52:53], off offset:-4096 nt
	global_load_dword v63, v[52:53], off nt
	v_add_co_u32_e32 v52, vcc, s22, v2
	s_mov_b32 s22, 0x3b000
	s_nop 0
	v_addc_co_u32_e32 v53, vcc, 0, v3, vcc
	global_load_dword v64, v[52:53], off offset:-4096 nt
	global_load_dword v60, v[52:53], off nt
	v_add_co_u32_e32 v52, vcc, s22, v2
	s_mov_b32 s22, 0x3d000
	s_nop 0
	v_addc_co_u32_e32 v53, vcc, 0, v3, vcc
	global_load_dword v62, v[52:53], off offset:-4096 nt
	global_load_dword v59, v[52:53], off nt
	v_add_co_u32_e32 v52, vcc, s22, v2
	s_mov_b32 s22, 0x3f000
	s_nop 0
	v_addc_co_u32_e32 v53, vcc, 0, v3, vcc
	v_add_co_u32_e32 v86, vcc, s22, v2
	s_movk_i32 s22, 0x7000
	s_nop 0
	v_addc_co_u32_e32 v87, vcc, 0, v3, vcc
	global_load_dword v56, v[52:53], off offset:-4096 nt
	s_nop 0
	global_load_dword v53, v[52:53], off nt
	s_nop 0
	global_load_dword v55, v[86:87], off offset:-4096 nt
	global_load_dword v52, v[86:87], off nt
	v_add_co_u32_e32 v86, vcc, s22, v2
	s_movk_i32 s22, 0x6000
	s_nop 0
	v_addc_co_u32_e32 v87, vcc, 0, v3, vcc
	global_load_dword v88, v[86:87], off nt
	v_add_co_u32_e32 v86, vcc, s22, v2
	s_movk_i32 s22, 0x3000
	s_nop 0
	v_addc_co_u32_e32 v87, vcc, 0, v3, vcc
	global_load_dword v89, v[86:87], off nt
	v_add_co_u32_e32 v86, vcc, s38, v2
	s_nop 1
	v_addc_co_u32_e32 v87, vcc, 0, v3, vcc
	global_load_dword v90, v[86:87], off nt
	v_add_co_u32_e32 v86, vcc, s70, v2
	s_nop 1
	v_addc_co_u32_e32 v87, vcc, 0, v3, vcc
	global_load_dword v91, v[86:87], off nt
	v_add_co_u32_e32 v86, vcc, s22, v2
	s_movk_i32 s22, 0x2000
	s_nop 0
	v_addc_co_u32_e32 v87, vcc, 0, v3, vcc
	global_load_dword v92, v[86:87], off nt
	v_add_co_u32_e32 v86, vcc, s22, v2
	s_movk_i32 s22, 0x1000
	s_nop 0
	v_addc_co_u32_e32 v87, vcc, 0, v3, vcc
	v_add_co_u32_e32 v2, vcc, s22, v2
	global_load_dword v86, v[86:87], off nt
	s_nop 0
	v_addc_co_u32_e32 v3, vcc, 0, v3, vcc
	global_load_dword v2, v[2:3], off nt
	s_nop 0
	global_load_dword v3, v50, s[0:1] nt
	s_movk_i32 s1, 0x7fff
	s_mov_b32 s0, 0xffff0000
	s_waitcnt vmcnt(0)
	v_bfe_u32 v50, v3, 16, 1
	v_add3_u32 v3, v3, v50, s1
	v_bfe_u32 v50, v2, 16, 1
	v_lshrrev_b32_e32 v3, 16, v3
	v_add3_u32 v2, v2, v50, s1
	v_and_or_b32 v2, v2, s0, v3
	v_bfe_u32 v3, v86, 16, 1
	v_add3_u32 v3, v86, v3, s1
	v_bfe_u32 v50, v92, 16, 1
	v_lshrrev_b32_e32 v3, 16, v3
	v_add3_u32 v50, v92, v50, s1
	v_and_or_b32 v3, v50, s0, v3
	ds_write2_b32 v21, v2, v3 offset1:65
	v_bfe_u32 v2, v91, 16, 1
	v_add3_u32 v2, v91, v2, s1
	v_bfe_u32 v3, v90, 16, 1
	v_lshrrev_b32_e32 v2, 16, v2
	v_add3_u32 v3, v90, v3, s1
	v_and_or_b32 v2, v3, s0, v2
	v_bfe_u32 v3, v89, 16, 1
	v_add3_u32 v3, v89, v3, s1
	v_bfe_u32 v50, v88, 16, 1
	v_lshrrev_b32_e32 v3, 16, v3
	v_add3_u32 v50, v88, v50, s1
	v_and_or_b32 v3, v50, s0, v3
	ds_write2_b32 v21, v2, v3 offset0:130 offset1:195
	v_bfe_u32 v2, v5, 16, 1
	v_add3_u32 v2, v5, v2, s1
	v_bfe_u32 v3, v4, 16, 1
	v_lshrrev_b32_e32 v2, 16, v2
	v_add3_u32 v3, v4, v3, s1
	v_and_or_b32 v2, v3, s0, v2
	v_bfe_u32 v3, v7, 16, 1
	v_add3_u32 v3, v7, v3, s1
	v_bfe_u32 v4, v6, 16, 1
	v_lshrrev_b32_e32 v3, 16, v3
	v_add3_u32 v4, v6, v4, s1
	v_and_or_b32 v3, v4, s0, v3
	v_add_u32_e32 v4, 0x400, v21
	ds_write2_b32 v4, v2, v3 offset0:4 offset1:69
	v_bfe_u32 v2, v9, 16, 1
	v_add3_u32 v2, v9, v2, s1
	v_bfe_u32 v3, v8, 16, 1
	v_lshrrev_b32_e32 v2, 16, v2
	v_add3_u32 v3, v8, v3, s1
	v_and_or_b32 v2, v3, s0, v2
	v_bfe_u32 v3, v13, 16, 1
	v_add3_u32 v3, v13, v3, s1
	v_bfe_u32 v5, v11, 16, 1
	v_lshrrev_b32_e32 v3, 16, v3
	v_add3_u32 v5, v11, v5, s1
	v_and_or_b32 v3, v5, s0, v3
	ds_write2_b32 v4, v2, v3 offset0:134 offset1:199
	v_bfe_u32 v2, v12, 16, 1
	v_add3_u32 v2, v12, v2, s1
	v_bfe_u32 v3, v10, 16, 1
	v_lshrrev_b32_e32 v2, 16, v2
	v_add3_u32 v3, v10, v3, s1
	v_and_or_b32 v2, v3, s0, v2
	v_bfe_u32 v3, v18, 16, 1
	v_add3_u32 v3, v18, v3, s1
	v_bfe_u32 v4, v17, 16, 1
	v_lshrrev_b32_e32 v3, 16, v3
	v_add3_u32 v4, v17, v4, s1
	v_and_or_b32 v3, v4, s0, v3
	v_add_u32_e32 v4, 0x800, v21
	ds_write2_b32 v4, v2, v3 offset0:8 offset1:73
	v_bfe_u32 v2, v41, 16, 1
	v_add3_u32 v2, v41, v2, s1
	v_bfe_u32 v3, v19, 16, 1
	v_lshrrev_b32_e32 v2, 16, v2
	v_add3_u32 v3, v19, v3, s1
	v_and_or_b32 v2, v3, s0, v2
	v_bfe_u32 v3, v45, 16, 1
	v_add3_u32 v3, v45, v3, s1
	v_bfe_u32 v5, v43, 16, 1
	v_lshrrev_b32_e32 v3, 16, v3
	v_add3_u32 v5, v43, v5, s1
	v_and_or_b32 v3, v5, s0, v3
	ds_write2_b32 v4, v2, v3 offset0:138 offset1:203
	v_bfe_u32 v2, v44, 16, 1
	v_add3_u32 v2, v44, v2, s1
	v_bfe_u32 v3, v42, 16, 1
	v_lshrrev_b32_e32 v2, 16, v2
	v_add3_u32 v3, v42, v3, s1
	v_and_or_b32 v2, v3, s0, v2
	v_bfe_u32 v3, v47, 16, 1
	v_add3_u32 v3, v47, v3, s1
	v_bfe_u32 v4, v46, 16, 1
	v_lshrrev_b32_e32 v3, 16, v3
	v_add3_u32 v4, v46, v4, s1
	v_and_or_b32 v3, v4, s0, v3
	v_add_u32_e32 v4, 0xc00, v21
	ds_write2_b32 v4, v2, v3 offset0:12 offset1:77
	v_bfe_u32 v2, v49, 16, 1
	v_add3_u32 v2, v49, v2, s1
	v_bfe_u32 v3, v48, 16, 1
	v_lshrrev_b32_e32 v2, 16, v2
	v_add3_u32 v3, v48, v3, s1
	v_and_or_b32 v2, v3, s0, v2
	v_bfe_u32 v3, v61, 16, 1
	v_add3_u32 v3, v61, v3, s1
	v_bfe_u32 v5, v57, 16, 1
	v_lshrrev_b32_e32 v3, 16, v3
	v_add3_u32 v5, v57, v5, s1
	v_and_or_b32 v3, v5, s0, v3
	ds_write2_b32 v4, v2, v3 offset0:142 offset1:207
	v_bfe_u32 v2, v58, 16, 1
	v_add3_u32 v2, v58, v2, s1
	v_bfe_u32 v3, v54, 16, 1
	v_lshrrev_b32_e32 v2, 16, v2
	v_add3_u32 v3, v54, v3, s1
	v_and_or_b32 v2, v3, s0, v2
	v_bfe_u32 v3, v69, 16, 1
	v_add3_u32 v3, v69, v3, s1
	v_bfe_u32 v4, v66, 16, 1
	v_lshrrev_b32_e32 v3, 16, v3
	v_add3_u32 v4, v66, v4, s1
	v_and_or_b32 v3, v4, s0, v3
	v_add_u32_e32 v4, 0x1000, v21
	ds_write2_b32 v4, v2, v3 offset0:16 offset1:81
	v_bfe_u32 v2, v77, 16, 1
; __device__ __forceinline__ unsigned pk2(float lo, float hi) { return f2bf(lo) | (f2bf(hi) << 16); }
; #define LDS_WAIT() asm volatile("s_waitcnt lgkmcnt(0)" ::: "memory")
; __device__ __forceinline__ void transpose_item(const float* W, int N, bf16* WT, int ldt, LAS unsigned* scr, int item, int lane, int mode, int aux) {
;     ...
;     for (int i = 0; i < 32; ++i) scr[i * 65 + lane] = okc ? pk2(v[2 * i], v[2 * i + 1]) : 0u;
;     LDS_WAIT();
;     const int c = lane & 7;
; #pragma unroll
;     for (int j = 0; j < 8; ++j) { const int nn = (lane >> 3) + 8 * j, n = n0 + nn;
;         v4u o; o.x = scr[(4 * c + 0) * 65 + nn]; o.y = scr[(4 * c + 1) * 65 + nn]; o.z = scr[(4 * c + 2) * 65 + nn]; o.w = scr[(4 * c + 3) * 65 + nn];
;         if (n < N) *(v4u*)(WT + (size_t)rowmap(mode, aux, n) * ldt + k0 + 8 * c) = o; }
;     LDS_WAIT();
	v_add3_u32 v2, v77, v2, s1
	v_bfe_u32 v3, v73, 16, 1
	v_lshrrev_b32_e32 v2, 16, v2
	v_add3_u32 v3, v73, v3, s1
	v_and_or_b32 v2, v3, s0, v2
	v_bfe_u32 v3, v85, 16, 1
	v_add3_u32 v3, v85, v3, s1
	v_bfe_u32 v5, v83, 16, 1
	v_lshrrev_b32_e32 v3, 16, v3
	v_add3_u32 v5, v83, v5, s1
	v_and_or_b32 v3, v5, s0, v3
	ds_write2_b32 v4, v2, v3 offset0:146 offset1:211
	v_bfe_u32 v2, v84, 16, 1
	v_add3_u32 v2, v84, v2, s1
	v_bfe_u32 v3, v81, 16, 1
	v_lshrrev_b32_e32 v2, 16, v2
	v_add3_u32 v3, v81, v3, s1
	v_and_or_b32 v2, v3, s0, v2
	v_bfe_u32 v3, v82, 16, 1
	v_add3_u32 v3, v82, v3, s1
	v_bfe_u32 v4, v80, 16, 1
	v_lshrrev_b32_e32 v3, 16, v3
	v_add3_u32 v4, v80, v4, s1
	v_and_or_b32 v3, v4, s0, v3
	v_add_u32_e32 v4, 0x1400, v21
	ds_write2_b32 v4, v2, v3 offset0:20 offset1:85
	v_bfe_u32 v2, v79, 16, 1
	v_add3_u32 v2, v79, v2, s1
	v_bfe_u32 v3, v76, 16, 1
	v_lshrrev_b32_e32 v2, 16, v2
	v_add3_u32 v3, v76, v3, s1
	v_and_or_b32 v2, v3, s0, v2
	v_bfe_u32 v3, v78, 16, 1
	v_add3_u32 v3, v78, v3, s1
	v_bfe_u32 v5, v74, 16, 1
	v_lshrrev_b32_e32 v3, 16, v3
	v_add3_u32 v5, v74, v5, s1
	v_and_or_b32 v3, v5, s0, v3
	ds_write2_b32 v4, v2, v3 offset0:150 offset1:215
	v_bfe_u32 v2, v75, 16, 1
	v_add3_u32 v2, v75, v2, s1
	v_bfe_u32 v3, v71, 16, 1
	v_lshrrev_b32_e32 v2, 16, v2
	v_add3_u32 v3, v71, v3, s1
	v_and_or_b32 v2, v3, s0, v2
	v_bfe_u32 v3, v72, 16, 1
	v_add3_u32 v3, v72, v3, s1
	v_bfe_u32 v4, v70, 16, 1
	v_lshrrev_b32_e32 v3, 16, v3
	v_add3_u32 v4, v70, v4, s1
	v_and_or_b32 v3, v4, s0, v3
	v_add_u32_e32 v4, 0x1800, v21
	ds_write2_b32 v4, v2, v3 offset0:24 offset1:89
	v_bfe_u32 v2, v68, 16, 1
	v_add3_u32 v2, v68, v2, s1
	v_bfe_u32 v3, v65, 16, 1
	v_lshrrev_b32_e32 v2, 16, v2
	v_add3_u32 v3, v65, v3, s1
	v_and_or_b32 v2, v3, s0, v2
	v_bfe_u32 v3, v67, 16, 1
	v_add3_u32 v3, v67, v3, s1
	v_bfe_u32 v5, v63, 16, 1
	v_lshrrev_b32_e32 v3, 16, v3
	v_add3_u32 v5, v63, v5, s1
	v_and_or_b32 v3, v5, s0, v3
	ds_write2_b32 v4, v2, v3 offset0:154 offset1:219
	v_bfe_u32 v2, v64, 16, 1
	v_add3_u32 v2, v64, v2, s1
	v_bfe_u32 v3, v60, 16, 1
	v_lshrrev_b32_e32 v2, 16, v2
	v_add3_u32 v3, v60, v3, s1
	v_and_or_b32 v2, v3, s0, v2
	v_bfe_u32 v3, v62, 16, 1
	v_add3_u32 v3, v62, v3, s1
	v_bfe_u32 v4, v59, 16, 1
	v_lshrrev_b32_e32 v3, 16, v3
	v_add3_u32 v4, v59, v4, s1
	v_and_or_b32 v3, v4, s0, v3
	v_add_u32_e32 v4, 0x1c00, v21
	ds_write2_b32 v4, v2, v3 offset0:28 offset1:93
	v_bfe_u32 v2, v56, 16, 1
	v_add3_u32 v2, v56, v2, s1
	v_bfe_u32 v3, v53, 16, 1
	v_lshrrev_b32_e32 v2, 16, v2
	v_add3_u32 v3, v53, v3, s1
	v_and_or_b32 v2, v3, s0, v2
	v_bfe_u32 v3, v55, 16, 1
	v_add3_u32 v3, v55, v3, s1
	v_bfe_u32 v5, v52, 16, 1
	v_lshrrev_b32_e32 v3, 16, v3
	v_add3_u32 v5, v52, v5, s1
	v_and_or_b32 v3, v5, s0, v3
	ds_write2_b32 v4, v2, v3 offset0:158 offset1:223
	s_waitcnt lgkmcnt(0)
	s_lshl_b32 s0, s23, 1
	ds_read2_b32 v[2:3], v23 offset0:65 offset1:73
	ds_read2_b32 v[12:13], v23 offset0:130 offset1:138
	ds_read2_b32 v[4:5], v23 offset0:195 offset1:203
	ds_read2_b32 v[18:19], v23 offset1:8
	s_add_u32 s0, s3, s0
	s_addc_u32 s1, s21, 0
	v_mov_b32_e32 v17, v51
	v_lshl_add_u64 v[10:11], s[0:1], 0, v[16:17]
	v_or_b32_e32 v17, s2, v22
	v_lshlrev_b32_e32 v50, 9, v17
	s_waitcnt lgkmcnt(0)
	v_mov_b32_e32 v6, v18
	v_mov_b32_e32 v7, v2
	v_mov_b32_e32 v8, v12
	v_mov_b32_e32 v9, v4
	v_lshl_add_u64 v[42:43], v[10:11], 0, v[50:51]
	global_store_dwordx4 v[42:43], v[6:9], off
	v_mov_b32_e32 v2, v19
	v_mov_b32_e32 v4, v13
	v_or_b32_e32 v6, s2, v24
	v_lshlrev_b32_e32 v50, 9, v6
	v_lshl_add_u64 v[6:7], v[10:11], 0, v[50:51]
	global_store_dwordx4 v[6:7], v[2:5], off
	ds_read2_b32 v[12:13], v23 offset0:16 offset1:24
	ds_read2_b32 v[2:3], v23 offset0:81 offset1:89
	ds_read2_b32 v[18:19], v23 offset0:146 offset1:154
	ds_read2_b32 v[4:5], v23 offset0:211 offset1:219
	v_or_b32_e32 v17, s2, v25
	v_lshlrev_b32_e32 v50, 9, v17
	s_waitcnt lgkmcnt(3)
	v_mov_b32_e32 v6, v12
	s_waitcnt lgkmcnt(2)
	v_mov_b32_e32 v7, v2
	s_waitcnt lgkmcnt(1)
	v_mov_b32_e32 v8, v18
	s_waitcnt lgkmcnt(0)
	v_mov_b32_e32 v9, v4
	v_lshl_add_u64 v[42:43], v[10:11], 0, v[50:51]
	global_store_dwordx4 v[42:43], v[6:9], off
	v_mov_b32_e32 v2, v13
	v_mov_b32_e32 v4, v19
	v_or_b32_e32 v6, s2, v26
	v_lshlrev_b32_e32 v50, 9, v6
	v_lshl_add_u64 v[6:7], v[10:11], 0, v[50:51]
	global_store_dwordx4 v[6:7], v[2:5], off
	ds_read2_b32 v[2:3], v23 offset0:97 offset1:105
	ds_read2_b32 v[12:13], v23 offset0:162 offset1:170
	ds_read2_b32 v[4:5], v23 offset0:227 offset1:235
	ds_read2_b32 v[18:19], v23 offset0:32 offset1:40
	v_or_b32_e32 v17, s2, v27
	v_lshlrev_b32_e32 v50, 9, v17
	s_waitcnt lgkmcnt(3)
	v_mov_b32_e32 v7, v2
	s_waitcnt lgkmcnt(2)
	v_mov_b32_e32 v8, v12
	s_waitcnt lgkmcnt(0)
	v_mov_b32_e32 v6, v18
	v_mov_b32_e32 v9, v4
	v_lshl_add_u64 v[42:43], v[10:11], 0, v[50:51]
	global_store_dwordx4 v[42:43], v[6:9], off
	v_mov_b32_e32 v2, v19
	v_mov_b32_e32 v4, v13
	v_or_b32_e32 v6, s2, v28
	v_lshlrev_b32_e32 v50, 9, v6
	v_lshl_add_u64 v[6:7], v[10:11], 0, v[50:51]
	global_store_dwordx4 v[6:7], v[2:5], off
	ds_read2_b32 v[12:13], v23 offset0:48 offset1:56
	ds_read2_b32 v[2:3], v23 offset0:113 offset1:121
	ds_read2_b32 v[18:19], v23 offset0:178 offset1:186
	ds_read2_b32 v[4:5], v23 offset0:243 offset1:251
	v_or_b32_e32 v17, s2, v29
	v_lshlrev_b32_e32 v50, 9, v17
	s_waitcnt lgkmcnt(3)
	v_mov_b32_e32 v6, v12
	s_waitcnt lgkmcnt(2)
	v_mov_b32_e32 v7, v2
	s_waitcnt lgkmcnt(1)
	v_mov_b32_e32 v8, v18
	s_waitcnt lgkmcnt(0)
	v_mov_b32_e32 v9, v4
	v_lshl_add_u64 v[42:43], v[10:11], 0, v[50:51]
	global_store_dwordx4 v[42:43], v[6:9], off
	v_mov_b32_e32 v2, v13
	v_mov_b32_e32 v4, v19
	v_or_b32_e32 v6, s2, v30
	v_lshlrev_b32_e32 v50, 9, v6
	v_lshl_add_u64 v[6:7], v[10:11], 0, v[50:51]
	global_store_dwordx4 v[6:7], v[2:5], off
	s_waitcnt lgkmcnt(0)

; __device__ __forceinline__ unsigned pk4_fp8(float a, float b, float c, float d) { int w = 0; w = __builtin_amdgcn_cvt_pk_fp8_f32(a, b, w, false); w = __builtin_amdgcn_cvt_pk_fp8_f32(c, d, w, true); return (unsigned)w; }
; __device__ __forceinline__ void transpose_item8(const float* W, int N, unsigned char* WT, int ldt, int item, int lane, int mode, int aux) {
;     const int nblk = (N + 63) >> 6, kb = item / nblk, nb = item - kb * nblk, k0 = 64 * kb, n0 = 64 * nb;
;     const int ncol = n0 + lane;
;     const float* wp = W + (size_t)k0 * N + ncol;
;     float v[64];
; #pragma unroll
;     for (int i = 0; i < 64; ++i) v[i] = wp[(size_t)i * N];
;     unsigned o[16];
; #pragma unroll
;     for (int q = 0; q < 16; ++q) o[q] = pk4_fp8(fminf(fmaxf(v[4 * q] * 64.f, -448.f), 448.f), fminf(fmaxf(v[4 * q + 1] * 64.f, -448.f), 448.f), fminf(fmaxf(v[4 * q + 2] * 64.f, -448.f), 448.f), fminf(fmaxf(v[4 * q + 3] * 64.f, -448.f), 448.f));
.LBB0_1136:
	s_andn2_b64 vcc, exec, s[0:1]
	s_cbranch_vccnz .LBB0_1071
	s_ashr_i32 s0, s17, 8
	s_add_i32 s2, s0, s6
	s_ashr_i32 s3, s2, 31
	s_lshl_b64 s[2:3], s[2:3], 22
	s_add_u32 s2, s78, s2
	s_addc_u32 s3, s79, s3
	s_lshl_b32 s1, s17, 2
	v_readlane_b32 s22, v254, 32
	s_and_b32 s22, s1, 0x3c0
	s_lshl_b32 s1, s17, 6
	s_and_b32 s1, s1, 0x3c0
	s_lshl_b32 s17, s22, 12
	v_or_b32_e32 v2, s1, v20
	s_add_u32 s2, s2, s17
	s_addc_u32 s3, s3, 0
	v_lshlrev_b32_e32 v50, 2, v2
	v_lshl_add_u64 v[2:3], s[2:3], 0, v[50:51]
	global_load_dword v17, v50, s[2:3] nt
	s_movk_i32 s2, 0x2000
	v_add_co_u32_e32 v4, vcc, s2, v2
	s_movk_i32 s2, 0x6000
	s_nop 0
	v_addc_co_u32_e32 v5, vcc, 0, v3, vcc
	global_load_dword v19, v[4:5], off offset:-4096 nt
	global_load_dword v41, v[4:5], off nt
	v_add_co_u32_e32 v4, vcc, s70, v2
	s_lshl_b32 s1, s1, 2
	s_nop 0
	v_addc_co_u32_e32 v5, vcc, 0, v3, vcc
	global_load_dword v42, v[4:5], off offset:-4096 nt
	global_load_dword v43, v[4:5], off nt
	v_add_co_u32_e32 v4, vcc, s2, v2
	s_mov_b32 s2, 0x8000
	s_nop 0
	v_addc_co_u32_e32 v5, vcc, 0, v3, vcc
	global_load_dword v44, v[4:5], off offset:-4096 nt
	global_load_dword v45, v[4:5], off nt
	v_add_co_u32_e32 v4, vcc, s2, v2
	s_mov_b32 s2, 0xa000
	s_nop 0
	v_addc_co_u32_e32 v5, vcc, 0, v3, vcc
	global_load_dword v46, v[4:5], off offset:-4096 nt
	global_load_dword v47, v[4:5], off nt
	v_add_co_u32_e32 v4, vcc, s2, v2
	s_mov_b32 s2, 0xc000
	s_nop 0
	v_addc_co_u32_e32 v5, vcc, 0, v3, vcc
	global_load_dword v48, v[4:5], off offset:-4096 nt
	global_load_dword v49, v[4:5], off nt
	v_add_co_u32_e32 v4, vcc, s2, v2
	s_mov_b32 s2, 0xe000
	s_nop 0
	v_addc_co_u32_e32 v5, vcc, 0, v3, vcc
	global_load_dword v50, v[4:5], off offset:-4096 nt
	global_load_dword v52, v[4:5], off nt
	v_add_co_u32_e32 v4, vcc, s2, v2
	s_mov_b32 s2, 0x10000
	s_nop 0
	v_addc_co_u32_e32 v5, vcc, 0, v3, vcc
	global_load_dword v53, v[4:5], off offset:-4096 nt
	global_load_dword v54, v[4:5], off nt
	v_add_co_u32_e32 v4, vcc, s2, v2
	s_mov_b32 s2, 0x12000
	s_nop 0
	v_addc_co_u32_e32 v5, vcc, 0, v3, vcc
	global_load_dword v55, v[4:5], off offset:-4096 nt
	global_load_dword v10, v[4:5], off nt
	v_add_co_u32_e32 v4, vcc, s2, v2
	s_mov_b32 s2, 0x14000
	s_nop 0
	v_addc_co_u32_e32 v5, vcc, 0, v3, vcc
	global_load_dword v56, v[4:5], off offset:-4096 nt
	global_load_dword v57, v[4:5], off nt
	v_add_co_u32_e32 v4, vcc, s2, v2
	s_mov_b32 s2, 0x16000
	s_nop 0
	v_addc_co_u32_e32 v5, vcc, 0, v3, vcc
	global_load_dword v58, v[4:5], off offset:-4096 nt
	global_load_dword v11, v[4:5], off nt
	v_add_co_u32_e32 v4, vcc, s2, v2
	s_mov_b32 s2, 0x18000
	s_nop 0
	v_addc_co_u32_e32 v5, vcc, 0, v3, vcc
	global_load_dword v59, v[4:5], off offset:-4096 nt
	global_load_dword v60, v[4:5], off nt
	v_add_co_u32_e32 v4, vcc, s2, v2
	s_mov_b32 s2, 0x1a000
	s_nop 0
	v_addc_co_u32_e32 v5, vcc, 0, v3, vcc
	global_load_dword v61, v[4:5], off offset:-4096 nt
	global_load_dword v12, v[4:5], off nt
	v_add_co_u32_e32 v4, vcc, s2, v2
	s_mov_b32 s2, 0x1c000
	s_nop 0
	v_addc_co_u32_e32 v5, vcc, 0, v3, vcc
	global_load_dword v62, v[4:5], off offset:-4096 nt
	global_load_dword v63, v[4:5], off nt
	v_add_co_u32_e32 v4, vcc, s2, v2
	s_mov_b32 s2, 0x1e000
	s_nop 0
	v_addc_co_u32_e32 v5, vcc, 0, v3, vcc
	global_load_dword v64, v[4:5], off offset:-4096 nt
	global_load_dword v13, v[4:5], off nt
	v_add_co_u32_e32 v4, vcc, s2, v2
	s_mov_b32 s2, 0x20000
	s_nop 0
	v_addc_co_u32_e32 v5, vcc, 0, v3, vcc
	global_load_dword v65, v[4:5], off offset:-4096 nt
	global_load_dword v66, v[4:5], off nt
	v_add_co_u32_e32 v4, vcc, s2, v2
	s_mov_b32 s2, 0x22000
	s_nop 0
	v_addc_co_u32_e32 v5, vcc, 0, v3, vcc
	global_load_dword v67, v[4:5], off offset:-4096 nt
	global_load_dword v6, v[4:5], off nt
	v_add_co_u32_e32 v4, vcc, s2, v2
	s_mov_b32 s2, 0x24000
	s_nop 0
	v_addc_co_u32_e32 v5, vcc, 0, v3, vcc
	global_load_dword v68, v[4:5], off offset:-4096 nt
	global_load_dword v69, v[4:5], off nt
	v_add_co_u32_e32 v4, vcc, s2, v2
	s_mov_b32 s2, 0x26000
	s_nop 0
	v_addc_co_u32_e32 v5, vcc, 0, v3, vcc
	global_load_dword v70, v[4:5], off offset:-4096 nt
	global_load_dword v7, v[4:5], off nt
	v_add_co_u32_e32 v4, vcc, s2, v2
	s_mov_b32 s2, 0x28000
	s_nop 0
	v_addc_co_u32_e32 v5, vcc, 0, v3, vcc
	global_load_dword v71, v[4:5], off offset:-4096 nt
	global_load_dword v72, v[4:5], off nt
	v_add_co_u32_e32 v4, vcc, s2, v2
	s_mov_b32 s2, 0x2a000
	s_nop 0
	v_addc_co_u32_e32 v5, vcc, 0, v3, vcc
	global_load_dword v73, v[4:5], off offset:-4096 nt
	global_load_dword v8, v[4:5], off nt
	v_add_co_u32_e32 v4, vcc, s2, v2
	s_mov_b32 s2, 0x2c000
	s_nop 0
	v_addc_co_u32_e32 v5, vcc, 0, v3, vcc
	global_load_dword v74, v[4:5], off offset:-4096 nt
	global_load_dword v75, v[4:5], off nt
	v_add_co_u32_e32 v4, vcc, s2, v2
	s_mov_b32 s2, 0x2e000
	s_nop 0
	v_addc_co_u32_e32 v5, vcc, 0, v3, vcc
	global_load_dword v76, v[4:5], off offset:-4096 nt
	global_load_dword v9, v[4:5], off nt
	v_add_co_u32_e32 v4, vcc, s2, v2
	s_mov_b32 s2, 0x30000
	s_nop 0
	v_addc_co_u32_e32 v5, vcc, 0, v3, vcc
	global_load_dword v77, v[4:5], off offset:-4096 nt
	global_load_dword v78, v[4:5], off nt
	v_add_co_u32_e32 v4, vcc, s2, v2
	s_mov_b32 s2, 0x32000
	s_nop 0
	v_addc_co_u32_e32 v5, vcc, 0, v3, vcc
	global_load_dword v79, v[4:5], off offset:-4096 nt
	global_load_dword v80, v[4:5], off nt
	v_add_co_u32_e32 v4, vcc, s2, v2
	s_mov_b32 s2, 0x34000
	s_nop 0
	v_addc_co_u32_e32 v5, vcc, 0, v3, vcc
	global_load_dword v81, v[4:5], off offset:-4096 nt
	global_load_dword v82, v[4:5], off nt
	v_add_co_u32_e32 v4, vcc, s2, v2
	s_mov_b32 s2, 0x36000
	s_nop 0
	v_addc_co_u32_e32 v5, vcc, 0, v3, vcc
	global_load_dword v83, v[4:5], off offset:-4096 nt
	global_load_dword v84, v[4:5], off nt
	v_add_co_u32_e32 v4, vcc, s2, v2
	s_mov_b32 s2, 0x38000
	s_nop 0
	v_addc_co_u32_e32 v5, vcc, 0, v3, vcc
	global_load_dword v85, v[4:5], off offset:-4096 nt
	global_load_dword v86, v[4:5], off nt
	v_add_co_u32_e32 v4, vcc, s2, v2
	s_mov_b32 s2, 0x3a000
	s_nop 0
	v_addc_co_u32_e32 v5, vcc, 0, v3, vcc
	global_load_dword v87, v[4:5], off offset:-4096 nt
	global_load_dword v88, v[4:5], off nt
	v_add_co_u32_e32 v4, vcc, s2, v2
	s_mov_b32 s2, 0x3c000
	s_nop 0
	v_addc_co_u32_e32 v5, vcc, 0, v3, vcc
	global_load_dword v89, v[4:5], off offset:-4096 nt
	global_load_dword v90, v[4:5], off nt
	v_add_co_u32_e32 v4, vcc, s2, v2
	s_mov_b32 s2, 0x3e000
	s_nop 0
	v_addc_co_u32_e32 v5, vcc, 0, v3, vcc
	global_load_dword v91, v[4:5], off offset:-4096 nt
	global_load_dword v92, v[4:5], off nt
	v_add_co_u32_e32 v4, vcc, s2, v2
	s_mov_b32 s2, 0x3f000
	s_nop 0
	v_addc_co_u32_e32 v5, vcc, 0, v3, vcc
	global_load_dword v93, v[4:5], off offset:-4096 nt
	s_nop 0
	global_load_dword v4, v[4:5], off nt
	v_add_co_u32_e32 v2, vcc, s2, v2
	s_lshl_b32 s2, s0, 6
	s_nop 0
	v_addc_co_u32_e32 v3, vcc, 0, v3, vcc
	global_load_dword v2, v[2:3], off nt
	s_and_b32 s2, s2, 0xffffff80
	s_add_i32 s1, s1, s2
	s_lshl_b32 s0, s0, 4
	v_or_b32_e32 v3, s1, v31
	s_and_b32 s0, s0, 16
	v_or3_b32 v18, v3, s0, v210
	s_mov_b32 s0, 0xc3e00000
	s_waitcnt vmcnt(23)
; __device__ __forceinline__ unsigned pk4_fp8(float a, float b, float c, float d) { int w = 0; w = __builtin_amdgcn_cvt_pk_fp8_f32(a, b, w, false); w = __builtin_amdgcn_cvt_pk_fp8_f32(c, d, w, true); return (unsigned)w; }
; __device__ __forceinline__ void transpose_item8(const float* W, int N, unsigned char* WT, int ldt, int item, int lane, int mode, int aux) {
;     ...
;     for (int i = 0; i < 64; ++i) v[i] = wp[(size_t)i * N];
;     unsigned o[16];
; #pragma unroll
;     for (int q = 0; q < 16; ++q) o[q] = pk4_fp8(fminf(fmaxf(v[4 * q] * 64.f, -448.f), 448.f), fminf(fmaxf(v[4 * q + 1] * 64.f, -448.f), 448.f), fminf(fmaxf(v[4 * q + 2] * 64.f, -448.f), 448.f), fminf(fmaxf(v[4 * q + 3] * 64.f, -448.f), 448.f));
;     v4u* dst = (v4u*)(WT + (size_t)rowmap(mode, aux, ncol) * ldt + k0);
; #pragma unroll
;     for (int q = 0; q < 4; ++q) dst[q] = (v4u){o[4 * q], o[4 * q + 1], o[4 * q + 2], o[4 * q + 3]};
	v_mul_f32_e32 v8, 0x42800000, v8
	v_mul_f32_e32 v7, 0x42800000, v7
	v_mul_f32_e32 v6, 0x42800000, v6
	v_mul_f32_e32 v13, 0x42800000, v13
	v_mul_f32_e32 v12, 0x42800000, v12
	v_mul_f32_e32 v11, 0x42800000, v11
	v_mul_f32_e32 v10, 0x42800000, v10
	v_mul_f32_e32 v55, 0x42800000, v55
	v_mul_f32_e32 v52, 0x42800000, v52
	v_mul_f32_e32 v53, 0x42800000, v53
	v_med3_f32 v52, v52, s0, v236
	v_med3_f32 v53, v53, s0, v236
	s_waitcnt vmcnt(19)
	v_mul_f32_e32 v9, 0x42800000, v9
	v_mul_f32_e32 v54, 0x42800000, v54
	v_med3_f32 v54, v54, s0, v236
	v_mul_f32_e32 v47, 0x42800000, v47
	v_mul_f32_e32 v48, 0x42800000, v48
	v_mul_f32_e32 v43, 0x42800000, v43
	v_mul_f32_e32 v44, 0x42800000, v44
	v_mul_f32_e32 v17, 0x42800000, v17
	v_mul_f32_e32 v19, 0x42800000, v19
	v_med3_f32 v47, v47, s0, v236
	v_med3_f32 v48, v48, s0, v236
	v_med3_f32 v43, v43, s0, v236
	v_med3_f32 v44, v44, s0, v236
	v_med3_f32 v17, v17, s0, v236
	v_med3_f32 v19, v19, s0, v236
	s_waitcnt vmcnt(17)
	v_mul_f32_e32 v78, 0x42800000, v78
	s_waitcnt vmcnt(16)
	v_mul_f32_e32 v79, 0x42800000, v79
	v_mul_f32_e32 v75, 0x42800000, v75
	v_mul_f32_e32 v76, 0x42800000, v76
	v_mul_f32_e32 v72, 0x42800000, v72
	v_mul_f32_e32 v73, 0x42800000, v73
	v_mul_f32_e32 v69, 0x42800000, v69
	v_mul_f32_e32 v70, 0x42800000, v70
	v_mul_f32_e32 v66, 0x42800000, v66
	v_mul_f32_e32 v67, 0x42800000, v67
	v_mul_f32_e32 v63, 0x42800000, v63
	v_mul_f32_e32 v64, 0x42800000, v64
	v_mul_f32_e32 v60, 0x42800000, v60
	v_mul_f32_e32 v61, 0x42800000, v61
	v_mul_f32_e32 v57, 0x42800000, v57
	v_mul_f32_e32 v58, 0x42800000, v58
	v_mul_f32_e32 v49, 0x42800000, v49
	v_mul_f32_e32 v50, 0x42800000, v50
	v_mul_f32_e32 v45, 0x42800000, v45
	v_mul_f32_e32 v46, 0x42800000, v46
	v_mul_f32_e32 v41, 0x42800000, v41
	v_mul_f32_e32 v42, 0x42800000, v42
	v_med3_f32 v78, v78, s0, v236
	v_med3_f32 v79, v79, s0, v236
	v_med3_f32 v75, v75, s0, v236
	v_med3_f32 v76, v76, s0, v236
	v_med3_f32 v72, v72, s0, v236
	v_med3_f32 v73, v73, s0, v236
	v_med3_f32 v69, v69, s0, v236
	v_med3_f32 v70, v70, s0, v236
	v_med3_f32 v66, v66, s0, v236
	v_med3_f32 v67, v67, s0, v236
	v_med3_f32 v63, v63, s0, v236
	v_med3_f32 v64, v64, s0, v236
	v_med3_f32 v60, v60, s0, v236
	v_med3_f32 v61, v61, s0, v236
	v_med3_f32 v57, v57, s0, v236
	v_med3_f32 v58, v58, s0, v236
	s_waitcnt vmcnt(2)
	v_mul_f32_e32 v5, 0x42800000, v93
	s_waitcnt vmcnt(1)
	v_mul_f32_e32 v3, 0x42800000, v4
	v_mul_f32_e32 v4, 0x42800000, v92
	v_med3_f32 v4, v4, s0, v236
	v_med3_f32 v92, v5, s0, v236
	v_mov_b32_e32 v5, v51
	v_cvt_pk_fp8_f32 v5, v4, v92
	v_mul_f32_e32 v4, 0x42800000, v88
	v_med3_f32 v88, v4, s0, v236
	v_mul_f32_e32 v4, 0x42800000, v89
	v_med3_f32 v89, v4, s0, v236
	v_mov_b32_e32 v4, v51
	s_waitcnt vmcnt(0)
	v_mul_f32_e32 v2, 0x42800000, v2
	v_cvt_pk_fp8_f32 v4, v88, v89
	v_med3_f32 v3, v3, s0, v236
	v_med3_f32 v2, v2, s0, v236
	v_cvt_pk_fp8_f32 v5, v3, v2 op_sel:[0,0,1]
	v_mul_f32_e32 v2, 0x42800000, v90
	v_mul_f32_e32 v3, 0x42800000, v91
	v_med3_f32 v2, v2, s0, v236
	v_med3_f32 v3, v3, s0, v236
	v_cvt_pk_fp8_f32 v4, v2, v3 op_sel:[0,0,1]
	v_mul_f32_e32 v3, 0x42800000, v87
	v_mul_f32_e32 v2, 0x42800000, v86
	v_med3_f32 v86, v3, s0, v236
	v_mul_f32_e32 v3, 0x42800000, v84
	v_med3_f32 v84, v3, s0, v236
	v_mul_f32_e32 v3, 0x42800000, v85
	v_med3_f32 v85, v3, s0, v236
	v_mov_b32_e32 v3, v51
	v_cvt_pk_fp8_f32 v3, v84, v85
	v_med3_f32 v2, v2, s0, v236
	v_med3_f32 v49, v49, s0, v236
	v_med3_f32 v50, v50, s0, v236
	v_cvt_pk_fp8_f32 v3, v2, v86 op_sel:[0,0,1]
	v_mul_f32_e32 v2, 0x42800000, v82
	v_med3_f32 v82, v2, s0, v236
	v_mul_f32_e32 v2, 0x42800000, v83
	v_med3_f32 v83, v2, s0, v236
	v_mul_f32_e32 v2, 0x42800000, v80
	v_med3_f32 v80, v2, s0, v236
	v_mul_f32_e32 v2, 0x42800000, v81
	v_med3_f32 v81, v2, s0, v236
	v_mov_b32_e32 v2, v51
	v_cvt_pk_fp8_f32 v2, v80, v81
	v_med3_f32 v80, v9, s0, v236
	v_mul_f32_e32 v9, 0x42800000, v77
	v_med3_f32 v77, v9, s0, v236
	v_mov_b32_e32 v9, v51
	v_cvt_pk_fp8_f32 v9, v80, v77
	v_med3_f32 v77, v8, s0, v236
	v_mul_f32_e32 v8, 0x42800000, v74
	v_med3_f32 v74, v8, s0, v236
	v_mov_b32_e32 v8, v51
	v_cvt_pk_fp8_f32 v8, v77, v74
	v_med3_f32 v74, v7, s0, v236
	v_mul_f32_e32 v7, 0x42800000, v71
	v_med3_f32 v71, v7, s0, v236
	v_mov_b32_e32 v7, v51
	v_cvt_pk_fp8_f32 v7, v74, v71
	v_med3_f32 v71, v6, s0, v236
	v_mul_f32_e32 v6, 0x42800000, v68
	v_med3_f32 v68, v6, s0, v236
	v_mov_b32_e32 v6, v51
	v_cvt_pk_fp8_f32 v6, v71, v68
	v_med3_f32 v68, v13, s0, v236
	v_mul_f32_e32 v13, 0x42800000, v65
	v_med3_f32 v65, v13, s0, v236
	v_mov_b32_e32 v13, v51
	v_cvt_pk_fp8_f32 v13, v68, v65
	v_med3_f32 v65, v12, s0, v236
	v_mul_f32_e32 v12, 0x42800000, v62
	v_med3_f32 v62, v12, s0, v236
	v_mov_b32_e32 v12, v51
	v_cvt_pk_fp8_f32 v12, v65, v62
	v_med3_f32 v62, v11, s0, v236
	v_mul_f32_e32 v11, 0x42800000, v59
	v_med3_f32 v59, v11, s0, v236
	v_mov_b32_e32 v11, v51
	v_cvt_pk_fp8_f32 v11, v62, v59
	v_med3_f32 v59, v10, s0, v236
	v_mul_f32_e32 v10, 0x42800000, v56
	v_med3_f32 v56, v10, s0, v236
	v_mov_b32_e32 v10, v51
	v_cvt_pk_fp8_f32 v10, v59, v56
	v_med3_f32 v56, v55, s0, v236
	v_mov_b32_e32 v55, v51
	v_cvt_pk_fp8_f32 v55, v52, v53
	v_mov_b32_e32 v53, v51
	v_mov_b32_e32 v52, v51
	v_cvt_pk_fp8_f32 v53, v43, v44
	v_cvt_pk_fp8_f32 v55, v54, v56 op_sel:[0,0,1]
	v_mov_b32_e32 v54, v51
	v_cvt_pk_fp8_f32 v54, v47, v48
	v_cvt_pk_fp8_f32 v52, v17, v19
	v_med3_f32 v45, v45, s0, v236
	v_med3_f32 v46, v46, s0, v236
	v_med3_f32 v41, v41, s0, v236
	v_med3_f32 v42, v42, s0, v236
	v_ashrrev_i32_e32 v19, 31, v18
	v_readlane_b32 s0, v254, 3
	v_readlane_b32 s23, v254, 33
	v_cvt_pk_fp8_f32 v54, v49, v50 op_sel:[0,0,1]
	v_cvt_pk_fp8_f32 v53, v45, v46 op_sel:[0,0,1]
	v_cvt_pk_fp8_f32 v52, v41, v42 op_sel:[0,0,1]
	v_lshlrev_b64 v[18:19], 10, v[18:19]
	v_readlane_b32 s1, v254, 4
	v_cvt_pk_fp8_f32 v13, v66, v67 op_sel:[0,0,1]
	v_cvt_pk_fp8_f32 v12, v63, v64 op_sel:[0,0,1]
	v_cvt_pk_fp8_f32 v11, v60, v61 op_sel:[0,0,1]
	v_cvt_pk_fp8_f32 v10, v57, v58 op_sel:[0,0,1]
	v_lshl_add_u64 v[18:19], s[0:1], 0, v[18:19]
	s_mov_b32 s1, s23
	v_cvt_pk_fp8_f32 v9, v78, v79 op_sel:[0,0,1]
	v_cvt_pk_fp8_f32 v8, v75, v76 op_sel:[0,0,1]
	v_cvt_pk_fp8_f32 v7, v72, v73 op_sel:[0,0,1]
	v_cvt_pk_fp8_f32 v6, v69, v70 op_sel:[0,0,1]
	v_writelane_b32 v254, s0, 32
	v_cvt_pk_fp8_f32 v2, v82, v83 op_sel:[0,0,1]
	v_lshl_add_u64 v[18:19], v[18:19], 0, s[22:23]
	v_writelane_b32 v254, s1, 33
	global_store_dwordx4 v[18:19], v[52:55], off
	global_store_dwordx4 v[18:19], v[10:13], off offset:16
	global_store_dwordx4 v[18:19], v[6:9], off offset:32
	global_store_dwordx4 v[18:19], v[2:5], off offset:48
	s_branch .LBB0_1071

; __device__ __forceinline__ void phase_scan_chunk(const Args& a, LAS unsigned char* lds, const WCtx& w, int l) {
;     ...
;             GLA_LOAD(0);
.LBB0_1431:
	s_bfe_u32 s22, s23, 0x40002
	s_lshl_b32 s2, s23, 6
	s_and_b32 s27, s2, 0xc0
	s_lshl_b32 s26, s22, 8
	v_readlane_b32 s2, v253, 41
	s_bitset1_b32 s26, 15
	v_readlane_b32 s3, v253, 42
	v_or_b32_e32 v4, s26, v114
	s_mov_b32 s15, s5
	v_mov_b64_e32 v[2:3], s[2:3]
	v_mad_u64_u32 v[2:3], s[2:3], v4, s4, v[2:3]
	s_lshl_b32 s14, s27, 1
	v_lshl_add_u64 v[2:3], v[2:3], 0, s[14:15]
	s_waitcnt vmcnt(0)
	v_lshlrev_b32_e32 v50, 1, v116
	v_lshl_add_u64 v[2:3], v[2:3], 0, v[50:51]
	v_lshl_add_u64 v[6:7], v[2:3], 0, v[42:43]
	v_lshl_add_u64 v[8:9], v[6:7], 0, v[42:43]
	v_lshl_add_u64 v[10:11], v[8:9], 0, v[42:43]
	v_lshl_add_u64 v[12:13], v[10:11], 0, v[42:43]
	v_lshl_add_u64 v[14:15], v[12:13], 0, v[42:43]
	v_lshl_add_u64 v[16:17], v[14:15], 0, v[42:43]
	v_lshl_add_u64 v[18:19], v[16:17], 0, v[42:43]
	v_lshl_add_u64 v[20:21], v[18:19], 0, v[42:43]
	v_lshl_add_u64 v[22:23], v[20:21], 0, v[42:43]
	s_waitcnt vmcnt(0)
	v_lshl_add_u64 v[24:25], v[22:23], 0, v[42:43]
	v_lshl_add_u64 v[26:27], v[24:25], 0, v[42:43]
	v_lshl_add_u64 v[28:29], v[26:27], 0, v[42:43]
	s_movk_i32 s2, 0xc00
	v_lshl_add_u64 v[30:31], v[28:29], 0, v[42:43]
	v_mad_u64_u32 v[4:5], s[2:3], v4, s2, v[40:41]
	v_lshl_add_u64 v[32:33], v[30:31], 0, v[42:43]
	s_lshl_b32 s2, s27, 2
	s_mov_b32 s3, s5
	v_lshl_add_u64 v[34:35], v[32:33], 0, v[42:43]
	v_lshl_add_u64 v[4:5], v[4:5], 0, s[2:3]
	global_load_ushort v170, v[2:3], off
	global_load_ushort v171, v[6:7], off
	global_load_ushort v172, v[8:9], off
	global_load_ushort v173, v[10:11], off
	global_load_ushort v174, v[12:13], off
	global_load_ushort v175, v[14:15], off
	global_load_ushort v176, v[16:17], off
	global_load_ushort v177, v[18:19], off
	global_load_ushort v178, v[20:21], off
	global_load_ushort v179, v[22:23], off
	global_load_ushort v180, v[24:25], off
	global_load_ushort v181, v[26:27], off
	global_load_ushort v182, v[28:29], off
	global_load_ushort v183, v[30:31], off
	global_load_ushort v184, v[32:33], off
	global_load_ushort v185, v[34:35], off
	v_lshlrev_b32_e32 v50, 2, v116
	global_load_ushort v186, v[2:3], off offset:512
	global_load_ushort v187, v[6:7], off offset:512
	global_load_ushort v188, v[8:9], off offset:512
	global_load_ushort v189, v[10:11], off offset:512
	global_load_ushort v190, v[12:13], off offset:512
	global_load_ushort v191, v[14:15], off offset:512
	global_load_ushort v192, v[16:17], off offset:512
	global_load_ushort v193, v[18:19], off offset:512
	global_load_ushort v194, v[20:21], off offset:512
	global_load_ushort v195, v[22:23], off offset:512
	global_load_ushort v197, v[24:25], off offset:512
	global_load_ushort v199, v[26:27], off offset:512
	global_load_ushort v200, v[28:29], off offset:512
	global_load_ushort v201, v[30:31], off offset:512
	global_load_ushort v202, v[32:33], off offset:512
	global_load_ushort v203, v[34:35], off offset:512
	v_lshl_add_u64 v[2:3], v[4:5], 0, v[50:51]
	v_lshl_add_u64 v[4:5], v[2:3], 0, v[44:45]
	v_lshl_add_u64 v[6:7], v[4:5], 0, v[44:45]
	v_lshl_add_u64 v[8:9], v[6:7], 0, v[44:45]
	v_lshl_add_u64 v[10:11], v[8:9], 0, v[44:45]
	global_load_dword v50, v[2:3], off
	global_load_dword v204, v[4:5], off
	global_load_dword v205, v[6:7], off
	global_load_dword v206, v[8:9], off
	global_load_dword v207, v[10:11], off
	v_lshl_add_u64 v[2:3], v[10:11], 0, v[44:45]
	global_load_dword v208, v[2:3], off
	v_lshl_add_u64 v[2:3], v[2:3], 0, v[44:45]
	global_load_dword v209, v[2:3], off
	v_lshl_add_u64 v[2:3], v[2:3], 0, v[44:45]
	global_load_dword v210, v[2:3], off
	v_lshl_add_u64 v[2:3], v[2:3], 0, v[44:45]
	global_load_dword v211, v[2:3], off
	v_lshl_add_u64 v[2:3], v[2:3], 0, v[44:45]
	global_load_dword v212, v[2:3], off
	v_lshl_add_u64 v[2:3], v[2:3], 0, v[44:45]
	global_load_dword v213, v[2:3], off
	v_lshl_add_u64 v[2:3], v[2:3], 0, v[44:45]
	global_load_dword v214, v[2:3], off
	v_lshl_add_u64 v[2:3], v[2:3], 0, v[44:45]
	global_load_dword v215, v[2:3], off
	v_lshl_add_u64 v[2:3], v[2:3], 0, v[44:45]
	global_load_dword v216, v[2:3], off
	v_lshl_add_u64 v[2:3], v[2:3], 0, v[44:45]
	global_load_dword v217, v[2:3], off
	v_lshl_add_u64 v[2:3], v[2:3], 0, v[44:45]
	global_load_dword v218, v[2:3], off
	v_mov_b32_e32 v64, 0
	v_lshl_add_u64 v[58:59], v[38:39], 0, s[14:15]
	v_lshl_add_u64 v[60:61], v[46:47], 0, s[14:15]
	v_lshl_add_u64 v[62:63], v[48:49], 0, s[2:3]
	s_lshl_b32 s27, s22, 11
	s_mov_b32 s28, 0
	s_mov_b32 s29, 0
	s_mov_b32 s30, 0
	v_mov_b32_e32 v65, v64
	v_mov_b32_e32 v66, v64
	v_mov_b32_e32 v67, v64
	v_mov_b32_e32 v68, v64
	v_mov_b32_e32 v69, v64
	v_mov_b32_e32 v70, v64
	v_mov_b32_e32 v71, v64
	v_mov_b32_e32 v72, v64
	v_mov_b32_e32 v73, v64
	v_mov_b32_e32 v74, v64
	v_mov_b32_e32 v75, v64
	v_mov_b32_e32 v76, v64
	v_mov_b32_e32 v77, v64
	v_mov_b32_e32 v78, v64
	v_mov_b32_e32 v79, v64
	s_waitcnt vmcnt(0)
	s_branch .LBB0_1433

; __device__ __forceinline__ float bf2f(unsigned b) { return __uint_as_float(b << 16); }
; __device__ __forceinline__ float expc(float x) { return __expf(fminf(x, 80.f)); }
; #define LBAR() asm volatile("s_waitcnt lgkmcnt(0)\n\ts_barrier" ::: "memory")
; __device__ __forceinline__ void phase_scan_chunk(const Args& a, LAS unsigned char* lds, const WCtx& w, int l) {
;     ...
;             for (int c = 0; c < 36; ++c) {
;                 float lc[16], kk[16], qq[16], vvv[16]; float run = 0.f;
; #pragma unroll
;                 for (int ii = 0; ii < 16; ++ii) { kk[ii] = 1.0f - __expf(rz[ii]); run += rz[ii]; lc[ii] = run; qq[ii] = bf2f(rq[ii]); vvv[ii] = bf2f(rv[ii]); }
;                 QSUM[iq * 64 + d] = run;
;                 LBAR();
;                 const float s0 = QSUM[d], s1 = QSUM[64 + d], s2 = QSUM[128 + d], s3 = QSUM[192 + d];
;                 const float off = (iq > 0 ? s0 : 0.f) + (iq > 1 ? s1 : 0.f) + (iq > 2 ? s2 : 0.f), g31 = s0 + s1, g63 = g31 + s2 + s3;
;                 { float kd[16];
;                   const float e2 = __expf(g63 - g31);
; #pragma unroll
;                   for (int ii = 0; ii < 16; ++ii) { const int i = 16 * iq + ii; const float gi = off + lc[ii]; const float ea = __expf(gi), eb = expc(g31 - gi);
.LBB0_1433:
	s_waitcnt vmcnt(31)
	v_add_f32_e32 v24, 0, v50
	s_waitcnt vmcnt(30)
	v_add_f32_e32 v8, v24, v204
	s_waitcnt vmcnt(29)
	v_add_f32_e32 v10, v8, v205
	s_waitcnt vmcnt(28)
	v_add_f32_e32 v12, v10, v206
	s_waitcnt vmcnt(27)
	v_add_f32_e32 v14, v12, v207
	s_waitcnt vmcnt(26)
	v_add_f32_e32 v16, v14, v208
	s_waitcnt vmcnt(25)
	v_add_f32_e32 v18, v16, v209
	s_waitcnt vmcnt(24)
	v_add_f32_e32 v20, v18, v210
	s_waitcnt vmcnt(23)
	v_add_f32_e32 v21, v20, v211
	s_waitcnt vmcnt(22)
	v_add_f32_e32 v19, v21, v212
	s_waitcnt vmcnt(21)
	v_add_f32_e32 v17, v19, v213
	s_waitcnt vmcnt(20)
	v_add_f32_e32 v15, v17, v214
	s_waitcnt vmcnt(19)
	v_add_f32_e32 v13, v15, v215
	s_waitcnt vmcnt(18)
	v_add_f32_e32 v11, v13, v216
	v_mul_f32_e32 v2, 0x3fb8aa3b, v50
	s_waitcnt vmcnt(17)
	v_add_f32_e32 v9, v11, v217
	v_exp_f32_e32 v2, v2
	s_waitcnt vmcnt(16)
	v_add_f32_e32 v6, v9, v218
	ds_write_b32 v115, v6
	s_waitcnt lgkmcnt(0)
	s_barrier
	ds_read2st64_b32 v[4:5], v120 offset1:1
	v_sub_f32_e32 v23, 1.0, v2
	ds_read2st64_b32 v[2:3], v120 offset0:2 offset1:3
	v_lshlrev_b32_e32 v22, 16, v170
	s_waitcnt lgkmcnt(1)
	v_cndmask_b32_e64 v7, v4, 0, s[36:37]
	v_cndmask_b32_e64 v25, 0, v5, s[40:41]
	v_add_f32_e32 v7, v7, v25
	s_waitcnt lgkmcnt(0)
	v_cndmask_b32_e64 v25, 0, v2, s[44:45]
	v_add_f32_e32 v7, v7, v25
	v_add_f32_e32 v5, v4, v5
	v_add_f32_e32 v4, v24, v7
	v_mul_f32_e32 v24, 0x3fb8aa3b, v4
	v_sub_f32_e32 v4, v5, v4
	v_exp_f32_e32 v25, v24
	v_min_f32_e32 v4, 0x42a00000, v4
	v_mul_f32_e32 v4, 0x3fb8aa3b, v4
	v_exp_f32_e32 v24, v4
	v_mul_f32_e32 v4, v25, v22
	v_cvt_pk_bf16_f32 v4, v4, v4
	ds_write_b16 v132, v4
	v_mul_f32_e32 v4, v23, v24
	v_cvt_pk_bf16_f32 v26, v4, v4
	ds_write_b16 v132, v26 offset:9216
	s_and_saveexec_b64 s[2:3], s[42:43]
	s_xor_b64 s[2:3], exec, s[2:3]
	s_cbranch_execz .LBB0_1435
	v_max_f32_e32 v22, v25, v25
	v_max_f32_e32 v22, 0x554ad2e, v22
	v_rcp_f32_e32 v22, v22
	s_nop 0
	v_mul_f32_e32 v22, v23, v22
	v_cvt_pk_bf16_f32 v22, v22, v22
	ds_write_b16 v133, v22 offset:23040

; __device__ __forceinline__ void phase_scan_chunk(const Args& a, LAS unsigned char* lds, const WCtx& w, int l) {
;     ...
;         const int mix = pi >> 6, b = (pi & 63) >> 2, h = pi & 3;
;         const int chain = (b * 4 + h) * 2 + dir;
;         f32x16 S = zero16();
;         bf16* so = SO + (size_t)(mix * 2 + dir) * MT * 256 + h * 64 + 32 * wn + r;
;         {
;             const int i = tl >> 2, dq = tl & 3;
;             const float al = expf(mix == 1 ? a.in[I_GDN_ALOG][(l * 2 + dir) * 4 + h] : a.in[I_SSD_ALOG][(l * 2 + dir) * 4 + h]);
;             const float dtb = mix == 1 ? a.in[I_GDN_DTB][(l * 2 + dir) * 4 + h] : a.in[I_SSD_DTB][(l * 2 + dir) * 4 + h];
;             v4u rq0s[2], rq1s[2], rk0s[2], rk1s[2], ra0s[2], ra1s[2], rb0s[2], rb1s[2]; float rs0s[2] = {0.f, 0.f}, rs1s[2] = {0.f, 0.f};
; #pragma unroll
;             for (int u = 0; u < 2; ++u) { rq0s[u] = rq1s[u] = rk0s[u] = rk1s[u] = ra0s[u] = ra1s[u] = rb0s[u] = rb1s[u] = (v4u){0u, 0u, 0u, 0u}; }
;     ...
;             SD_LOAD(0, 0); SD_LOAD(1, 1);
;             for (int c2 = 0; c2 < 36; c2 += 2) {
.LBB0_1534:
	s_nop 0
	v_readlane_b32 s2, v254, 5
	v_readlane_b32 s3, v254, 6
	v_lshl_add_u32 v4, s29, 1, v160
	s_waitcnt vmcnt(13)
	v_cmp_ngt_f32_e32 vcc, s12, v12
	v_mov_b64_e32 v[2:3], s[2:3]
	s_mov_b32 s2, 0x1200000
	v_mad_i64_i32 v[2:3], s[2:3], v4, s2, v[2:3]
	v_mul_f32_e32 v4, 0x3fb8aa3b, v12
	v_rndne_f32_e32 v5, v4
	v_sub_f32_e32 v6, v4, v5
	v_fma_f32 v4, v12, s11, -v4
	v_readlane_b32 s2, v254, 32
	v_fmac_f32_e32 v4, 0x32a5705f, v12
	v_readlane_b32 s3, v254, 33
	s_lshl_b32 s2, s30, 1
	v_add_f32_e32 v4, v6, v4
	v_exp_f32_e32 v4, v4
	v_cvt_i32_f32_e32 v5, v5
	v_writelane_b32 v254, s2, 32
	s_mov_b64 s[94:95], 0x800
	s_mov_b32 s30, 64
	v_writelane_b32 v254, s3, 33
	v_lshl_add_u64 v[2:3], v[2:3], 0, s[2:3]
	v_readlane_b32 s2, v255, 13
	v_readlane_b32 s3, v255, 14
	v_or_b32_e32 v217, s28, v192
	v_or_b32_e32 v218, s28, v193
	v_lshl_add_u64 v[2:3], s[2:3], 1, v[2:3]
	v_lshl_add_u64 v[136:137], v[118:119], 1, v[2:3]
	v_ldexp_f32 v2, v4, v5
	v_cndmask_b32_e32 v2, 0, v2, vcc
	v_cmp_nlt_f32_e32 vcc, s13, v12
	s_bfe_u32 s2, s25, 0x60001
	s_mulk_i32 s2, 0x48
	v_cndmask_b32_e32 v216, v235, v2, vcc
	v_mul_i32_i24_e32 v2, 36, v160
	v_add_u32_e32 v2, s2, v2
	s_cmp_eq_u32 s29, 2
	v_ashrrev_i32_e32 v3, 31, v2
	s_cselect_b64 s[84:85], -1, 0
	s_cmp_lg_u32 s29, 2
	v_lshlrev_b64 v[2:3], 13, v[2:3]
	s_cselect_b64 s[86:87], -1, 0
	s_lshl_b32 s2, s90, 5
	v_lshl_add_u64 v[138:139], v[134:135], 0, v[2:3]
	s_lshl_b32 s29, s23, 11
	s_and_b32 s31, s2, 64
	s_mov_b32 s34, 0
	s_movk_i32 s35, 0xffc0
	v_mov_b32_e32 v141, v140
	v_mov_b32_e32 v154, v140
	v_mov_b32_e32 v155, v140
	v_mov_b32_e32 v152, v140
	v_mov_b32_e32 v153, v140
	v_mov_b32_e32 v150, v140
	v_mov_b32_e32 v151, v140
	v_mov_b32_e32 v148, v140
	v_mov_b32_e32 v149, v140
	v_mov_b32_e32 v146, v140
	v_mov_b32_e32 v147, v140
	v_mov_b32_e32 v144, v140
	v_mov_b32_e32 v145, v140
	v_mov_b32_e32 v142, v140
	v_mov_b32_e32 v143, v140
	s_waitcnt vmcnt(0)
	s_branch .LBB0_1536

; __device__ __forceinline__ float sigmoid_acc(float x) { return 1.0f / (1.0f + expf(-x)); }
; __device__ __forceinline__ float softplus_acc(float x) { return x > 20.f ? x : log1pf(expf(x)); }
; __device__ __forceinline__ void phase_scan_chunk(const Args& a, LAS unsigned char* lds, const WCtx& w, int l) {
;     ...
;                 if (gw4 == 0) { const float sp = softplus_acc(rs0s[u] + dtb); float g = -al * sp;
;                     g = wave_scan(g);
;                     G[lane] = g; EG[lane] = __expf(g); BD[lane] = (mix == 1) ? sigmoid_acc(rs1s[u]) : sp; }
.LBB0_1536:
	s_and_b64 vcc, exec, s[70:71]
	s_cbranch_vccnz .LBB0_1542
	s_waitcnt vmcnt(22)
	v_add_f32_e32 v2, v211, v212
	v_cmp_nlt_f32_e32 vcc, s10, v2
	s_and_saveexec_b64 s[2:3], vcc
	s_cbranch_execz .LBB0_1539
	v_mul_f32_e32 v3, 0x3fb8aa3b, v2
	v_rndne_f32_e32 v4, v3
	v_sub_f32_e32 v5, v3, v4
	v_fma_f32 v3, v2, s11, -v3
	v_fmac_f32_e32 v3, 0x32a5705f, v2
	v_add_f32_e32 v3, v5, v3
	v_cvt_i32_f32_e32 v4, v4
	v_exp_f32_e32 v3, v3
	v_cmp_ngt_f32_e32 vcc, s12, v2
	v_ldexp_f32 v3, v3, v4
	s_nop 0
	v_cndmask_b32_e32 v3, 0, v3, vcc
	v_cmp_nlt_f32_e32 vcc, s13, v2
	s_nop 1
	v_cndmask_b32_e32 v16, v235, v3, vcc
	v_add_f32_e32 v4, 1.0, v16
	v_add_f32_e32 v2, -1.0, v4
	v_sub_f32_e32 v3, v2, v4
	v_add_f32_e32 v3, 1.0, v3
	v_sub_f32_e32 v2, v16, v2
	v_add_f32_e32 v5, v2, v3
	v_frexp_mant_f32_e32 v6, v4
	v_cvt_f64_f32_e32 v[2:3], v4
	v_frexp_exp_i32_f64_e32 v2, v[2:3]
	v_cmp_gt_f32_e32 vcc, s14, v6
	s_nop 1
	v_subbrev_co_u32_e32 v10, vcc, 0, v2, vcc
	v_sub_u32_e32 v2, 0, v10
	v_ldexp_f32 v3, v4, v2
	v_add_f32_e32 v4, -1.0, v3
	v_add_f32_e32 v6, 1.0, v3
	v_ldexp_f32 v2, v5, v2
	v_add_f32_e32 v5, 1.0, v4
	v_add_f32_e32 v7, -1.0, v6
	v_sub_f32_e32 v5, v3, v5
	v_sub_f32_e32 v3, v3, v7
	v_add_f32_e32 v5, v2, v5
	v_add_f32_e32 v2, v2, v3
	v_add_f32_e32 v11, v6, v2
	v_rcp_f32_e32 v13, v11
	v_sub_f32_e32 v3, v6, v11
	v_add_f32_e32 v12, v2, v3
	v_add_f32_e32 v3, v4, v5
	v_mul_f32_e32 v15, v3, v13
	v_sub_f32_e32 v2, v4, v3
	v_mul_f32_e32 v4, v11, v15
	v_fma_f32 v6, v15, v11, -v4
	v_fmac_f32_e32 v6, v15, v12
	v_add_f32_e32 v14, v5, v2
	v_add_f32_e32 v2, v4, v6
	v_sub_f32_e32 v5, v3, v2
	v_pk_add_f32 v[8:9], v[2:3], v[4:5] neg_lo:[0,1] neg_hi:[0,1]
	v_mov_b32_e32 v7, v2
	v_pk_add_f32 v[2:3], v[8:9], v[6:7] neg_lo:[0,1] neg_hi:[0,1]
	v_cmp_neq_f32_e32 vcc, s22, v16
	v_add_f32_e32 v3, v14, v3
	v_add_f32_e32 v2, v2, v3
	v_add_f32_e32 v3, v5, v2
	v_mul_f32_e32 v14, v13, v3
	v_mul_f32_e32 v4, v11, v14
	v_fma_f32 v6, v14, v11, -v4
	v_fmac_f32_e32 v6, v14, v12
	v_sub_f32_e32 v5, v5, v3
	v_add_f32_e32 v11, v2, v5
	v_add_f32_e32 v2, v4, v6
	v_sub_f32_e32 v5, v3, v2
	v_pk_add_f32 v[8:9], v[2:3], v[4:5] neg_lo:[0,1] neg_hi:[0,1]
	v_mov_b32_e32 v7, v2
	v_pk_add_f32 v[2:3], v[8:9], v[6:7] neg_lo:[0,1] neg_hi:[0,1]
	s_nop 0
	v_add_f32_e32 v3, v11, v3
	v_add_f32_e32 v2, v2, v3
	v_add_f32_e32 v3, v15, v14
	v_add_f32_e32 v2, v5, v2
	v_sub_f32_e32 v4, v3, v15
	v_mul_f32_e32 v2, v13, v2
	v_sub_f32_e32 v4, v14, v4
	v_add_f32_e32 v4, v4, v2
	v_add_f32_e32 v6, v3, v4
	v_mul_f32_e32 v7, v6, v6
	v_fmamk_f32 v2, v7, 0x3e9b6dac, v250
	v_fmaak_f32 v199, v7, v2, 0x3f2aaada
	v_cvt_f32_i32_e32 v2, v10
	v_sub_f32_e32 v3, v6, v3
	v_sub_f32_e32 v3, v4, v3
	v_ldexp_f32 v8, v3, 1
	v_mul_f32_e32 v3, v6, v7
	v_ldexp_f32 v5, v6, 1
	v_pk_mul_f32 v[6:7], v[2:3], v[198:199]
	s_nop 0
	v_fma_f32 v4, v2, s15, -v6
	v_fmac_f32_e32 v4, 0xb102e308, v2
	v_pk_add_f32 v[2:3], v[6:7], v[4:5]
	s_nop 0
	v_sub_f32_e32 v5, v3, v5
	v_sub_f32_e32 v5, v7, v5
	v_add_f32_e32 v9, v8, v5
	v_mov_b32_e32 v8, v6
	v_pk_add_f32 v[6:7], v[2:3], v[6:7] neg_lo:[0,1] neg_hi:[0,1]
	v_pk_add_f32 v[10:11], v[2:3], v[8:9]
	v_mov_b32_e32 v5, v2
	v_mov_b32_e32 v7, v11
	v_pk_add_f32 v[12:13], v[4:5], v[6:7] neg_lo:[0,1] neg_hi:[0,1]
	v_pk_add_f32 v[4:5], v[4:5], v[6:7]
	v_mov_b32_e32 v8, v9
	v_pk_add_f32 v[6:7], v[4:5], v[2:3] op_sel:[1,0] op_sel_hi:[0,1] neg_lo:[0,1] neg_hi:[0,1]
	v_pk_add_f32 v[14:15], v[10:11], v[6:7] op_sel_hi:[1,0] neg_lo:[0,1] neg_hi:[0,1]
	v_mov_b32_e32 v10, v11
	v_mov_b32_e32 v11, v5
	v_pk_mov_b32 v[6:7], v[2:3], v[6:7] op_sel:[1,0]
	v_mov_b32_e32 v9, v2
	v_pk_add_f32 v[6:7], v[10:11], v[6:7] neg_lo:[0,1] neg_hi:[0,1]
	v_mov_b32_e32 v14, v12
	v_pk_add_f32 v[2:3], v[8:9], v[6:7] neg_lo:[0,1] neg_hi:[0,1]
	v_mov_b32_e32 v13, v5
	v_pk_add_f32 v[6:7], v[14:15], v[2:3]
	s_nop 0
	v_pk_add_f32 v[8:9], v[6:7], v[6:7] op_sel:[0,1] op_sel_hi:[1,0]
	s_nop 0
	v_pk_add_f32 v[4:5], v[4:5], v[8:9] op_sel:[1,0] op_sel_hi:[0,1]
	v_mov_b32_e32 v7, v4
	v_pk_add_f32 v[10:11], v[6:7], v[12:13] neg_lo:[0,1] neg_hi:[0,1]
	v_mov_b32_e32 v3, v8
	v_sub_f32_e32 v5, v6, v10
	v_pk_add_f32 v[2:3], v[2:3], v[10:11] neg_lo:[0,1] neg_hi:[0,1]
	v_sub_f32_e32 v5, v12, v5
	v_add_f32_e32 v2, v2, v5
	v_add_f32_e32 v2, v2, v3
	v_add_f32_e32 v2, v4, v2
	v_cndmask_b32_e32 v2, v235, v2, vcc
	v_cmp_lt_f32_e64 vcc, |v16|, s16
	s_nop 1
	v_cndmask_b32_e32 v2, v2, v16, vcc

; #define LAS __attribute__((address_space(3)))
; __device__ __forceinline__ bf16 bfr(float x) { return (bf16)cvt_pk_bf16(x, x); }
; __device__ __forceinline__ void unpack8(const v4u u, float (&f)[8]) { f[0] = bf2f(u.x & 0xffffu); f[1] = bf2f(u.x >> 16); f[2] = bf2f(u.y & 0xffffu); f[3] = bf2f(u.y >> 16); f[4] = bf2f(u.z & 0xffffu); f[5] = bf2f(u.z >> 16); f[6] = bf2f(u.w & 0xffffu); f[7] = bf2f(u.w >> 16); }
; __device__ __forceinline__ void phase_scan_chunk(const Args& a, LAS unsigned char* lds, const WCtx& w, int l) {
;     ...
;                 { const float gi = G[i], g63 = G[63]; const float kdsc = __expf(g63 - gi), vsc = (mix == 2) ? BD[i] : 1.0f;
;                   const int colsw = ((((i >> 3) ^ dq) << 3) | (i & 7)); LAS bf16* kdb = TKD + 16 * dq * TS + colsw; LAS bf16* vtb = TVT + 16 * dq * TS + colsw;
;                   *(LAS v4u*)(TQ + i * TS + 16 * dq) = rq0s[u]; *(LAS v4u*)(TQ + i * TS + 16 * dq + 8) = rq1s[u];
;                   *(LAS v4u*)(TK + i * TS + 16 * dq) = rk0s[u]; *(LAS v4u*)(TK + i * TS + 16 * dq + 8) = rk1s[u];
;                   float kf[8];
;                   unpack8(rk0s[u], kf);
; #pragma unroll
;                   for (int t = 0; t < 8; ++t) kdb[t * TS] = bfr(kf[t] * kdsc);
;                   unpack8(rk1s[u], kf);
; #pragma unroll
;                   for (int t = 0; t < 8; ++t) kdb[(8 + t) * TS] = bfr(kf[t] * kdsc);
;                   if (mix == 2) { unpack8(ra0s[u], kf);
; #pragma unroll
;                       for (int t = 0; t < 8; ++t) vtb[t * TS] = bfr(kf[t] * vsc);
;                       unpack8(ra1s[u], kf);
; #pragma unroll
;                       for (int t = 0; t < 8; ++t) vtb[(8 + t) * TS] = bfr(kf[t] * vsc); }
;                   else { *(LAS v4u*)(TX + i * TS + 16 * dq) = ra0s[u]; *(LAS v4u*)(TX + i * TS + 16 * dq + 8) = ra1s[u];
;                          *(LAS v4u*)(TVT + swz(i, 16 * dq)) = rb0s[u]; *(LAS v4u*)(TVT + swz(i, 16 * dq + 8)) = rb1s[u]; } }
.LBB0_1544:
	s_waitcnt lgkmcnt(0)
	v_sub_f32_e32 v3, v4, v3
	v_mul_f32_e32 v3, 0x3fb8aa3b, v3
	v_exp_f32_e32 v3, v3
	s_waitcnt vmcnt(24)
	v_lshlrev_b32_e32 v4, 16, v72
	s_waitcnt vmcnt(22)
	ds_write_b128 v171, v[80:83]
	ds_write_b128 v171, v[76:79] offset:16
	ds_write_b128 v171, v[72:75] offset:9216
	ds_write_b128 v171, v[68:71] offset:9232
	v_and_b32_e32 v5, 0xffff0000, v72
	v_mul_f32_e32 v4, v3, v4
	v_cvt_pk_bf16_f32 v4, v4, v4
	ds_write_b16 v170, v4 offset:27648
	v_mul_f32_e32 v4, v3, v5
	v_lshlrev_b32_e32 v6, 16, v73
	v_cvt_pk_bf16_f32 v4, v4, v4
	ds_write_b16 v170, v4 offset:27792
	v_mul_f32_e32 v4, v3, v6
	v_and_b32_e32 v7, 0xffff0000, v73
	v_cvt_pk_bf16_f32 v4, v4, v4
	ds_write_b16 v170, v4 offset:27936
	v_mul_f32_e32 v4, v3, v7
	v_lshlrev_b32_e32 v8, 16, v74
	v_cvt_pk_bf16_f32 v4, v4, v4
	ds_write_b16 v170, v4 offset:28080
	v_mul_f32_e32 v4, v3, v8
	v_and_b32_e32 v9, 0xffff0000, v74
	v_cvt_pk_bf16_f32 v4, v4, v4
	ds_write_b16 v170, v4 offset:28224
	v_mul_f32_e32 v4, v3, v9
	v_lshlrev_b32_e32 v10, 16, v75
	v_cvt_pk_bf16_f32 v4, v4, v4
	ds_write_b16 v170, v4 offset:28368
	v_mul_f32_e32 v4, v3, v10
	v_and_b32_e32 v11, 0xffff0000, v75
	v_cvt_pk_bf16_f32 v4, v4, v4
	ds_write_b16 v170, v4 offset:28512
	v_mul_f32_e32 v4, v3, v11
	v_cvt_pk_bf16_f32 v4, v4, v4
	ds_write_b16 v170, v4 offset:28656
	v_lshlrev_b32_e32 v4, 16, v68
	v_mul_f32_e32 v4, v3, v4
	v_and_b32_e32 v5, 0xffff0000, v68
	v_cvt_pk_bf16_f32 v4, v4, v4
	ds_write_b16 v170, v4 offset:28800
	v_mul_f32_e32 v4, v3, v5
	v_lshlrev_b32_e32 v6, 16, v69
	v_cvt_pk_bf16_f32 v4, v4, v4
	ds_write_b16 v170, v4 offset:28944
	v_mul_f32_e32 v4, v3, v6
	v_and_b32_e32 v7, 0xffff0000, v69
	v_cvt_pk_bf16_f32 v4, v4, v4
	ds_write_b16 v170, v4 offset:29088
	v_mul_f32_e32 v4, v3, v7
	v_lshlrev_b32_e32 v8, 16, v70
	v_cvt_pk_bf16_f32 v4, v4, v4
	ds_write_b16 v170, v4 offset:29232
	v_mul_f32_e32 v4, v3, v8
	v_and_b32_e32 v9, 0xffff0000, v70
	v_cvt_pk_bf16_f32 v4, v4, v4
	ds_write_b16 v170, v4 offset:29376
	v_mul_f32_e32 v4, v3, v9
	v_lshlrev_b32_e32 v10, 16, v71
	v_and_b32_e32 v11, 0xffff0000, v71
	v_cvt_pk_bf16_f32 v4, v4, v4
	ds_write_b16 v170, v4 offset:29520
	v_mul_f32_e32 v4, v3, v10
	v_mul_f32_e32 v3, v3, v11
	s_mov_b64 s[2:3], -1
	s_and_b64 vcc, exec, s[86:87]
	v_cvt_pk_bf16_f32 v4, v4, v4
	ds_write_b16 v170, v4 offset:29664
	v_cvt_pk_bf16_f32 v3, v3, v3
	ds_write_b16 v170, v3 offset:29808
	s_cbranch_vccz .LBB0_1546
	ds_write_b128 v171, v[64:67] offset:18432
	ds_write_b128 v171, v[60:63] offset:18448
	ds_write_b128 v172, v[52:55] offset:36864
	ds_write_b128 v173, v[56:59] offset:36864
	s_mov_b64 s[2:3], 0

; __device__ __forceinline__ void transpose_item8(const float* W, int N, unsigned char* WT, int ldt, int item, int lane, int mode, int aux) {
;     const int nblk = (N + 63) >> 6, kb = item / nblk, nb = item - kb * nblk, k0 = 64 * kb, n0 = 64 * nb;
;     const int ncol = n0 + lane;
;     const float* wp = W + (size_t)k0 * N + ncol;
;     float v[64];
; #pragma unroll
;     for (int i = 0; i < 64; ++i) v[i] = wp[(size_t)i * N];
; __device__ __forceinline__ void convert_rest(const Args& a, LAS unsigned char* lds, int wave, int lane, int gw, int ngw, int l, int it0, int it1) {
;     ...
;     for (int it = it0 + gw; it < it1; it += ngw) {
;         int r = it;
;         if (r < WI_G) { const int g = r >> 8; transpose_item8(a.in[I_WGATE] + (size_t)(l * 4 + g) * 1024 * 1024, 1024, ws + WS_WG, 1024, r & 255, lane, 2, g); continue; } r -= WI_G;
;         if (r < WI_BR) { const int g = r >> 6; transpose_item(a.in[I_WBR] + (size_t)(l * 4 + g) * 256 * 1024, 1024, (bf16*)(ws + WS_WBR) + (size_t)g * 1024 * 256, 256, scr, r & 63, lane, 0, 0); continue; } r -= WI_BR;
;         if (r < WI_OUT) { transpose_item(a.in[I_WOUT] + (size_t)l * 1024 * 1024, 1024, (bf16*)(ws + WS_WOUT), 1024, scr, r, lane, 0, 0); continue; } r -= WI_OUT;
;         if (r < WI_FF) { const int e = r >> 8; transpose_item8(a.in[I_WFFG] + (size_t)(l * 16 + e) * 1024 * 1024, 1024, ws + WS_WGU + (size_t)e * 2048 * 1024, 1024, r & 255, lane, 3, 0); continue; } r -= WI_FF;
;         if (r < WI_FF) { const int e = r >> 8; transpose_item8(a.in[I_WFFU] + (size_t)(l * 16 + e) * 1024 * 1024, 1024, ws + WS_WGU + (size_t)e * 2048 * 1024, 1024, r & 255, lane, 4, 0); continue; } r -= WI_FF;
.LBB0_1593:
	s_add_i32 s16, s9, 0x1600
	s_cmpk_gt_i32 s16, 0x3ff
	s_mov_b64 s[0:1], -1
	s_cbranch_scc0 .LBB0_1653
	s_cmpk_gt_u32 s16, 0x4ff
	s_cbranch_scc0 .LBB0_1650
	s_cmpk_gt_u32 s16, 0x5ff
	s_cbranch_scc0 .LBB0_1601
	v_readlane_b32 s2, v254, 32
	s_add_i32 s0, s14, 0xfffe8000
	v_readlane_b32 s3, v254, 33
	s_mov_b32 s23, s3
	s_and_b32 s22, s10, 0x3c0
	s_and_b32 s3, s0, 0x3c0
	v_writelane_b32 v254, s22, 32
	s_lshl_b32 s2, s22, 12
	v_or_b32_e32 v17, s3, v116
	v_writelane_b32 v254, s23, 33
	s_cmpk_gt_u32 s16, 0x15ff
	s_mov_b64 s[0:1], -1
	v_lshlrev_b32_e32 v50, 2, v17
	s_cbranch_scc0 .LBB0_1598
	v_readlane_b32 s26, v254, 32
	s_lshr_b32 s0, s9, 8
	v_readlane_b32 s27, v254, 33
	s_add_i32 s24, s0, s5
	s_mov_b32 s25, s27
	v_readlane_b32 s56, v252, 41
	s_lshl_b64 s[24:25], s[24:25], 22
	v_readlane_b32 s62, v252, 47
	v_readlane_b32 s63, v252, 48
	s_add_u32 s17, s62, s24
	s_mov_b32 s1, s27
	s_addc_u32 s22, s63, s25
	s_lshl_b64 s[0:1], s[0:1], 21
	v_readlane_b32 s19, v253, 61
	s_add_u32 s0, s19, s0
	v_readlane_b32 s19, v253, 62
	s_addc_u32 s1, s19, s1
	s_add_u32 s24, s17, s2
	s_addc_u32 s25, s22, 0
	v_lshl_add_u64 v[2:3], s[24:25], 0, v[50:51]
	s_movk_i32 s17, 0x2000
	v_readlane_b32 s70, v252, 55
	v_add_co_u32_e32 v4, vcc, s17, v2
	s_movk_i32 s70, 0x4000
	s_nop 0
	v_addc_co_u32_e32 v5, vcc, 0, v3, vcc
	global_load_dword v18, v50, s[24:25] nt
	global_load_dword v19, v[4:5], off offset:-4096 nt
	global_load_dword v41, v[4:5], off nt
	v_add_co_u32_e32 v4, vcc, s70, v2
	s_movk_i32 s17, 0x6000
	s_nop 0
	v_addc_co_u32_e32 v5, vcc, 0, v3, vcc
	global_load_dword v42, v[4:5], off offset:-4096 nt
	global_load_dword v43, v[4:5], off nt
	v_add_co_u32_e32 v4, vcc, s17, v2
	s_mov_b32 s17, 0x8000
	s_nop 0
	v_addc_co_u32_e32 v5, vcc, 0, v3, vcc
	global_load_dword v44, v[4:5], off offset:-4096 nt
	global_load_dword v45, v[4:5], off nt
	v_add_co_u32_e32 v4, vcc, s17, v2
	s_mov_b32 s17, 0xa000
	s_nop 0
	v_addc_co_u32_e32 v5, vcc, 0, v3, vcc
	global_load_dword v46, v[4:5], off offset:-4096 nt
	global_load_dword v47, v[4:5], off nt
	v_add_co_u32_e32 v4, vcc, s17, v2
	s_mov_b32 s17, 0xc000
	s_nop 0
	v_addc_co_u32_e32 v5, vcc, 0, v3, vcc
	global_load_dword v48, v[4:5], off offset:-4096 nt
	global_load_dword v49, v[4:5], off nt
	v_add_co_u32_e32 v4, vcc, s17, v2
	s_mov_b32 s17, 0xe000
	s_nop 0
	v_addc_co_u32_e32 v5, vcc, 0, v3, vcc
	global_load_dword v52, v[4:5], off offset:-4096 nt
	global_load_dword v53, v[4:5], off nt
	v_add_co_u32_e32 v4, vcc, s17, v2
	s_mov_b32 s17, 0x10000
	s_nop 0
	v_addc_co_u32_e32 v5, vcc, 0, v3, vcc
	global_load_dword v54, v[4:5], off offset:-4096 nt
	global_load_dword v55, v[4:5], off nt
	v_add_co_u32_e32 v4, vcc, s17, v2
	s_mov_b32 s17, 0x12000
	s_nop 0
	v_addc_co_u32_e32 v5, vcc, 0, v3, vcc
	global_load_dword v56, v[4:5], off offset:-4096 nt
	global_load_dword v10, v[4:5], off nt
	v_add_co_u32_e32 v4, vcc, s17, v2
	s_mov_b32 s17, 0x14000
	s_nop 0
	v_addc_co_u32_e32 v5, vcc, 0, v3, vcc
	global_load_dword v57, v[4:5], off offset:-4096 nt
	global_load_dword v58, v[4:5], off nt
	v_add_co_u32_e32 v4, vcc, s17, v2
	s_mov_b32 s17, 0x16000
	s_nop 0
	v_addc_co_u32_e32 v5, vcc, 0, v3, vcc
	global_load_dword v59, v[4:5], off offset:-4096 nt
	global_load_dword v11, v[4:5], off nt
	v_add_co_u32_e32 v4, vcc, s17, v2
	s_mov_b32 s17, 0x18000
	s_nop 0
	v_addc_co_u32_e32 v5, vcc, 0, v3, vcc
	global_load_dword v60, v[4:5], off offset:-4096 nt
	global_load_dword v61, v[4:5], off nt
	v_add_co_u32_e32 v4, vcc, s17, v2
	s_mov_b32 s17, 0x1a000
	s_nop 0
	v_addc_co_u32_e32 v5, vcc, 0, v3, vcc
	global_load_dword v62, v[4:5], off offset:-4096 nt
	global_load_dword v12, v[4:5], off nt
	v_add_co_u32_e32 v4, vcc, s17, v2
	s_mov_b32 s17, 0x1c000
	s_nop 0
	v_addc_co_u32_e32 v5, vcc, 0, v3, vcc
	global_load_dword v63, v[4:5], off offset:-4096 nt
	global_load_dword v64, v[4:5], off nt
	v_add_co_u32_e32 v4, vcc, s17, v2
	s_mov_b32 s17, 0x1e000
	s_nop 0
	v_addc_co_u32_e32 v5, vcc, 0, v3, vcc
	global_load_dword v65, v[4:5], off offset:-4096 nt
	global_load_dword v13, v[4:5], off nt
	v_add_co_u32_e32 v4, vcc, s17, v2
	s_mov_b32 s17, 0x20000
	s_nop 0
	v_addc_co_u32_e32 v5, vcc, 0, v3, vcc
	global_load_dword v66, v[4:5], off offset:-4096 nt
	global_load_dword v67, v[4:5], off nt
	v_add_co_u32_e32 v4, vcc, s17, v2
	s_mov_b32 s17, 0x22000
	s_nop 0
	v_addc_co_u32_e32 v5, vcc, 0, v3, vcc
	global_load_dword v68, v[4:5], off offset:-4096 nt
	global_load_dword v6, v[4:5], off nt
	v_add_co_u32_e32 v4, vcc, s17, v2
	s_mov_b32 s17, 0x24000
	s_nop 0
	v_addc_co_u32_e32 v5, vcc, 0, v3, vcc
	global_load_dword v69, v[4:5], off offset:-4096 nt
	global_load_dword v70, v[4:5], off nt
	v_add_co_u32_e32 v4, vcc, s17, v2
	s_mov_b32 s17, 0x26000
	s_nop 0
	v_addc_co_u32_e32 v5, vcc, 0, v3, vcc
	global_load_dword v71, v[4:5], off offset:-4096 nt
	global_load_dword v7, v[4:5], off nt
	v_add_co_u32_e32 v4, vcc, s17, v2
	s_mov_b32 s17, 0x28000
	s_nop 0
	v_addc_co_u32_e32 v5, vcc, 0, v3, vcc
	global_load_dword v72, v[4:5], off offset:-4096 nt
	global_load_dword v73, v[4:5], off nt
	v_add_co_u32_e32 v4, vcc, s17, v2
	s_mov_b32 s17, 0x2a000
	s_nop 0
	v_addc_co_u32_e32 v5, vcc, 0, v3, vcc
	global_load_dword v74, v[4:5], off offset:-4096 nt
	global_load_dword v8, v[4:5], off nt
	v_add_co_u32_e32 v4, vcc, s17, v2
	s_mov_b32 s17, 0x2c000
	s_nop 0
	v_addc_co_u32_e32 v5, vcc, 0, v3, vcc
	global_load_dword v75, v[4:5], off offset:-4096 nt
	global_load_dword v76, v[4:5], off nt
	v_add_co_u32_e32 v4, vcc, s17, v2
	s_mov_b32 s17, 0x2e000
	s_nop 0
	v_addc_co_u32_e32 v5, vcc, 0, v3, vcc
	global_load_dword v77, v[4:5], off offset:-4096 nt
	global_load_dword v9, v[4:5], off nt
	v_add_co_u32_e32 v4, vcc, s17, v2
; __device__ __forceinline__ unsigned pk4_fp8(float a, float b, float c, float d) { int w = 0; w = __builtin_amdgcn_cvt_pk_fp8_f32(a, b, w, false); w = __builtin_amdgcn_cvt_pk_fp8_f32(c, d, w, true); return (unsigned)w; }
; __device__ __forceinline__ void transpose_item8(const float* W, int N, unsigned char* WT, int ldt, int item, int lane, int mode, int aux) {
;     ...
;     const float* wp = W + (size_t)k0 * N + ncol;
;     float v[64];
; #pragma unroll
;     for (int i = 0; i < 64; ++i) v[i] = wp[(size_t)i * N];
;     unsigned o[16];
; #pragma unroll
;     for (int q = 0; q < 16; ++q) o[q] = pk4_fp8(fminf(fmaxf(v[4 * q] * 64.f, -448.f), 448.f), fminf(fmaxf(v[4 * q + 1] * 64.f, -448.f), 448.f), fminf(fmaxf(v[4 * q + 2] * 64.f, -448.f), 448.f), fminf(fmaxf(v[4 * q + 3] * 64.f, -448.f), 448.f));
	s_mov_b32 s17, 0x30000
	s_nop 0
	v_addc_co_u32_e32 v5, vcc, 0, v3, vcc
	global_load_dword v78, v[4:5], off offset:-4096 nt
	global_load_dword v79, v[4:5], off nt
	v_add_co_u32_e32 v4, vcc, s17, v2
	s_mov_b32 s17, 0x32000
	s_nop 0
	v_addc_co_u32_e32 v5, vcc, 0, v3, vcc
	global_load_dword v80, v[4:5], off offset:-4096 nt
	global_load_dword v81, v[4:5], off nt
	v_add_co_u32_e32 v4, vcc, s17, v2
	s_mov_b32 s17, 0x34000
	s_nop 0
	v_addc_co_u32_e32 v5, vcc, 0, v3, vcc
	global_load_dword v82, v[4:5], off offset:-4096 nt
	global_load_dword v83, v[4:5], off nt
	v_add_co_u32_e32 v4, vcc, s17, v2
	s_mov_b32 s17, 0x36000
	s_nop 0
	v_addc_co_u32_e32 v5, vcc, 0, v3, vcc
	global_load_dword v84, v[4:5], off offset:-4096 nt
	global_load_dword v85, v[4:5], off nt
	v_add_co_u32_e32 v4, vcc, s17, v2
	s_mov_b32 s17, 0x38000
	s_nop 0
	v_addc_co_u32_e32 v5, vcc, 0, v3, vcc
	global_load_dword v86, v[4:5], off offset:-4096 nt
	global_load_dword v87, v[4:5], off nt
	v_add_co_u32_e32 v4, vcc, s17, v2
	s_mov_b32 s17, 0x3a000
	s_nop 0
	v_addc_co_u32_e32 v5, vcc, 0, v3, vcc
	global_load_dword v88, v[4:5], off offset:-4096 nt
	global_load_dword v89, v[4:5], off nt
	v_add_co_u32_e32 v4, vcc, s17, v2
	s_mov_b32 s17, 0x3c000
	s_nop 0
	v_addc_co_u32_e32 v5, vcc, 0, v3, vcc
	global_load_dword v90, v[4:5], off offset:-4096 nt
	global_load_dword v91, v[4:5], off nt
	v_add_co_u32_e32 v4, vcc, s17, v2
	s_mov_b32 s17, 0x3e000
	s_nop 0
	v_addc_co_u32_e32 v5, vcc, 0, v3, vcc
	global_load_dword v92, v[4:5], off offset:-4096 nt
	global_load_dword v93, v[4:5], off nt
	v_add_co_u32_e32 v4, vcc, s17, v2
	s_mov_b32 s17, 0x3f000
	s_nop 0
	v_addc_co_u32_e32 v5, vcc, 0, v3, vcc
	global_load_dword v94, v[4:5], off offset:-4096 nt
	s_nop 0
	global_load_dword v4, v[4:5], off nt
	v_add_co_u32_e32 v2, vcc, s17, v2
	s_mov_b32 s17, 0xc3e00000
	s_nop 0
	v_addc_co_u32_e32 v3, vcc, 0, v3, vcc
	global_load_dword v2, v[2:3], off nt
	s_waitcnt vmcnt(27)
	v_mul_f32_e32 v7, 0x42800000, v7
	v_mul_f32_e32 v6, 0x42800000, v6
	v_mul_f32_e32 v13, 0x42800000, v13
	v_mul_f32_e32 v12, 0x42800000, v12
	v_mul_f32_e32 v11, 0x42800000, v11
	v_mul_f32_e32 v10, 0x42800000, v10
	v_mul_f32_e32 v55, 0x42800000, v55
	s_waitcnt vmcnt(23)
	v_mul_f32_e32 v8, 0x42800000, v8
	v_mul_f32_e32 v53, 0x42800000, v53
	v_mul_f32_e32 v54, 0x42800000, v54
	v_med3_f32 v53, v53, s17, v236
	v_med3_f32 v54, v54, s17, v236
	v_mul_f32_e32 v47, 0x42800000, v47
	v_mul_f32_e32 v48, 0x42800000, v48
	v_med3_f32 v47, v47, s17, v236
	v_med3_f32 v48, v48, s17, v236
	v_mul_f32_e32 v49, 0x42800000, v49
	v_mul_f32_e32 v52, 0x42800000, v52
	v_med3_f32 v49, v49, s17, v236
	s_waitcnt vmcnt(19)
	v_mul_f32_e32 v9, 0x42800000, v9
	v_med3_f32 v52, v52, s17, v236
	v_mul_f32_e32 v43, 0x42800000, v43
	v_mul_f32_e32 v44, 0x42800000, v44
	v_mul_f32_e32 v18, 0x42800000, v18
	v_mul_f32_e32 v19, 0x42800000, v19
	v_med3_f32 v43, v43, s17, v236
	v_med3_f32 v44, v44, s17, v236
	v_med3_f32 v18, v18, s17, v236
	v_med3_f32 v19, v19, s17, v236
	v_mul_f32_e32 v45, 0x42800000, v45
	v_mul_f32_e32 v46, 0x42800000, v46
	v_mul_f32_e32 v41, 0x42800000, v41
	v_mul_f32_e32 v42, 0x42800000, v42
	v_mul_f32_e32 v67, 0x42800000, v67
	v_mul_f32_e32 v68, 0x42800000, v68
	v_mul_f32_e32 v64, 0x42800000, v64
	v_mul_f32_e32 v65, 0x42800000, v65
	v_mul_f32_e32 v61, 0x42800000, v61
	v_mul_f32_e32 v62, 0x42800000, v62
	v_mul_f32_e32 v58, 0x42800000, v58
	v_mul_f32_e32 v59, 0x42800000, v59
	v_med3_f32 v45, v45, s17, v236
	v_med3_f32 v46, v46, s17, v236
	v_med3_f32 v41, v41, s17, v236
	v_med3_f32 v42, v42, s17, v236
	s_waitcnt vmcnt(17)
	v_mul_f32_e32 v79, 0x42800000, v79
	s_waitcnt vmcnt(16)
	v_mul_f32_e32 v80, 0x42800000, v80
	v_mul_f32_e32 v76, 0x42800000, v76
	v_mul_f32_e32 v77, 0x42800000, v77
	v_mul_f32_e32 v73, 0x42800000, v73
	v_mul_f32_e32 v74, 0x42800000, v74
	v_mul_f32_e32 v70, 0x42800000, v70
	v_mul_f32_e32 v71, 0x42800000, v71
	v_med3_f32 v67, v67, s17, v236
	v_med3_f32 v68, v68, s17, v236
	v_med3_f32 v64, v64, s17, v236
	v_med3_f32 v65, v65, s17, v236
	v_med3_f32 v61, v61, s17, v236
	v_med3_f32 v62, v62, s17, v236
	v_med3_f32 v58, v58, s17, v236
	v_med3_f32 v59, v59, s17, v236
	v_med3_f32 v79, v79, s17, v236
	v_med3_f32 v80, v80, s17, v236
	v_med3_f32 v76, v76, s17, v236
	v_med3_f32 v77, v77, s17, v236
	v_med3_f32 v73, v73, s17, v236
	v_med3_f32 v74, v74, s17, v236
	v_med3_f32 v70, v70, s17, v236
	v_med3_f32 v71, v71, s17, v236
	v_readlane_b32 s58, v252, 43
	v_readlane_b32 s59, v252, 44
	v_readlane_b32 s60, v252, 45
	s_waitcnt vmcnt(2)
	v_mul_f32_e32 v5, 0x42800000, v94
	s_waitcnt vmcnt(1)
	v_mul_f32_e32 v3, 0x42800000, v4
	v_mul_f32_e32 v4, 0x42800000, v93
	v_med3_f32 v4, v4, s17, v236
	v_med3_f32 v93, v5, s17, v236
	v_mov_b32_e32 v5, v51
	v_cvt_pk_fp8_f32 v5, v4, v93
	v_mul_f32_e32 v4, 0x42800000, v89
	v_med3_f32 v89, v4, s17, v236
	v_mul_f32_e32 v4, 0x42800000, v90
	v_med3_f32 v90, v4, s17, v236
	v_mov_b32_e32 v4, v51
	s_waitcnt vmcnt(0)
; __device__ __forceinline__ unsigned pk4_fp8(float a, float b, float c, float d) { int w = 0; w = __builtin_amdgcn_cvt_pk_fp8_f32(a, b, w, false); w = __builtin_amdgcn_cvt_pk_fp8_f32(c, d, w, true); return (unsigned)w; }
; __device__ __forceinline__ void transpose_item8(const float* W, int N, unsigned char* WT, int ldt, int item, int lane, int mode, int aux) {
;     ...
;     for (int q = 0; q < 16; ++q) o[q] = pk4_fp8(fminf(fmaxf(v[4 * q] * 64.f, -448.f), 448.f), fminf(fmaxf(v[4 * q + 1] * 64.f, -448.f), 448.f), fminf(fmaxf(v[4 * q + 2] * 64.f, -448.f), 448.f), fminf(fmaxf(v[4 * q + 3] * 64.f, -448.f), 448.f));
;     v4u* dst = (v4u*)(WT + (size_t)rowmap(mode, aux, ncol) * ldt + k0);
; #pragma unroll
;     for (int q = 0; q < 4; ++q) dst[q] = (v4u){o[4 * q], o[4 * q + 1], o[4 * q + 2], o[4 * q + 3]};
	v_mul_f32_e32 v2, 0x42800000, v2
	v_cvt_pk_fp8_f32 v4, v89, v90
	v_med3_f32 v3, v3, s17, v236
	v_med3_f32 v2, v2, s17, v236
	v_cvt_pk_fp8_f32 v5, v3, v2 op_sel:[0,0,1]
	v_mul_f32_e32 v2, 0x42800000, v91
	v_mul_f32_e32 v3, 0x42800000, v92
	v_med3_f32 v2, v2, s17, v236
	v_med3_f32 v3, v3, s17, v236
	v_cvt_pk_fp8_f32 v4, v2, v3 op_sel:[0,0,1]
	v_mul_f32_e32 v3, 0x42800000, v88
	v_mul_f32_e32 v2, 0x42800000, v87
	v_med3_f32 v87, v3, s17, v236
	v_mul_f32_e32 v3, 0x42800000, v85
	v_med3_f32 v85, v3, s17, v236
	v_mul_f32_e32 v3, 0x42800000, v86
	v_med3_f32 v86, v3, s17, v236
	v_mov_b32_e32 v3, v51
	v_cvt_pk_fp8_f32 v3, v85, v86
	v_med3_f32 v2, v2, s17, v236
	v_readlane_b32 s61, v252, 46
	v_readlane_b32 s64, v252, 49
	v_cvt_pk_fp8_f32 v3, v2, v87 op_sel:[0,0,1]
	v_mul_f32_e32 v2, 0x42800000, v83
	v_med3_f32 v83, v2, s17, v236
	v_mul_f32_e32 v2, 0x42800000, v84
	v_med3_f32 v84, v2, s17, v236
	v_mul_f32_e32 v2, 0x42800000, v81
	v_med3_f32 v81, v2, s17, v236
	v_mul_f32_e32 v2, 0x42800000, v82
	v_med3_f32 v82, v2, s17, v236
	v_mov_b32_e32 v2, v51
	v_cvt_pk_fp8_f32 v2, v81, v82
	v_med3_f32 v81, v9, s17, v236
	v_mul_f32_e32 v9, 0x42800000, v78
	v_med3_f32 v78, v9, s17, v236
	v_mov_b32_e32 v9, v51
	v_cvt_pk_fp8_f32 v9, v81, v78
	v_med3_f32 v78, v8, s17, v236
	v_mul_f32_e32 v8, 0x42800000, v75
	v_med3_f32 v75, v8, s17, v236
	v_mov_b32_e32 v8, v51
	v_cvt_pk_fp8_f32 v8, v78, v75
	v_med3_f32 v75, v7, s17, v236
	v_mul_f32_e32 v7, 0x42800000, v72
	v_med3_f32 v72, v7, s17, v236
	v_mov_b32_e32 v7, v51
	v_cvt_pk_fp8_f32 v7, v75, v72
	v_med3_f32 v72, v6, s17, v236
	v_mul_f32_e32 v6, 0x42800000, v69
	v_med3_f32 v69, v6, s17, v236
	v_mov_b32_e32 v6, v51
	v_cvt_pk_fp8_f32 v6, v72, v69
	v_med3_f32 v69, v13, s17, v236
	v_mul_f32_e32 v13, 0x42800000, v66
	v_med3_f32 v66, v13, s17, v236
	v_mov_b32_e32 v13, v51
	v_cvt_pk_fp8_f32 v13, v69, v66
	v_med3_f32 v66, v12, s17, v236
	v_mul_f32_e32 v12, 0x42800000, v63
	v_med3_f32 v63, v12, s17, v236
	v_mov_b32_e32 v12, v51
	v_cvt_pk_fp8_f32 v12, v66, v63
	v_med3_f32 v63, v11, s17, v236
	v_mul_f32_e32 v11, 0x42800000, v60
	v_med3_f32 v60, v11, s17, v236
	v_mov_b32_e32 v11, v51
	v_cvt_pk_fp8_f32 v11, v63, v60
	v_med3_f32 v60, v10, s17, v236
	v_mul_f32_e32 v10, 0x42800000, v57
	v_med3_f32 v57, v10, s17, v236
	v_mov_b32_e32 v10, v51
	v_cvt_pk_fp8_f32 v10, v60, v57
	v_med3_f32 v57, v55, s17, v236
	v_mul_f32_e32 v55, 0x42800000, v56
	v_med3_f32 v56, v55, s17, v236
	v_mov_b32_e32 v55, v51
	v_cvt_pk_fp8_f32 v55, v53, v54
	v_mov_b32_e32 v54, v51
	v_cvt_pk_fp8_f32 v54, v47, v48
	v_mov_b32_e32 v53, v51
	v_cvt_pk_fp8_f32 v53, v43, v44
	v_cvt_pk_fp8_f32 v55, v57, v56 op_sel:[0,0,1]
	v_cvt_pk_fp8_f32 v54, v49, v52 op_sel:[0,0,1]
	v_mov_b32_e32 v52, v51
	v_cvt_pk_fp8_f32 v52, v18, v19
	v_lshlrev_b32_e32 v18, 10, v17
	v_and_b32_e32 v18, 0x1fc00, v18
	v_cvt_pk_fp8_f32 v53, v45, v46 op_sel:[0,0,1]
	v_cvt_pk_fp8_f32 v52, v41, v42 op_sel:[0,0,1]
	v_lshl_or_b32 v18, s3, 11, v18
	v_cvt_pk_fp8_f32 v13, v67, v68 op_sel:[0,0,1]
	v_cvt_pk_fp8_f32 v12, v64, v65 op_sel:[0,0,1]
	v_cvt_pk_fp8_f32 v11, v61, v62 op_sel:[0,0,1]
	v_cvt_pk_fp8_f32 v10, v58, v59 op_sel:[0,0,1]
	v_or_b32_e32 v18, 0x20000, v18
	v_mov_b32_e32 v19, v51
	v_cvt_pk_fp8_f32 v9, v79, v80 op_sel:[0,0,1]
	v_cvt_pk_fp8_f32 v8, v76, v77 op_sel:[0,0,1]
	v_cvt_pk_fp8_f32 v7, v73, v74 op_sel:[0,0,1]
	v_cvt_pk_fp8_f32 v6, v70, v71 op_sel:[0,0,1]
	v_lshl_add_u64 v[18:19], s[0:1], 0, v[18:19]
	v_readlane_b32 s68, v252, 53
	v_readlane_b32 s69, v252, 54
	v_readlane_b32 s71, v252, 56
	s_mov_b32 s58, 0x3f6c835e
	v_readlane_b32 s60, v255, 2
	v_cvt_pk_fp8_f32 v2, v83, v84 op_sel:[0,0,1]
	v_lshl_add_u64 v[18:19], v[18:19], 0, s[26:27]
	v_readlane_b32 s57, v252, 42
	v_readlane_b32 s65, v252, 50
	v_readlane_b32 s66, v252, 51
	v_readlane_b32 s67, v252, 52
	s_movk_i32 s64, 0x440
	s_movk_i32 s68, 0x2200
	s_movk_i32 s71, 0x1ff
	s_mov_b32 s69, 0x7f800000
	s_mov_b32 s59, 0xbec3ef15
	v_readlane_b32 s61, v255, 3
	v_readlane_b32 s62, v255, 4
	s_mov_b32 s63, 0xbf6c835e
	global_store_dwordx4 v[18:19], v[52:55], off
	global_store_dwordx4 v[18:19], v[10:13], off offset:16
	global_store_dwordx4 v[18:19], v[6:9], off offset:32
	global_store_dwordx4 v[18:19], v[2:5], off offset:48
	s_mov_b64 s[0:1], 0
.LBB0_1598:
	s_andn2_b64 vcc, exec, s[0:1]
	s_cbranch_vccnz .LBB0_1600
; __device__ __forceinline__ void transpose_item8(const float* W, int N, unsigned char* WT, int ldt, int item, int lane, int mode, int aux) {
;     const int nblk = (N + 63) >> 6, kb = item / nblk, nb = item - kb * nblk, k0 = 64 * kb, n0 = 64 * nb;
;     const int ncol = n0 + lane;
;     const float* wp = W + (size_t)k0 * N + ncol;
;     float v[64];
; #pragma unroll
;     for (int i = 0; i < 64; ++i) v[i] = wp[(size_t)i * N];
; __device__ __forceinline__ void convert_rest(const Args& a, LAS unsigned char* lds, int wave, int lane, int gw, int ngw, int l, int it0, int it1) {
;     ...
;         if (r < WI_FF) { const int e = r >> 8; transpose_item8(a.in[I_WFFG] + (size_t)(l * 16 + e) * 1024 * 1024, 1024, ws + WS_WGU + (size_t)e * 2048 * 1024, 1024, r & 255, lane, 3, 0); continue; } r -= WI_FF;
	s_add_i32 s0, s9, 0x1000
	v_readlane_b32 s22, v254, 32
	s_lshr_b32 s0, s0, 8
	v_readlane_b32 s23, v254, 33
	s_add_i32 s24, s0, s5
	s_mov_b32 s25, s23
	v_readlane_b32 s56, v252, 41
	s_lshl_b64 s[24:25], s[24:25], 22
	v_readlane_b32 s60, v252, 45
	v_readlane_b32 s61, v252, 46
	s_add_u32 s3, s60, s24
	s_mov_b32 s1, s23
	s_addc_u32 s17, s61, s25
	s_lshl_b64 s[0:1], s[0:1], 21
	v_readlane_b32 s19, v253, 61
	s_add_u32 s0, s19, s0
	v_readlane_b32 s19, v253, 62
	s_addc_u32 s1, s19, s1
	s_add_u32 s2, s3, s2
	s_addc_u32 s3, s17, 0
	v_lshl_add_u64 v[2:3], s[2:3], 0, v[50:51]
	global_load_dword v18, v50, s[2:3] nt
	s_movk_i32 s2, 0x2000
	v_readlane_b32 s70, v252, 55
	v_add_co_u32_e32 v4, vcc, s2, v2
	s_movk_i32 s70, 0x4000
	s_nop 0
	v_addc_co_u32_e32 v5, vcc, 0, v3, vcc
	global_load_dword v19, v[4:5], off offset:-4096 nt
	global_load_dword v41, v[4:5], off nt
	v_add_co_u32_e32 v4, vcc, s70, v2
	s_movk_i32 s2, 0x6000
	s_nop 0
	v_addc_co_u32_e32 v5, vcc, 0, v3, vcc
	global_load_dword v42, v[4:5], off offset:-4096 nt
	global_load_dword v43, v[4:5], off nt
	v_add_co_u32_e32 v4, vcc, s2, v2
	s_mov_b32 s2, 0x8000
	s_nop 0
	v_addc_co_u32_e32 v5, vcc, 0, v3, vcc
	global_load_dword v44, v[4:5], off offset:-4096 nt
	global_load_dword v45, v[4:5], off nt
	v_add_co_u32_e32 v4, vcc, s2, v2
	s_mov_b32 s2, 0xa000
	s_nop 0
	v_addc_co_u32_e32 v5, vcc, 0, v3, vcc
	global_load_dword v46, v[4:5], off offset:-4096 nt
	global_load_dword v47, v[4:5], off nt
	v_add_co_u32_e32 v4, vcc, s2, v2
	s_mov_b32 s2, 0xc000
	s_nop 0
	v_addc_co_u32_e32 v5, vcc, 0, v3, vcc
	global_load_dword v48, v[4:5], off offset:-4096 nt
	global_load_dword v49, v[4:5], off nt
	v_add_co_u32_e32 v4, vcc, s2, v2
	s_mov_b32 s2, 0xe000
	s_nop 0
	v_addc_co_u32_e32 v5, vcc, 0, v3, vcc
	global_load_dword v50, v[4:5], off offset:-4096 nt
	global_load_dword v52, v[4:5], off nt
	v_add_co_u32_e32 v4, vcc, s2, v2
	s_mov_b32 s2, 0x10000
	s_nop 0
	v_addc_co_u32_e32 v5, vcc, 0, v3, vcc
	global_load_dword v53, v[4:5], off offset:-4096 nt
	global_load_dword v54, v[4:5], off nt
	v_add_co_u32_e32 v4, vcc, s2, v2
	s_mov_b32 s2, 0x12000
	s_nop 0
	v_addc_co_u32_e32 v5, vcc, 0, v3, vcc
	global_load_dword v55, v[4:5], off offset:-4096 nt
	global_load_dword v10, v[4:5], off nt
	v_add_co_u32_e32 v4, vcc, s2, v2
	s_mov_b32 s2, 0x14000
	s_nop 0
	v_addc_co_u32_e32 v5, vcc, 0, v3, vcc
	global_load_dword v56, v[4:5], off offset:-4096 nt
	global_load_dword v57, v[4:5], off nt
	v_add_co_u32_e32 v4, vcc, s2, v2
	s_mov_b32 s2, 0x16000
	s_nop 0
	v_addc_co_u32_e32 v5, vcc, 0, v3, vcc
	global_load_dword v58, v[4:5], off offset:-4096 nt
	global_load_dword v11, v[4:5], off nt
	v_add_co_u32_e32 v4, vcc, s2, v2
	s_mov_b32 s2, 0x18000
	s_nop 0
	v_addc_co_u32_e32 v5, vcc, 0, v3, vcc
	global_load_dword v59, v[4:5], off offset:-4096 nt
	global_load_dword v60, v[4:5], off nt
	v_add_co_u32_e32 v4, vcc, s2, v2
	s_mov_b32 s2, 0x1a000
	s_nop 0
	v_addc_co_u32_e32 v5, vcc, 0, v3, vcc
	global_load_dword v61, v[4:5], off offset:-4096 nt
	global_load_dword v12, v[4:5], off nt
	v_add_co_u32_e32 v4, vcc, s2, v2
	s_mov_b32 s2, 0x1c000
	s_nop 0
	v_addc_co_u32_e32 v5, vcc, 0, v3, vcc
	global_load_dword v62, v[4:5], off offset:-4096 nt
	global_load_dword v63, v[4:5], off nt
	v_add_co_u32_e32 v4, vcc, s2, v2
	s_mov_b32 s2, 0x1e000
	s_nop 0
	v_addc_co_u32_e32 v5, vcc, 0, v3, vcc
	global_load_dword v64, v[4:5], off offset:-4096 nt
	global_load_dword v13, v[4:5], off nt
	v_add_co_u32_e32 v4, vcc, s2, v2
	s_mov_b32 s2, 0x20000
	s_nop 0
	v_addc_co_u32_e32 v5, vcc, 0, v3, vcc
	global_load_dword v65, v[4:5], off offset:-4096 nt
	global_load_dword v66, v[4:5], off nt
	v_add_co_u32_e32 v4, vcc, s2, v2
	s_mov_b32 s2, 0x22000
	s_nop 0
	v_addc_co_u32_e32 v5, vcc, 0, v3, vcc
	global_load_dword v67, v[4:5], off offset:-4096 nt
	global_load_dword v6, v[4:5], off nt
	v_add_co_u32_e32 v4, vcc, s2, v2
	s_mov_b32 s2, 0x24000
	s_nop 0
	v_addc_co_u32_e32 v5, vcc, 0, v3, vcc
	global_load_dword v68, v[4:5], off offset:-4096 nt
	global_load_dword v69, v[4:5], off nt
	v_add_co_u32_e32 v4, vcc, s2, v2
	s_mov_b32 s2, 0x26000
	s_nop 0
	v_addc_co_u32_e32 v5, vcc, 0, v3, vcc
	global_load_dword v70, v[4:5], off offset:-4096 nt
	global_load_dword v7, v[4:5], off nt
	v_add_co_u32_e32 v4, vcc, s2, v2
	s_mov_b32 s2, 0x28000
	s_nop 0
	v_addc_co_u32_e32 v5, vcc, 0, v3, vcc
	global_load_dword v71, v[4:5], off offset:-4096 nt
	global_load_dword v72, v[4:5], off nt
	v_add_co_u32_e32 v4, vcc, s2, v2
	s_mov_b32 s2, 0x2a000
	s_nop 0
	v_addc_co_u32_e32 v5, vcc, 0, v3, vcc
	global_load_dword v73, v[4:5], off offset:-4096 nt
	global_load_dword v8, v[4:5], off nt
	v_add_co_u32_e32 v4, vcc, s2, v2
	s_mov_b32 s2, 0x2c000
	s_nop 0
	v_addc_co_u32_e32 v5, vcc, 0, v3, vcc
	global_load_dword v74, v[4:5], off offset:-4096 nt
	global_load_dword v75, v[4:5], off nt
	v_add_co_u32_e32 v4, vcc, s2, v2
	s_mov_b32 s2, 0x2e000
	s_nop 0
	v_addc_co_u32_e32 v5, vcc, 0, v3, vcc
	global_load_dword v76, v[4:5], off offset:-4096 nt
	global_load_dword v9, v[4:5], off nt
	v_add_co_u32_e32 v4, vcc, s2, v2
	s_mov_b32 s2, 0x30000
	s_nop 0
	v_addc_co_u32_e32 v5, vcc, 0, v3, vcc
	global_load_dword v77, v[4:5], off offset:-4096 nt
	global_load_dword v78, v[4:5], off nt
	v_add_co_u32_e32 v4, vcc, s2, v2
	s_mov_b32 s2, 0x32000
	s_nop 0
	v_addc_co_u32_e32 v5, vcc, 0, v3, vcc
	global_load_dword v79, v[4:5], off offset:-4096 nt
	global_load_dword v80, v[4:5], off nt
	v_add_co_u32_e32 v4, vcc, s2, v2
	s_mov_b32 s2, 0x34000
	s_nop 0
	v_addc_co_u32_e32 v5, vcc, 0, v3, vcc
	global_load_dword v81, v[4:5], off offset:-4096 nt
	global_load_dword v82, v[4:5], off nt
	v_add_co_u32_e32 v4, vcc, s2, v2
	s_mov_b32 s2, 0x36000
	s_nop 0
	v_addc_co_u32_e32 v5, vcc, 0, v3, vcc
	global_load_dword v83, v[4:5], off offset:-4096 nt
	global_load_dword v84, v[4:5], off nt
	v_add_co_u32_e32 v4, vcc, s2, v2
	s_mov_b32 s2, 0x38000
	s_nop 0
	v_addc_co_u32_e32 v5, vcc, 0, v3, vcc
	global_load_dword v85, v[4:5], off offset:-4096 nt
	global_load_dword v86, v[4:5], off nt
	v_add_co_u32_e32 v4, vcc, s2, v2
	s_mov_b32 s2, 0x3a000
	s_nop 0
	v_addc_co_u32_e32 v5, vcc, 0, v3, vcc
	global_load_dword v87, v[4:5], off offset:-4096 nt
	global_load_dword v88, v[4:5], off nt
	v_add_co_u32_e32 v4, vcc, s2, v2
	s_mov_b32 s2, 0x3c000
	s_nop 0
	v_addc_co_u32_e32 v5, vcc, 0, v3, vcc
	global_load_dword v89, v[4:5], off offset:-4096 nt
	global_load_dword v90, v[4:5], off nt
	v_add_co_u32_e32 v4, vcc, s2, v2
	s_mov_b32 s2, 0x3e000
	s_nop 0
	v_addc_co_u32_e32 v5, vcc, 0, v3, vcc
	global_load_dword v91, v[4:5], off offset:-4096 nt
	global_load_dword v92, v[4:5], off nt
	v_add_co_u32_e32 v4, vcc, s2, v2
	s_mov_b32 s2, 0x3f000
	s_nop 0
	v_addc_co_u32_e32 v5, vcc, 0, v3, vcc
	global_load_dword v93, v[4:5], off offset:-4096 nt
	s_nop 0
	global_load_dword v4, v[4:5], off nt
	v_add_co_u32_e32 v2, vcc, s2, v2
	s_and_b32 s2, s12, 0x700
	s_nop 0
	v_addc_co_u32_e32 v3, vcc, 0, v3, vcc
	global_load_dword v2, v[2:3], off nt
	v_and_b32_e32 v3, 0x7f, v17
	v_or_b32_e32 v17, s2, v3
	s_mov_b32 s2, 0xc3e00000
	s_waitcnt vmcnt(27)
; __device__ __forceinline__ unsigned pk4_fp8(float a, float b, float c, float d) { int w = 0; w = __builtin_amdgcn_cvt_pk_fp8_f32(a, b, w, false); w = __builtin_amdgcn_cvt_pk_fp8_f32(c, d, w, true); return (unsigned)w; }
; __device__ __forceinline__ void transpose_item8(const float* W, int N, unsigned char* WT, int ldt, int item, int lane, int mode, int aux) {
;     ...
;     for (int q = 0; q < 16; ++q) o[q] = pk4_fp8(fminf(fmaxf(v[4 * q] * 64.f, -448.f), 448.f), fminf(fmaxf(v[4 * q + 1] * 64.f, -448.f), 448.f), fminf(fmaxf(v[4 * q + 2] * 64.f, -448.f), 448.f), fminf(fmaxf(v[4 * q + 3] * 64.f, -448.f), 448.f));
;     v4u* dst = (v4u*)(WT + (size_t)rowmap(mode, aux, ncol) * ldt + k0);
; #pragma unroll
;     for (int q = 0; q < 4; ++q) dst[q] = (v4u){o[4 * q], o[4 * q + 1], o[4 * q + 2], o[4 * q + 3]};
	v_mul_f32_e32 v7, 0x42800000, v7
	v_mul_f32_e32 v6, 0x42800000, v6
	v_mul_f32_e32 v13, 0x42800000, v13
	v_mul_f32_e32 v12, 0x42800000, v12
	s_waitcnt vmcnt(23)
	v_mul_f32_e32 v8, 0x42800000, v8
	v_mul_f32_e32 v11, 0x42800000, v11
	v_mul_f32_e32 v10, 0x42800000, v10
	v_mul_f32_e32 v55, 0x42800000, v55
	v_mul_f32_e32 v52, 0x42800000, v52
	v_mul_f32_e32 v53, 0x42800000, v53
	v_med3_f32 v52, v52, s2, v236
	v_med3_f32 v53, v53, s2, v236
	v_mul_f32_e32 v54, 0x42800000, v54
	v_med3_f32 v54, v54, s2, v236
	v_mul_f32_e32 v47, 0x42800000, v47
	v_mul_f32_e32 v48, 0x42800000, v48
	s_waitcnt vmcnt(19)
	v_mul_f32_e32 v9, 0x42800000, v9
	v_mul_f32_e32 v43, 0x42800000, v43
	v_mul_f32_e32 v44, 0x42800000, v44
	v_mul_f32_e32 v18, 0x42800000, v18
	v_mul_f32_e32 v19, 0x42800000, v19
	v_med3_f32 v47, v47, s2, v236
	v_med3_f32 v48, v48, s2, v236
	v_med3_f32 v43, v43, s2, v236
	v_med3_f32 v44, v44, s2, v236
	v_med3_f32 v18, v18, s2, v236
	v_med3_f32 v19, v19, s2, v236
	v_mul_f32_e32 v49, 0x42800000, v49
	v_mul_f32_e32 v50, 0x42800000, v50
	v_mul_f32_e32 v45, 0x42800000, v45
	v_mul_f32_e32 v46, 0x42800000, v46
	v_mul_f32_e32 v41, 0x42800000, v41
	v_mul_f32_e32 v42, 0x42800000, v42
	v_mul_f32_e32 v66, 0x42800000, v66
	v_mul_f32_e32 v67, 0x42800000, v67
	v_mul_f32_e32 v63, 0x42800000, v63
	v_mul_f32_e32 v64, 0x42800000, v64
	v_mul_f32_e32 v60, 0x42800000, v60
	v_mul_f32_e32 v61, 0x42800000, v61
	v_mul_f32_e32 v57, 0x42800000, v57
	v_mul_f32_e32 v58, 0x42800000, v58
	v_med3_f32 v49, v49, s2, v236
	v_med3_f32 v50, v50, s2, v236
	v_med3_f32 v45, v45, s2, v236
	v_med3_f32 v46, v46, s2, v236
	v_med3_f32 v41, v41, s2, v236
	v_med3_f32 v42, v42, s2, v236
	s_waitcnt vmcnt(17)
	v_mul_f32_e32 v78, 0x42800000, v78
	s_waitcnt vmcnt(16)
	v_mul_f32_e32 v79, 0x42800000, v79
	v_mul_f32_e32 v75, 0x42800000, v75
	v_mul_f32_e32 v76, 0x42800000, v76
	v_mul_f32_e32 v72, 0x42800000, v72
	v_mul_f32_e32 v73, 0x42800000, v73
	v_mul_f32_e32 v69, 0x42800000, v69
	v_mul_f32_e32 v70, 0x42800000, v70
	v_med3_f32 v66, v66, s2, v236
	v_med3_f32 v67, v67, s2, v236
	v_med3_f32 v63, v63, s2, v236
	v_med3_f32 v64, v64, s2, v236
	v_med3_f32 v60, v60, s2, v236
	v_med3_f32 v61, v61, s2, v236
	v_med3_f32 v57, v57, s2, v236
	v_med3_f32 v58, v58, s2, v236
	v_readlane_b32 s58, v252, 43
	v_readlane_b32 s59, v252, 44
	v_med3_f32 v78, v78, s2, v236
	v_med3_f32 v79, v79, s2, v236
	v_med3_f32 v75, v75, s2, v236
	v_med3_f32 v76, v76, s2, v236
	s_waitcnt vmcnt(2)
	v_mul_f32_e32 v5, 0x42800000, v93
	s_waitcnt vmcnt(1)
	v_mul_f32_e32 v3, 0x42800000, v4
	v_mul_f32_e32 v4, 0x42800000, v92
	v_med3_f32 v4, v4, s2, v236
	v_med3_f32 v92, v5, s2, v236
	v_mov_b32_e32 v5, v51
	v_cvt_pk_fp8_f32 v5, v4, v92
	v_mul_f32_e32 v4, 0x42800000, v88
	v_med3_f32 v88, v4, s2, v236
	v_mul_f32_e32 v4, 0x42800000, v89
	v_med3_f32 v89, v4, s2, v236
	v_mov_b32_e32 v4, v51
	s_waitcnt vmcnt(0)
	v_mul_f32_e32 v2, 0x42800000, v2
	v_cvt_pk_fp8_f32 v4, v88, v89
	v_med3_f32 v3, v3, s2, v236
	v_med3_f32 v2, v2, s2, v236
	v_cvt_pk_fp8_f32 v5, v3, v2 op_sel:[0,0,1]
	v_mul_f32_e32 v2, 0x42800000, v90
	v_mul_f32_e32 v3, 0x42800000, v91
	v_med3_f32 v2, v2, s2, v236
	v_med3_f32 v3, v3, s2, v236
	v_cvt_pk_fp8_f32 v4, v2, v3 op_sel:[0,0,1]
	v_mul_f32_e32 v3, 0x42800000, v87
	v_mul_f32_e32 v2, 0x42800000, v86
	v_med3_f32 v86, v3, s2, v236
	v_mul_f32_e32 v3, 0x42800000, v84
	v_med3_f32 v84, v3, s2, v236
	v_mul_f32_e32 v3, 0x42800000, v85
	v_med3_f32 v85, v3, s2, v236
	v_mov_b32_e32 v3, v51
	v_cvt_pk_fp8_f32 v3, v84, v85
	v_med3_f32 v2, v2, s2, v236
	v_med3_f32 v72, v72, s2, v236
	v_med3_f32 v73, v73, s2, v236
	v_cvt_pk_fp8_f32 v3, v2, v86 op_sel:[0,0,1]
	v_mul_f32_e32 v2, 0x42800000, v82
	v_med3_f32 v82, v2, s2, v236
	v_mul_f32_e32 v2, 0x42800000, v83
	v_med3_f32 v83, v2, s2, v236
	v_mul_f32_e32 v2, 0x42800000, v80
	v_med3_f32 v80, v2, s2, v236
	v_mul_f32_e32 v2, 0x42800000, v81
	v_med3_f32 v81, v2, s2, v236
	v_mov_b32_e32 v2, v51
	v_cvt_pk_fp8_f32 v2, v80, v81
	v_med3_f32 v80, v9, s2, v236
	v_mul_f32_e32 v9, 0x42800000, v77
	v_med3_f32 v77, v9, s2, v236
	v_mov_b32_e32 v9, v51
	v_cvt_pk_fp8_f32 v9, v80, v77
	v_med3_f32 v77, v8, s2, v236
	v_mul_f32_e32 v8, 0x42800000, v74
	v_med3_f32 v74, v8, s2, v236
	v_mov_b32_e32 v8, v51
	v_cvt_pk_fp8_f32 v8, v77, v74
	v_med3_f32 v74, v7, s2, v236
	v_mul_f32_e32 v7, 0x42800000, v71
	v_med3_f32 v71, v7, s2, v236
	v_mov_b32_e32 v7, v51
	v_cvt_pk_fp8_f32 v7, v74, v71
	v_med3_f32 v71, v6, s2, v236
	v_mul_f32_e32 v6, 0x42800000, v68
	v_med3_f32 v68, v6, s2, v236
	v_mov_b32_e32 v6, v51
	v_cvt_pk_fp8_f32 v6, v71, v68
	v_med3_f32 v68, v13, s2, v236
	v_mul_f32_e32 v13, 0x42800000, v65
	v_med3_f32 v65, v13, s2, v236
	v_mov_b32_e32 v13, v51
	v_cvt_pk_fp8_f32 v13, v68, v65
	v_med3_f32 v65, v12, s2, v236
	v_mul_f32_e32 v12, 0x42800000, v62
	v_med3_f32 v62, v12, s2, v236
	v_mov_b32_e32 v12, v51
	v_cvt_pk_fp8_f32 v12, v65, v62
	v_med3_f32 v62, v11, s2, v236
	v_mul_f32_e32 v11, 0x42800000, v59
	v_med3_f32 v59, v11, s2, v236
	v_mov_b32_e32 v11, v51
	v_cvt_pk_fp8_f32 v11, v62, v59
	v_med3_f32 v59, v10, s2, v236
	v_mul_f32_e32 v10, 0x42800000, v56
	v_med3_f32 v56, v10, s2, v236
	v_mov_b32_e32 v10, v51
	v_cvt_pk_fp8_f32 v10, v59, v56
	v_med3_f32 v56, v55, s2, v236
	v_mov_b32_e32 v55, v51
	v_cvt_pk_fp8_f32 v55, v52, v53
	v_mov_b32_e32 v53, v51
	v_mov_b32_e32 v52, v51
	v_cvt_pk_fp8_f32 v53, v43, v44
	v_cvt_pk_fp8_f32 v55, v54, v56 op_sel:[0,0,1]
	v_mov_b32_e32 v54, v51
	v_cvt_pk_fp8_f32 v54, v47, v48
	v_cvt_pk_fp8_f32 v52, v18, v19
	v_cvt_pk_fp8_f32 v53, v45, v46 op_sel:[0,0,1]
	v_med3_f32 v69, v69, s2, v236
	v_cvt_pk_fp8_f32 v54, v49, v50 op_sel:[0,0,1]
	v_cvt_pk_fp8_f32 v52, v41, v42 op_sel:[0,0,1]
	v_med3_f32 v70, v70, s2, v236
	v_cvt_pk_fp8_f32 v13, v66, v67 op_sel:[0,0,1]
	v_cvt_pk_fp8_f32 v12, v63, v64 op_sel:[0,0,1]
	v_cvt_pk_fp8_f32 v11, v60, v61 op_sel:[0,0,1]
	v_cvt_pk_fp8_f32 v10, v57, v58 op_sel:[0,0,1]
	v_lshlrev_b32_e32 v50, 10, v17
	v_readlane_b32 s62, v252, 47
	v_readlane_b32 s63, v252, 48
	v_readlane_b32 s64, v252, 49
	v_readlane_b32 s68, v252, 53
	v_readlane_b32 s69, v252, 54
	v_readlane_b32 s71, v252, 56
	s_mov_b32 s58, 0x3f6c835e
	v_readlane_b32 s60, v255, 2
	v_cvt_pk_fp8_f32 v9, v78, v79 op_sel:[0,0,1]
	v_cvt_pk_fp8_f32 v8, v75, v76 op_sel:[0,0,1]
	v_cvt_pk_fp8_f32 v7, v72, v73 op_sel:[0,0,1]
	v_cvt_pk_fp8_f32 v6, v69, v70 op_sel:[0,0,1]
	v_lshl_add_u64 v[18:19], s[0:1], 0, v[50:51]
	s_movk_i32 s64, 0x440
	s_mov_b32 s63, 0xbf6c835e
	v_readlane_b32 s62, v255, 4
	s_movk_i32 s68, 0x2200
	s_movk_i32 s71, 0x1ff
	s_mov_b32 s69, 0x7f800000
	s_mov_b32 s59, 0xbec3ef15
	v_readlane_b32 s61, v255, 3
	v_cvt_pk_fp8_f32 v2, v82, v83 op_sel:[0,0,1]
	v_lshl_add_u64 v[18:19], v[18:19], 0, s[22:23]
	v_readlane_b32 s57, v252, 42
	v_readlane_b32 s65, v252, 50
	v_readlane_b32 s66, v252, 51
	v_readlane_b32 s67, v252, 52
	global_store_dwordx4 v[18:19], v[52:55], off
	global_store_dwordx4 v[18:19], v[10:13], off offset:16
	global_store_dwordx4 v[18:19], v[6:9], off offset:32
	global_store_dwordx4 v[18:19], v[2:5], off offset:48

; #define LAS __attribute__((address_space(3)))
; __device__ __forceinline__ void transpose_item(const float* W, int N, bf16* WT, int ldt, LAS unsigned* scr, int item, int lane, int mode, int aux) {
;     const int nblk = (N + 63) >> 6, kb = item / nblk, nb = item - kb * nblk, k0 = 64 * kb, n0 = 64 * nb;
;     const int ncol = n0 + lane; const bool okc = ncol < N;
;     const float* wp = W + (size_t)k0 * N + (okc ? ncol : 0);
;     float v[64];
; #pragma unroll
;     for (int i = 0; i < 64; ++i) v[i] = wp[(size_t)i * N];
; __device__ __forceinline__ void convert_rest(const Args& a, LAS unsigned char* lds, int wave, int lane, int gw, int ngw, int l, int it0, int it1) {
;     ...
;         if (r < WI_OUT) { transpose_item(a.in[I_WOUT] + (size_t)l * 1024 * 1024, 1024, (bf16*)(ws + WS_WOUT), 1024, scr, r, lane, 0, 0); continue; } r -= WI_OUT;
.LBB0_1601:
	s_andn2_b64 vcc, exec, s[0:1]
	s_cbranch_vccnz .LBB0_1649
	s_lshl_b32 s0, s4, 6
	s_and_b32 s17, s0, 0x3c00
	s_bfe_u32 s23, s16, 0x40004
	s_sub_i32 s0, s14, s17
	v_add_u32_e32 v81, s0, v40
	s_lshl_b32 s0, s23, 18
	s_add_u32 s2, s7, s0
	s_movk_i32 s0, 0x400
	v_cmp_gt_i32_e64 s[0:1], s0, v81
	s_addc_u32 s3, s8, 0
	s_nop 0
	v_cndmask_b32_e64 v2, 0, v81, s[0:1]
	v_ashrrev_i32_e32 v3, 31, v2
	v_lshl_add_u64 v[2:3], v[2:3], 2, s[2:3]
	s_mov_b32 s2, 0xd000
	v_add_co_u32_e32 v4, vcc, s2, v2
	s_mov_b32 s2, 0xf000
	s_nop 0
	v_addc_co_u32_e32 v5, vcc, 0, v3, vcc
	v_add_co_u32_e32 v6, vcc, s2, v2
	s_mov_b32 s2, 0x11000
	s_nop 0
	v_addc_co_u32_e32 v7, vcc, 0, v3, vcc
	v_add_co_u32_e32 v8, vcc, s2, v2
	s_mov_b32 s2, 0x13000
	s_nop 0
	v_addc_co_u32_e32 v9, vcc, 0, v3, vcc
	v_add_co_u32_e32 v10, vcc, s2, v2
	s_mov_b32 s2, 0x15000
	s_nop 0
	v_addc_co_u32_e32 v11, vcc, 0, v3, vcc
	v_add_co_u32_e32 v12, vcc, s2, v2
	s_mov_b32 s2, 0x17000
	s_nop 0
	v_addc_co_u32_e32 v13, vcc, 0, v3, vcc
	v_add_co_u32_e32 v18, vcc, s2, v2
	s_mov_b32 s2, 0x19000
	s_nop 0
	v_addc_co_u32_e32 v19, vcc, 0, v3, vcc
	global_load_dword v76, v[8:9], off offset:-4096 nt
	global_load_dword v75, v[8:9], off nt
	global_load_dword v74, v[10:11], off offset:-4096 nt
	global_load_dword v73, v[10:11], off nt
	global_load_dword v68, v[12:13], off offset:-4096 nt
	global_load_dword v66, v[12:13], off nt
	global_load_dword v67, v[18:19], off offset:-4096 nt
	global_load_dword v65, v[18:19], off nt
	v_add_co_u32_e32 v8, vcc, s2, v2
	s_mov_b32 s2, 0x1b000
	s_nop 0
	v_addc_co_u32_e32 v9, vcc, 0, v3, vcc
	v_add_co_u32_e32 v10, vcc, s2, v2
	s_mov_b32 s2, 0x1d000
	s_nop 0
	v_addc_co_u32_e32 v11, vcc, 0, v3, vcc
	v_add_co_u32_e32 v12, vcc, s2, v2
	s_mov_b32 s2, 0x1f000
	s_nop 0
	v_addc_co_u32_e32 v13, vcc, 0, v3, vcc
	v_add_co_u32_e32 v18, vcc, s2, v2
	s_mov_b32 s2, 0x21000
	s_nop 0
	v_addc_co_u32_e32 v19, vcc, 0, v3, vcc
	global_load_dword v72, v[8:9], off offset:-4096 nt
	global_load_dword v71, v[8:9], off nt
	global_load_dword v70, v[10:11], off offset:-4096 nt
	global_load_dword v69, v[10:11], off nt
	global_load_dword v60, v[12:13], off offset:-4096 nt
	global_load_dword v58, v[12:13], off nt
	global_load_dword v59, v[18:19], off offset:-4096 nt
	global_load_dword v57, v[18:19], off nt
	v_add_co_u32_e32 v8, vcc, s2, v2
	s_mov_b32 s2, 0x23000
	s_nop 0
	v_addc_co_u32_e32 v9, vcc, 0, v3, vcc
	v_add_co_u32_e32 v10, vcc, s2, v2
	s_mov_b32 s2, 0x25000
	s_nop 0
	v_addc_co_u32_e32 v11, vcc, 0, v3, vcc
	v_add_co_u32_e32 v12, vcc, s2, v2
	s_mov_b32 s2, 0x27000
	s_nop 0
	v_addc_co_u32_e32 v13, vcc, 0, v3, vcc
	v_add_co_u32_e32 v18, vcc, s2, v2
	s_mov_b32 s2, 0x29000
	s_nop 0
	v_addc_co_u32_e32 v19, vcc, 0, v3, vcc
	global_load_dword v64, v[8:9], off offset:-4096 nt
	global_load_dword v63, v[8:9], off nt
	global_load_dword v62, v[10:11], off offset:-4096 nt
	global_load_dword v61, v[10:11], off nt
	global_load_dword v52, v[12:13], off offset:-4096 nt
	global_load_dword v49, v[12:13], off nt
	global_load_dword v50, v[18:19], off offset:-4096 nt
	global_load_dword v48, v[18:19], off nt
	v_add_co_u32_e32 v8, vcc, s2, v2
	s_mov_b32 s2, 0x2b000
	s_nop 0
	v_addc_co_u32_e32 v9, vcc, 0, v3, vcc
	v_add_co_u32_e32 v10, vcc, s2, v2
	s_mov_b32 s2, 0x2d000
	s_nop 0
	v_addc_co_u32_e32 v11, vcc, 0, v3, vcc
	v_add_co_u32_e32 v12, vcc, s2, v2
	s_mov_b32 s2, 0x2f000
	s_nop 0
	v_addc_co_u32_e32 v13, vcc, 0, v3, vcc
	v_add_co_u32_e32 v18, vcc, s2, v2
	s_mov_b32 s2, 0x31000
	s_nop 0
	v_addc_co_u32_e32 v19, vcc, 0, v3, vcc
	global_load_dword v56, v[8:9], off offset:-4096 nt
	global_load_dword v55, v[8:9], off nt
	global_load_dword v54, v[10:11], off offset:-4096 nt
	global_load_dword v53, v[10:11], off nt
	global_load_dword v43, v[12:13], off offset:-4096 nt
	global_load_dword v41, v[12:13], off nt
	global_load_dword v42, v[18:19], off offset:-4096 nt
	s_nop 0
	global_load_dword v19, v[18:19], off nt
	v_add_co_u32_e32 v8, vcc, s2, v2
	s_mov_b32 s2, 0x33000
	s_nop 0
	v_addc_co_u32_e32 v9, vcc, 0, v3, vcc
	v_add_co_u32_e32 v10, vcc, s2, v2
	s_mov_b32 s2, 0x35000
	s_nop 0
	v_addc_co_u32_e32 v11, vcc, 0, v3, vcc
	v_add_co_u32_e32 v12, vcc, s2, v2
	s_mov_b32 s2, 0x37000
	s_nop 0
	v_addc_co_u32_e32 v13, vcc, 0, v3, vcc
	v_add_co_u32_e32 v78, vcc, s2, v2
	s_mov_b32 s2, 0x39000
	s_nop 0
	v_addc_co_u32_e32 v79, vcc, 0, v3, vcc
	global_load_dword v47, v[8:9], off offset:-4096 nt
	global_load_dword v46, v[8:9], off nt
	global_load_dword v45, v[10:11], off offset:-4096 nt
	global_load_dword v44, v[10:11], off nt
	s_nop 0
	global_load_dword v11, v[12:13], off offset:-4096 nt
	global_load_dword v9, v[12:13], off nt
	global_load_dword v10, v[78:79], off offset:-4096 nt
	global_load_dword v8, v[78:79], off nt
	v_add_co_u32_e32 v12, vcc, s2, v2
	s_mov_b32 s2, 0x3b000
	s_nop 0
	v_addc_co_u32_e32 v13, vcc, 0, v3, vcc
	v_add_co_u32_e32 v78, vcc, s2, v2
	s_mov_b32 s2, 0x3c000
	s_nop 0
	v_addc_co_u32_e32 v79, vcc, 0, v3, vcc
	v_add_co_u32_e32 v82, vcc, s2, v2
	global_load_dword v17, v[12:13], off offset:-4096 nt
	s_nop 0
	global_load_dword v13, v[12:13], off nt
	s_nop 0
	global_load_dword v18, v[78:79], off offset:-4096 nt
	global_load_dword v12, v[78:79], off nt
	v_addc_co_u32_e32 v83, vcc, 0, v3, vcc
	v_add_co_u32_e32 v84, vcc, 0x3d000, v2
	s_movk_i32 s2, 0x3ff
	s_nop 0
	v_addc_co_u32_e32 v85, vcc, 0, v3, vcc
	v_add_co_u32_e32 v86, vcc, 0x3e000, v2
	v_cmp_lt_i32_e64 s[36:37], s2, v81
	s_nop 0
	v_addc_co_u32_e32 v87, vcc, 0, v3, vcc
	v_add_co_u32_e32 v88, vcc, 0x3f000, v2
	s_nop 1
	v_addc_co_u32_e32 v89, vcc, 0, v3, vcc
	global_load_dword v80, v[4:5], off offset:-4096 nt
	global_load_dword v79, v[4:5], off nt
	global_load_dword v78, v[6:7], off offset:-4096 nt
	global_load_dword v77, v[6:7], off nt
	s_nop 0
	global_load_dword v7, v[82:83], off nt
	global_load_dword v6, v[84:85], off nt
	global_load_dword v5, v[86:87], off nt
	global_load_dword v4, v[88:89], off nt
	s_and_saveexec_b64 s[2:3], s[36:37]
	s_xor_b64 s[2:3], exec, s[2:3]
	s_cbranch_execz .LBB0_1604
	ds_write2_b32 v20, v51, v51 offset1:65
	ds_write2_b32 v20, v51, v51 offset0:130 offset1:195
; __device__ __forceinline__ unsigned pk2(float lo, float hi) { return f2bf(lo) | (f2bf(hi) << 16); }
; __device__ __forceinline__ void transpose_item(const float* W, int N, bf16* WT, int ldt, LAS unsigned* scr, int item, int lane, int mode, int aux) {
;     ...
;     const float* wp = W + (size_t)k0 * N + (okc ? ncol : 0);
;     float v[64];
; #pragma unroll
;     for (int i = 0; i < 64; ++i) v[i] = wp[(size_t)i * N];
; #pragma unroll
;     for (int i = 0; i < 32; ++i) scr[i * 65 + lane] = okc ? pk2(v[2 * i], v[2 * i + 1]) : 0u;
.LBB0_1604:
	s_or_saveexec_b64 s[2:3], s[2:3]
	v_mov_b32_e32 v81, 0
	v_mov_b32_e32 v82, 0
	s_xor_b64 exec, exec, s[2:3]
	s_cbranch_execz .LBB0_1606
	v_add_co_u32_e32 v82, vcc, 0xb000, v2
	s_movk_i32 s19, 0x6000
	s_nop 0
	v_addc_co_u32_e32 v83, vcc, 0, v3, vcc
	global_load_dword v84, v[82:83], off nt
	v_add_co_u32_e32 v82, vcc, 0xa000, v2
	s_movk_i32 s21, 0x7fff
	s_nop 0
	v_addc_co_u32_e32 v83, vcc, 0, v3, vcc
	global_load_dword v85, v[82:83], off nt
	v_add_co_u32_e32 v82, vcc, 0x9000, v2
	s_nop 1
	v_addc_co_u32_e32 v83, vcc, 0, v3, vcc
	global_load_dword v81, v[82:83], off nt
	v_add_co_u32_e32 v82, vcc, 0x8000, v2
	s_nop 1
	v_addc_co_u32_e32 v83, vcc, 0, v3, vcc
	global_load_dword v86, v[82:83], off nt
	v_add_co_u32_e32 v82, vcc, 0x7000, v2
	s_nop 1
	v_addc_co_u32_e32 v83, vcc, 0, v3, vcc
	global_load_dword v87, v[82:83], off nt
	v_add_co_u32_e32 v82, vcc, s19, v2
	s_movk_i32 s19, 0x3000
	s_nop 0
	v_addc_co_u32_e32 v83, vcc, 0, v3, vcc
	global_load_dword v88, v[82:83], off nt
	v_add_co_u32_e32 v82, vcc, 0x5000, v2
	s_nop 1
	v_addc_co_u32_e32 v83, vcc, 0, v3, vcc
	global_load_dword v89, v[82:83], off nt
	v_add_co_u32_e32 v82, vcc, s70, v2
	s_nop 1
	v_addc_co_u32_e32 v83, vcc, 0, v3, vcc
	global_load_dword v90, v[82:83], off nt
	v_add_co_u32_e32 v82, vcc, s19, v2
	s_movk_i32 s19, 0x2000
	s_nop 0
	v_addc_co_u32_e32 v83, vcc, 0, v3, vcc
	global_load_dword v91, v[82:83], off nt
	v_add_co_u32_e32 v82, vcc, s19, v2
	s_movk_i32 s19, 0x1000
	s_nop 0
	v_addc_co_u32_e32 v83, vcc, 0, v3, vcc
	global_load_dword v92, v[82:83], off nt
	v_add_co_u32_e32 v82, vcc, s19, v2
	s_mov_b32 s19, 0xffff0000
	s_nop 0
	v_addc_co_u32_e32 v83, vcc, 0, v3, vcc
	global_load_dword v82, v[82:83], off nt
	s_nop 0
	global_load_dword v2, v[2:3], off nt
	s_waitcnt vmcnt(5)
	v_bfe_u32 v83, v89, 16, 1
	v_add3_u32 v83, v89, v83, s21
	s_waitcnt vmcnt(0)
	v_bfe_u32 v3, v2, 16, 1
	v_add3_u32 v2, v2, v3, s21
	v_bfe_u32 v3, v82, 16, 1
	v_lshrrev_b32_e32 v2, 16, v2
	v_add3_u32 v3, v82, v3, s21
	v_and_or_b32 v2, v3, s19, v2
	v_bfe_u32 v3, v92, 16, 1
	v_add3_u32 v3, v92, v3, s21
	v_bfe_u32 v82, v91, 16, 1
	v_lshrrev_b32_e32 v3, 16, v3
	v_add3_u32 v82, v91, v82, s21
	v_and_or_b32 v3, v82, s19, v3
	v_bfe_u32 v82, v90, 16, 1
	v_add3_u32 v82, v90, v82, s21
	v_lshrrev_b32_e32 v82, 16, v82
	v_and_or_b32 v82, v83, s19, v82
	v_bfe_u32 v83, v88, 16, 1
	v_add3_u32 v83, v88, v83, s21
	v_bfe_u32 v88, v87, 16, 1
	v_lshrrev_b32_e32 v83, 16, v83
	v_add3_u32 v87, v87, v88, s21
	v_and_or_b32 v83, v87, s19, v83
	ds_write2_b32 v20, v2, v3 offset1:65
	ds_write2_b32 v20, v82, v83 offset0:130 offset1:195
	v_bfe_u32 v2, v86, 16, 1
	v_add3_u32 v2, v86, v2, s21
	v_bfe_u32 v3, v81, 16, 1
	v_lshrrev_b32_e32 v2, 16, v2
	v_add3_u32 v3, v81, v3, s21
	v_and_or_b32 v81, v3, s19, v2
	v_bfe_u32 v2, v85, 16, 1
	v_add3_u32 v2, v85, v2, s21
	v_bfe_u32 v3, v84, 16, 1
	v_lshrrev_b32_e32 v2, 16, v2
	v_add3_u32 v3, v84, v3, s21
	v_and_or_b32 v82, v3, s19, v2

; #define LAS __attribute__((address_space(3)))
; __device__ __forceinline__ void transpose_item(const float* W, int N, bf16* WT, int ldt, LAS unsigned* scr, int item, int lane, int mode, int aux) {
;     const int nblk = (N + 63) >> 6, kb = item / nblk, nb = item - kb * nblk, k0 = 64 * kb, n0 = 64 * nb;
;     const int ncol = n0 + lane; const bool okc = ncol < N;
;     const float* wp = W + (size_t)k0 * N + (okc ? ncol : 0);
;     float v[64];
; #pragma unroll
;     for (int i = 0; i < 64; ++i) v[i] = wp[(size_t)i * N];
; __device__ __forceinline__ void convert_rest(const Args& a, LAS unsigned char* lds, int wave, int lane, int gw, int ngw, int l, int it0, int it1) {
;     ...
;         if (r < WI_BR) { const int g = r >> 6; transpose_item(a.in[I_WBR] + (size_t)(l * 4 + g) * 256 * 1024, 1024, (bf16*)(ws + WS_WBR) + (size_t)g * 1024 * 256, 256, scr, r & 63, lane, 0, 0); continue; } r -= WI_BR;
.LBB0_1650:
	s_andn2_b64 vcc, exec, s[0:1]
	s_cbranch_vccnz .LBB0_1652
	v_readlane_b32 s2, v254, 32
	s_add_i32 s0, s9, 0x1200
	v_readlane_b32 s3, v254, 33
	s_lshr_b32 s0, s0, 6
	s_mov_b32 s23, s3
	s_add_i32 s22, s0, s6
	s_mov_b32 s1, s23
	s_lshl_b64 s[2:3], s[22:23], 20
	v_writelane_b32 v254, s0, 32
	s_add_u32 s22, s82, s2
	s_addc_u32 s24, s83, s3
	v_writelane_b32 v254, s1, 33
	s_mov_b32 s1, s23
	s_lshl_b64 s[0:1], s[0:1], 19
	v_readlane_b32 s2, v254, 1
	s_add_u32 s3, s2, s0
	v_readlane_b32 s0, v254, 2
	s_addc_u32 s17, s0, s1
	s_and_b32 s23, s10, 0xc0
	s_add_i32 s0, s14, 0xfffe8000
	s_and_b32 s2, s0, 0x3c0
	s_lshl_b32 s0, s23, 12
	v_or_b32_e32 v2, s2, v116
	s_add_u32 s0, s22, s0
	s_addc_u32 s1, s24, 0
	v_lshlrev_b32_e32 v50, 2, v2
	v_lshl_add_u64 v[2:3], s[0:1], 0, v[50:51]
	s_mov_b32 s19, 0x9000
	v_add_co_u32_e32 v6, vcc, s19, v2
	s_mov_b32 s19, 0xb000
	s_nop 0
	v_addc_co_u32_e32 v7, vcc, 0, v3, vcc
	v_add_co_u32_e32 v8, vcc, s19, v2
	s_mov_b32 s19, 0xd000
	s_nop 0
	v_addc_co_u32_e32 v9, vcc, 0, v3, vcc
	v_add_co_u32_e32 v10, vcc, s19, v2
	s_mov_b32 s19, 0xf000
	s_nop 0
	v_addc_co_u32_e32 v11, vcc, 0, v3, vcc
	global_load_dword v5, v[6:7], off offset:-4096 nt
	global_load_dword v4, v[6:7], off nt
	s_nop 0
	global_load_dword v7, v[8:9], off offset:-4096 nt
	global_load_dword v6, v[8:9], off nt
	s_nop 0
	global_load_dword v9, v[10:11], off offset:-4096 nt
	global_load_dword v8, v[10:11], off nt
	v_add_co_u32_e32 v10, vcc, s19, v2
	s_mov_b32 s19, 0x11000
	s_nop 0
	v_addc_co_u32_e32 v11, vcc, 0, v3, vcc
	v_add_co_u32_e32 v18, vcc, s19, v2
	s_mov_b32 s19, 0x13000
	s_nop 0
	v_addc_co_u32_e32 v19, vcc, 0, v3, vcc
	v_add_co_u32_e32 v42, vcc, s19, v2
	s_mov_b32 s19, 0x15000
	s_nop 0
	v_addc_co_u32_e32 v43, vcc, 0, v3, vcc
	global_load_dword v13, v[10:11], off offset:-4096 nt
	s_nop 0
	global_load_dword v11, v[10:11], off nt
	s_nop 0
	global_load_dword v12, v[18:19], off offset:-4096 nt
	global_load_dword v10, v[18:19], off nt
	s_nop 0
	global_load_dword v18, v[42:43], off offset:-4096 nt
	global_load_dword v17, v[42:43], off nt
	v_add_co_u32_e32 v42, vcc, s19, v2
	s_mov_b32 s19, 0x17000
	s_nop 0
	v_addc_co_u32_e32 v43, vcc, 0, v3, vcc
	global_load_dword v41, v[42:43], off offset:-4096 nt
	global_load_dword v19, v[42:43], off nt
	v_add_co_u32_e32 v42, vcc, s19, v2
	s_mov_b32 s19, 0x19000
	s_nop 0
	v_addc_co_u32_e32 v43, vcc, 0, v3, vcc
	v_add_co_u32_e32 v46, vcc, s19, v2
	s_mov_b32 s19, 0x1b000
	s_nop 0
	v_addc_co_u32_e32 v47, vcc, 0, v3, vcc
	v_add_co_u32_e32 v48, vcc, s19, v2
	s_mov_b32 s19, 0x1d000
	s_nop 0
	v_addc_co_u32_e32 v49, vcc, 0, v3, vcc
	v_add_co_u32_e32 v52, vcc, s19, v2
	s_mov_b32 s19, 0x1f000
	s_nop 0
	v_addc_co_u32_e32 v53, vcc, 0, v3, vcc
	global_load_dword v45, v[42:43], off offset:-4096 nt
	s_nop 0
	global_load_dword v43, v[42:43], off nt
	s_nop 0
	global_load_dword v44, v[46:47], off offset:-4096 nt
	global_load_dword v42, v[46:47], off nt
	s_nop 0
	global_load_dword v47, v[48:49], off offset:-4096 nt
	global_load_dword v46, v[48:49], off nt
	s_nop 0
	global_load_dword v49, v[52:53], off offset:-4096 nt
	global_load_dword v48, v[52:53], off nt
	v_add_co_u32_e32 v52, vcc, s19, v2
	s_mov_b32 s19, 0x21000
	s_nop 0
	v_addc_co_u32_e32 v53, vcc, 0, v3, vcc
	global_load_dword v61, v[52:53], off offset:-4096 nt
	global_load_dword v57, v[52:53], off nt
	v_add_co_u32_e32 v52, vcc, s19, v2
	s_mov_b32 s19, 0x23000
	s_nop 0
	v_addc_co_u32_e32 v53, vcc, 0, v3, vcc
	global_load_dword v58, v[52:53], off offset:-4096 nt
	global_load_dword v54, v[52:53], off nt
	v_add_co_u32_e32 v52, vcc, s19, v2
	s_mov_b32 s19, 0x25000
	s_nop 0
	v_addc_co_u32_e32 v53, vcc, 0, v3, vcc
	global_load_dword v69, v[52:53], off offset:-4096 nt
	global_load_dword v66, v[52:53], off nt
	v_add_co_u32_e32 v52, vcc, s19, v2
	s_mov_b32 s19, 0x27000
	s_nop 0
	v_addc_co_u32_e32 v53, vcc, 0, v3, vcc
	global_load_dword v77, v[52:53], off offset:-4096 nt
	global_load_dword v73, v[52:53], off nt
	v_add_co_u32_e32 v52, vcc, s19, v2
	s_mov_b32 s19, 0x29000
	s_nop 0
	v_addc_co_u32_e32 v53, vcc, 0, v3, vcc
	global_load_dword v85, v[52:53], off offset:-4096 nt
	global_load_dword v83, v[52:53], off nt
	v_add_co_u32_e32 v52, vcc, s19, v2
	s_mov_b32 s19, 0x2b000
	s_nop 0
	v_addc_co_u32_e32 v53, vcc, 0, v3, vcc
	global_load_dword v84, v[52:53], off offset:-4096 nt
	global_load_dword v81, v[52:53], off nt
	v_add_co_u32_e32 v52, vcc, s19, v2
	s_mov_b32 s19, 0x2d000
	s_nop 0
	v_addc_co_u32_e32 v53, vcc, 0, v3, vcc
	global_load_dword v82, v[52:53], off offset:-4096 nt
	global_load_dword v80, v[52:53], off nt
	v_add_co_u32_e32 v52, vcc, s19, v2
	s_mov_b32 s19, 0x2f000
	s_nop 0
	v_addc_co_u32_e32 v53, vcc, 0, v3, vcc
	global_load_dword v79, v[52:53], off offset:-4096 nt
	global_load_dword v76, v[52:53], off nt
	v_add_co_u32_e32 v52, vcc, s19, v2
	s_mov_b32 s19, 0x31000
	s_nop 0
	v_addc_co_u32_e32 v53, vcc, 0, v3, vcc
	global_load_dword v78, v[52:53], off offset:-4096 nt
	global_load_dword v74, v[52:53], off nt
	v_add_co_u32_e32 v52, vcc, s19, v2
	s_mov_b32 s19, 0x33000
	s_nop 0
	v_addc_co_u32_e32 v53, vcc, 0, v3, vcc
	global_load_dword v75, v[52:53], off offset:-4096 nt
	global_load_dword v71, v[52:53], off nt
	v_add_co_u32_e32 v52, vcc, s19, v2
	s_mov_b32 s19, 0x35000
	s_nop 0
	v_addc_co_u32_e32 v53, vcc, 0, v3, vcc
	global_load_dword v72, v[52:53], off offset:-4096 nt
	global_load_dword v70, v[52:53], off nt
	v_add_co_u32_e32 v52, vcc, s19, v2
	s_mov_b32 s19, 0x37000
	s_nop 0
	v_addc_co_u32_e32 v53, vcc, 0, v3, vcc
	global_load_dword v68, v[52:53], off offset:-4096 nt
	global_load_dword v65, v[52:53], off nt
	v_add_co_u32_e32 v52, vcc, s19, v2
	s_mov_b32 s19, 0x39000
	s_nop 0
; __device__ __forceinline__ unsigned pk2(float lo, float hi) { return f2bf(lo) | (f2bf(hi) << 16); }
; #define LDS_WAIT() asm volatile("s_waitcnt lgkmcnt(0)" ::: "memory")
; __device__ __forceinline__ void transpose_item(const float* W, int N, bf16* WT, int ldt, LAS unsigned* scr, int item, int lane, int mode, int aux) {
;     ...
;     const float* wp = W + (size_t)k0 * N + (okc ? ncol : 0);
;     float v[64];
; #pragma unroll
;     for (int i = 0; i < 64; ++i) v[i] = wp[(size_t)i * N];
; #pragma unroll
;     for (int i = 0; i < 32; ++i) scr[i * 65 + lane] = okc ? pk2(v[2 * i], v[2 * i + 1]) : 0u;
;     LDS_WAIT();
;     const int c = lane & 7;
; #pragma unroll
;     for (int j = 0; j < 8; ++j) { const int nn = (lane >> 3) + 8 * j, n = n0 + nn;
;         v4u o; o.x = scr[(4 * c + 0) * 65 + nn]; o.y = scr[(4 * c + 1) * 65 + nn]; o.z = scr[(4 * c + 2) * 65 + nn]; o.w = scr[(4 * c + 3) * 65 + nn];
;         if (n < N) *(v4u*)(WT + (size_t)rowmap(mode, aux, n) * ldt + k0 + 8 * c) = o; }
	v_addc_co_u32_e32 v53, vcc, 0, v3, vcc
	global_load_dword v67, v[52:53], off offset:-4096 nt
	global_load_dword v63, v[52:53], off nt
	v_add_co_u32_e32 v52, vcc, s19, v2
	s_mov_b32 s19, 0x3b000
	s_nop 0
	v_addc_co_u32_e32 v53, vcc, 0, v3, vcc
	global_load_dword v64, v[52:53], off offset:-4096 nt
	global_load_dword v60, v[52:53], off nt
	v_add_co_u32_e32 v52, vcc, s19, v2
	s_mov_b32 s19, 0x3d000
	s_nop 0
	v_addc_co_u32_e32 v53, vcc, 0, v3, vcc
	global_load_dword v62, v[52:53], off offset:-4096 nt
	global_load_dword v59, v[52:53], off nt
	v_add_co_u32_e32 v52, vcc, s19, v2
	s_mov_b32 s19, 0x3f000
	s_nop 0
	v_addc_co_u32_e32 v53, vcc, 0, v3, vcc
	v_add_co_u32_e32 v86, vcc, s19, v2
	s_movk_i32 s19, 0x7000
	s_nop 0
	v_addc_co_u32_e32 v87, vcc, 0, v3, vcc
	global_load_dword v56, v[52:53], off offset:-4096 nt
	s_nop 0
	global_load_dword v53, v[52:53], off nt
	s_nop 0
	global_load_dword v55, v[86:87], off offset:-4096 nt
	global_load_dword v52, v[86:87], off nt
	v_add_co_u32_e32 v86, vcc, s19, v2
	s_movk_i32 s19, 0x6000
	s_nop 0
	v_addc_co_u32_e32 v87, vcc, 0, v3, vcc
	global_load_dword v88, v[86:87], off nt
	v_add_co_u32_e32 v86, vcc, s19, v2
	s_movk_i32 s19, 0x3000
	s_nop 0
	v_addc_co_u32_e32 v87, vcc, 0, v3, vcc
	global_load_dword v89, v[86:87], off nt
	v_add_co_u32_e32 v86, vcc, s38, v2
	s_nop 1
	v_addc_co_u32_e32 v87, vcc, 0, v3, vcc
	global_load_dword v90, v[86:87], off nt
	v_add_co_u32_e32 v86, vcc, s70, v2
	s_nop 1
	v_addc_co_u32_e32 v87, vcc, 0, v3, vcc
	global_load_dword v91, v[86:87], off nt
	v_add_co_u32_e32 v86, vcc, s19, v2
	s_movk_i32 s19, 0x2000
	s_nop 0
	v_addc_co_u32_e32 v87, vcc, 0, v3, vcc
	global_load_dword v92, v[86:87], off nt
	v_add_co_u32_e32 v86, vcc, s19, v2
	s_movk_i32 s19, 0x1000
	s_nop 0
	v_addc_co_u32_e32 v87, vcc, 0, v3, vcc
	v_add_co_u32_e32 v2, vcc, s19, v2
	global_load_dword v86, v[86:87], off nt
	s_nop 0
	v_addc_co_u32_e32 v3, vcc, 0, v3, vcc
	global_load_dword v2, v[2:3], off nt
	s_nop 0
	global_load_dword v3, v50, s[0:1] nt
	s_movk_i32 s1, 0x7fff
	s_mov_b32 s0, 0xffff0000
	s_waitcnt vmcnt(0)
	v_bfe_u32 v50, v3, 16, 1
	v_add3_u32 v3, v3, v50, s1
	v_bfe_u32 v50, v2, 16, 1
	v_lshrrev_b32_e32 v3, 16, v3
	v_add3_u32 v2, v2, v50, s1
	v_and_or_b32 v2, v2, s0, v3
	v_bfe_u32 v3, v86, 16, 1
	v_add3_u32 v3, v86, v3, s1
	v_bfe_u32 v50, v92, 16, 1
	v_lshrrev_b32_e32 v3, 16, v3
	v_add3_u32 v50, v92, v50, s1
	v_and_or_b32 v3, v50, s0, v3
	ds_write2_b32 v20, v2, v3 offset1:65
	v_bfe_u32 v2, v91, 16, 1
	v_add3_u32 v2, v91, v2, s1
	v_bfe_u32 v3, v90, 16, 1
	v_lshrrev_b32_e32 v2, 16, v2
	v_add3_u32 v3, v90, v3, s1
	v_and_or_b32 v2, v3, s0, v2
	v_bfe_u32 v3, v89, 16, 1
	v_add3_u32 v3, v89, v3, s1
	v_bfe_u32 v50, v88, 16, 1
	v_lshrrev_b32_e32 v3, 16, v3
	v_add3_u32 v50, v88, v50, s1
	v_and_or_b32 v3, v50, s0, v3
	ds_write2_b32 v20, v2, v3 offset0:130 offset1:195
	v_bfe_u32 v2, v5, 16, 1
	v_add3_u32 v2, v5, v2, s1
	v_bfe_u32 v3, v4, 16, 1
	v_lshrrev_b32_e32 v2, 16, v2
	v_add3_u32 v3, v4, v3, s1
	v_and_or_b32 v2, v3, s0, v2
	v_bfe_u32 v3, v7, 16, 1
	v_add3_u32 v3, v7, v3, s1
	v_bfe_u32 v4, v6, 16, 1
	v_lshrrev_b32_e32 v3, 16, v3
	v_add3_u32 v4, v6, v4, s1
	v_and_or_b32 v3, v4, s0, v3
	v_add_u32_e32 v4, 0x400, v20
	ds_write2_b32 v4, v2, v3 offset0:4 offset1:69
	v_bfe_u32 v2, v9, 16, 1
	v_add3_u32 v2, v9, v2, s1
	v_bfe_u32 v3, v8, 16, 1
	v_lshrrev_b32_e32 v2, 16, v2
	v_add3_u32 v3, v8, v3, s1
	v_and_or_b32 v2, v3, s0, v2
	v_bfe_u32 v3, v13, 16, 1
	v_add3_u32 v3, v13, v3, s1
	v_bfe_u32 v5, v11, 16, 1
	v_lshrrev_b32_e32 v3, 16, v3
	v_add3_u32 v5, v11, v5, s1
	v_and_or_b32 v3, v5, s0, v3
	ds_write2_b32 v4, v2, v3 offset0:134 offset1:199
	v_bfe_u32 v2, v12, 16, 1
	v_add3_u32 v2, v12, v2, s1
	v_bfe_u32 v3, v10, 16, 1
	v_lshrrev_b32_e32 v2, 16, v2
	v_add3_u32 v3, v10, v3, s1
	v_and_or_b32 v2, v3, s0, v2
	v_bfe_u32 v3, v18, 16, 1
	v_add3_u32 v3, v18, v3, s1
	v_bfe_u32 v4, v17, 16, 1
	v_lshrrev_b32_e32 v3, 16, v3
	v_add3_u32 v4, v17, v4, s1
	v_and_or_b32 v3, v4, s0, v3
	v_add_u32_e32 v4, 0x800, v20
	ds_write2_b32 v4, v2, v3 offset0:8 offset1:73
	v_bfe_u32 v2, v41, 16, 1
	v_add3_u32 v2, v41, v2, s1
	v_bfe_u32 v3, v19, 16, 1
	v_lshrrev_b32_e32 v2, 16, v2
	v_add3_u32 v3, v19, v3, s1
	v_and_or_b32 v2, v3, s0, v2
	v_bfe_u32 v3, v45, 16, 1
	v_add3_u32 v3, v45, v3, s1
	v_bfe_u32 v5, v43, 16, 1
	v_lshrrev_b32_e32 v3, 16, v3
	v_add3_u32 v5, v43, v5, s1
	v_and_or_b32 v3, v5, s0, v3
	ds_write2_b32 v4, v2, v3 offset0:138 offset1:203
	v_bfe_u32 v2, v44, 16, 1
	v_add3_u32 v2, v44, v2, s1
	v_bfe_u32 v3, v42, 16, 1
	v_lshrrev_b32_e32 v2, 16, v2
	v_add3_u32 v3, v42, v3, s1
	v_and_or_b32 v2, v3, s0, v2
	v_bfe_u32 v3, v47, 16, 1
	v_add3_u32 v3, v47, v3, s1
	v_bfe_u32 v4, v46, 16, 1
	v_lshrrev_b32_e32 v3, 16, v3
	v_add3_u32 v4, v46, v4, s1
	v_and_or_b32 v3, v4, s0, v3
	v_add_u32_e32 v4, 0xc00, v20
	ds_write2_b32 v4, v2, v3 offset0:12 offset1:77
	v_bfe_u32 v2, v49, 16, 1
	v_add3_u32 v2, v49, v2, s1
	v_bfe_u32 v3, v48, 16, 1
	v_lshrrev_b32_e32 v2, 16, v2
	v_add3_u32 v3, v48, v3, s1
	v_and_or_b32 v2, v3, s0, v2
	v_bfe_u32 v3, v61, 16, 1
	v_add3_u32 v3, v61, v3, s1
	v_bfe_u32 v5, v57, 16, 1
	v_lshrrev_b32_e32 v3, 16, v3
	v_add3_u32 v5, v57, v5, s1
	v_and_or_b32 v3, v5, s0, v3
	ds_write2_b32 v4, v2, v3 offset0:142 offset1:207
	v_bfe_u32 v2, v58, 16, 1
	v_add3_u32 v2, v58, v2, s1
	v_bfe_u32 v3, v54, 16, 1
	v_lshrrev_b32_e32 v2, 16, v2
	v_add3_u32 v3, v54, v3, s1
	v_and_or_b32 v2, v3, s0, v2
	v_bfe_u32 v3, v69, 16, 1
	v_add3_u32 v3, v69, v3, s1
	v_bfe_u32 v4, v66, 16, 1
	v_lshrrev_b32_e32 v3, 16, v3
	v_add3_u32 v4, v66, v4, s1
	v_and_or_b32 v3, v4, s0, v3
	v_add_u32_e32 v4, 0x1000, v20
	ds_write2_b32 v4, v2, v3 offset0:16 offset1:81
	v_bfe_u32 v2, v77, 16, 1
; __device__ __forceinline__ unsigned pk2(float lo, float hi) { return f2bf(lo) | (f2bf(hi) << 16); }
; #define LDS_WAIT() asm volatile("s_waitcnt lgkmcnt(0)" ::: "memory")
; __device__ __forceinline__ void transpose_item(const float* W, int N, bf16* WT, int ldt, LAS unsigned* scr, int item, int lane, int mode, int aux) {
;     ...
;     for (int i = 0; i < 32; ++i) scr[i * 65 + lane] = okc ? pk2(v[2 * i], v[2 * i + 1]) : 0u;
;     LDS_WAIT();
;     const int c = lane & 7;
; #pragma unroll
;     for (int j = 0; j < 8; ++j) { const int nn = (lane >> 3) + 8 * j, n = n0 + nn;
;         v4u o; o.x = scr[(4 * c + 0) * 65 + nn]; o.y = scr[(4 * c + 1) * 65 + nn]; o.z = scr[(4 * c + 2) * 65 + nn]; o.w = scr[(4 * c + 3) * 65 + nn];
;         if (n < N) *(v4u*)(WT + (size_t)rowmap(mode, aux, n) * ldt + k0 + 8 * c) = o; }
	v_add3_u32 v2, v77, v2, s1
	v_bfe_u32 v3, v73, 16, 1
	v_lshrrev_b32_e32 v2, 16, v2
	v_add3_u32 v3, v73, v3, s1
	v_and_or_b32 v2, v3, s0, v2
	v_bfe_u32 v3, v85, 16, 1
	v_add3_u32 v3, v85, v3, s1
	v_bfe_u32 v5, v83, 16, 1
	v_lshrrev_b32_e32 v3, 16, v3
	v_add3_u32 v5, v83, v5, s1
	v_and_or_b32 v3, v5, s0, v3
	ds_write2_b32 v4, v2, v3 offset0:146 offset1:211
	v_bfe_u32 v2, v84, 16, 1
	v_add3_u32 v2, v84, v2, s1
	v_bfe_u32 v3, v81, 16, 1
	v_lshrrev_b32_e32 v2, 16, v2
	v_add3_u32 v3, v81, v3, s1
	v_and_or_b32 v2, v3, s0, v2
	v_bfe_u32 v3, v82, 16, 1
	v_add3_u32 v3, v82, v3, s1
	v_bfe_u32 v4, v80, 16, 1
	v_lshrrev_b32_e32 v3, 16, v3
	v_add3_u32 v4, v80, v4, s1
	v_and_or_b32 v3, v4, s0, v3
	v_add_u32_e32 v4, 0x1400, v20
	ds_write2_b32 v4, v2, v3 offset0:20 offset1:85
	v_bfe_u32 v2, v79, 16, 1
	v_add3_u32 v2, v79, v2, s1
	v_bfe_u32 v3, v76, 16, 1
	v_lshrrev_b32_e32 v2, 16, v2
	v_add3_u32 v3, v76, v3, s1
	v_and_or_b32 v2, v3, s0, v2
	v_bfe_u32 v3, v78, 16, 1
	v_add3_u32 v3, v78, v3, s1
	v_bfe_u32 v5, v74, 16, 1
	v_lshrrev_b32_e32 v3, 16, v3
	v_add3_u32 v5, v74, v5, s1
	v_and_or_b32 v3, v5, s0, v3
	ds_write2_b32 v4, v2, v3 offset0:150 offset1:215
	v_bfe_u32 v2, v75, 16, 1
	v_add3_u32 v2, v75, v2, s1
	v_bfe_u32 v3, v71, 16, 1
	v_lshrrev_b32_e32 v2, 16, v2
	v_add3_u32 v3, v71, v3, s1
	v_and_or_b32 v2, v3, s0, v2
	v_bfe_u32 v3, v72, 16, 1
	v_add3_u32 v3, v72, v3, s1
	v_bfe_u32 v4, v70, 16, 1
	v_lshrrev_b32_e32 v3, 16, v3
	v_add3_u32 v4, v70, v4, s1
	v_and_or_b32 v3, v4, s0, v3
	v_add_u32_e32 v4, 0x1800, v20
	ds_write2_b32 v4, v2, v3 offset0:24 offset1:89
	v_bfe_u32 v2, v68, 16, 1
	v_add3_u32 v2, v68, v2, s1
	v_bfe_u32 v3, v65, 16, 1
	v_lshrrev_b32_e32 v2, 16, v2
	v_add3_u32 v3, v65, v3, s1
	v_and_or_b32 v2, v3, s0, v2
	v_bfe_u32 v3, v67, 16, 1
	v_add3_u32 v3, v67, v3, s1
	v_bfe_u32 v5, v63, 16, 1
	v_lshrrev_b32_e32 v3, 16, v3
	v_add3_u32 v5, v63, v5, s1
	v_and_or_b32 v3, v5, s0, v3
	ds_write2_b32 v4, v2, v3 offset0:154 offset1:219
	v_bfe_u32 v2, v64, 16, 1
	v_add3_u32 v2, v64, v2, s1
	v_bfe_u32 v3, v60, 16, 1
	v_lshrrev_b32_e32 v2, 16, v2
	v_add3_u32 v3, v60, v3, s1
	v_and_or_b32 v2, v3, s0, v2
	v_bfe_u32 v3, v62, 16, 1
	v_add3_u32 v3, v62, v3, s1
	v_bfe_u32 v4, v59, 16, 1
	v_lshrrev_b32_e32 v3, 16, v3
	v_add3_u32 v4, v59, v4, s1
	v_and_or_b32 v3, v4, s0, v3
	v_add_u32_e32 v4, 0x1c00, v20
	ds_write2_b32 v4, v2, v3 offset0:28 offset1:93
	v_bfe_u32 v2, v56, 16, 1
	v_add3_u32 v2, v56, v2, s1
	v_bfe_u32 v3, v53, 16, 1
	v_lshrrev_b32_e32 v2, 16, v2
	v_add3_u32 v3, v53, v3, s1
	v_and_or_b32 v2, v3, s0, v2
	v_bfe_u32 v3, v55, 16, 1
	v_add3_u32 v3, v55, v3, s1
	v_bfe_u32 v5, v52, 16, 1
	v_lshrrev_b32_e32 v3, 16, v3
	v_add3_u32 v5, v52, v5, s1
	v_and_or_b32 v3, v5, s0, v3
	ds_write2_b32 v4, v2, v3 offset0:158 offset1:223
	s_waitcnt lgkmcnt(0)
	s_lshl_b32 s0, s23, 1
	ds_read2_b32 v[2:3], v22 offset0:65 offset1:73
	ds_read2_b32 v[12:13], v22 offset0:130 offset1:138
	ds_read2_b32 v[4:5], v22 offset0:195 offset1:203
	ds_read2_b32 v[18:19], v22 offset1:8
	s_add_u32 s0, s3, s0
	s_addc_u32 s1, s17, 0
	v_mov_b32_e32 v17, v51
	v_lshl_add_u64 v[10:11], s[0:1], 0, v[16:17]
	v_or_b32_e32 v17, s2, v21
	v_lshlrev_b32_e32 v50, 9, v17
	s_waitcnt lgkmcnt(0)
	v_mov_b32_e32 v6, v18
	v_mov_b32_e32 v7, v2
	v_mov_b32_e32 v8, v12
	v_mov_b32_e32 v9, v4
	v_lshl_add_u64 v[42:43], v[10:11], 0, v[50:51]
	global_store_dwordx4 v[42:43], v[6:9], off
	v_mov_b32_e32 v2, v19
	v_mov_b32_e32 v4, v13
	v_or_b32_e32 v6, s2, v23
	v_lshlrev_b32_e32 v50, 9, v6
	v_lshl_add_u64 v[6:7], v[10:11], 0, v[50:51]
	global_store_dwordx4 v[6:7], v[2:5], off
	ds_read2_b32 v[12:13], v22 offset0:16 offset1:24
	ds_read2_b32 v[2:3], v22 offset0:81 offset1:89
	ds_read2_b32 v[18:19], v22 offset0:146 offset1:154
	ds_read2_b32 v[4:5], v22 offset0:211 offset1:219
	v_or_b32_e32 v17, s2, v24
	v_lshlrev_b32_e32 v50, 9, v17
	s_waitcnt lgkmcnt(3)
	v_mov_b32_e32 v6, v12
	s_waitcnt lgkmcnt(2)
	v_mov_b32_e32 v7, v2
	s_waitcnt lgkmcnt(1)
	v_mov_b32_e32 v8, v18
	s_waitcnt lgkmcnt(0)
	v_mov_b32_e32 v9, v4
	v_lshl_add_u64 v[42:43], v[10:11], 0, v[50:51]
	global_store_dwordx4 v[42:43], v[6:9], off
	v_mov_b32_e32 v2, v13
	v_mov_b32_e32 v4, v19
	v_or_b32_e32 v6, s2, v25
	v_lshlrev_b32_e32 v50, 9, v6
	v_lshl_add_u64 v[6:7], v[10:11], 0, v[50:51]
	global_store_dwordx4 v[6:7], v[2:5], off
	ds_read2_b32 v[2:3], v22 offset0:97 offset1:105
	ds_read2_b32 v[12:13], v22 offset0:162 offset1:170
	ds_read2_b32 v[4:5], v22 offset0:227 offset1:235
	ds_read2_b32 v[18:19], v22 offset0:32 offset1:40
	v_or_b32_e32 v17, s2, v26
	v_lshlrev_b32_e32 v50, 9, v17
	s_waitcnt lgkmcnt(3)
	v_mov_b32_e32 v7, v2
	s_waitcnt lgkmcnt(2)
	v_mov_b32_e32 v8, v12
	s_waitcnt lgkmcnt(0)
	v_mov_b32_e32 v6, v18
	v_mov_b32_e32 v9, v4
	v_lshl_add_u64 v[42:43], v[10:11], 0, v[50:51]
	global_store_dwordx4 v[42:43], v[6:9], off
	v_mov_b32_e32 v2, v19
	v_mov_b32_e32 v4, v13
	v_or_b32_e32 v6, s2, v27
	v_lshlrev_b32_e32 v50, 9, v6
	v_lshl_add_u64 v[6:7], v[10:11], 0, v[50:51]
	global_store_dwordx4 v[6:7], v[2:5], off
	ds_read2_b32 v[12:13], v22 offset0:48 offset1:56
	ds_read2_b32 v[2:3], v22 offset0:113 offset1:121
	ds_read2_b32 v[18:19], v22 offset0:178 offset1:186
	ds_read2_b32 v[4:5], v22 offset0:243 offset1:251
	v_or_b32_e32 v17, s2, v28
	v_lshlrev_b32_e32 v50, 9, v17
	s_waitcnt lgkmcnt(3)
	v_mov_b32_e32 v6, v12
	s_waitcnt lgkmcnt(2)
	v_mov_b32_e32 v7, v2
	s_waitcnt lgkmcnt(1)
	v_mov_b32_e32 v8, v18
	s_waitcnt lgkmcnt(0)
	v_mov_b32_e32 v9, v4
	v_lshl_add_u64 v[42:43], v[10:11], 0, v[50:51]
	global_store_dwordx4 v[42:43], v[6:9], off
	v_mov_b32_e32 v2, v13
	v_mov_b32_e32 v4, v19
	v_or_b32_e32 v6, s2, v29
	v_lshlrev_b32_e32 v50, 9, v6
	v_lshl_add_u64 v[6:7], v[10:11], 0, v[50:51]
	global_store_dwordx4 v[6:7], v[2:5], off
	s_waitcnt lgkmcnt(0)

; __device__ __forceinline__ void transpose_item8(const float* W, int N, unsigned char* WT, int ldt, int item, int lane, int mode, int aux) {
;     const int nblk = (N + 63) >> 6, kb = item / nblk, nb = item - kb * nblk, k0 = 64 * kb, n0 = 64 * nb;
;     const int ncol = n0 + lane;
;     const float* wp = W + (size_t)k0 * N + ncol;
;     float v[64];
; #pragma unroll
;     for (int i = 0; i < 64; ++i) v[i] = wp[(size_t)i * N];
;     unsigned o[16];
; #pragma unroll
;     for (int q = 0; q < 16; ++q) o[q] = pk4_fp8(fminf(fmaxf(v[4 * q] * 64.f, -448.f), 448.f), fminf(fmaxf(v[4 * q + 1] * 64.f, -448.f), 448.f), fminf(fmaxf(v[4 * q + 2] * 64.f, -448.f), 448.f), fminf(fmaxf(v[4 * q + 3] * 64.f, -448.f), 448.f));
;     v4u* dst = (v4u*)(WT + (size_t)rowmap(mode, aux, ncol) * ldt + k0);
; #pragma unroll
;     for (int q = 0; q < 4; ++q) dst[q] = (v4u){o[4 * q], o[4 * q + 1], o[4 * q + 2], o[4 * q + 3]};
; __device__ __forceinline__ void convert_rest(const Args& a, LAS unsigned char* lds, int wave, int lane, int gw, int ngw, int l, int it0, int it1) {
;     ...
;         if (r < WI_G) { const int g = r >> 8; transpose_item8(a.in[I_WGATE] + (size_t)(l * 4 + g) * 1024 * 1024, 1024, ws + WS_WG, 1024, r & 255, lane, 2, g); continue; } r -= WI_G;
;         if (r < WI_BR) { const int g = r >> 6; transpose_item(a.in[I_WBR] + (size_t)(l * 4 + g) * 256 * 1024, 1024, (bf16*)(ws + WS_WBR) + (size_t)g * 1024 * 256, 256, scr, r & 63, lane, 0, 0); continue; } r -= WI_BR;
;         if (r < WI_OUT) { transpose_item(a.in[I_WOUT] + (size_t)l * 1024 * 1024, 1024, (bf16*)(ws + WS_WOUT), 1024, scr, r, lane, 0, 0); continue; } r -= WI_OUT;
;         if (r < WI_FF) { const int e = r >> 8; transpose_item8(a.in[I_WFFG] + (size_t)(l * 16 + e) * 1024 * 1024, 1024, ws + WS_WGU + (size_t)e * 2048 * 1024, 1024, r & 255, lane, 3, 0); continue; } r -= WI_FF;
;         if (r < WI_FF) { const int e = r >> 8; transpose_item8(a.in[I_WFFU] + (size_t)(l * 16 + e) * 1024 * 1024, 1024, ws + WS_WGU + (size_t)e * 2048 * 1024, 1024, r & 255, lane, 4, 0); continue; } r -= WI_FF;
;         { const int e = r >> 8; transpose_item8(a.in[I_WFFD] + (size_t)(l * 16 + e) * 1024 * 1024, 1024, ws + WS_WDN + (size_t)e * 1024 * 1024, 1024, r & 255, lane, 0, 0); }
.LBB0_1653:
	s_andn2_b64 vcc, exec, s[0:1]
	s_cbranch_vccnz .LBB0_1592
	s_ashr_i32 s0, s16, 8
	s_add_i32 s2, s0, s6
	s_ashr_i32 s3, s2, 31
	s_lshl_b64 s[2:3], s[2:3], 22
	s_add_u32 s2, s78, s2
	s_addc_u32 s3, s79, s3
	s_lshl_b32 s1, s16, 2
	v_readlane_b32 s22, v254, 32
	s_and_b32 s22, s1, 0x3c0
	s_lshl_b32 s1, s16, 6
	s_and_b32 s1, s1, 0x3c0
	s_lshl_b32 s16, s22, 12
	v_or_b32_e32 v2, s1, v116
	s_add_u32 s2, s2, s16
	s_addc_u32 s3, s3, 0
	v_lshlrev_b32_e32 v50, 2, v2
	v_lshl_add_u64 v[2:3], s[2:3], 0, v[50:51]
	global_load_dword v17, v50, s[2:3] nt
	s_movk_i32 s2, 0x2000
	v_add_co_u32_e32 v4, vcc, s2, v2
	s_movk_i32 s2, 0x6000
	s_nop 0
	v_addc_co_u32_e32 v5, vcc, 0, v3, vcc
	global_load_dword v19, v[4:5], off offset:-4096 nt
	global_load_dword v41, v[4:5], off nt
	v_add_co_u32_e32 v4, vcc, s70, v2
	s_lshl_b32 s1, s1, 2
	s_nop 0
	v_addc_co_u32_e32 v5, vcc, 0, v3, vcc
	global_load_dword v42, v[4:5], off offset:-4096 nt
	global_load_dword v43, v[4:5], off nt
	v_add_co_u32_e32 v4, vcc, s2, v2
	s_mov_b32 s2, 0x8000
	s_nop 0
	v_addc_co_u32_e32 v5, vcc, 0, v3, vcc
	global_load_dword v44, v[4:5], off offset:-4096 nt
	global_load_dword v45, v[4:5], off nt
	v_add_co_u32_e32 v4, vcc, s2, v2
	s_mov_b32 s2, 0xa000
	s_nop 0
	v_addc_co_u32_e32 v5, vcc, 0, v3, vcc
	global_load_dword v46, v[4:5], off offset:-4096 nt
	global_load_dword v47, v[4:5], off nt
	v_add_co_u32_e32 v4, vcc, s2, v2
	s_mov_b32 s2, 0xc000
	s_nop 0
	v_addc_co_u32_e32 v5, vcc, 0, v3, vcc
	global_load_dword v48, v[4:5], off offset:-4096 nt
	global_load_dword v49, v[4:5], off nt
	v_add_co_u32_e32 v4, vcc, s2, v2
	s_mov_b32 s2, 0xe000
	s_nop 0
	v_addc_co_u32_e32 v5, vcc, 0, v3, vcc
	global_load_dword v50, v[4:5], off offset:-4096 nt
	global_load_dword v52, v[4:5], off nt
	v_add_co_u32_e32 v4, vcc, s2, v2
	s_mov_b32 s2, 0x10000
	s_nop 0
	v_addc_co_u32_e32 v5, vcc, 0, v3, vcc
	global_load_dword v53, v[4:5], off offset:-4096 nt
	global_load_dword v54, v[4:5], off nt
	v_add_co_u32_e32 v4, vcc, s2, v2
	s_mov_b32 s2, 0x12000
	s_nop 0
	v_addc_co_u32_e32 v5, vcc, 0, v3, vcc
	global_load_dword v55, v[4:5], off offset:-4096 nt
	global_load_dword v10, v[4:5], off nt
	v_add_co_u32_e32 v4, vcc, s2, v2
	s_mov_b32 s2, 0x14000
	s_nop 0
	v_addc_co_u32_e32 v5, vcc, 0, v3, vcc
	global_load_dword v56, v[4:5], off offset:-4096 nt
	global_load_dword v57, v[4:5], off nt
	v_add_co_u32_e32 v4, vcc, s2, v2
	s_mov_b32 s2, 0x16000
	s_nop 0
	v_addc_co_u32_e32 v5, vcc, 0, v3, vcc
	global_load_dword v58, v[4:5], off offset:-4096 nt
	global_load_dword v11, v[4:5], off nt
	v_add_co_u32_e32 v4, vcc, s2, v2
	s_mov_b32 s2, 0x18000
	s_nop 0
	v_addc_co_u32_e32 v5, vcc, 0, v3, vcc
	global_load_dword v59, v[4:5], off offset:-4096 nt
	global_load_dword v60, v[4:5], off nt
	v_add_co_u32_e32 v4, vcc, s2, v2
	s_mov_b32 s2, 0x1a000
	s_nop 0
	v_addc_co_u32_e32 v5, vcc, 0, v3, vcc
	global_load_dword v61, v[4:5], off offset:-4096 nt
	global_load_dword v12, v[4:5], off nt
	v_add_co_u32_e32 v4, vcc, s2, v2
	s_mov_b32 s2, 0x1c000
	s_nop 0
	v_addc_co_u32_e32 v5, vcc, 0, v3, vcc
	global_load_dword v62, v[4:5], off offset:-4096 nt
	global_load_dword v63, v[4:5], off nt
	v_add_co_u32_e32 v4, vcc, s2, v2
	s_mov_b32 s2, 0x1e000
	s_nop 0
	v_addc_co_u32_e32 v5, vcc, 0, v3, vcc
	global_load_dword v64, v[4:5], off offset:-4096 nt
	global_load_dword v13, v[4:5], off nt
	v_add_co_u32_e32 v4, vcc, s2, v2
	s_mov_b32 s2, 0x20000
	s_nop 0
	v_addc_co_u32_e32 v5, vcc, 0, v3, vcc
	global_load_dword v65, v[4:5], off offset:-4096 nt
	global_load_dword v66, v[4:5], off nt
	v_add_co_u32_e32 v4, vcc, s2, v2
	s_mov_b32 s2, 0x22000
	s_nop 0
	v_addc_co_u32_e32 v5, vcc, 0, v3, vcc
	global_load_dword v67, v[4:5], off offset:-4096 nt
	global_load_dword v6, v[4:5], off nt
	v_add_co_u32_e32 v4, vcc, s2, v2
	s_mov_b32 s2, 0x24000
	s_nop 0
	v_addc_co_u32_e32 v5, vcc, 0, v3, vcc
	global_load_dword v68, v[4:5], off offset:-4096 nt
	global_load_dword v69, v[4:5], off nt
	v_add_co_u32_e32 v4, vcc, s2, v2
	s_mov_b32 s2, 0x26000
	s_nop 0
	v_addc_co_u32_e32 v5, vcc, 0, v3, vcc
	global_load_dword v70, v[4:5], off offset:-4096 nt
	global_load_dword v7, v[4:5], off nt
	v_add_co_u32_e32 v4, vcc, s2, v2
	s_mov_b32 s2, 0x28000
	s_nop 0
	v_addc_co_u32_e32 v5, vcc, 0, v3, vcc
	global_load_dword v71, v[4:5], off offset:-4096 nt
	global_load_dword v72, v[4:5], off nt
	v_add_co_u32_e32 v4, vcc, s2, v2
	s_mov_b32 s2, 0x2a000
	s_nop 0
	v_addc_co_u32_e32 v5, vcc, 0, v3, vcc
	global_load_dword v73, v[4:5], off offset:-4096 nt
	global_load_dword v8, v[4:5], off nt
	v_add_co_u32_e32 v4, vcc, s2, v2
	s_mov_b32 s2, 0x2c000
	s_nop 0
	v_addc_co_u32_e32 v5, vcc, 0, v3, vcc
	global_load_dword v74, v[4:5], off offset:-4096 nt
	global_load_dword v75, v[4:5], off nt
	v_add_co_u32_e32 v4, vcc, s2, v2
	s_mov_b32 s2, 0x2e000
	s_nop 0
	v_addc_co_u32_e32 v5, vcc, 0, v3, vcc
	global_load_dword v76, v[4:5], off offset:-4096 nt
	global_load_dword v9, v[4:5], off nt
	v_add_co_u32_e32 v4, vcc, s2, v2
	s_mov_b32 s2, 0x30000
	s_nop 0
	v_addc_co_u32_e32 v5, vcc, 0, v3, vcc
	global_load_dword v77, v[4:5], off offset:-4096 nt
	global_load_dword v78, v[4:5], off nt
	v_add_co_u32_e32 v4, vcc, s2, v2
	s_mov_b32 s2, 0x32000
	s_nop 0
	v_addc_co_u32_e32 v5, vcc, 0, v3, vcc
	global_load_dword v79, v[4:5], off offset:-4096 nt
	global_load_dword v80, v[4:5], off nt
	v_add_co_u32_e32 v4, vcc, s2, v2
	s_mov_b32 s2, 0x34000
	s_nop 0
	v_addc_co_u32_e32 v5, vcc, 0, v3, vcc
	global_load_dword v81, v[4:5], off offset:-4096 nt
	global_load_dword v82, v[4:5], off nt
	v_add_co_u32_e32 v4, vcc, s2, v2
	s_mov_b32 s2, 0x36000
	s_nop 0
	v_addc_co_u32_e32 v5, vcc, 0, v3, vcc
	global_load_dword v83, v[4:5], off offset:-4096 nt
	global_load_dword v84, v[4:5], off nt
	v_add_co_u32_e32 v4, vcc, s2, v2
	s_mov_b32 s2, 0x38000
	s_nop 0
	v_addc_co_u32_e32 v5, vcc, 0, v3, vcc
	global_load_dword v85, v[4:5], off offset:-4096 nt
	global_load_dword v86, v[4:5], off nt
	v_add_co_u32_e32 v4, vcc, s2, v2
	s_mov_b32 s2, 0x3a000
	s_nop 0
	v_addc_co_u32_e32 v5, vcc, 0, v3, vcc
	global_load_dword v87, v[4:5], off offset:-4096 nt
	global_load_dword v88, v[4:5], off nt
	v_add_co_u32_e32 v4, vcc, s2, v2
	s_mov_b32 s2, 0x3c000
	s_nop 0
	v_addc_co_u32_e32 v5, vcc, 0, v3, vcc
	global_load_dword v89, v[4:5], off offset:-4096 nt
	global_load_dword v90, v[4:5], off nt
	v_add_co_u32_e32 v4, vcc, s2, v2
	s_mov_b32 s2, 0x3e000
	s_nop 0
	v_addc_co_u32_e32 v5, vcc, 0, v3, vcc
	global_load_dword v91, v[4:5], off offset:-4096 nt
	global_load_dword v92, v[4:5], off nt
	v_add_co_u32_e32 v4, vcc, s2, v2
	s_mov_b32 s2, 0x3f000
	s_nop 0
	v_addc_co_u32_e32 v5, vcc, 0, v3, vcc
	global_load_dword v93, v[4:5], off offset:-4096 nt
	s_nop 0
	global_load_dword v4, v[4:5], off nt
	v_add_co_u32_e32 v2, vcc, s2, v2
	s_lshl_b32 s2, s0, 6
	s_nop 0
	v_addc_co_u32_e32 v3, vcc, 0, v3, vcc
	global_load_dword v2, v[2:3], off nt
	s_and_b32 s2, s2, 0xffffff80
	s_add_i32 s1, s1, s2
	s_lshl_b32 s0, s0, 4
	v_or_b32_e32 v3, s1, v30
	s_and_b32 s0, s0, 16
	v_or3_b32 v18, v3, s0, v31
	s_mov_b32 s0, 0xc3e00000
	s_waitcnt vmcnt(23)
; __device__ __forceinline__ unsigned pk4_fp8(float a, float b, float c, float d) { int w = 0; w = __builtin_amdgcn_cvt_pk_fp8_f32(a, b, w, false); w = __builtin_amdgcn_cvt_pk_fp8_f32(c, d, w, true); return (unsigned)w; }
; __device__ __forceinline__ void transpose_item8(const float* W, int N, unsigned char* WT, int ldt, int item, int lane, int mode, int aux) {
;     ...
;     for (int i = 0; i < 64; ++i) v[i] = wp[(size_t)i * N];
;     unsigned o[16];
; #pragma unroll
;     for (int q = 0; q < 16; ++q) o[q] = pk4_fp8(fminf(fmaxf(v[4 * q] * 64.f, -448.f), 448.f), fminf(fmaxf(v[4 * q + 1] * 64.f, -448.f), 448.f), fminf(fmaxf(v[4 * q + 2] * 64.f, -448.f), 448.f), fminf(fmaxf(v[4 * q + 3] * 64.f, -448.f), 448.f));
;     v4u* dst = (v4u*)(WT + (size_t)rowmap(mode, aux, ncol) * ldt + k0);
; #pragma unroll
;     for (int q = 0; q < 4; ++q) dst[q] = (v4u){o[4 * q], o[4 * q + 1], o[4 * q + 2], o[4 * q + 3]};
	v_mul_f32_e32 v8, 0x42800000, v8
	v_mul_f32_e32 v7, 0x42800000, v7
	v_mul_f32_e32 v6, 0x42800000, v6
	v_mul_f32_e32 v13, 0x42800000, v13
	v_mul_f32_e32 v12, 0x42800000, v12
	v_mul_f32_e32 v11, 0x42800000, v11
	v_mul_f32_e32 v10, 0x42800000, v10
	v_mul_f32_e32 v55, 0x42800000, v55
	v_mul_f32_e32 v52, 0x42800000, v52
	v_mul_f32_e32 v53, 0x42800000, v53
	v_med3_f32 v52, v52, s0, v236
	v_med3_f32 v53, v53, s0, v236
	s_waitcnt vmcnt(19)
	v_mul_f32_e32 v9, 0x42800000, v9
	v_mul_f32_e32 v54, 0x42800000, v54
	v_med3_f32 v54, v54, s0, v236
	v_mul_f32_e32 v47, 0x42800000, v47
	v_mul_f32_e32 v48, 0x42800000, v48
	v_mul_f32_e32 v43, 0x42800000, v43
	v_mul_f32_e32 v44, 0x42800000, v44
	v_mul_f32_e32 v17, 0x42800000, v17
	v_mul_f32_e32 v19, 0x42800000, v19
	v_med3_f32 v47, v47, s0, v236
	v_med3_f32 v48, v48, s0, v236
	v_med3_f32 v43, v43, s0, v236
	v_med3_f32 v44, v44, s0, v236
	v_med3_f32 v17, v17, s0, v236
	v_med3_f32 v19, v19, s0, v236
	s_waitcnt vmcnt(17)
	v_mul_f32_e32 v78, 0x42800000, v78
	s_waitcnt vmcnt(16)
	v_mul_f32_e32 v79, 0x42800000, v79
	v_mul_f32_e32 v75, 0x42800000, v75
	v_mul_f32_e32 v76, 0x42800000, v76
	v_mul_f32_e32 v72, 0x42800000, v72
	v_mul_f32_e32 v73, 0x42800000, v73
	v_mul_f32_e32 v69, 0x42800000, v69
	v_mul_f32_e32 v70, 0x42800000, v70
	v_mul_f32_e32 v66, 0x42800000, v66
	v_mul_f32_e32 v67, 0x42800000, v67
	v_mul_f32_e32 v63, 0x42800000, v63
	v_mul_f32_e32 v64, 0x42800000, v64
	v_mul_f32_e32 v60, 0x42800000, v60
	v_mul_f32_e32 v61, 0x42800000, v61
	v_mul_f32_e32 v57, 0x42800000, v57
	v_mul_f32_e32 v58, 0x42800000, v58
	v_mul_f32_e32 v49, 0x42800000, v49
	v_mul_f32_e32 v50, 0x42800000, v50
	v_mul_f32_e32 v45, 0x42800000, v45
	v_mul_f32_e32 v46, 0x42800000, v46
	v_mul_f32_e32 v41, 0x42800000, v41
	v_mul_f32_e32 v42, 0x42800000, v42
	v_med3_f32 v78, v78, s0, v236
	v_med3_f32 v79, v79, s0, v236
	v_med3_f32 v75, v75, s0, v236
	v_med3_f32 v76, v76, s0, v236
	v_med3_f32 v72, v72, s0, v236
	v_med3_f32 v73, v73, s0, v236
	v_med3_f32 v69, v69, s0, v236
	v_med3_f32 v70, v70, s0, v236
	v_med3_f32 v66, v66, s0, v236
	v_med3_f32 v67, v67, s0, v236
	v_med3_f32 v63, v63, s0, v236
	v_med3_f32 v64, v64, s0, v236
	v_med3_f32 v60, v60, s0, v236
	v_med3_f32 v61, v61, s0, v236
	v_med3_f32 v57, v57, s0, v236
	v_med3_f32 v58, v58, s0, v236
	s_waitcnt vmcnt(2)
	v_mul_f32_e32 v5, 0x42800000, v93
	s_waitcnt vmcnt(1)
	v_mul_f32_e32 v3, 0x42800000, v4
	v_mul_f32_e32 v4, 0x42800000, v92
	v_med3_f32 v4, v4, s0, v236
	v_med3_f32 v92, v5, s0, v236
	v_mov_b32_e32 v5, v51
	v_cvt_pk_fp8_f32 v5, v4, v92
	v_mul_f32_e32 v4, 0x42800000, v88
	v_med3_f32 v88, v4, s0, v236
	v_mul_f32_e32 v4, 0x42800000, v89
	v_med3_f32 v89, v4, s0, v236
	v_mov_b32_e32 v4, v51
	s_waitcnt vmcnt(0)
	v_mul_f32_e32 v2, 0x42800000, v2
	v_cvt_pk_fp8_f32 v4, v88, v89
	v_med3_f32 v3, v3, s0, v236
	v_med3_f32 v2, v2, s0, v236
	v_cvt_pk_fp8_f32 v5, v3, v2 op_sel:[0,0,1]
	v_mul_f32_e32 v2, 0x42800000, v90
	v_mul_f32_e32 v3, 0x42800000, v91
	v_med3_f32 v2, v2, s0, v236
	v_med3_f32 v3, v3, s0, v236
	v_cvt_pk_fp8_f32 v4, v2, v3 op_sel:[0,0,1]
	v_mul_f32_e32 v3, 0x42800000, v87
	v_mul_f32_e32 v2, 0x42800000, v86
	v_med3_f32 v86, v3, s0, v236
	v_mul_f32_e32 v3, 0x42800000, v84
	v_med3_f32 v84, v3, s0, v236
	v_mul_f32_e32 v3, 0x42800000, v85
	v_med3_f32 v85, v3, s0, v236
	v_mov_b32_e32 v3, v51
	v_cvt_pk_fp8_f32 v3, v84, v85
	v_med3_f32 v2, v2, s0, v236
	v_med3_f32 v49, v49, s0, v236
	v_med3_f32 v50, v50, s0, v236
	v_cvt_pk_fp8_f32 v3, v2, v86 op_sel:[0,0,1]
	v_mul_f32_e32 v2, 0x42800000, v82
	v_med3_f32 v82, v2, s0, v236
	v_mul_f32_e32 v2, 0x42800000, v83
	v_med3_f32 v83, v2, s0, v236
	v_mul_f32_e32 v2, 0x42800000, v80
	v_med3_f32 v80, v2, s0, v236
	v_mul_f32_e32 v2, 0x42800000, v81
	v_med3_f32 v81, v2, s0, v236
	v_mov_b32_e32 v2, v51
	v_cvt_pk_fp8_f32 v2, v80, v81
	v_med3_f32 v80, v9, s0, v236
	v_mul_f32_e32 v9, 0x42800000, v77
	v_med3_f32 v77, v9, s0, v236
	v_mov_b32_e32 v9, v51
	v_cvt_pk_fp8_f32 v9, v80, v77
	v_med3_f32 v77, v8, s0, v236
	v_mul_f32_e32 v8, 0x42800000, v74
	v_med3_f32 v74, v8, s0, v236
	v_mov_b32_e32 v8, v51
	v_cvt_pk_fp8_f32 v8, v77, v74
	v_med3_f32 v74, v7, s0, v236
	v_mul_f32_e32 v7, 0x42800000, v71
	v_med3_f32 v71, v7, s0, v236
	v_mov_b32_e32 v7, v51
	v_cvt_pk_fp8_f32 v7, v74, v71
	v_med3_f32 v71, v6, s0, v236
	v_mul_f32_e32 v6, 0x42800000, v68
	v_med3_f32 v68, v6, s0, v236
	v_mov_b32_e32 v6, v51
	v_cvt_pk_fp8_f32 v6, v71, v68
	v_med3_f32 v68, v13, s0, v236
	v_mul_f32_e32 v13, 0x42800000, v65
	v_med3_f32 v65, v13, s0, v236
	v_mov_b32_e32 v13, v51
	v_cvt_pk_fp8_f32 v13, v68, v65
	v_med3_f32 v65, v12, s0, v236
	v_mul_f32_e32 v12, 0x42800000, v62
	v_med3_f32 v62, v12, s0, v236
	v_mov_b32_e32 v12, v51
	v_cvt_pk_fp8_f32 v12, v65, v62
	v_med3_f32 v62, v11, s0, v236
	v_mul_f32_e32 v11, 0x42800000, v59
	v_med3_f32 v59, v11, s0, v236
	v_mov_b32_e32 v11, v51
	v_cvt_pk_fp8_f32 v11, v62, v59
	v_med3_f32 v59, v10, s0, v236
	v_mul_f32_e32 v10, 0x42800000, v56
	v_med3_f32 v56, v10, s0, v236
	v_mov_b32_e32 v10, v51
	v_cvt_pk_fp8_f32 v10, v59, v56
	v_med3_f32 v56, v55, s0, v236
	v_mov_b32_e32 v55, v51
	v_cvt_pk_fp8_f32 v55, v52, v53
	v_mov_b32_e32 v53, v51
	v_mov_b32_e32 v52, v51
	v_cvt_pk_fp8_f32 v53, v43, v44
	v_cvt_pk_fp8_f32 v55, v54, v56 op_sel:[0,0,1]
	v_mov_b32_e32 v54, v51
	v_cvt_pk_fp8_f32 v54, v47, v48
	v_cvt_pk_fp8_f32 v52, v17, v19
	v_med3_f32 v45, v45, s0, v236
	v_med3_f32 v46, v46, s0, v236
	v_med3_f32 v41, v41, s0, v236
	v_med3_f32 v42, v42, s0, v236
	v_ashrrev_i32_e32 v19, 31, v18
	v_readlane_b32 s0, v254, 3
	v_readlane_b32 s23, v254, 33
	v_cvt_pk_fp8_f32 v54, v49, v50 op_sel:[0,0,1]
	v_cvt_pk_fp8_f32 v53, v45, v46 op_sel:[0,0,1]
	v_cvt_pk_fp8_f32 v52, v41, v42 op_sel:[0,0,1]
	v_lshlrev_b64 v[18:19], 10, v[18:19]
	v_readlane_b32 s1, v254, 4
	v_cvt_pk_fp8_f32 v13, v66, v67 op_sel:[0,0,1]
	v_cvt_pk_fp8_f32 v12, v63, v64 op_sel:[0,0,1]
	v_cvt_pk_fp8_f32 v11, v60, v61 op_sel:[0,0,1]
	v_cvt_pk_fp8_f32 v10, v57, v58 op_sel:[0,0,1]
	v_lshl_add_u64 v[18:19], s[0:1], 0, v[18:19]
	s_mov_b32 s1, s23
	v_cvt_pk_fp8_f32 v9, v78, v79 op_sel:[0,0,1]
	v_cvt_pk_fp8_f32 v8, v75, v76 op_sel:[0,0,1]
	v_cvt_pk_fp8_f32 v7, v72, v73 op_sel:[0,0,1]
	v_cvt_pk_fp8_f32 v6, v69, v70 op_sel:[0,0,1]
	v_writelane_b32 v254, s0, 32
	v_cvt_pk_fp8_f32 v2, v82, v83 op_sel:[0,0,1]
	v_lshl_add_u64 v[18:19], v[18:19], 0, s[22:23]
	v_writelane_b32 v254, s1, 33
	global_store_dwordx4 v[18:19], v[52:55], off
	global_store_dwordx4 v[18:19], v[10:13], off offset:16
	global_store_dwordx4 v[18:19], v[6:9], off offset:32
	global_store_dwordx4 v[18:19], v[2:5], off offset:48
	s_branch .LBB0_1592

; __device__ __forceinline__ void fin_load(FinRow& R, const bf16* ZB, const bf16* PB, const bf16* SO, const float* FO, int row, int ch) {
; #pragma unroll
;     for (int k = 0; k < 6; ++k) R.so[k] = *(const v2u*)(SO + ((size_t)k * MT + row) * 256 + ch);
;     R.zg[0] = *(const v2u*)(ZB + (size_t)row * NZB + 512 + ch); R.zg[1] = *(const v2u*)(ZB + (size_t)row * NZB + 1536 + ch); R.zg[2] = *(const v2u*)(ZB + (size_t)row * NZB + 2560 + ch);
;     R.px = *(const v2u*)(PB + (size_t)row * NPB + 768 + ch);
;     R.fo0 = *(const f32x4*)(FO + (size_t)row * 256 + ch); R.fo1 = (f32x4){0.f, 0.f, 0.f, 0.f};
; }
; __device__ __forceinline__ void phase_finish(const Args& a, const WCtx& w, int l, int nrows) {
;     const bf16* ZB = (const bf16*)(a.ws + WS_ZB); const bf16* PB = (const bf16*)(a.ws + WS_PB); const bf16* SO = (const bf16*)(a.ws + WS_SO); const float* FO = (const float*)(a.ws + WS_FO);
;     bf16* OUTS = (bf16*)(a.ws + WS_OUTS);
;     const int ch = 4 * w.lane, hd = w.lane >> 4;
;     const f32x4 nwa = *(const f32x4*)(a.in[I_HGRN_NW] + l * 256 + ch), nwb = *(const f32x4*)(a.in[I_GDN_NW] + l * 256 + ch), nwd = *(const f32x4*)(a.in[I_SSD_NW] + l * 256 + ch);
;     const float dsk = a.in[I_SSD_D][l * 4 + hd];
;     int row = w.gw; FinRow R, Rn;
;     if (row < nrows) fin_load(R, ZB, PB, SO, FO, row, ch);
;     while (row < nrows) {
;         const int nrow = row + w.NGW;
;         if (nrow < nrows) fin_load(Rn, ZB, PB, SO, FO, nrow, ch);
.LBB0_1711:
	s_andn2_b64 vcc, exec, s[0:1]
	s_cbranch_vccnz .LBB0_1771
	v_mov_b32_e32 v10, v0
	v_readlane_b32 s0, v252, 0
	v_readlane_b32 s2, v254, 60
	v_readfirstlane_b32 s1, v10
	s_ashr_i32 s1, s1, 6
	s_lshl_b32 s0, s0, 3
	v_readlane_b32 s3, v254, 61
	s_add_i32 s0, s0, s1
	s_load_dword s10, s[2:3], 0x0
	s_mov_b64 s[2:3], s[52:53]
	s_cmp_ge_i32 s0, s19
	s_waitcnt lgkmcnt(0)
	s_cbranch_scc1 .LBB0_1717
	v_readlane_b32 s1, v255, 7
	v_readlane_b32 s4, v254, 32
	v_readlane_b32 s5, v254, 33
	s_lshl_b32 s4, s1, 8
	s_lshl_b32 s2, s10, 3
	s_mov_b32 s3, s5
	s_lshl_b64 s[4:5], s[4:5], 2
	v_readlane_b32 s56, v252, 25
	v_readlane_b32 s57, v252, 26
	s_add_u32 s6, s56, s4
	v_readlane_b32 s64, v252, 33
	s_addc_u32 s7, s57, s5
	v_and_b32_e32 v12, 63, v10
	v_writelane_b32 v254, s2, 32
	v_readlane_b32 s65, v252, 34
	s_add_u32 s8, s64, s4
	v_writelane_b32 v254, s3, 33
	s_waitcnt vmcnt(0)
	v_lshlrev_b32_e32 v28, 4, v12
	s_addc_u32 s9, s65, s5
	v_bfe_u32 v10, v10, 4, 2
	global_load_dwordx4 v[2:5], v28, s[6:7] nt
	global_load_dwordx4 v[6:9], v28, s[8:9] nt
	s_add_u32 s4, s76, s4
	v_lshl_or_b32 v10, s1, 2, v10
	v_mov_b32_e32 v11, v51
	v_readlane_b32 s6, v254, 5
	s_addc_u32 s5, s77, s5
	v_lshl_add_u64 v[10:11], v[10:11], 2, s[74:75]
	s_ashr_i32 s1, s0, 31
	v_lshlrev_b32_e32 v14, 3, v12
	v_mov_b32_e32 v15, v51
	v_readlane_b32 s7, v254, 6
	global_load_dword v22, v[10:11], off nt
	s_mov_b32 s3, 0x1200000
	v_lshl_add_u64 v[10:11], s[6:7], 0, v[14:15]
	s_lshl_b64 s[6:7], s[0:1], 9
	v_lshl_add_u64 v[10:11], v[10:11], 0, s[6:7]
	v_add_co_u32_e32 v12, vcc, s3, v10
	s_mov_b32 s3, 0x2400000
	s_nop 0
	v_addc_co_u32_e32 v13, vcc, 0, v11, vcc
	v_add_co_u32_e32 v16, vcc, s3, v10
	s_mov_b32 s3, 0x3600000
	s_nop 0
	v_addc_co_u32_e32 v17, vcc, 0, v11, vcc
	v_add_co_u32_e32 v18, vcc, s3, v10
	s_mov_b32 s3, 0x4800000
	s_nop 0
	v_addc_co_u32_e32 v19, vcc, 0, v11, vcc
	global_load_dwordx2 v[76:77], v[10:11], off nt
	global_load_dwordx2 v[74:75], v[12:13], off nt
	global_load_dwordx2 v[68:69], v[16:17], off nt
	global_load_dwordx2 v[70:71], v[18:19], off nt
	v_add_co_u32_e32 v12, vcc, s3, v10
	s_mov_b32 s3, 0x5a00000
	s_nop 0
	v_addc_co_u32_e32 v13, vcc, 0, v11, vcc
	s_mul_i32 s6, s0, 0x1600
	v_readlane_b32 s8, v253, 41
	v_add_co_u32_e32 v10, vcc, s3, v10
	s_mul_hi_i32 s3, s0, 0x1600
	v_readlane_b32 s9, v253, 42
	s_add_u32 s6, s8, s6
	s_addc_u32 s7, s9, s3
	v_addc_co_u32_e32 v11, vcc, 0, v11, vcc
	v_lshl_add_u64 v[16:17], s[6:7], 0, v[14:15]
	s_movk_i32 s3, 0x1000
	s_mul_i32 s8, s0, 0xa00
	v_readlane_b32 s12, v253, 43
	v_add_co_u32_e32 v16, vcc, s3, v16
	s_mul_hi_i32 s3, s0, 0xa00
	v_readlane_b32 s13, v253, 44
	s_add_u32 s8, s12, s8
	s_addc_u32 s9, s13, s3
	v_addc_co_u32_e32 v17, vcc, 0, v17, vcc
	global_load_dwordx2 v[52:53], v[12:13], off nt
	global_load_dwordx2 v[48:49], v[10:11], off nt
	global_load_dwordx2 v[72:73], v14, s[6:7] offset:1024 nt
	global_load_dwordx2 v[36:37], v[16:17], off offset:1024 nt
	global_load_dwordx2 v[66:67], v14, s[6:7] offset:3072 nt
	global_load_dwordx2 v[38:39], v14, s[8:9] offset:1536 nt
	s_lshl_b64 s[6:7], s[0:1], 10
	v_readlane_b32 s8, v253, 47
	v_readlane_b32 s9, v253, 48
	s_add_u32 s6, s8, s6
	s_addc_u32 s7, s9, s7
	global_load_dwordx4 v[10:13], v28, s[4:5] nt
	global_load_dwordx4 v[18:21], v28, s[6:7] nt
	s_add_i32 s12, s0, s2
	s_lshl_b64 s[4:5], s[0:1], 11
	s_ashr_i32 s3, s2, 31
	s_ashr_i32 s13, s12, 31
	v_or_b32_e32 v24, s4, v14
	v_mov_b32_e32 v25, s5
	s_lshl_b64 s[4:5], s[2:3], 11
	s_lshl_b64 s[6:7], s[12:13], 10
	s_add_u32 s1, s6, 0x38800000
	s_addc_u32 s6, s7, 0
	v_mov_b32_e32 v29, s6
	s_lshl_b64 s[6:7], s[2:3], 10
	s_mul_i32 s8, s12, 0xa00
	v_or_b32_e32 v28, s1, v28
	s_mul_hi_i32 s1, s12, 0xa00
	s_add_u32 s8, s8, 0x29e00600
	v_readlane_b32 s58, v252, 27
	v_readlane_b32 s59, v252, 28
	v_readlane_b32 s60, v252, 29
	v_readlane_b32 s61, v252, 30
	s_addc_u32 s1, s1, 0
	v_readlane_b32 s62, v252, 31
	v_readlane_b32 s63, v252, 32
	v_readlane_b32 s68, v252, 37
	v_readlane_b32 s69, v252, 38
	v_readlane_b32 s70, v252, 39
	v_readlane_b32 s71, v252, 40
	s_mov_b32 s58, 0x3f6c835e
	v_readlane_b32 s60, v255, 2
	v_mov_b32_e32 v31, s1
	s_mul_hi_i32 s1, s12, 0x1600
	s_mul_i32 s11, s12, 0x1600
	s_lshl_b64 s[12:13], s[12:13], 9
	s_mov_b32 s63, 0xbf6c835e
	v_readlane_b32 s62, v255, 4
	s_movk_i32 s68, 0x2200
	s_movk_i32 s71, 0x1ff
	s_mov_b32 s69, 0x7f800000
	s_movk_i32 s70, 0x4000
	s_mov_b32 s59, 0xbec3ef15
	v_readlane_b32 s61, v255, 3
	s_movk_i32 s64, 0x440
	s_waitcnt vmcnt(12)
	v_mov_b32_e32 v23, v22
	v_mov_b32_e32 v26, v22
	v_mov_b32_e32 v27, v22
	v_or_b32_e32 v30, s8, v14
	s_mul_i32 s8, s10, 0x5000
	s_mul_hi_i32 s9, s2, 0xa00
	v_or_b32_e32 v32, s11, v14
	v_mov_b32_e32 v33, s1
	s_mul_i32 s10, s10, 0xb000
	s_mul_hi_i32 s11, s2, 0x1600
	v_or_b32_e32 v34, s12, v14
	v_mov_b32_e32 v35, s13
	s_lshl_b64 s[12:13], s[2:3], 9
	v_readlane_b32 s66, v252, 35
	v_readlane_b32 s67, v252, 36
	s_branch .LBB0_1715

; __device__ __forceinline__ void fin_load(FinRow& R, const bf16* ZB, const bf16* PB, const bf16* SO, const float* FO, int row, int ch) {
; #pragma unroll
;     for (int k = 0; k < 6; ++k) R.so[k] = *(const v2u*)(SO + ((size_t)k * MT + row) * 256 + ch);
;     R.zg[0] = *(const v2u*)(ZB + (size_t)row * NZB + 512 + ch); R.zg[1] = *(const v2u*)(ZB + (size_t)row * NZB + 1536 + ch); R.zg[2] = *(const v2u*)(ZB + (size_t)row * NZB + 2560 + ch);
;     R.px = *(const v2u*)(PB + (size_t)row * NPB + 768 + ch);
;     R.fo0 = *(const f32x4*)(FO + (size_t)row * 256 + ch); R.fo1 = (f32x4){0.f, 0.f, 0.f, 0.f};
; }
; __device__ __forceinline__ void phase_finish(const Args& a, const WCtx& w, int l, int nrows) {
;     ...
;     while (row < nrows) {
;         const int nrow = row + w.NGW;
;         if (nrow < nrows) fin_load(Rn, ZB, PB, SO, FO, nrow, ch);
.LBB0_1715:
	s_add_i32 s0, s0, s2
	s_cmp_ge_i32 s0, s19
	s_cselect_b64 s[14:15], -1, 0
	s_and_b64 vcc, exec, s[14:15]
	s_cbranch_vccnz .LBB0_1714
	v_lshl_add_u64 v[14:15], s[52:53], 0, v[34:35]
	v_add_co_u32_e32 v16, vcc, 0x2f800000, v14
	v_lshl_add_u64 v[62:63], s[52:53], 0, v[32:33]
	s_nop 0
	v_addc_co_u32_e32 v17, vcc, 0, v15, vcc
	v_add_co_u32_e32 v42, vcc, 0x30a00000, v14
	s_nop 1
	v_addc_co_u32_e32 v43, vcc, 0, v15, vcc
	v_add_co_u32_e32 v44, vcc, 0x31c00000, v14
	s_nop 1
	v_addc_co_u32_e32 v45, vcc, 0, v15, vcc
	v_add_co_u32_e32 v46, vcc, 0x32e00000, v14
	s_nop 1
	v_addc_co_u32_e32 v47, vcc, 0, v15, vcc
	global_load_dwordx2 v[40:41], v[16:17], off nt
	s_nop 0
	global_load_dwordx2 v[42:43], v[42:43], off nt
	s_nop 0
	global_load_dwordx2 v[44:45], v[44:45], off nt
	s_nop 0
	global_load_dwordx2 v[46:47], v[46:47], off nt
	v_add_co_u32_e32 v16, vcc, 0x34000000, v14
	s_nop 1
	v_addc_co_u32_e32 v17, vcc, 0, v15, vcc
	v_add_co_u32_e32 v14, vcc, 0x35200000, v14
	s_nop 1
	v_addc_co_u32_e32 v15, vcc, 0, v15, vcc
	v_add_co_u32_e32 v60, vcc, 0x16c00000, v62
	s_nop 1
	v_addc_co_u32_e32 v61, vcc, 0, v63, vcc
	global_load_dwordx2 v[54:55], v[16:17], off nt
	global_load_dwordx2 v[56:57], v[14:15], off nt
	global_load_dwordx2 v[58:59], v[60:61], off offset:1024 nt
	s_nop 0
	global_load_dwordx2 v[60:61], v[60:61], off offset:3072 nt
	v_add_co_u32_e32 v14, vcc, 0x16c01000, v62
	v_lshl_add_u64 v[16:17], s[52:53], 0, v[30:31]
	s_nop 0
	v_addc_co_u32_e32 v15, vcc, 0, v63, vcc
	global_load_dwordx2 v[62:63], v[14:15], off offset:1024 nt
	global_load_dwordx2 v[64:65], v[16:17], off nt
	v_lshl_add_u64 v[14:15], s[52:53], 0, v[28:29]
	global_load_dwordx4 v[14:17], v[14:15], off nt
	s_branch .LBB0_1714

; __device__ __forceinline__ unsigned cvt_pk_bf16(float lo, float hi) { unsigned r; asm volatile("v_cvt_pk_bf16_f32 %0, %1, %2" : "=v"(r) : "v"(lo), "v"(hi)); return r; }
;     __device__ __forceinline__ void operator()(EPI_SIG) const {
;         const int g = u.pn >> 2, ct = u.pn & 3;
; #pragma unroll
;         for (int ai = 0; ai < 2; ++ai)
; #pragma unroll
;             for (int m = 0; m < 4; ++m)
; #pragma unroll
;                 for (int bj = 0; bj < 2; ++bj) { const int pn = ct * 4 + bj * 2 + (wc >> 1), wave_m = wr * 4 + (wc & 1) * 2 + (fq >> 1);
; #pragma unroll
;                     for (int n = 0; n < 2; ++n) { const int lane_m = ((fq & 1) * 2 + n) * 16 + fr; const f32x4 v = acc[ai][bj][m][n];
;                         v2u w; w.x = cvt_pk_bf16(v[0], v[1]); w.y = cvt_pk_bf16(v[2], v[3]);
;                         *(v2u*)(P2 + ((((((size_t)u.pm * 16 + pn) * 2 + ai) * 4 + m) * 8 + wave_m) * 4 + g) * 256 + lane_m * 4) = w; } }
;     }
.LBB0_1786:
	s_lshl_b32 s3, s61, 3
	s_and_b32 s3, s3, 24
	s_or_b32 s11, s3, s57
	s_ashr_i32 s41, s40, 31
	s_lshl_b64 s[14:15], s[40:41], 10
	s_lshl_b32 s11, s11, 5
	s_or_b32 s14, s11, s14
	s_ashr_i32 s2, s61, 2
	v_cvt_pk_bf16_f32 v128, v128, v129
	v_cvt_pk_bf16_f32 v129, v130, v131
	v_lshl_add_u64 v[130:131], s[14:15], 0, v[140:141]
	s_ashr_i32 s3, s2, 31
	v_lshlrev_b64 v[130:131], 11, v[130:131]
	s_lshl_b64 s[2:3], s[2:3], 9
	v_lshl_add_u64 v[130:131], s[6:7], 0, v[130:131]
	v_lshl_add_u64 v[130:131], v[130:131], 0, s[2:3]
	v_lshl_add_u64 v[130:131], v[130:131], 0, v[50:51]
	s_or_b32 s16, s14, 0x80
	s_mov_b32 s17, s15
	flat_store_dwordx2 v[130:131], v[128:129] nt
	v_cvt_pk_bf16_f32 v124, v124, v125
	v_cvt_pk_bf16_f32 v125, v126, v127
	flat_store_dwordx2 v[130:131], v[124:125] offset:128 nt
	v_cvt_pk_bf16_f32 v120, v120, v121
	v_cvt_pk_bf16_f32 v121, v122, v123
	v_lshl_add_u64 v[122:123], s[16:17], 0, v[140:141]
	v_lshlrev_b64 v[122:123], 11, v[122:123]
	v_lshl_add_u64 v[122:123], s[6:7], 0, v[122:123]
	v_lshl_add_u64 v[122:123], v[122:123], 0, s[2:3]
	v_lshl_add_u64 v[122:123], v[122:123], 0, v[50:51]
	flat_store_dwordx2 v[122:123], v[120:121] nt
	v_cvt_pk_bf16_f32 v108, v108, v109
	v_cvt_pk_bf16_f32 v109, v110, v111
	v_lshl_add_u64 v[110:111], s[14:15], 0, v[142:143]
	v_lshlrev_b64 v[110:111], 11, v[110:111]
	v_lshl_add_u64 v[110:111], s[6:7], 0, v[110:111]
	v_lshl_add_u64 v[110:111], v[110:111], 0, s[2:3]
	flat_store_dwordx2 v[122:123], v[108:109] offset:128 nt
	v_cvt_pk_bf16_f32 v108, v116, v117
	v_cvt_pk_bf16_f32 v109, v118, v119
	v_lshl_add_u64 v[110:111], v[110:111], 0, v[50:51]
	flat_store_dwordx2 v[110:111], v[108:109] nt
	v_cvt_pk_bf16_f32 v108, v112, v113
	v_cvt_pk_bf16_f32 v109, v114, v115
	flat_store_dwordx2 v[110:111], v[108:109] offset:128 nt
	v_cvt_pk_bf16_f32 v100, v100, v101
	v_cvt_pk_bf16_f32 v101, v102, v103
	v_lshl_add_u64 v[102:103], s[16:17], 0, v[142:143]
	v_lshlrev_b64 v[102:103], 11, v[102:103]
	v_lshl_add_u64 v[102:103], s[6:7], 0, v[102:103]
	v_lshl_add_u64 v[102:103], v[102:103], 0, s[2:3]
	v_lshl_add_u64 v[102:103], v[102:103], 0, v[50:51]
	flat_store_dwordx2 v[102:103], v[100:101] nt
	v_cvt_pk_bf16_f32 v92, v92, v93
	v_cvt_pk_bf16_f32 v93, v94, v95
	v_lshl_add_u64 v[94:95], s[14:15], 0, v[144:145]
	v_lshlrev_b64 v[94:95], 11, v[94:95]
	v_lshl_add_u64 v[94:95], s[6:7], 0, v[94:95]
	v_lshl_add_u64 v[94:95], v[94:95], 0, s[2:3]
	flat_store_dwordx2 v[102:103], v[92:93] offset:128 nt
	v_cvt_pk_bf16_f32 v92, v104, v105
	v_cvt_pk_bf16_f32 v93, v106, v107
	v_lshl_add_u64 v[94:95], v[94:95], 0, v[50:51]
	flat_store_dwordx2 v[94:95], v[92:93] nt
	v_cvt_pk_bf16_f32 v92, v96, v97
	v_cvt_pk_bf16_f32 v93, v98, v99
	flat_store_dwordx2 v[94:95], v[92:93] offset:128 nt
	v_cvt_pk_bf16_f32 v84, v84, v85
	v_cvt_pk_bf16_f32 v85, v86, v87
	v_lshl_add_u64 v[86:87], s[16:17], 0, v[144:145]
	v_lshlrev_b64 v[86:87], 11, v[86:87]
	v_lshl_add_u64 v[86:87], s[6:7], 0, v[86:87]
	v_lshl_add_u64 v[86:87], v[86:87], 0, s[2:3]
	v_lshl_add_u64 v[86:87], v[86:87], 0, v[50:51]
	flat_store_dwordx2 v[86:87], v[84:85] nt
	v_cvt_pk_bf16_f32 v76, v76, v77
	v_cvt_pk_bf16_f32 v77, v78, v79
	v_lshl_add_u64 v[78:79], s[14:15], 0, v[146:147]
	v_lshlrev_b64 v[78:79], 11, v[78:79]
	v_lshl_add_u64 v[78:79], s[6:7], 0, v[78:79]
	v_lshl_add_u64 v[78:79], v[78:79], 0, s[2:3]
	flat_store_dwordx2 v[86:87], v[76:77] offset:128 nt
	v_cvt_pk_bf16_f32 v76, v88, v89
	v_cvt_pk_bf16_f32 v77, v90, v91
	v_lshl_add_u64 v[78:79], v[78:79], 0, v[50:51]
	flat_store_dwordx2 v[78:79], v[76:77] nt
	v_cvt_pk_bf16_f32 v76, v80, v81
	v_cvt_pk_bf16_f32 v77, v82, v83
	flat_store_dwordx2 v[78:79], v[76:77] offset:128 nt
	v_cvt_pk_bf16_f32 v72, v72, v73
	v_cvt_pk_bf16_f32 v73, v74, v75
	v_lshl_add_u64 v[74:75], s[16:17], 0, v[146:147]
	v_lshlrev_b64 v[74:75], 11, v[74:75]
	v_lshl_add_u64 v[74:75], s[6:7], 0, v[74:75]
	v_lshl_add_u64 v[74:75], v[74:75], 0, s[2:3]
	v_lshl_add_u64 v[74:75], v[74:75], 0, v[50:51]
	s_or_b32 s16, s14, 32
	flat_store_dwordx2 v[74:75], v[72:73] nt
	v_cvt_pk_bf16_f32 v68, v68, v69
	v_cvt_pk_bf16_f32 v69, v70, v71
; __device__ __forceinline__ unsigned cvt_pk_bf16(float lo, float hi) { unsigned r; asm volatile("v_cvt_pk_bf16_f32 %0, %1, %2" : "=v"(r) : "v"(lo), "v"(hi)); return r; }
; #define PG8_BAR __builtin_amdgcn_s_barrier()
;     ...
;         if constexpr (ALIGN_EPI) { if (wr == 0) PG8_BAR; }
;         if constexpr (FP8) asm volatile("s_nop 7\n\ts_nop 7\n\ts_nop 3" ::: "memory");
;         E(acc, cur, wr, wc, fr, fq); S.done(cur);
;         if (!has_next) break;
; #pragma unroll
;         for (int a = 0; a < 2; ++a)
; #pragma unroll
;             for (int b = 0; b < 2; ++b)
; #pragma unroll
;                 for (int m = 0; m < 4; ++m)
; #pragma unroll
;                     for (int n = 0; n < 2; ++n) acc[a][b][m][n] = (f32x4){0.f, 0.f, 0.f, 0.f};
;         cur = nxt; cA = nA; cB = nB; ++ui;
;         if constexpr (GATHER) {
; #pragma unroll
;             for (int i = 0; i < 2; ++i) { gc0[i] = (unsigned)gn0r[i] * (unsigned)(g.lda * ESZ) + gC2[i]; gc1[i] = (unsigned)gn1r[i] * (unsigned)(g.lda * ESZ) + gC2[i]; } }
;         if constexpr (ALIGN_EPI) { if (wr == 1) PG8_BAR; }
;     __device__ __forceinline__ void operator()(EPI_SIG) const {
;         const int g = u.pn >> 2, ct = u.pn & 3;
; #pragma unroll
;         for (int ai = 0; ai < 2; ++ai)
; #pragma unroll
;             for (int m = 0; m < 4; ++m)
; #pragma unroll
;                 for (int bj = 0; bj < 2; ++bj) { const int pn = ct * 4 + bj * 2 + (wc >> 1), wave_m = wr * 4 + (wc & 1) * 2 + (fq >> 1);
; #pragma unroll
;                     for (int n = 0; n < 2; ++n) { const int lane_m = ((fq & 1) * 2 + n) * 16 + fr; const f32x4 v = acc[ai][bj][m][n];
;                         v2u w; w.x = cvt_pk_bf16(v[0], v[1]); w.y = cvt_pk_bf16(v[2], v[3]);
;                         *(v2u*)(P2 + ((((((size_t)u.pm * 16 + pn) * 2 + ai) * 4 + m) * 8 + wave_m) * 4 + g) * 256 + lane_m * 4) = w; } }
;     }
	flat_store_dwordx2 v[74:75], v[68:69] offset:128 nt
	v_cvt_pk_bf16_f32 v64, v64, v65
	v_cvt_pk_bf16_f32 v65, v66, v67
	v_lshl_add_u64 v[66:67], s[16:17], 0, v[140:141]
	v_lshlrev_b64 v[66:67], 11, v[66:67]
	v_lshl_add_u64 v[66:67], s[6:7], 0, v[66:67]
	v_lshl_add_u64 v[66:67], v[66:67], 0, s[2:3]
	v_lshl_add_u64 v[66:67], v[66:67], 0, v[50:51]
	s_or_b32 s14, s14, 0xa0
	flat_store_dwordx2 v[66:67], v[64:65] nt
	v_cvt_pk_bf16_f32 v60, v60, v61
	v_cvt_pk_bf16_f32 v61, v62, v63
	flat_store_dwordx2 v[66:67], v[60:61] offset:128 nt
	v_cvt_pk_bf16_f32 v52, v52, v53
	v_cvt_pk_bf16_f32 v53, v54, v55
	v_lshl_add_u64 v[54:55], s[14:15], 0, v[140:141]
	v_lshlrev_b64 v[54:55], 11, v[54:55]
	v_lshl_add_u64 v[54:55], s[6:7], 0, v[54:55]
	v_lshl_add_u64 v[54:55], v[54:55], 0, s[2:3]
	v_lshl_add_u64 v[54:55], v[54:55], 0, v[50:51]
	flat_store_dwordx2 v[54:55], v[52:53] nt
	v_cvt_pk_bf16_f32 v34, v34, v35
	v_cvt_pk_bf16_f32 v35, v36, v37
	v_lshl_add_u64 v[36:37], s[16:17], 0, v[142:143]
	v_lshlrev_b64 v[36:37], 11, v[36:37]
	v_lshl_add_u64 v[36:37], s[6:7], 0, v[36:37]
	v_lshl_add_u64 v[36:37], v[36:37], 0, s[2:3]
	flat_store_dwordx2 v[54:55], v[34:35] offset:128 nt
	v_cvt_pk_bf16_f32 v34, v46, v47
	v_cvt_pk_bf16_f32 v35, v48, v49
	v_lshl_add_u64 v[36:37], v[36:37], 0, v[50:51]
	flat_store_dwordx2 v[36:37], v[34:35] nt
	v_cvt_pk_bf16_f32 v34, v38, v39
	v_cvt_pk_bf16_f32 v35, v40, v41
	flat_store_dwordx2 v[36:37], v[34:35] offset:128 nt
	v_cvt_pk_bf16_f32 v18, v18, v19
	v_cvt_pk_bf16_f32 v19, v20, v21
	v_lshl_add_u64 v[20:21], s[14:15], 0, v[142:143]
	v_lshlrev_b64 v[20:21], 11, v[20:21]
	v_lshl_add_u64 v[20:21], s[6:7], 0, v[20:21]
	v_lshl_add_u64 v[20:21], v[20:21], 0, s[2:3]
	v_lshl_add_u64 v[20:21], v[20:21], 0, v[50:51]
	flat_store_dwordx2 v[20:21], v[18:19] nt
	v_cvt_pk_bf16_f32 v10, v10, v11
	v_cvt_pk_bf16_f32 v11, v12, v13
	v_lshl_add_u64 v[12:13], s[16:17], 0, v[144:145]
	v_lshlrev_b64 v[12:13], 11, v[12:13]
	v_lshl_add_u64 v[12:13], s[6:7], 0, v[12:13]
	v_lshl_add_u64 v[12:13], v[12:13], 0, s[2:3]
	flat_store_dwordx2 v[20:21], v[10:11] offset:128 nt
	v_cvt_pk_bf16_f32 v10, v22, v23
	v_cvt_pk_bf16_f32 v11, v24, v25
	v_lshl_add_u64 v[12:13], v[12:13], 0, v[50:51]
	flat_store_dwordx2 v[12:13], v[10:11] nt
	v_cvt_pk_bf16_f32 v10, v14, v15
	v_cvt_pk_bf16_f32 v11, v16, v17
	flat_store_dwordx2 v[12:13], v[10:11] offset:128 nt
	v_lshl_add_u64 v[12:13], s[14:15], 0, v[144:145]
	v_lshlrev_b64 v[12:13], 11, v[12:13]
	v_lshl_add_u64 v[12:13], s[6:7], 0, v[12:13]
	v_lshl_add_u64 v[12:13], v[12:13], 0, s[2:3]
	v_cvt_pk_bf16_f32 v10, v56, v57
	v_cvt_pk_bf16_f32 v11, v58, v59
	v_lshl_add_u64 v[12:13], v[12:13], 0, v[50:51]
	flat_store_dwordx2 v[12:13], v[10:11] nt
	v_cvt_pk_bf16_f32 v10, v42, v43
	v_cvt_pk_bf16_f32 v11, v44, v45
	flat_store_dwordx2 v[12:13], v[10:11] offset:128 nt
	v_cvt_pk_bf16_f32 v6, v6, v7
	v_cvt_pk_bf16_f32 v7, v8, v9
	v_lshl_add_u64 v[8:9], s[16:17], 0, v[146:147]
	v_lshlrev_b64 v[8:9], 11, v[8:9]
	v_lshl_add_u64 v[8:9], s[6:7], 0, v[8:9]
	v_lshl_add_u64 v[8:9], v[8:9], 0, s[2:3]
	v_lshl_add_u64 v[8:9], v[8:9], 0, v[50:51]
	flat_store_dwordx2 v[8:9], v[6:7] nt
	v_cvt_pk_bf16_f32 v2, v2, v3
	v_cvt_pk_bf16_f32 v3, v4, v5
	v_lshl_add_u64 v[4:5], s[14:15], 0, v[146:147]
	v_lshlrev_b64 v[4:5], 11, v[4:5]
	v_lshl_add_u64 v[4:5], s[6:7], 0, v[4:5]
	v_lshl_add_u64 v[4:5], v[4:5], 0, s[2:3]
	v_readlane_b32 s34, v255, 0
	s_mov_b32 s30, 0x3f3504f3
	flat_store_dwordx2 v[8:9], v[2:3] offset:128 nt
	v_cvt_pk_bf16_f32 v2, v30, v31
	v_cvt_pk_bf16_f32 v3, v32, v33
	v_lshl_add_u64 v[4:5], v[4:5], 0, v[50:51]
	s_andn2_b64 vcc, exec, s[0:1]
	s_mov_b64 s[0:1], -1
	v_readlane_b32 s35, v255, 1
	s_mov_b32 s31, 0xbf3504f3
	s_movk_i32 s68, 0x2200
	v_readlane_b32 s62, v255, 4
	s_mov_b32 s63, 0xbf6c835e
	s_movk_i32 s64, 0x440
	flat_store_dwordx2 v[4:5], v[2:3] nt
	v_cvt_pk_bf16_f32 v2, v26, v27
	v_cvt_pk_bf16_f32 v3, v28, v29
	flat_store_dwordx2 v[4:5], v[2:3] offset:128 nt
	s_cbranch_vccnz .LBB0_1779
	s_andn2_b64 vcc, exec, s[4:5]
	s_cbranch_vccnz .LBB0_1778
	s_barrier
	s_branch .LBB0_1778

; __device__ __forceinline__ float bf2f(unsigned b) { return __uint_as_float(b << 16); }
; __device__ __forceinline__ unsigned cvt_pk_bf16(float lo, float hi) { unsigned r; asm volatile("v_cvt_pk_bf16_f32 %0, %1, %2" : "=v"(r) : "v"(lo), "v"(hi)); return r; }
; __device__ __forceinline__ float sigmoid_fast(float x) { return __builtin_amdgcn_rcpf(1.0f + __expf(-x)); }
;     ...
;         if constexpr (FP8) asm volatile("s_nop 7\n\ts_nop 7\n\ts_nop 3" ::: "memory");
;     __device__ __forceinline__ void operator()(EPI_SIG) const {
;         const int row0 = u.pm * 256 + wr * 64 + fr, oc = u.pn * 64 + wc * 16 + 4 * fq;
;         f32x4 bv[4];
; #pragma unroll
;         for (int g = 0; g < 4; ++g) bv[g] = *(const f32x4*)(bg + g * 1024 + oc);
; #pragma unroll
;         for (int ai = 0; ai < 2; ++ai)
; #pragma unroll
;             for (int m = 0; m < 4; ++m) { const int row = row0 + ai * 128 + m * 16; const bf16* prow = P + (((((size_t)u.pm * 16 + u.pn) * 2 + ai) * 4 + m) * 8 + (wr * 4 + wc)) * 1024 + (fq * 16 + fr) * 4;
;                 v2u pw[4];
; #pragma unroll
;                 for (int g = 0; g < 4; ++g) pw[g] = *(const v2u*)(prow + g * 256);
;                 f32x4 t = (f32x4){0.f, 0.f, 0.f, 0.f};
; #pragma unroll
;                 for (int bj = 0; bj < 2; ++bj)
; #pragma unroll
;                     for (int n = 0; n < 2; ++n) { const int g = 2 * bj + n; const f32x4 a = acc[ai][bj][m][n] + bv[g];
;                         t[0] += sigmoid_fast(a[0]) * bf2f(pw[g].x & 0xffffu); t[1] += sigmoid_fast(a[1]) * bf2f(pw[g].x >> 16);
;                         t[2] += sigmoid_fast(a[2]) * bf2f(pw[g].y & 0xffffu); t[3] += sigmoid_fast(a[3]) * bf2f(pw[g].y >> 16); }
;                 v2u w; w.x = cvt_pk_bf16(t[0], t[1]); w.y = cvt_pk_bf16(t[2], t[3]);
;                 *(v2u*)(T + (size_t)row * 1024 + oc) = w; }
;     }
.LBB0_1859:
	v_lshl_or_b32 v18, s44, 6, v190
	v_ashrrev_i32_e32 v19, 31, v18
	s_nop 7
	s_nop 7
	s_nop 3
	v_lshl_add_u64 v[2:3], v[18:19], 2, s[8:9]
	global_load_dwordx4 v[14:17], v[2:3], off
	v_add_co_u32_e32 v4, vcc, 0x1000, v2
	s_ashr_i32 s47, s46, 31
	s_nop 0
	v_addc_co_u32_e32 v5, vcc, 0, v3, vcc
	global_load_dwordx4 v[10:13], v[4:5], off
	s_ashr_i32 s45, s44, 31
	v_add_co_u32_e32 v4, vcc, 0x2000, v2
	s_lshl_b64 s[2:3], s[46:47], 21
	s_lshl_b64 s[14:15], s[44:45], 17
	v_addc_co_u32_e32 v5, vcc, 0, v3, vcc
	s_add_u32 s44, s2, s14
	v_add_co_u32_e32 v2, vcc, 0x3000, v2
	s_addc_u32 s45, s3, s15
	s_nop 0
	v_addc_co_u32_e32 v3, vcc, 0, v3, vcc
	v_lshl_add_u64 v[24:25], v[168:169], 0, s[44:45]
	global_load_dwordx4 v[6:9], v[4:5], off
	v_lshl_add_u32 v20, s46, 8, v50
	global_load_dwordx4 v[2:5], v[2:3], off
	s_nop 0
	global_load_dwordx2 v[26:27], v[24:25], off nt
	global_load_dwordx2 v[28:29], v[24:25], off offset:512 nt
	global_load_dwordx2 v[22:23], v[24:25], off offset:1024 nt
	s_nop 0
	global_load_dwordx2 v[24:25], v[24:25], off offset:1536 nt
	s_add_u32 s14, s44, 0x10000
	s_addc_u32 s15, s45, 0
	v_lshl_add_u64 v[206:207], v[170:171], 0, s[44:45]
	global_load_dwordx2 v[200:201], v[206:207], off nt
	global_load_dwordx2 v[202:203], v[206:207], off offset:512 nt
	global_load_dwordx2 v[204:205], v[206:207], off offset:1024 nt
	s_nop 0
	global_load_dwordx2 v[206:207], v[206:207], off offset:1536 nt
	v_lshl_add_u64 v[214:215], v[172:173], 0, s[44:45]
	global_load_dwordx2 v[208:209], v[214:215], off nt
	global_load_dwordx2 v[210:211], v[214:215], off offset:512 nt
	global_load_dwordx2 v[212:213], v[214:215], off offset:1024 nt
	s_nop 0
	global_load_dwordx2 v[214:215], v[214:215], off offset:1536 nt
	v_lshl_add_u64 v[222:223], v[174:175], 0, s[44:45]
	global_load_dwordx2 v[216:217], v[222:223], off nt
	global_load_dwordx2 v[218:219], v[222:223], off offset:512 nt
	global_load_dwordx2 v[220:221], v[222:223], off offset:1024 nt
	s_nop 0
	global_load_dwordx2 v[222:223], v[222:223], off offset:1536 nt
	v_lshl_add_u64 v[248:249], v[168:169], 0, s[14:15]
	global_load_dwordx2 v[242:243], v[248:249], off nt
	global_load_dwordx2 v[244:245], v[248:249], off offset:512 nt
	global_load_dwordx2 v[246:247], v[248:249], off offset:1024 nt
	s_nop 0
	global_load_dwordx2 v[248:249], v[248:249], off offset:1536 nt
	s_mov_b32 s2, 0x40000
	s_mov_b32 s58, 0x3f6c835e
	s_mov_b32 s59, 0xbec3ef15
	s_waitcnt vmcnt(16)
	v_pk_add_f32 v[32:33], v[160:161], v[14:15]
	s_nop 0
	v_mul_f32_e32 v21, 0xbfb8aa3b, v32
	v_exp_f32_e32 v21, v21
	v_pk_add_f32 v[30:31], v[162:163], v[16:17]
	v_pk_add_f32 v[144:145], v[144:145], v[14:15]
	v_pk_add_f32 v[128:129], v[128:129], v[14:15]
	v_add_f32_e32 v21, 1.0, v21
	v_rcp_f32_e32 v32, v21
	v_mul_f32_e32 v21, 0xbfb8aa3b, v33
	v_exp_f32_e32 v21, v21
	v_pk_add_f32 v[156:157], v[156:157], v[10:11]
	v_pk_add_f32 v[158:159], v[158:159], v[12:13]
	v_pk_add_f32 v[140:141], v[140:141], v[10:11]
	v_add_f32_e32 v21, 1.0, v21
	v_rcp_f32_e32 v160, v21
	v_mul_f32_e32 v21, 0xbfb8aa3b, v30
	v_exp_f32_e32 v21, v21
	v_pk_add_f32 v[142:143], v[142:143], v[12:13]
	v_pk_add_f32 v[124:125], v[124:125], v[10:11]
	v_pk_add_f32 v[126:127], v[126:127], v[12:13]
	v_add_f32_e32 v21, 1.0, v21
	v_rcp_f32_e32 v30, v21
	v_mul_f32_e32 v21, 0xbfb8aa3b, v31
	v_exp_f32_e32 v21, v21
	v_mul_f32_e32 v31, 0xbfb8aa3b, v157
	v_exp_f32_e32 v31, v31
	s_waitcnt lgkmcnt(0)
	v_lshlrev_b32_e32 v181, 16, v28
	v_add_f32_e32 v21, 1.0, v21
	v_rcp_f32_e32 v162, v21
	v_mul_f32_e32 v21, 0xbfb8aa3b, v156
	v_exp_f32_e32 v21, v21
	v_add_f32_e32 v31, 1.0, v31
	v_lshlrev_b32_e32 v180, 16, v26
	v_rcp_f32_e32 v161, v31
	v_add_f32_e32 v21, 1.0, v21
	v_rcp_f32_e32 v33, v21
	v_pk_add_f32 v[148:149], v[148:149], v[2:3]
	v_pk_add_f32 v[150:151], v[150:151], v[4:5]
	v_pk_add_f32 v[132:133], v[132:133], v[2:3]
	v_pk_mul_f32 v[32:33], v[32:33], v[180:181]
	v_pk_add_f32 v[134:135], v[134:135], v[4:5]
	v_add_f32_e32 v21, 0, v32
	v_add_f32_e32 v21, v21, v33
	v_and_b32_e32 v33, 0xffff0000, v28
	v_and_b32_e32 v32, 0xffff0000, v26
	v_pk_mul_f32 v[32:33], v[160:161], v[32:33]
	v_and_b32_e32 v28, 0xffff0000, v27
	v_add_f32_e32 v26, 0, v32
	v_add_f32_e32 v156, v26, v33
	v_mul_f32_e32 v26, 0xbfb8aa3b, v158
	v_exp_f32_e32 v26, v26
	v_lshlrev_b32_e32 v33, 16, v29
	v_lshlrev_b32_e32 v32, 16, v27
	v_and_b32_e32 v29, 0xffff0000, v29
	v_add_f32_e32 v26, 1.0, v26
	v_rcp_f32_e32 v31, v26
	v_pk_add_f32 v[116:117], v[116:117], v[2:3]
	v_pk_add_f32 v[118:119], v[118:119], v[4:5]
	v_pk_add_f32 v[112:113], v[112:113], v[14:15]
	v_pk_mul_f32 v[30:31], v[30:31], v[32:33]
	v_pk_add_f32 v[108:109], v[108:109], v[10:11]
	v_add_f32_e32 v26, 0, v30
	v_add_f32_e32 v33, v26, v31
	v_mul_f32_e32 v26, 0xbfb8aa3b, v159
	v_exp_f32_e32 v26, v26
	v_pk_add_f32 v[110:111], v[110:111], v[12:13]
	v_pk_add_f32 v[100:101], v[100:101], v[2:3]
	v_pk_add_f32 v[102:103], v[102:103], v[4:5]
	v_add_f32_e32 v26, 1.0, v26
	v_rcp_f32_e32 v163, v26
	v_pk_add_f32 v[92:93], v[92:93], v[10:11]
	v_pk_add_f32 v[94:95], v[94:95], v[12:13]
	v_pk_add_f32 v[84:85], v[84:85], v[2:3]
	v_pk_mul_f32 v[26:27], v[162:163], v[28:29]
	v_pk_add_f32 v[28:29], v[152:153], v[6:7]
	v_add_f32_e32 v26, 0, v26
	v_add_f32_e32 v157, v26, v27
	v_pk_add_f32 v[26:27], v[154:155], v[8:9]
	v_mul_f32_e32 v29, 0xbfb8aa3b, v29
	v_mul_f32_e32 v27, 0xbfb8aa3b, v27
	v_exp_f32_e32 v27, v27
	v_exp_f32_e32 v29, v29
	v_mul_f32_e32 v28, 0xbfb8aa3b, v28
	v_exp_f32_e32 v28, v28
	v_add_f32_e32 v27, 1.0, v27
	v_rcp_f32_e32 v32, v27
	v_mul_f32_e32 v27, 0xbfb8aa3b, v148
	v_exp_f32_e32 v27, v27
	v_add_f32_e32 v29, 1.0, v29
	v_rcp_f32_e32 v30, v29
	v_add_f32_e32 v28, 1.0, v28
	v_add_f32_e32 v27, 1.0, v27
; __device__ __forceinline__ float bf2f(unsigned b) { return __uint_as_float(b << 16); }
; __device__ __forceinline__ unsigned cvt_pk_bf16(float lo, float hi) { unsigned r; asm volatile("v_cvt_pk_bf16_f32 %0, %1, %2" : "=v"(r) : "v"(lo), "v"(hi)); return r; }
; __device__ __forceinline__ float sigmoid_fast(float x) { return __builtin_amdgcn_rcpf(1.0f + __expf(-x)); }
;     __device__ __forceinline__ void operator()(EPI_SIG) const {
;     ...
;             for (int m = 0; m < 4; ++m) { const int row = row0 + ai * 128 + m * 16; const bf16* prow = P + (((((size_t)u.pm * 16 + u.pn) * 2 + ai) * 4 + m) * 8 + (wr * 4 + wc)) * 1024 + (fq * 16 + fr) * 4;
;                 v2u pw[4];
; #pragma unroll
;                 for (int g = 0; g < 4; ++g) pw[g] = *(const v2u*)(prow + g * 256);
;                 f32x4 t = (f32x4){0.f, 0.f, 0.f, 0.f};
; #pragma unroll
;                 for (int bj = 0; bj < 2; ++bj)
; #pragma unroll
;                     for (int n = 0; n < 2; ++n) { const int g = 2 * bj + n; const f32x4 a = acc[ai][bj][m][n] + bv[g];
;                         t[0] += sigmoid_fast(a[0]) * bf2f(pw[g].x & 0xffffu); t[1] += sigmoid_fast(a[1]) * bf2f(pw[g].x >> 16);
;                         t[2] += sigmoid_fast(a[2]) * bf2f(pw[g].y & 0xffffu); t[3] += sigmoid_fast(a[3]) * bf2f(pw[g].y >> 16); }
;                 v2u w; w.x = cvt_pk_bf16(t[0], t[1]); w.y = cvt_pk_bf16(t[2], t[3]);
;                 *(v2u*)(T + (size_t)row * 1024 + oc) = w; }
	v_rcp_f32_e32 v29, v27
	v_mul_f32_e32 v27, 0xbfb8aa3b, v149
	v_exp_f32_e32 v27, v27
	v_rcp_f32_e32 v28, v28
	v_lshlrev_b32_e32 v153, 16, v24
	v_lshlrev_b32_e32 v152, 16, v22
	v_add_f32_e32 v27, 1.0, v27
	v_rcp_f32_e32 v31, v27
	v_pk_mul_f32 v[28:29], v[28:29], v[152:153]
	v_mul_f32_e32 v26, 0xbfb8aa3b, v26
	v_add_f32_e32 v21, v21, v28
	v_add_f32_e32 v21, v21, v29
	v_and_b32_e32 v29, 0xffff0000, v24
	v_and_b32_e32 v28, 0xffff0000, v22
	v_pk_mul_f32 v[28:29], v[30:31], v[28:29]
	v_exp_f32_e32 v26, v26
	v_add_f32_e32 v22, v156, v28
	v_add_f32_e32 v30, v22, v29
	v_mul_f32_e32 v22, 0xbfb8aa3b, v150
	v_exp_f32_e32 v22, v22
	v_add_f32_e32 v26, 1.0, v26
	v_rcp_f32_e32 v26, v26
	v_lshlrev_b32_e32 v29, 16, v25
	v_add_f32_e32 v22, 1.0, v22
	v_rcp_f32_e32 v27, v22
	v_lshlrev_b32_e32 v28, 16, v23
	v_and_b32_e32 v25, 0xffff0000, v25
	v_and_b32_e32 v24, 0xffff0000, v23
	v_pk_mul_f32 v[26:27], v[26:27], v[28:29]
	v_pk_add_f32 v[76:77], v[76:77], v[10:11]
	v_add_f32_e32 v22, v33, v26
	v_add_f32_e32 v26, v22, v27
	v_mul_f32_e32 v22, 0xbfb8aa3b, v151
	v_exp_f32_e32 v22, v22
	v_pk_add_f32 v[78:79], v[78:79], v[12:13]
	v_pk_add_f32 v[68:69], v[68:69], v[2:3]
	v_pk_add_f32 v[60:61], v[60:61], v[10:11]
	v_add_f32_e32 v22, 1.0, v22
	v_rcp_f32_e32 v33, v22
	v_pk_add_f32 v[62:63], v[62:63], v[12:13]
	v_pk_add_f32 v[52:53], v[52:53], v[2:3]
	v_pk_add_f32 v[10:11], v[42:43], v[10:11]
	v_pk_mul_f32 v[22:23], v[32:33], v[24:25]
	v_cvt_pk_bf16_f32 v24, v21, v30
	v_ashrrev_i32_e32 v21, 31, v20
	v_add_f32_e32 v22, v157, v22
	v_add_f32_e32 v22, v22, v23
	v_cvt_pk_bf16_f32 v25, v26, v22
	v_lshlrev_b64 v[22:23], 11, v[20:21]
	v_lshl_add_u64 v[26:27], s[6:7], 0, v[22:23]
	v_lshlrev_b64 v[22:23], 1, v[18:19]
	v_lshl_add_u64 v[18:19], v[26:27], 0, v[22:23]
	global_store_dwordx2 v[18:19], v[24:25], off
	v_mul_f32_e32 v21, 0xbfb8aa3b, v144
	v_exp_f32_e32 v21, v21
	v_pk_add_f32 v[32:33], v[146:147], v[16:17]
	v_mul_f32_e32 v10, 0xbfb8aa3b, v10
	v_exp_f32_e32 v10, v10
	v_add_f32_e32 v21, 1.0, v21
	v_rcp_f32_e32 v144, v21
	v_mul_f32_e32 v21, 0xbfb8aa3b, v145
	v_exp_f32_e32 v21, v21
	v_add_f32_e32 v10, 1.0, v10
	v_pk_add_f32 v[12:13], v[44:45], v[12:13]
	v_pk_add_f32 v[2:3], v[34:35], v[2:3]
	v_add_f32_e32 v21, 1.0, v21
	v_rcp_f32_e32 v146, v21
	v_mul_f32_e32 v21, 0xbfb8aa3b, v32
	v_exp_f32_e32 v21, v21
	v_mul_f32_e32 v2, 0xbfb8aa3b, v2
	v_exp_f32_e32 v2, v2
	v_add_f32_e32 v21, 1.0, v21
	v_rcp_f32_e32 v32, v21
	v_mul_f32_e32 v21, 0xbfb8aa3b, v33
	v_exp_f32_e32 v21, v21
	v_mul_f32_e32 v33, 0xbfb8aa3b, v141
	v_exp_f32_e32 v33, v33
	v_add_f32_e32 v2, 1.0, v2
	v_add_f32_e32 v21, 1.0, v21
	v_rcp_f32_e32 v148, v21
	v_mul_f32_e32 v21, 0xbfb8aa3b, v140
	v_exp_f32_e32 v21, v21
	v_add_f32_e32 v33, 1.0, v33
	v_rcp_f32_e32 v147, v33
	v_add_f32_e32 v21, 1.0, v21
	v_rcp_f32_e32 v145, v21
	s_waitcnt vmcnt(12)
	v_mov_b64_e32 v[28:29], v[200:201]
	v_mov_b64_e32 v[30:31], v[202:203]
	v_mov_b64_e32 v[24:25], v[204:205]
	v_mov_b64_e32 v[26:27], v[206:207]
	v_lshl_add_u64 v[206:207], v[170:171], 0, s[14:15]
	global_load_dwordx2 v[200:201], v[206:207], off nt
	global_load_dwordx2 v[202:203], v[206:207], off offset:512 nt
	global_load_dwordx2 v[204:205], v[206:207], off offset:1024 nt
	s_nop 0
	global_load_dwordx2 v[206:207], v[206:207], off offset:1536 nt
	v_and_b32_e32 v140, 0xffff0000, v28
	v_and_b32_e32 v141, 0xffff0000, v30
	v_lshlrev_b32_e32 v151, 16, v30
	v_lshlrev_b32_e32 v150, 16, v28
	v_pk_mul_f32 v[140:141], v[146:147], v[140:141]
	v_pk_mul_f32 v[144:145], v[144:145], v[150:151]
	v_add_f32_e32 v28, 0, v140
	v_add_f32_e32 v21, 0, v144
	v_add_f32_e32 v144, v28, v141
	v_mul_f32_e32 v28, 0xbfb8aa3b, v142
	v_exp_f32_e32 v28, v28
	v_lshlrev_b32_e32 v141, 16, v31
	v_lshlrev_b32_e32 v140, 16, v29
	v_and_b32_e32 v31, 0xffff0000, v31
	v_add_f32_e32 v28, 1.0, v28
	v_rcp_f32_e32 v33, v28
	v_and_b32_e32 v30, 0xffff0000, v29
	v_add_f32_e32 v21, v21, v145
	v_pk_mul_f32 v[32:33], v[32:33], v[140:141]
	s_nop 0
	v_add_f32_e32 v28, 0, v32
	v_add_f32_e32 v140, v28, v33
	v_mul_f32_e32 v28, 0xbfb8aa3b, v143
	v_exp_f32_e32 v28, v28
	s_nop 0
	v_add_f32_e32 v28, 1.0, v28
	v_rcp_f32_e32 v149, v28
	s_nop 0
	v_pk_mul_f32 v[28:29], v[148:149], v[30:31]
	s_nop 0
	v_add_f32_e32 v28, 0, v28
	v_add_f32_e32 v141, v28, v29
	v_pk_add_f32 v[28:29], v[138:139], v[8:9]
	v_pk_add_f32 v[30:31], v[136:137], v[6:7]
	v_mul_f32_e32 v29, 0xbfb8aa3b, v29
	v_exp_f32_e32 v29, v29
	v_mul_f32_e32 v31, 0xbfb8aa3b, v31
	v_exp_f32_e32 v31, v31
	v_mul_f32_e32 v30, 0xbfb8aa3b, v30
	v_add_f32_e32 v29, 1.0, v29
	v_rcp_f32_e32 v136, v29
	v_mul_f32_e32 v29, 0xbfb8aa3b, v132
	v_exp_f32_e32 v29, v29
	v_exp_f32_e32 v30, v30
	v_add_f32_e32 v31, 1.0, v31
	v_rcp_f32_e32 v32, v31
	v_add_f32_e32 v29, 1.0, v29
	v_rcp_f32_e32 v31, v29
	v_mul_f32_e32 v29, 0xbfb8aa3b, v133
	v_exp_f32_e32 v29, v29
	v_add_f32_e32 v30, 1.0, v30
	v_rcp_f32_e32 v30, v30
	v_lshlrev_b32_e32 v139, 16, v26
	v_add_f32_e32 v29, 1.0, v29
	v_lshlrev_b32_e32 v138, 16, v24
	v_rcp_f32_e32 v33, v29
	v_pk_mul_f32 v[30:31], v[30:31], v[138:139]
	v_mul_f32_e32 v28, 0xbfb8aa3b, v28
	v_add_f32_e32 v21, v21, v30
	v_add_f32_e32 v21, v21, v31
	v_and_b32_e32 v31, 0xffff0000, v26
	v_and_b32_e32 v30, 0xffff0000, v24
	v_pk_mul_f32 v[30:31], v[32:33], v[30:31]
	v_exp_f32_e32 v28, v28
	v_add_f32_e32 v24, v144, v30
	v_add_f32_e32 v32, v24, v31
	v_mul_f32_e32 v24, 0xbfb8aa3b, v134
	v_exp_f32_e32 v24, v24
	v_add_f32_e32 v28, 1.0, v28
	v_rcp_f32_e32 v28, v28
	v_lshlrev_b32_e32 v31, 16, v27
	v_add_f32_e32 v24, 1.0, v24
	v_rcp_f32_e32 v29, v24
	v_lshlrev_b32_e32 v30, 16, v25
	v_and_b32_e32 v27, 0xffff0000, v27
	v_and_b32_e32 v26, 0xffff0000, v25
	v_pk_mul_f32 v[28:29], v[28:29], v[30:31]
	s_nop 0
	v_add_f32_e32 v24, v140, v28
	v_add_f32_e32 v28, v24, v29
	v_mul_f32_e32 v24, 0xbfb8aa3b, v135
	v_exp_f32_e32 v24, v24
	s_nop 0
	v_add_f32_e32 v24, 1.0, v24
	v_rcp_f32_e32 v137, v24
	s_nop 0
	v_pk_mul_f32 v[24:25], v[136:137], v[26:27]
	s_nop 0
	v_add_f32_e32 v24, v141, v24
	v_add_f32_e32 v25, v24, v25
	v_or_b32_e32 v24, 16, v20
	v_cvt_pk_bf16_f32 v26, v21, v32
	v_cvt_pk_bf16_f32 v27, v28, v25
	v_ashrrev_i32_e32 v25, 31, v24
	v_lshlrev_b64 v[24:25], 11, v[24:25]
	v_lshl_add_u64 v[24:25], s[6:7], 0, v[24:25]
	v_lshl_add_u64 v[24:25], v[24:25], 0, v[22:23]
	global_store_dwordx2 v[24:25], v[26:27], off
	v_mul_f32_e32 v21, 0xbfb8aa3b, v128
	v_exp_f32_e32 v21, v21
	v_pk_add_f32 v[32:33], v[130:131], v[16:17]
	v_add_f32_e32 v21, 1.0, v21
	v_rcp_f32_e32 v128, v21
	v_mul_f32_e32 v21, 0xbfb8aa3b, v129
	v_exp_f32_e32 v21, v21
	s_waitcnt vmcnt(12)
; __device__ __forceinline__ float bf2f(unsigned b) { return __uint_as_float(b << 16); }
; __device__ __forceinline__ unsigned cvt_pk_bf16(float lo, float hi) { unsigned r; asm volatile("v_cvt_pk_bf16_f32 %0, %1, %2" : "=v"(r) : "v"(lo), "v"(hi)); return r; }
; __device__ __forceinline__ float sigmoid_fast(float x) { return __builtin_amdgcn_rcpf(1.0f + __expf(-x)); }
;     __device__ __forceinline__ void operator()(EPI_SIG) const {
;     ...
;             for (int m = 0; m < 4; ++m) { const int row = row0 + ai * 128 + m * 16; const bf16* prow = P + (((((size_t)u.pm * 16 + u.pn) * 2 + ai) * 4 + m) * 8 + (wr * 4 + wc)) * 1024 + (fq * 16 + fr) * 4;
;                 v2u pw[4];
; #pragma unroll
;                 for (int g = 0; g < 4; ++g) pw[g] = *(const v2u*)(prow + g * 256);
;                 f32x4 t = (f32x4){0.f, 0.f, 0.f, 0.f};
; #pragma unroll
;                 for (int bj = 0; bj < 2; ++bj)
; #pragma unroll
;                     for (int n = 0; n < 2; ++n) { const int g = 2 * bj + n; const f32x4 a = acc[ai][bj][m][n] + bv[g];
;                         t[0] += sigmoid_fast(a[0]) * bf2f(pw[g].x & 0xffffu); t[1] += sigmoid_fast(a[1]) * bf2f(pw[g].x >> 16);
;                         t[2] += sigmoid_fast(a[2]) * bf2f(pw[g].y & 0xffffu); t[3] += sigmoid_fast(a[3]) * bf2f(pw[g].y >> 16); }
;                 v2u w; w.x = cvt_pk_bf16(t[0], t[1]); w.y = cvt_pk_bf16(t[2], t[3]);
;                 *(v2u*)(T + (size_t)row * 1024 + oc) = w; }
	v_mov_b64_e32 v[28:29], v[208:209]
	v_mov_b64_e32 v[30:31], v[210:211]
	v_mov_b64_e32 v[24:25], v[212:213]
	v_mov_b64_e32 v[26:27], v[214:215]
	v_lshl_add_u64 v[214:215], v[172:173], 0, s[14:15]
	global_load_dwordx2 v[208:209], v[214:215], off nt
	global_load_dwordx2 v[210:211], v[214:215], off offset:512 nt
	global_load_dwordx2 v[212:213], v[214:215], off offset:1024 nt
	s_nop 0
	global_load_dwordx2 v[214:215], v[214:215], off offset:1536 nt
	v_lshlrev_b32_e32 v134, 16, v28
	v_add_f32_e32 v21, 1.0, v21
	v_rcp_f32_e32 v130, v21
	v_mul_f32_e32 v21, 0xbfb8aa3b, v32
	v_exp_f32_e32 v21, v21
	v_lshlrev_b32_e32 v135, 16, v30
	v_add_f32_e32 v21, 1.0, v21
	v_rcp_f32_e32 v32, v21
	v_mul_f32_e32 v21, 0xbfb8aa3b, v33
	v_exp_f32_e32 v21, v21
	v_mul_f32_e32 v33, 0xbfb8aa3b, v125
	v_exp_f32_e32 v33, v33
	v_and_b32_e32 v125, 0xffff0000, v30
	v_add_f32_e32 v21, 1.0, v21
	v_rcp_f32_e32 v132, v21
	v_mul_f32_e32 v21, 0xbfb8aa3b, v124
	v_exp_f32_e32 v21, v21
	v_add_f32_e32 v33, 1.0, v33
	v_rcp_f32_e32 v131, v33
	v_and_b32_e32 v124, 0xffff0000, v28
	v_add_f32_e32 v21, 1.0, v21
	v_rcp_f32_e32 v129, v21
	v_pk_mul_f32 v[124:125], v[130:131], v[124:125]
	v_and_b32_e32 v30, 0xffff0000, v29
	v_add_f32_e32 v28, 0, v124
	v_pk_mul_f32 v[128:129], v[128:129], v[134:135]
	v_lshlrev_b32_e32 v124, 16, v29
	v_add_f32_e32 v21, 0, v128
	v_add_f32_e32 v128, v28, v125
	v_mul_f32_e32 v28, 0xbfb8aa3b, v126
	v_exp_f32_e32 v28, v28
	v_lshlrev_b32_e32 v125, 16, v31
	v_and_b32_e32 v31, 0xffff0000, v31
	v_add_f32_e32 v21, v21, v129
	v_add_f32_e32 v28, 1.0, v28
	v_rcp_f32_e32 v33, v28
	s_nop 0
	v_pk_mul_f32 v[32:33], v[32:33], v[124:125]
	s_nop 0
	v_add_f32_e32 v28, 0, v32
	v_add_f32_e32 v124, v28, v33
	v_mul_f32_e32 v28, 0xbfb8aa3b, v127
	v_exp_f32_e32 v28, v28
	s_nop 0
	v_add_f32_e32 v28, 1.0, v28
	v_rcp_f32_e32 v133, v28
	s_nop 0
	v_pk_mul_f32 v[28:29], v[132:133], v[30:31]
	s_nop 0
	v_add_f32_e32 v28, 0, v28
	v_add_f32_e32 v125, v28, v29
	v_pk_add_f32 v[28:29], v[122:123], v[8:9]
	v_pk_add_f32 v[30:31], v[120:121], v[6:7]
	v_mul_f32_e32 v29, 0xbfb8aa3b, v29
	v_exp_f32_e32 v29, v29
	v_mul_f32_e32 v31, 0xbfb8aa3b, v31
	v_exp_f32_e32 v31, v31
	v_mul_f32_e32 v30, 0xbfb8aa3b, v30
	v_add_f32_e32 v29, 1.0, v29
	v_rcp_f32_e32 v120, v29
	v_mul_f32_e32 v29, 0xbfb8aa3b, v116
	v_exp_f32_e32 v29, v29
	v_exp_f32_e32 v30, v30
	v_add_f32_e32 v31, 1.0, v31
	v_rcp_f32_e32 v32, v31
	v_add_f32_e32 v29, 1.0, v29
	v_rcp_f32_e32 v31, v29
	v_mul_f32_e32 v29, 0xbfb8aa3b, v117
	v_exp_f32_e32 v29, v29
	v_add_f32_e32 v30, 1.0, v30
	v_rcp_f32_e32 v30, v30
	v_lshlrev_b32_e32 v123, 16, v26
	v_add_f32_e32 v29, 1.0, v29
	v_lshlrev_b32_e32 v122, 16, v24
	v_rcp_f32_e32 v33, v29
	v_pk_mul_f32 v[30:31], v[30:31], v[122:123]
	v_mul_f32_e32 v28, 0xbfb8aa3b, v28
	v_add_f32_e32 v21, v21, v30
	v_add_f32_e32 v21, v21, v31
	v_and_b32_e32 v31, 0xffff0000, v26
	v_and_b32_e32 v30, 0xffff0000, v24
	v_pk_mul_f32 v[30:31], v[32:33], v[30:31]
	v_exp_f32_e32 v28, v28
	v_add_f32_e32 v24, v128, v30
	v_add_f32_e32 v32, v24, v31
	v_mul_f32_e32 v24, 0xbfb8aa3b, v118
	v_exp_f32_e32 v24, v24
	v_add_f32_e32 v28, 1.0, v28
	v_rcp_f32_e32 v28, v28
	v_lshlrev_b32_e32 v31, 16, v27
	v_add_f32_e32 v24, 1.0, v24
	v_rcp_f32_e32 v29, v24
	v_lshlrev_b32_e32 v30, 16, v25
	v_and_b32_e32 v27, 0xffff0000, v27
	v_and_b32_e32 v26, 0xffff0000, v25
	v_pk_mul_f32 v[28:29], v[28:29], v[30:31]
	s_nop 0
	v_add_f32_e32 v24, v124, v28
	v_add_f32_e32 v28, v24, v29
	v_mul_f32_e32 v24, 0xbfb8aa3b, v119
	v_exp_f32_e32 v24, v24
	s_nop 0
	v_add_f32_e32 v24, 1.0, v24
	v_rcp_f32_e32 v121, v24
	s_nop 0
	v_pk_mul_f32 v[24:25], v[120:121], v[26:27]
	s_nop 0
	v_add_f32_e32 v24, v125, v24
	v_add_f32_e32 v25, v24, v25
	v_or_b32_e32 v24, 32, v20
	v_cvt_pk_bf16_f32 v26, v21, v32
	v_cvt_pk_bf16_f32 v27, v28, v25
	v_ashrrev_i32_e32 v25, 31, v24
	v_lshlrev_b64 v[24:25], 11, v[24:25]
	v_lshl_add_u64 v[24:25], s[6:7], 0, v[24:25]
	v_lshl_add_u64 v[24:25], v[24:25], 0, v[22:23]
	global_store_dwordx2 v[24:25], v[26:27], off
	v_mul_f32_e32 v21, 0xbfb8aa3b, v112
	v_exp_f32_e32 v21, v21
	v_pk_add_f32 v[32:33], v[114:115], v[16:17]
	v_or_b32_e32 v20, 48, v20
	s_bitset1_b32 s44, 16
	v_add_f32_e32 v21, 1.0, v21
	v_rcp_f32_e32 v112, v21
	v_mul_f32_e32 v21, 0xbfb8aa3b, v113
	v_exp_f32_e32 v21, v21
	s_waitcnt vmcnt(12)
; __device__ __forceinline__ float bf2f(unsigned b) { return __uint_as_float(b << 16); }
; __device__ __forceinline__ unsigned cvt_pk_bf16(float lo, float hi) { unsigned r; asm volatile("v_cvt_pk_bf16_f32 %0, %1, %2" : "=v"(r) : "v"(lo), "v"(hi)); return r; }
; __device__ __forceinline__ float sigmoid_fast(float x) { return __builtin_amdgcn_rcpf(1.0f + __expf(-x)); }
;     __device__ __forceinline__ void operator()(EPI_SIG) const {
;     ...
;             for (int m = 0; m < 4; ++m) { const int row = row0 + ai * 128 + m * 16; const bf16* prow = P + (((((size_t)u.pm * 16 + u.pn) * 2 + ai) * 4 + m) * 8 + (wr * 4 + wc)) * 1024 + (fq * 16 + fr) * 4;
;                 v2u pw[4];
; #pragma unroll
;                 for (int g = 0; g < 4; ++g) pw[g] = *(const v2u*)(prow + g * 256);
;                 f32x4 t = (f32x4){0.f, 0.f, 0.f, 0.f};
; #pragma unroll
;                 for (int bj = 0; bj < 2; ++bj)
; #pragma unroll
;                     for (int n = 0; n < 2; ++n) { const int g = 2 * bj + n; const f32x4 a = acc[ai][bj][m][n] + bv[g];
;                         t[0] += sigmoid_fast(a[0]) * bf2f(pw[g].x & 0xffffu); t[1] += sigmoid_fast(a[1]) * bf2f(pw[g].x >> 16);
;                         t[2] += sigmoid_fast(a[2]) * bf2f(pw[g].y & 0xffffu); t[3] += sigmoid_fast(a[3]) * bf2f(pw[g].y >> 16); }
;                 v2u w; w.x = cvt_pk_bf16(t[0], t[1]); w.y = cvt_pk_bf16(t[2], t[3]);
;                 *(v2u*)(T + (size_t)row * 1024 + oc) = w; }
	v_mov_b64_e32 v[28:29], v[216:217]
	v_mov_b64_e32 v[30:31], v[218:219]
	v_mov_b64_e32 v[24:25], v[220:221]
	v_mov_b64_e32 v[26:27], v[222:223]
	v_lshl_add_u64 v[222:223], v[174:175], 0, s[14:15]
	global_load_dwordx2 v[216:217], v[222:223], off nt
	global_load_dwordx2 v[218:219], v[222:223], off offset:512 nt
	global_load_dwordx2 v[220:221], v[222:223], off offset:1024 nt
	s_nop 0
	global_load_dwordx2 v[222:223], v[222:223], off offset:1536 nt
	v_lshlrev_b32_e32 v118, 16, v28
	v_add_f32_e32 v21, 1.0, v21
	v_rcp_f32_e32 v114, v21
	v_mul_f32_e32 v21, 0xbfb8aa3b, v32
	v_exp_f32_e32 v21, v21
	v_lshlrev_b32_e32 v119, 16, v30
	v_add_f32_e32 v21, 1.0, v21
	v_rcp_f32_e32 v32, v21
	v_mul_f32_e32 v21, 0xbfb8aa3b, v33
	v_exp_f32_e32 v21, v21
	v_mul_f32_e32 v33, 0xbfb8aa3b, v109
	v_exp_f32_e32 v33, v33
	v_and_b32_e32 v109, 0xffff0000, v30
	v_add_f32_e32 v21, 1.0, v21
	v_rcp_f32_e32 v116, v21
	v_mul_f32_e32 v21, 0xbfb8aa3b, v108
	v_exp_f32_e32 v21, v21
	v_add_f32_e32 v33, 1.0, v33
	v_rcp_f32_e32 v115, v33
	v_and_b32_e32 v108, 0xffff0000, v28
	v_add_f32_e32 v21, 1.0, v21
	v_rcp_f32_e32 v113, v21
	v_pk_mul_f32 v[108:109], v[114:115], v[108:109]
	v_and_b32_e32 v30, 0xffff0000, v29
	v_add_f32_e32 v28, 0, v108
	v_pk_mul_f32 v[112:113], v[112:113], v[118:119]
	v_lshlrev_b32_e32 v108, 16, v29
	v_add_f32_e32 v21, 0, v112
	v_add_f32_e32 v112, v28, v109
	v_mul_f32_e32 v28, 0xbfb8aa3b, v110
	v_exp_f32_e32 v28, v28
	v_lshlrev_b32_e32 v109, 16, v31
	v_and_b32_e32 v31, 0xffff0000, v31
	v_add_f32_e32 v21, v21, v113
	v_add_f32_e32 v28, 1.0, v28
	v_rcp_f32_e32 v33, v28
	s_nop 0
	v_pk_mul_f32 v[32:33], v[32:33], v[108:109]
	s_nop 0
	v_add_f32_e32 v28, 0, v32
	v_add_f32_e32 v108, v28, v33
	v_mul_f32_e32 v28, 0xbfb8aa3b, v111
	v_exp_f32_e32 v28, v28
	s_nop 0
	v_add_f32_e32 v28, 1.0, v28
	v_rcp_f32_e32 v117, v28
	s_nop 0
	v_pk_mul_f32 v[28:29], v[116:117], v[30:31]
	s_nop 0
	v_add_f32_e32 v28, 0, v28
	v_add_f32_e32 v109, v28, v29
	v_pk_add_f32 v[28:29], v[106:107], v[8:9]
	v_pk_add_f32 v[30:31], v[104:105], v[6:7]
	v_mul_f32_e32 v29, 0xbfb8aa3b, v29
	v_exp_f32_e32 v29, v29
	v_mul_f32_e32 v31, 0xbfb8aa3b, v31
	v_exp_f32_e32 v31, v31
	v_mul_f32_e32 v30, 0xbfb8aa3b, v30
	v_add_f32_e32 v29, 1.0, v29
	v_rcp_f32_e32 v104, v29
	v_mul_f32_e32 v29, 0xbfb8aa3b, v100
	v_exp_f32_e32 v29, v29
	v_exp_f32_e32 v30, v30
	v_add_f32_e32 v31, 1.0, v31
	v_rcp_f32_e32 v32, v31
	v_add_f32_e32 v29, 1.0, v29
	v_rcp_f32_e32 v31, v29
	v_mul_f32_e32 v29, 0xbfb8aa3b, v101
	v_exp_f32_e32 v29, v29
	v_add_f32_e32 v30, 1.0, v30
	v_rcp_f32_e32 v30, v30
	v_lshlrev_b32_e32 v107, 16, v26
	v_add_f32_e32 v29, 1.0, v29
	v_lshlrev_b32_e32 v106, 16, v24
	v_rcp_f32_e32 v33, v29
	v_pk_mul_f32 v[30:31], v[30:31], v[106:107]
	v_mul_f32_e32 v28, 0xbfb8aa3b, v28
	v_add_f32_e32 v21, v21, v30
	v_add_f32_e32 v21, v21, v31
	v_and_b32_e32 v31, 0xffff0000, v26
	v_and_b32_e32 v30, 0xffff0000, v24
	v_pk_mul_f32 v[30:31], v[32:33], v[30:31]
	v_exp_f32_e32 v28, v28
	v_add_f32_e32 v24, v112, v30
	v_add_f32_e32 v32, v24, v31
	v_mul_f32_e32 v24, 0xbfb8aa3b, v102
	v_exp_f32_e32 v24, v24
	v_add_f32_e32 v28, 1.0, v28
	v_rcp_f32_e32 v28, v28
	v_lshlrev_b32_e32 v31, 16, v27
	v_add_f32_e32 v24, 1.0, v24
	v_rcp_f32_e32 v29, v24
	v_lshlrev_b32_e32 v30, 16, v25
	v_and_b32_e32 v27, 0xffff0000, v27
	v_and_b32_e32 v26, 0xffff0000, v25
	v_pk_mul_f32 v[28:29], v[28:29], v[30:31]
	v_pk_add_f32 v[30:31], v[96:97], v[14:15]
	v_add_f32_e32 v24, v108, v28
	v_add_f32_e32 v28, v24, v29
	v_mul_f32_e32 v24, 0xbfb8aa3b, v103
	v_exp_f32_e32 v24, v24
	v_mul_f32_e32 v30, 0xbfb8aa3b, v30
	v_mul_f32_e32 v31, 0xbfb8aa3b, v31
	v_exp_f32_e32 v30, v30
	v_add_f32_e32 v24, 1.0, v24
	v_rcp_f32_e32 v105, v24
	v_exp_f32_e32 v31, v31
	v_add_f32_e32 v30, 1.0, v30
	v_rcp_f32_e32 v30, v30
	v_pk_mul_f32 v[24:25], v[104:105], v[26:27]
	v_add_f32_e32 v31, 1.0, v31
	v_add_f32_e32 v24, v109, v24
	v_add_f32_e32 v25, v24, v25
	v_cvt_pk_bf16_f32 v24, v21, v32
	v_ashrrev_i32_e32 v21, 31, v20
	v_lshlrev_b64 v[20:21], 11, v[20:21]
	v_lshl_add_u64 v[20:21], s[6:7], 0, v[20:21]
	v_lshl_add_u64 v[20:21], v[20:21], 0, v[22:23]
	v_cvt_pk_bf16_f32 v25, v28, v25
	global_store_dwordx2 v[20:21], v[24:25], off
	v_pk_add_f32 v[28:29], v[98:99], v[16:17]
	v_rcp_f32_e32 v32, v31
	v_mul_f32_e32 v29, 0xbfb8aa3b, v29
	v_exp_f32_e32 v29, v29
	v_mul_f32_e32 v28, 0xbfb8aa3b, v28
	v_exp_f32_e32 v28, v28
	v_add_f32_e32 v29, 1.0, v29
	v_rcp_f32_e32 v96, v29
	v_mul_f32_e32 v29, 0xbfb8aa3b, v92
	v_exp_f32_e32 v29, v29
	v_add_f32_e32 v28, 1.0, v28
	v_rcp_f32_e32 v28, v28
	v_add_f32_e32 v29, 1.0, v29
	v_rcp_f32_e32 v31, v29
	s_waitcnt vmcnt(12)
; __device__ __forceinline__ float bf2f(unsigned b) { return __uint_as_float(b << 16); }
; __device__ __forceinline__ unsigned cvt_pk_bf16(float lo, float hi) { unsigned r; asm volatile("v_cvt_pk_bf16_f32 %0, %1, %2" : "=v"(r) : "v"(lo), "v"(hi)); return r; }
; __device__ __forceinline__ float sigmoid_fast(float x) { return __builtin_amdgcn_rcpf(1.0f + __expf(-x)); }
;     __device__ __forceinline__ void operator()(EPI_SIG) const {
;     ...
;             for (int m = 0; m < 4; ++m) { const int row = row0 + ai * 128 + m * 16; const bf16* prow = P + (((((size_t)u.pm * 16 + u.pn) * 2 + ai) * 4 + m) * 8 + (wr * 4 + wc)) * 1024 + (fq * 16 + fr) * 4;
;                 v2u pw[4];
; #pragma unroll
;                 for (int g = 0; g < 4; ++g) pw[g] = *(const v2u*)(prow + g * 256);
;                 f32x4 t = (f32x4){0.f, 0.f, 0.f, 0.f};
; #pragma unroll
;                 for (int bj = 0; bj < 2; ++bj)
; #pragma unroll
;                     for (int n = 0; n < 2; ++n) { const int g = 2 * bj + n; const f32x4 a = acc[ai][bj][m][n] + bv[g];
;                         t[0] += sigmoid_fast(a[0]) * bf2f(pw[g].x & 0xffffu); t[1] += sigmoid_fast(a[1]) * bf2f(pw[g].x >> 16);
;                         t[2] += sigmoid_fast(a[2]) * bf2f(pw[g].y & 0xffffu); t[3] += sigmoid_fast(a[3]) * bf2f(pw[g].y >> 16); }
;                 v2u w; w.x = cvt_pk_bf16(t[0], t[1]); w.y = cvt_pk_bf16(t[2], t[3]);
;                 *(v2u*)(T + (size_t)row * 1024 + oc) = w; }
	v_mov_b64_e32 v[24:25], v[242:243]
	v_mov_b64_e32 v[26:27], v[244:245]
	v_mov_b64_e32 v[20:21], v[246:247]
	v_mov_b64_e32 v[22:23], v[248:249]
	v_lshlrev_b32_e32 v98, 16, v24
	v_lshlrev_b32_e32 v99, 16, v26
	v_pk_mul_f32 v[30:31], v[30:31], v[98:99]
	s_nop 0
	v_add_f32_e32 v29, 0, v30
	v_add_f32_e32 v92, v29, v31
	v_mul_f32_e32 v29, 0xbfb8aa3b, v93
	v_exp_f32_e32 v29, v29
	v_and_b32_e32 v31, 0xffff0000, v26
	v_and_b32_e32 v30, 0xffff0000, v24
	v_and_b32_e32 v26, 0xffff0000, v25
	v_add_f32_e32 v29, 1.0, v29
	v_rcp_f32_e32 v33, v29
	s_nop 0
	v_pk_mul_f32 v[30:31], v[32:33], v[30:31]
	s_nop 0
	v_add_f32_e32 v24, 0, v30
	v_add_f32_e32 v93, v24, v31
	v_mul_f32_e32 v24, 0xbfb8aa3b, v94
	v_exp_f32_e32 v24, v24
	v_lshlrev_b32_e32 v31, 16, v27
	v_lshlrev_b32_e32 v30, 16, v25
	v_and_b32_e32 v27, 0xffff0000, v27
	v_add_f32_e32 v24, 1.0, v24
	v_rcp_f32_e32 v29, v24
	v_pk_add_f32 v[32:33], v[86:87], v[4:5]
	v_lshlrev_b32_e32 v87, 16, v22
	v_lshlrev_b32_e32 v86, 16, v20
	v_pk_mul_f32 v[28:29], v[28:29], v[30:31]
	s_nop 0
	v_add_f32_e32 v24, 0, v28
	v_add_f32_e32 v31, v24, v29
	v_mul_f32_e32 v24, 0xbfb8aa3b, v95
	v_exp_f32_e32 v24, v24
	s_nop 0
	v_add_f32_e32 v24, 1.0, v24
	v_rcp_f32_e32 v97, v24
	s_nop 0
	v_pk_mul_f32 v[24:25], v[96:97], v[26:27]
	s_nop 0
	v_add_f32_e32 v24, 0, v24
	v_add_f32_e32 v94, v24, v25
	v_pk_add_f32 v[24:25], v[90:91], v[8:9]
	v_pk_add_f32 v[26:27], v[88:89], v[6:7]
	v_mul_f32_e32 v25, 0xbfb8aa3b, v25
	v_exp_f32_e32 v25, v25
	v_mul_f32_e32 v26, 0xbfb8aa3b, v26
	v_mul_f32_e32 v27, 0xbfb8aa3b, v27
	v_exp_f32_e32 v26, v26
	v_add_f32_e32 v25, 1.0, v25
	v_rcp_f32_e32 v30, v25
	v_mul_f32_e32 v25, 0xbfb8aa3b, v84
	v_exp_f32_e32 v27, v27
	v_exp_f32_e32 v25, v25
	v_add_f32_e32 v26, 1.0, v26
	v_rcp_f32_e32 v26, v26
	v_add_f32_e32 v27, 1.0, v27
	v_add_f32_e32 v25, 1.0, v25
	v_rcp_f32_e32 v28, v27
	v_rcp_f32_e32 v27, v25
	v_mul_f32_e32 v24, 0xbfb8aa3b, v24
	v_exp_f32_e32 v24, v24
	v_pk_mul_f32 v[26:27], v[26:27], v[86:87]
	s_nop 0
	v_add_f32_e32 v25, v92, v26
	v_add_f32_e32 v84, v25, v27
	v_mul_f32_e32 v25, 0xbfb8aa3b, v85
	v_exp_f32_e32 v25, v25
	v_and_b32_e32 v27, 0xffff0000, v22
	v_and_b32_e32 v26, 0xffff0000, v20
	v_add_f32_e32 v24, 1.0, v24
	v_add_f32_e32 v25, 1.0, v25
	v_rcp_f32_e32 v29, v25
	v_rcp_f32_e32 v24, v24
	v_and_b32_e32 v22, 0xffff0000, v21
	v_pk_mul_f32 v[26:27], v[28:29], v[26:27]
	s_nop 0
	v_add_f32_e32 v20, v93, v26
	v_add_f32_e32 v28, v20, v27
	v_mul_f32_e32 v20, 0xbfb8aa3b, v32
	v_exp_f32_e32 v20, v20
	v_lshlrev_b32_e32 v27, 16, v23
	v_lshlrev_b32_e32 v26, 16, v21
	v_and_b32_e32 v23, 0xffff0000, v23
	v_add_f32_e32 v20, 1.0, v20
	v_rcp_f32_e32 v25, v20
	s_nop 0
	v_pk_mul_f32 v[24:25], v[24:25], v[26:27]
	s_nop 0
	v_add_f32_e32 v20, v31, v24
	v_add_f32_e32 v24, v20, v25
	v_mul_f32_e32 v20, 0xbfb8aa3b, v33
	v_exp_f32_e32 v20, v20
	s_nop 0
	v_add_f32_e32 v20, 1.0, v20
	v_rcp_f32_e32 v31, v20
	s_nop 0
	v_pk_mul_f32 v[20:21], v[30:31], v[22:23]
	s_nop 0
	v_add_f32_e32 v20, v94, v20
	v_add_co_u32_e32 v22, vcc, s2, v18
	v_add_f32_e32 v21, v20, v21
	s_nop 0
	v_addc_co_u32_e32 v23, vcc, 0, v19, vcc
	v_cvt_pk_bf16_f32 v20, v84, v28
	v_cvt_pk_bf16_f32 v21, v24, v21
	global_store_dwordx2 v[22:23], v[20:21], off
	v_pk_add_f32 v[28:29], v[82:83], v[16:17]
	v_pk_add_f32 v[30:31], v[80:81], v[14:15]
	v_mul_f32_e32 v29, 0xbfb8aa3b, v29
	v_exp_f32_e32 v29, v29
	v_mul_f32_e32 v30, 0xbfb8aa3b, v30
	v_mul_f32_e32 v31, 0xbfb8aa3b, v31
	v_exp_f32_e32 v30, v30
	v_add_f32_e32 v29, 1.0, v29
	v_rcp_f32_e32 v80, v29
	v_mul_f32_e32 v29, 0xbfb8aa3b, v76
	v_exp_f32_e32 v31, v31
	v_exp_f32_e32 v29, v29
	v_add_f32_e32 v30, 1.0, v30
	v_rcp_f32_e32 v30, v30
	v_add_f32_e32 v31, 1.0, v31
	v_add_f32_e32 v29, 1.0, v29
	v_rcp_f32_e32 v32, v31
	v_rcp_f32_e32 v31, v29
	v_mul_f32_e32 v28, 0xbfb8aa3b, v28
	v_exp_f32_e32 v28, v28
	s_mov_b32 s2, 0x48000
	v_add_f32_e32 v28, 1.0, v28
	v_rcp_f32_e32 v28, v28
	s_waitcnt vmcnt(8)
	v_mov_b64_e32 v[24:25], v[200:201]
	v_mov_b64_e32 v[26:27], v[202:203]
	v_mov_b64_e32 v[20:21], v[204:205]
	v_mov_b64_e32 v[22:23], v[206:207]
	v_lshlrev_b32_e32 v82, 16, v24
	v_lshlrev_b32_e32 v83, 16, v26
	v_pk_mul_f32 v[30:31], v[30:31], v[82:83]
	s_nop 0
	v_add_f32_e32 v29, 0, v30
	v_add_f32_e32 v76, v29, v31
	v_mul_f32_e32 v29, 0xbfb8aa3b, v77
	v_exp_f32_e32 v29, v29
	v_and_b32_e32 v31, 0xffff0000, v26
	v_and_b32_e32 v30, 0xffff0000, v24
	v_and_b32_e32 v26, 0xffff0000, v25
	v_add_f32_e32 v29, 1.0, v29
	v_rcp_f32_e32 v33, v29
	s_nop 0
	v_pk_mul_f32 v[30:31], v[32:33], v[30:31]
	s_nop 0
	v_add_f32_e32 v24, 0, v30
	v_add_f32_e32 v77, v24, v31
	v_mul_f32_e32 v24, 0xbfb8aa3b, v78
	v_exp_f32_e32 v24, v24
	v_lshlrev_b32_e32 v31, 16, v27
	v_lshlrev_b32_e32 v30, 16, v25
	v_and_b32_e32 v27, 0xffff0000, v27
	v_add_f32_e32 v24, 1.0, v24
	v_rcp_f32_e32 v29, v24
	v_pk_add_f32 v[32:33], v[70:71], v[4:5]
	v_lshlrev_b32_e32 v71, 16, v22
	v_lshlrev_b32_e32 v70, 16, v20
	v_pk_mul_f32 v[28:29], v[28:29], v[30:31]
	s_nop 0
	v_add_f32_e32 v24, 0, v28
	v_add_f32_e32 v31, v24, v29
	v_mul_f32_e32 v24, 0xbfb8aa3b, v79
	v_exp_f32_e32 v24, v24
	s_nop 0
	v_add_f32_e32 v24, 1.0, v24
	v_rcp_f32_e32 v81, v24
	s_nop 0
	v_pk_mul_f32 v[24:25], v[80:81], v[26:27]
	s_nop 0
	v_add_f32_e32 v24, 0, v24
	v_add_f32_e32 v78, v24, v25
	v_pk_add_f32 v[24:25], v[74:75], v[8:9]
	v_pk_add_f32 v[26:27], v[72:73], v[6:7]
	v_mul_f32_e32 v25, 0xbfb8aa3b, v25
	v_exp_f32_e32 v25, v25
	v_mul_f32_e32 v26, 0xbfb8aa3b, v26
	v_mul_f32_e32 v27, 0xbfb8aa3b, v27
	v_exp_f32_e32 v26, v26
	v_add_f32_e32 v25, 1.0, v25
	v_rcp_f32_e32 v30, v25
	v_mul_f32_e32 v25, 0xbfb8aa3b, v68
	v_exp_f32_e32 v27, v27
	v_exp_f32_e32 v25, v25
	v_add_f32_e32 v26, 1.0, v26
	v_rcp_f32_e32 v26, v26
	v_add_f32_e32 v27, 1.0, v27
; __device__ __forceinline__ float bf2f(unsigned b) { return __uint_as_float(b << 16); }
; __device__ __forceinline__ unsigned cvt_pk_bf16(float lo, float hi) { unsigned r; asm volatile("v_cvt_pk_bf16_f32 %0, %1, %2" : "=v"(r) : "v"(lo), "v"(hi)); return r; }
; __device__ __forceinline__ float sigmoid_fast(float x) { return __builtin_amdgcn_rcpf(1.0f + __expf(-x)); }
;     __device__ __forceinline__ void operator()(EPI_SIG) const {
;     ...
;             for (int m = 0; m < 4; ++m) { const int row = row0 + ai * 128 + m * 16; const bf16* prow = P + (((((size_t)u.pm * 16 + u.pn) * 2 + ai) * 4 + m) * 8 + (wr * 4 + wc)) * 1024 + (fq * 16 + fr) * 4;
;                 v2u pw[4];
; #pragma unroll
;                 for (int g = 0; g < 4; ++g) pw[g] = *(const v2u*)(prow + g * 256);
;                 f32x4 t = (f32x4){0.f, 0.f, 0.f, 0.f};
; #pragma unroll
;                 for (int bj = 0; bj < 2; ++bj)
; #pragma unroll
;                     for (int n = 0; n < 2; ++n) { const int g = 2 * bj + n; const f32x4 a = acc[ai][bj][m][n] + bv[g];
;                         t[0] += sigmoid_fast(a[0]) * bf2f(pw[g].x & 0xffffu); t[1] += sigmoid_fast(a[1]) * bf2f(pw[g].x >> 16);
;                         t[2] += sigmoid_fast(a[2]) * bf2f(pw[g].y & 0xffffu); t[3] += sigmoid_fast(a[3]) * bf2f(pw[g].y >> 16); }
;                 v2u w; w.x = cvt_pk_bf16(t[0], t[1]); w.y = cvt_pk_bf16(t[2], t[3]);
;                 *(v2u*)(T + (size_t)row * 1024 + oc) = w; }
	v_add_f32_e32 v25, 1.0, v25
	v_rcp_f32_e32 v28, v27
	v_rcp_f32_e32 v27, v25
	v_mul_f32_e32 v24, 0xbfb8aa3b, v24
	v_exp_f32_e32 v24, v24
	v_pk_mul_f32 v[26:27], v[26:27], v[70:71]
	s_nop 0
	v_add_f32_e32 v25, v76, v26
	v_add_f32_e32 v68, v25, v27
	v_mul_f32_e32 v25, 0xbfb8aa3b, v69
	v_exp_f32_e32 v25, v25
	v_and_b32_e32 v27, 0xffff0000, v22
	v_and_b32_e32 v26, 0xffff0000, v20
	v_add_f32_e32 v24, 1.0, v24
	v_add_f32_e32 v25, 1.0, v25
	v_rcp_f32_e32 v29, v25
	v_rcp_f32_e32 v24, v24
	v_and_b32_e32 v22, 0xffff0000, v21
	v_pk_mul_f32 v[26:27], v[28:29], v[26:27]
	s_nop 0
	v_add_f32_e32 v20, v77, v26
	v_add_f32_e32 v28, v20, v27
	v_mul_f32_e32 v20, 0xbfb8aa3b, v32
	v_exp_f32_e32 v20, v20
	v_lshlrev_b32_e32 v27, 16, v23
	v_lshlrev_b32_e32 v26, 16, v21
	v_and_b32_e32 v23, 0xffff0000, v23
	v_add_f32_e32 v20, 1.0, v20
	v_rcp_f32_e32 v25, v20
	s_nop 0
	v_pk_mul_f32 v[24:25], v[24:25], v[26:27]
	s_nop 0
	v_add_f32_e32 v20, v31, v24
	v_add_f32_e32 v24, v20, v25
	v_mul_f32_e32 v20, 0xbfb8aa3b, v33
	v_exp_f32_e32 v20, v20
	s_nop 0
	v_add_f32_e32 v20, 1.0, v20
	v_rcp_f32_e32 v31, v20
	s_nop 0
	v_pk_mul_f32 v[20:21], v[30:31], v[22:23]
	s_nop 0
	v_add_f32_e32 v20, v78, v20
	v_add_co_u32_e32 v22, vcc, s2, v18
	v_add_f32_e32 v21, v20, v21
	s_nop 0
	v_addc_co_u32_e32 v23, vcc, 0, v19, vcc
	v_cvt_pk_bf16_f32 v20, v68, v28
	v_cvt_pk_bf16_f32 v21, v24, v21
	global_store_dwordx2 v[22:23], v[20:21], off
	v_pk_add_f32 v[28:29], v[66:67], v[16:17]
	v_pk_add_f32 v[30:31], v[64:65], v[14:15]
	v_mul_f32_e32 v29, 0xbfb8aa3b, v29
	v_exp_f32_e32 v29, v29
	v_mul_f32_e32 v30, 0xbfb8aa3b, v30
	v_mul_f32_e32 v31, 0xbfb8aa3b, v31
	v_exp_f32_e32 v30, v30
	v_add_f32_e32 v29, 1.0, v29
	v_rcp_f32_e32 v64, v29
	v_mul_f32_e32 v29, 0xbfb8aa3b, v60
	v_exp_f32_e32 v31, v31
	v_exp_f32_e32 v29, v29
	v_add_f32_e32 v30, 1.0, v30
	v_rcp_f32_e32 v30, v30
	v_add_f32_e32 v31, 1.0, v31
	v_add_f32_e32 v29, 1.0, v29
	v_rcp_f32_e32 v32, v31
	v_rcp_f32_e32 v31, v29
	v_mul_f32_e32 v28, 0xbfb8aa3b, v28
	v_exp_f32_e32 v28, v28
	s_mov_b32 s2, 0x50000
	v_pk_add_f32 v[14:15], v[46:47], v[14:15]
	v_pk_add_f32 v[16:17], v[48:49], v[16:17]
	v_add_f32_e32 v28, 1.0, v28
	v_rcp_f32_e32 v28, v28
	v_mul_f32_e32 v15, 0xbfb8aa3b, v15
	v_exp_f32_e32 v15, v15
	v_mul_f32_e32 v14, 0xbfb8aa3b, v14
	v_exp_f32_e32 v14, v14
	v_add_f32_e32 v15, 1.0, v15
	v_add_f32_e32 v14, 1.0, v14
	v_rcp_f32_e32 v14, v14
	s_waitcnt vmcnt(4)
	v_mov_b64_e32 v[24:25], v[208:209]
	v_mov_b64_e32 v[26:27], v[210:211]
	v_mov_b64_e32 v[20:21], v[212:213]
	v_mov_b64_e32 v[22:23], v[214:215]
	v_lshlrev_b32_e32 v66, 16, v24
	v_lshlrev_b32_e32 v67, 16, v26
	v_pk_mul_f32 v[30:31], v[30:31], v[66:67]
	s_nop 0
	v_add_f32_e32 v29, 0, v30
	v_add_f32_e32 v60, v29, v31
	v_mul_f32_e32 v29, 0xbfb8aa3b, v61
	v_exp_f32_e32 v29, v29
	v_and_b32_e32 v31, 0xffff0000, v26
	v_and_b32_e32 v30, 0xffff0000, v24
	v_and_b32_e32 v26, 0xffff0000, v25
	v_add_f32_e32 v29, 1.0, v29
	v_rcp_f32_e32 v33, v29
	s_nop 0
	v_pk_mul_f32 v[30:31], v[32:33], v[30:31]
	s_nop 0
	v_add_f32_e32 v24, 0, v30
	v_add_f32_e32 v61, v24, v31
	v_mul_f32_e32 v24, 0xbfb8aa3b, v62
	v_exp_f32_e32 v24, v24
	v_lshlrev_b32_e32 v31, 16, v27
	v_lshlrev_b32_e32 v30, 16, v25
	v_and_b32_e32 v27, 0xffff0000, v27
	v_add_f32_e32 v24, 1.0, v24
	v_rcp_f32_e32 v29, v24
	v_pk_add_f32 v[32:33], v[54:55], v[4:5]
	v_lshlrev_b32_e32 v55, 16, v22
	v_lshlrev_b32_e32 v54, 16, v20
	v_pk_mul_f32 v[28:29], v[28:29], v[30:31]
	v_pk_add_f32 v[4:5], v[36:37], v[4:5]
	v_add_f32_e32 v24, 0, v28
	v_add_f32_e32 v31, v24, v29
	v_mul_f32_e32 v24, 0xbfb8aa3b, v63
	v_exp_f32_e32 v24, v24
	s_nop 0
	v_add_f32_e32 v24, 1.0, v24
	v_rcp_f32_e32 v65, v24
	s_nop 0
	v_pk_mul_f32 v[24:25], v[64:65], v[26:27]
	s_nop 0
	v_add_f32_e32 v24, 0, v24
	v_add_f32_e32 v62, v24, v25
	v_pk_add_f32 v[24:25], v[58:59], v[8:9]
	v_pk_add_f32 v[26:27], v[56:57], v[6:7]
	v_mul_f32_e32 v25, 0xbfb8aa3b, v25
	v_exp_f32_e32 v25, v25
	v_mul_f32_e32 v26, 0xbfb8aa3b, v26
	v_mul_f32_e32 v27, 0xbfb8aa3b, v27
	v_exp_f32_e32 v26, v26
	v_add_f32_e32 v25, 1.0, v25
	v_rcp_f32_e32 v30, v25
	v_mul_f32_e32 v25, 0xbfb8aa3b, v52
	v_exp_f32_e32 v27, v27
	v_exp_f32_e32 v25, v25
	v_add_f32_e32 v26, 1.0, v26
	v_rcp_f32_e32 v26, v26
	v_add_f32_e32 v27, 1.0, v27
	v_add_f32_e32 v25, 1.0, v25
	v_rcp_f32_e32 v28, v27
	v_rcp_f32_e32 v27, v25
	v_mul_f32_e32 v24, 0xbfb8aa3b, v24
	v_exp_f32_e32 v24, v24
	v_pk_add_f32 v[6:7], v[38:39], v[6:7]
	v_pk_mul_f32 v[26:27], v[26:27], v[54:55]
	v_mul_f32_e32 v7, 0xbfb8aa3b, v7
	v_add_f32_e32 v25, v60, v26
	v_add_f32_e32 v52, v25, v27
	v_mul_f32_e32 v25, 0xbfb8aa3b, v53
	v_exp_f32_e32 v25, v25
	v_and_b32_e32 v27, 0xffff0000, v22
	v_and_b32_e32 v26, 0xffff0000, v20
	v_add_f32_e32 v24, 1.0, v24
	v_add_f32_e32 v25, 1.0, v25
	v_rcp_f32_e32 v29, v25
	v_rcp_f32_e32 v24, v24
	v_and_b32_e32 v22, 0xffff0000, v21
	v_exp_f32_e32 v7, v7
	v_pk_mul_f32 v[26:27], v[28:29], v[26:27]
	v_pk_add_f32 v[8:9], v[40:41], v[8:9]
	v_add_f32_e32 v20, v61, v26
	v_add_f32_e32 v28, v20, v27
	v_mul_f32_e32 v20, 0xbfb8aa3b, v32
	v_exp_f32_e32 v20, v20
	v_lshlrev_b32_e32 v27, 16, v23
	v_lshlrev_b32_e32 v26, 16, v21
	v_and_b32_e32 v23, 0xffff0000, v23
	v_add_f32_e32 v20, 1.0, v20
	v_rcp_f32_e32 v25, v20
	v_add_f32_e32 v7, 1.0, v7
	v_mul_f32_e32 v6, 0xbfb8aa3b, v6
	v_exp_f32_e32 v6, v6
	v_pk_mul_f32 v[24:25], v[24:25], v[26:27]
	v_add_f32_e32 v6, 1.0, v6
	v_add_f32_e32 v20, v31, v24
	v_add_f32_e32 v24, v20, v25
	v_mul_f32_e32 v20, 0xbfb8aa3b, v33
	v_exp_f32_e32 v20, v20
	v_rcp_f32_e32 v6, v6
	v_add_f32_e32 v20, 1.0, v20
	v_rcp_f32_e32 v31, v20
	s_nop 0
	v_pk_mul_f32 v[20:21], v[30:31], v[22:23]
	s_nop 0
	v_add_f32_e32 v20, v62, v20
	v_add_co_u32_e32 v22, vcc, s2, v18
	v_add_f32_e32 v21, v20, v21
	s_nop 0
	v_addc_co_u32_e32 v23, vcc, 0, v19, vcc
	v_cvt_pk_bf16_f32 v20, v52, v28
	v_cvt_pk_bf16_f32 v21, v24, v21
	global_store_dwordx2 v[22:23], v[20:21], off
	v_rcp_f32_e32 v28, v15
	v_mul_f32_e32 v15, 0xbfb8aa3b, v16
	v_exp_f32_e32 v15, v15
	s_mov_b64 s[2:3], -1
	v_add_f32_e32 v15, 1.0, v15
	v_rcp_f32_e32 v16, v15
	v_mul_f32_e32 v15, 0xbfb8aa3b, v17
	v_exp_f32_e32 v15, v15
	s_waitcnt vmcnt(4)
; __device__ __forceinline__ float bf2f(unsigned b) { return __uint_as_float(b << 16); }
; __device__ __forceinline__ unsigned cvt_pk_bf16(float lo, float hi) { unsigned r; asm volatile("v_cvt_pk_bf16_f32 %0, %1, %2" : "=v"(r) : "v"(lo), "v"(hi)); return r; }
; __device__ __forceinline__ float sigmoid_fast(float x) { return __builtin_amdgcn_rcpf(1.0f + __expf(-x)); }
; #define PG8_BAR __builtin_amdgcn_s_barrier()
;     ...
;         if constexpr (ALIGN_EPI) { if (wr == 1) PG8_BAR; }
;     __device__ __forceinline__ void operator()(EPI_SIG) const {
;     ...
;             for (int m = 0; m < 4; ++m) { const int row = row0 + ai * 128 + m * 16; const bf16* prow = P + (((((size_t)u.pm * 16 + u.pn) * 2 + ai) * 4 + m) * 8 + (wr * 4 + wc)) * 1024 + (fq * 16 + fr) * 4;
;                 v2u pw[4];
; #pragma unroll
;                 for (int g = 0; g < 4; ++g) pw[g] = *(const v2u*)(prow + g * 256);
;                 f32x4 t = (f32x4){0.f, 0.f, 0.f, 0.f};
; #pragma unroll
;                 for (int bj = 0; bj < 2; ++bj)
; #pragma unroll
;                     for (int n = 0; n < 2; ++n) { const int g = 2 * bj + n; const f32x4 a = acc[ai][bj][m][n] + bv[g];
;                         t[0] += sigmoid_fast(a[0]) * bf2f(pw[g].x & 0xffffu); t[1] += sigmoid_fast(a[1]) * bf2f(pw[g].x >> 16);
;                         t[2] += sigmoid_fast(a[2]) * bf2f(pw[g].y & 0xffffu); t[3] += sigmoid_fast(a[3]) * bf2f(pw[g].y >> 16); }
;                 v2u w; w.x = cvt_pk_bf16(t[0], t[1]); w.y = cvt_pk_bf16(t[2], t[3]);
;                 *(v2u*)(T + (size_t)row * 1024 + oc) = w; }
	v_mov_b64_e32 v[24:25], v[216:217]
	v_mov_b64_e32 v[26:27], v[218:219]
	v_mov_b64_e32 v[20:21], v[220:221]
	v_mov_b64_e32 v[22:23], v[222:223]
	v_lshlrev_b32_e32 v32, 16, v24
	v_add_f32_e32 v15, 1.0, v15
	v_rcp_f32_e32 v30, v15
	v_rcp_f32_e32 v15, v10
	v_lshlrev_b32_e32 v33, 16, v26
	v_pk_mul_f32 v[14:15], v[14:15], v[32:33]
	s_nop 0
	v_add_f32_e32 v10, 0, v14
	v_add_f32_e32 v32, v10, v15
	v_mul_f32_e32 v10, 0xbfb8aa3b, v11
	v_exp_f32_e32 v10, v10
	v_and_b32_e32 v11, 0xffff0000, v26
	v_lshlrev_b32_e32 v15, 16, v22
	v_lshlrev_b32_e32 v14, 16, v20
	v_add_f32_e32 v10, 1.0, v10
	v_rcp_f32_e32 v29, v10
	v_and_b32_e32 v10, 0xffff0000, v24
	v_pk_mul_f32 v[10:11], v[28:29], v[10:11]
	s_nop 0
	v_add_f32_e32 v10, 0, v10
	v_add_f32_e32 v24, v10, v11
	v_mul_f32_e32 v10, 0xbfb8aa3b, v12
	v_exp_f32_e32 v10, v10
	v_lshlrev_b32_e32 v11, 16, v27
	v_add_f32_e32 v10, 1.0, v10
	v_rcp_f32_e32 v17, v10
	v_lshlrev_b32_e32 v10, 16, v25
	v_pk_mul_f32 v[10:11], v[16:17], v[10:11]
	s_nop 0
	v_add_f32_e32 v10, 0, v10
	v_add_f32_e32 v16, v10, v11
	v_mul_f32_e32 v10, 0xbfb8aa3b, v13
	v_exp_f32_e32 v10, v10
	v_and_b32_e32 v11, 0xffff0000, v27
	v_add_f32_e32 v10, 1.0, v10
	v_rcp_f32_e32 v31, v10
	v_and_b32_e32 v10, 0xffff0000, v25
	v_pk_mul_f32 v[10:11], v[30:31], v[10:11]
	s_nop 0
	v_add_f32_e32 v10, 0, v10
	v_add_f32_e32 v17, v10, v11
	v_rcp_f32_e32 v10, v7
	v_mul_f32_e32 v7, 0xbfb8aa3b, v8
	v_exp_f32_e32 v7, v7
	s_nop 0
	v_add_f32_e32 v7, 1.0, v7
	v_rcp_f32_e32 v8, v7
	v_mul_f32_e32 v7, 0xbfb8aa3b, v9
	v_exp_f32_e32 v7, v7
	s_nop 0
	v_add_f32_e32 v7, 1.0, v7
	v_rcp_f32_e32 v12, v7
	v_rcp_f32_e32 v7, v2
	s_nop 0
	v_pk_mul_f32 v[6:7], v[6:7], v[14:15]
	s_nop 0
	v_add_f32_e32 v2, v32, v6
	v_add_f32_e32 v6, v2, v7
	v_mul_f32_e32 v2, 0xbfb8aa3b, v3
	v_exp_f32_e32 v2, v2
	v_and_b32_e32 v3, 0xffff0000, v22
	v_add_f32_e32 v2, 1.0, v2
	v_rcp_f32_e32 v11, v2
	v_and_b32_e32 v2, 0xffff0000, v20
	v_pk_mul_f32 v[2:3], v[10:11], v[2:3]
	s_nop 0
	v_add_f32_e32 v2, v24, v2
	v_add_f32_e32 v7, v2, v3
	v_mul_f32_e32 v2, 0xbfb8aa3b, v4
	v_exp_f32_e32 v2, v2
	v_lshlrev_b32_e32 v3, 16, v23
	v_add_f32_e32 v2, 1.0, v2
	v_rcp_f32_e32 v9, v2
	v_lshlrev_b32_e32 v2, 16, v21
	v_pk_mul_f32 v[2:3], v[8:9], v[2:3]
	s_nop 0
	v_add_f32_e32 v2, v16, v2
	v_add_f32_e32 v4, v2, v3
	v_mul_f32_e32 v2, 0xbfb8aa3b, v5
	v_exp_f32_e32 v2, v2
	v_and_b32_e32 v3, 0xffff0000, v23
	v_add_f32_e32 v2, 1.0, v2
	v_rcp_f32_e32 v13, v2
	v_and_b32_e32 v2, 0xffff0000, v21
	v_pk_mul_f32 v[2:3], v[12:13], v[2:3]
	s_nop 0
	v_add_f32_e32 v2, v17, v2
	v_add_f32_e32 v3, v2, v3
	v_cvt_pk_bf16_f32 v2, v6, v7
	v_cvt_pk_bf16_f32 v3, v4, v3
	v_add_co_u32_e32 v4, vcc, 0x58000, v18
	s_nop 1
	v_addc_co_u32_e32 v5, vcc, 0, v19, vcc
	s_andn2_b64 vcc, exec, s[0:1]
	global_store_dwordx2 v[4:5], v[2:3], off
	s_cbranch_vccnz .LBB0_1852
	s_andn2_b64 vcc, exec, s[4:5]
	s_cbranch_vccnz .LBB0_1851
	s_barrier
	s_branch .LBB0_1851

; __device__ __forceinline__ void transpose_item8(const float* W, int N, unsigned char* WT, int ldt, int item, int lane, int mode, int aux) {
;     const int nblk = (N + 63) >> 6, kb = item / nblk, nb = item - kb * nblk, k0 = 64 * kb, n0 = 64 * nb;
;     const int ncol = n0 + lane;
;     const float* wp = W + (size_t)k0 * N + ncol;
;     float v[64];
; #pragma unroll
;     for (int i = 0; i < 64; ++i) v[i] = wp[(size_t)i * N];
;     unsigned o[16];
; #pragma unroll
;     for (int q = 0; q < 16; ++q) o[q] = pk4_fp8(fminf(fmaxf(v[4 * q] * 64.f, -448.f), 448.f), fminf(fmaxf(v[4 * q + 1] * 64.f, -448.f), 448.f), fminf(fmaxf(v[4 * q + 2] * 64.f, -448.f), 448.f), fminf(fmaxf(v[4 * q + 3] * 64.f, -448.f), 448.f));
;     v4u* dst = (v4u*)(WT + (size_t)rowmap(mode, aux, ncol) * ldt + k0);
; #pragma unroll
;     for (int q = 0; q < 4; ++q) dst[q] = (v4u){o[4 * q], o[4 * q + 1], o[4 * q + 2], o[4 * q + 3]};
; __device__ __forceinline__ void convert_rest(const Args& a, LAS unsigned char* lds, int wave, int lane, int gw, int ngw, int l, int it0, int it1) {
;     ...
;     for (int it = it0 + gw; it < it1; it += ngw) {
;         int r = it;
;         if (r < WI_G) { const int g = r >> 8; transpose_item8(a.in[I_WGATE] + (size_t)(l * 4 + g) * 1024 * 1024, 1024, ws + WS_WG, 1024, r & 255, lane, 2, g); continue; } r -= WI_G;
;         if (r < WI_BR) { const int g = r >> 6; transpose_item(a.in[I_WBR] + (size_t)(l * 4 + g) * 256 * 1024, 1024, (bf16*)(ws + WS_WBR) + (size_t)g * 1024 * 256, 256, scr, r & 63, lane, 0, 0); continue; } r -= WI_BR;
;         if (r < WI_OUT) { transpose_item(a.in[I_WOUT] + (size_t)l * 1024 * 1024, 1024, (bf16*)(ws + WS_WOUT), 1024, scr, r, lane, 0, 0); continue; } r -= WI_OUT;
;         if (r < WI_FF) { const int e = r >> 8; transpose_item8(a.in[I_WFFG] + (size_t)(l * 16 + e) * 1024 * 1024, 1024, ws + WS_WGU + (size_t)e * 2048 * 1024, 1024, r & 255, lane, 3, 0); continue; } r -= WI_FF;
;         if (r < WI_FF) { const int e = r >> 8; transpose_item8(a.in[I_WFFU] + (size_t)(l * 16 + e) * 1024 * 1024, 1024, ws + WS_WGU + (size_t)e * 2048 * 1024, 1024, r & 255, lane, 4, 0); continue; } r -= WI_FF;
;         { const int e = r >> 8; transpose_item8(a.in[I_WFFD] + (size_t)(l * 16 + e) * 1024 * 1024, 1024, ws + WS_WDN + (size_t)e * 1024 * 1024, 1024, r & 255, lane, 0, 0); }
.LBB0_1943:
	s_cmpk_gt_i32 s6, 0x3ff
	s_mov_b64 s[0:1], -1
	s_cbranch_scc0 .LBB0_2007
	s_cmpk_gt_u32 s6, 0x4ff
	s_cbranch_scc0 .LBB0_2004
	s_cmpk_gt_u32 s6, 0x5ff
	s_cbranch_scc0 .LBB0_1955
	s_cmpk_gt_u32 s6, 0x15ff
	s_cbranch_scc0 .LBB0_1952
	s_cmpk_gt_u32 s6, 0x25ff
	s_cbranch_scc0 .LBB0_1949
	s_add_i32 s0, s6, 0xffffda00
	s_lshr_b32 s0, s0, 8
	v_readlane_b32 s22, v254, 32
	v_readlane_b32 s23, v254, 33
	s_add_i32 s22, s0, s7
	v_readlane_b32 s56, v252, 41
	s_lshl_b64 s[2:3], s[22:23], 22
	v_readlane_b32 s64, v252, 49
	v_readlane_b32 s65, v252, 50
	s_add_u32 s2, s64, s2
	s_mov_b32 s1, s23
	s_addc_u32 s3, s65, s3
	s_lshl_b64 s[0:1], s[0:1], 20
	v_readlane_b32 s17, v253, 59
	s_add_u32 s0, s17, s0
	v_readlane_b32 s17, v253, 60
	s_addc_u32 s1, s17, s1
	s_lshl_b32 s17, s6, 2
	s_and_b32 s22, s17, 0x3c0
	s_lshl_b32 s17, s6, 6
	s_and_b32 s17, s17, 0x3c0
	v_or_b32_e32 v17, s17, v20
	s_lshl_b32 s17, s22, 12
	s_add_u32 s2, s2, s17
	s_addc_u32 s3, s3, 0
	v_lshlrev_b32_e32 v50, 2, v17
	v_lshl_add_u64 v[2:3], s[2:3], 0, v[50:51]
	global_load_dword v18, v50, s[2:3] nt
	s_movk_i32 s2, 0x2000
	v_readlane_b32 s70, v252, 55
	v_add_co_u32_e32 v4, vcc, s2, v2
	s_movk_i32 s70, 0x4000
	s_nop 0
	v_addc_co_u32_e32 v5, vcc, 0, v3, vcc
	global_load_dword v19, v[4:5], off offset:-4096 nt
	global_load_dword v42, v[4:5], off nt
	v_add_co_u32_e32 v4, vcc, s70, v2
	s_movk_i32 s2, 0x6000
	s_nop 0
	v_addc_co_u32_e32 v5, vcc, 0, v3, vcc
	global_load_dword v43, v[4:5], off offset:-4096 nt
	global_load_dword v44, v[4:5], off nt
	v_add_co_u32_e32 v4, vcc, s2, v2
	s_mov_b32 s2, 0x8000
	s_nop 0
	v_addc_co_u32_e32 v5, vcc, 0, v3, vcc
	global_load_dword v45, v[4:5], off offset:-4096 nt
	global_load_dword v46, v[4:5], off nt
	v_add_co_u32_e32 v4, vcc, s2, v2
	s_mov_b32 s2, 0xa000
	s_nop 0
	v_addc_co_u32_e32 v5, vcc, 0, v3, vcc
	global_load_dword v47, v[4:5], off offset:-4096 nt
	global_load_dword v48, v[4:5], off nt
	v_add_co_u32_e32 v4, vcc, s2, v2
	s_mov_b32 s2, 0xc000
	s_nop 0
	v_addc_co_u32_e32 v5, vcc, 0, v3, vcc
	global_load_dword v49, v[4:5], off offset:-4096 nt
	global_load_dword v50, v[4:5], off nt
	v_add_co_u32_e32 v4, vcc, s2, v2
	s_mov_b32 s2, 0xe000
	s_nop 0
	v_addc_co_u32_e32 v5, vcc, 0, v3, vcc
	global_load_dword v52, v[4:5], off offset:-4096 nt
	global_load_dword v53, v[4:5], off nt
	v_add_co_u32_e32 v4, vcc, s2, v2
	s_mov_b32 s2, 0x10000
	s_nop 0
	v_addc_co_u32_e32 v5, vcc, 0, v3, vcc
	global_load_dword v54, v[4:5], off offset:-4096 nt
	global_load_dword v55, v[4:5], off nt
	v_add_co_u32_e32 v4, vcc, s2, v2
	s_mov_b32 s2, 0x12000
	s_nop 0
	v_addc_co_u32_e32 v5, vcc, 0, v3, vcc
	global_load_dword v56, v[4:5], off offset:-4096 nt
	global_load_dword v10, v[4:5], off nt
	v_add_co_u32_e32 v4, vcc, s2, v2
	s_mov_b32 s2, 0x14000
	s_nop 0
	v_addc_co_u32_e32 v5, vcc, 0, v3, vcc
	global_load_dword v57, v[4:5], off offset:-4096 nt
	global_load_dword v58, v[4:5], off nt
	v_add_co_u32_e32 v4, vcc, s2, v2
	s_mov_b32 s2, 0x16000
	s_nop 0
	v_addc_co_u32_e32 v5, vcc, 0, v3, vcc
	global_load_dword v59, v[4:5], off offset:-4096 nt
	global_load_dword v11, v[4:5], off nt
	v_add_co_u32_e32 v4, vcc, s2, v2
	s_mov_b32 s2, 0x18000
	s_nop 0
	v_addc_co_u32_e32 v5, vcc, 0, v3, vcc
	global_load_dword v60, v[4:5], off offset:-4096 nt
	global_load_dword v61, v[4:5], off nt
	v_add_co_u32_e32 v4, vcc, s2, v2
	s_mov_b32 s2, 0x1a000
	s_nop 0
	v_addc_co_u32_e32 v5, vcc, 0, v3, vcc
	global_load_dword v62, v[4:5], off offset:-4096 nt
	global_load_dword v12, v[4:5], off nt
	v_add_co_u32_e32 v4, vcc, s2, v2
	s_mov_b32 s2, 0x1c000
	s_nop 0
	v_addc_co_u32_e32 v5, vcc, 0, v3, vcc
	global_load_dword v63, v[4:5], off offset:-4096 nt
	global_load_dword v64, v[4:5], off nt
	v_add_co_u32_e32 v4, vcc, s2, v2
	s_mov_b32 s2, 0x1e000
	s_nop 0
	v_addc_co_u32_e32 v5, vcc, 0, v3, vcc
	global_load_dword v65, v[4:5], off offset:-4096 nt
	global_load_dword v13, v[4:5], off nt
	v_add_co_u32_e32 v4, vcc, s2, v2
	s_mov_b32 s2, 0x20000
	s_nop 0
	v_addc_co_u32_e32 v5, vcc, 0, v3, vcc
	global_load_dword v66, v[4:5], off offset:-4096 nt
	global_load_dword v67, v[4:5], off nt
	v_add_co_u32_e32 v4, vcc, s2, v2
	s_mov_b32 s2, 0x22000
	s_nop 0
	v_addc_co_u32_e32 v5, vcc, 0, v3, vcc
	global_load_dword v68, v[4:5], off offset:-4096 nt
	global_load_dword v6, v[4:5], off nt
	v_add_co_u32_e32 v4, vcc, s2, v2
	s_mov_b32 s2, 0x24000
	s_nop 0
	v_addc_co_u32_e32 v5, vcc, 0, v3, vcc
	global_load_dword v69, v[4:5], off offset:-4096 nt
	global_load_dword v70, v[4:5], off nt
	v_add_co_u32_e32 v4, vcc, s2, v2
	s_mov_b32 s2, 0x26000
	s_nop 0
	v_addc_co_u32_e32 v5, vcc, 0, v3, vcc
	global_load_dword v71, v[4:5], off offset:-4096 nt
	global_load_dword v7, v[4:5], off nt
	v_add_co_u32_e32 v4, vcc, s2, v2
	s_mov_b32 s2, 0x28000
	s_nop 0
	v_addc_co_u32_e32 v5, vcc, 0, v3, vcc
	global_load_dword v72, v[4:5], off offset:-4096 nt
	global_load_dword v73, v[4:5], off nt
	v_add_co_u32_e32 v4, vcc, s2, v2
	s_mov_b32 s2, 0x2a000
	s_nop 0
	v_addc_co_u32_e32 v5, vcc, 0, v3, vcc
	global_load_dword v74, v[4:5], off offset:-4096 nt
	global_load_dword v8, v[4:5], off nt
	v_add_co_u32_e32 v4, vcc, s2, v2
	s_mov_b32 s2, 0x2c000
	s_nop 0
	v_addc_co_u32_e32 v5, vcc, 0, v3, vcc
	global_load_dword v75, v[4:5], off offset:-4096 nt
	global_load_dword v76, v[4:5], off nt
	v_add_co_u32_e32 v4, vcc, s2, v2
	s_mov_b32 s2, 0x2e000
	s_nop 0
	v_addc_co_u32_e32 v5, vcc, 0, v3, vcc
	global_load_dword v77, v[4:5], off offset:-4096 nt
	global_load_dword v9, v[4:5], off nt
	v_add_co_u32_e32 v4, vcc, s2, v2
	s_mov_b32 s2, 0x30000
	s_nop 0
	v_addc_co_u32_e32 v5, vcc, 0, v3, vcc
	global_load_dword v78, v[4:5], off offset:-4096 nt
	global_load_dword v79, v[4:5], off nt
; __device__ __forceinline__ unsigned pk4_fp8(float a, float b, float c, float d) { int w = 0; w = __builtin_amdgcn_cvt_pk_fp8_f32(a, b, w, false); w = __builtin_amdgcn_cvt_pk_fp8_f32(c, d, w, true); return (unsigned)w; }
; __device__ __forceinline__ void transpose_item8(const float* W, int N, unsigned char* WT, int ldt, int item, int lane, int mode, int aux) {
;     ...
;     for (int i = 0; i < 64; ++i) v[i] = wp[(size_t)i * N];
;     unsigned o[16];
; #pragma unroll
;     for (int q = 0; q < 16; ++q) o[q] = pk4_fp8(fminf(fmaxf(v[4 * q] * 64.f, -448.f), 448.f), fminf(fmaxf(v[4 * q + 1] * 64.f, -448.f), 448.f), fminf(fmaxf(v[4 * q + 2] * 64.f, -448.f), 448.f), fminf(fmaxf(v[4 * q + 3] * 64.f, -448.f), 448.f));
;     v4u* dst = (v4u*)(WT + (size_t)rowmap(mode, aux, ncol) * ldt + k0);
; #pragma unroll
;     for (int q = 0; q < 4; ++q) dst[q] = (v4u){o[4 * q], o[4 * q + 1], o[4 * q + 2], o[4 * q + 3]};
	v_add_co_u32_e32 v4, vcc, s2, v2
	s_mov_b32 s2, 0x32000
	s_nop 0
	v_addc_co_u32_e32 v5, vcc, 0, v3, vcc
	global_load_dword v80, v[4:5], off offset:-4096 nt
	global_load_dword v81, v[4:5], off nt
	v_add_co_u32_e32 v4, vcc, s2, v2
	s_mov_b32 s2, 0x34000
	s_nop 0
	v_addc_co_u32_e32 v5, vcc, 0, v3, vcc
	global_load_dword v82, v[4:5], off offset:-4096 nt
	global_load_dword v83, v[4:5], off nt
	v_add_co_u32_e32 v4, vcc, s2, v2
	s_mov_b32 s2, 0x36000
	s_nop 0
	v_addc_co_u32_e32 v5, vcc, 0, v3, vcc
	global_load_dword v84, v[4:5], off offset:-4096 nt
	global_load_dword v85, v[4:5], off nt
	v_add_co_u32_e32 v4, vcc, s2, v2
	s_mov_b32 s2, 0x38000
	s_nop 0
	v_addc_co_u32_e32 v5, vcc, 0, v3, vcc
	global_load_dword v86, v[4:5], off offset:-4096 nt
	global_load_dword v87, v[4:5], off nt
	v_add_co_u32_e32 v4, vcc, s2, v2
	s_mov_b32 s2, 0x3a000
	s_nop 0
	v_addc_co_u32_e32 v5, vcc, 0, v3, vcc
	global_load_dword v88, v[4:5], off offset:-4096 nt
	global_load_dword v89, v[4:5], off nt
	v_add_co_u32_e32 v4, vcc, s2, v2
	s_mov_b32 s2, 0x3c000
	s_nop 0
	v_addc_co_u32_e32 v5, vcc, 0, v3, vcc
	global_load_dword v90, v[4:5], off offset:-4096 nt
	global_load_dword v91, v[4:5], off nt
	v_add_co_u32_e32 v4, vcc, s2, v2
	s_mov_b32 s2, 0x3e000
	s_nop 0
	v_addc_co_u32_e32 v5, vcc, 0, v3, vcc
	global_load_dword v92, v[4:5], off offset:-4096 nt
	global_load_dword v93, v[4:5], off nt
	v_add_co_u32_e32 v4, vcc, s2, v2
	s_mov_b32 s2, 0x3f000
	s_nop 0
	v_addc_co_u32_e32 v5, vcc, 0, v3, vcc
	global_load_dword v94, v[4:5], off offset:-4096 nt
	s_nop 0
	global_load_dword v4, v[4:5], off nt
	v_add_co_u32_e32 v2, vcc, s2, v2
	s_mov_b32 s2, 0xc3e00000
	s_nop 0
	v_addc_co_u32_e32 v3, vcc, 0, v3, vcc
	global_load_dword v2, v[2:3], off nt
	s_waitcnt vmcnt(27)
	v_mul_f32_e32 v7, 0x42800000, v7
	v_mul_f32_e32 v6, 0x42800000, v6
	v_mul_f32_e32 v13, 0x42800000, v13
	v_mul_f32_e32 v12, 0x42800000, v12
	v_mul_f32_e32 v11, 0x42800000, v11
	v_mul_f32_e32 v10, 0x42800000, v10
	v_mul_f32_e32 v55, 0x42800000, v55
	s_waitcnt vmcnt(23)
	v_mul_f32_e32 v8, 0x42800000, v8
	v_mul_f32_e32 v53, 0x42800000, v53
	v_mul_f32_e32 v54, 0x42800000, v54
	v_med3_f32 v53, v53, s2, v236
	v_med3_f32 v54, v54, s2, v236
	v_mul_f32_e32 v48, 0x42800000, v48
	v_mul_f32_e32 v49, 0x42800000, v49
	v_med3_f32 v48, v48, s2, v236
	v_med3_f32 v49, v49, s2, v236
	v_mul_f32_e32 v50, 0x42800000, v50
	v_mul_f32_e32 v52, 0x42800000, v52
	v_med3_f32 v50, v50, s2, v236
	s_waitcnt vmcnt(19)
	v_mul_f32_e32 v9, 0x42800000, v9
	v_med3_f32 v52, v52, s2, v236
	v_mul_f32_e32 v44, 0x42800000, v44
	v_mul_f32_e32 v45, 0x42800000, v45
	v_mul_f32_e32 v18, 0x42800000, v18
	v_mul_f32_e32 v19, 0x42800000, v19
	v_med3_f32 v44, v44, s2, v236
	v_med3_f32 v45, v45, s2, v236
	v_med3_f32 v18, v18, s2, v236
	v_med3_f32 v19, v19, s2, v236
	v_mul_f32_e32 v46, 0x42800000, v46
	v_mul_f32_e32 v47, 0x42800000, v47
	v_mul_f32_e32 v42, 0x42800000, v42
	v_mul_f32_e32 v43, 0x42800000, v43
	v_mul_f32_e32 v67, 0x42800000, v67
	v_mul_f32_e32 v68, 0x42800000, v68
	v_mul_f32_e32 v64, 0x42800000, v64
	v_mul_f32_e32 v65, 0x42800000, v65
	v_mul_f32_e32 v61, 0x42800000, v61
	v_mul_f32_e32 v62, 0x42800000, v62
	v_mul_f32_e32 v58, 0x42800000, v58
	v_mul_f32_e32 v59, 0x42800000, v59
	v_med3_f32 v46, v46, s2, v236
	v_med3_f32 v47, v47, s2, v236
	v_med3_f32 v42, v42, s2, v236
	v_med3_f32 v43, v43, s2, v236
	s_waitcnt vmcnt(17)
	v_mul_f32_e32 v79, 0x42800000, v79
	s_waitcnt vmcnt(16)
	v_mul_f32_e32 v80, 0x42800000, v80
	v_mul_f32_e32 v76, 0x42800000, v76
	v_mul_f32_e32 v77, 0x42800000, v77
	v_mul_f32_e32 v73, 0x42800000, v73
	v_mul_f32_e32 v74, 0x42800000, v74
	v_mul_f32_e32 v70, 0x42800000, v70
	v_mul_f32_e32 v71, 0x42800000, v71
	v_med3_f32 v67, v67, s2, v236
	v_med3_f32 v68, v68, s2, v236
	v_med3_f32 v64, v64, s2, v236
	v_med3_f32 v65, v65, s2, v236
	v_med3_f32 v61, v61, s2, v236
	v_med3_f32 v62, v62, s2, v236
	v_med3_f32 v58, v58, s2, v236
	v_med3_f32 v59, v59, s2, v236
	v_med3_f32 v79, v79, s2, v236
	v_med3_f32 v80, v80, s2, v236
	v_med3_f32 v76, v76, s2, v236
	v_med3_f32 v77, v77, s2, v236
	v_med3_f32 v73, v73, s2, v236
	v_med3_f32 v74, v74, s2, v236
	v_med3_f32 v70, v70, s2, v236
	v_med3_f32 v71, v71, s2, v236
	v_readlane_b32 s58, v252, 43
	v_readlane_b32 s59, v252, 44
	v_readlane_b32 s60, v252, 45
	s_waitcnt vmcnt(2)
	v_mul_f32_e32 v5, 0x42800000, v94
	s_waitcnt vmcnt(1)
	v_mul_f32_e32 v3, 0x42800000, v4
	v_mul_f32_e32 v4, 0x42800000, v93
	v_med3_f32 v4, v4, s2, v236
	v_med3_f32 v93, v5, s2, v236
	v_mov_b32_e32 v5, v51
	v_cvt_pk_fp8_f32 v5, v4, v93
	v_mul_f32_e32 v4, 0x42800000, v89
	v_med3_f32 v89, v4, s2, v236
	v_mul_f32_e32 v4, 0x42800000, v90
	v_med3_f32 v90, v4, s2, v236
	v_mov_b32_e32 v4, v51
	s_waitcnt vmcnt(0)
; __device__ __forceinline__ unsigned pk4_fp8(float a, float b, float c, float d) { int w = 0; w = __builtin_amdgcn_cvt_pk_fp8_f32(a, b, w, false); w = __builtin_amdgcn_cvt_pk_fp8_f32(c, d, w, true); return (unsigned)w; }
; __device__ __forceinline__ void transpose_item8(const float* W, int N, unsigned char* WT, int ldt, int item, int lane, int mode, int aux) {
;     ...
;     for (int i = 0; i < 64; ++i) v[i] = wp[(size_t)i * N];
;     unsigned o[16];
; #pragma unroll
;     for (int q = 0; q < 16; ++q) o[q] = pk4_fp8(fminf(fmaxf(v[4 * q] * 64.f, -448.f), 448.f), fminf(fmaxf(v[4 * q + 1] * 64.f, -448.f), 448.f), fminf(fmaxf(v[4 * q + 2] * 64.f, -448.f), 448.f), fminf(fmaxf(v[4 * q + 3] * 64.f, -448.f), 448.f));
;     v4u* dst = (v4u*)(WT + (size_t)rowmap(mode, aux, ncol) * ldt + k0);
; #pragma unroll
;     for (int q = 0; q < 4; ++q) dst[q] = (v4u){o[4 * q], o[4 * q + 1], o[4 * q + 2], o[4 * q + 3]};
; __device__ __forceinline__ void convert_rest(const Args& a, LAS unsigned char* lds, int wave, int lane, int gw, int ngw, int l, int it0, int it1) {
;     ...
;         if (r < WI_FF) { const int e = r >> 8; transpose_item8(a.in[I_WFFG] + (size_t)(l * 16 + e) * 1024 * 1024, 1024, ws + WS_WGU + (size_t)e * 2048 * 1024, 1024, r & 255, lane, 3, 0); continue; } r -= WI_FF;
;         if (r < WI_FF) { const int e = r >> 8; transpose_item8(a.in[I_WFFU] + (size_t)(l * 16 + e) * 1024 * 1024, 1024, ws + WS_WGU + (size_t)e * 2048 * 1024, 1024, r & 255, lane, 4, 0); continue; } r -= WI_FF;
	v_mul_f32_e32 v2, 0x42800000, v2
	v_cvt_pk_fp8_f32 v4, v89, v90
	v_med3_f32 v3, v3, s2, v236
	v_med3_f32 v2, v2, s2, v236
	v_cvt_pk_fp8_f32 v5, v3, v2 op_sel:[0,0,1]
	v_mul_f32_e32 v2, 0x42800000, v91
	v_mul_f32_e32 v3, 0x42800000, v92
	v_med3_f32 v2, v2, s2, v236
	v_med3_f32 v3, v3, s2, v236
	v_cvt_pk_fp8_f32 v4, v2, v3 op_sel:[0,0,1]
	v_mul_f32_e32 v3, 0x42800000, v88
	v_mul_f32_e32 v2, 0x42800000, v87
	v_med3_f32 v87, v3, s2, v236
	v_mul_f32_e32 v3, 0x42800000, v85
	v_med3_f32 v85, v3, s2, v236
	v_mul_f32_e32 v3, 0x42800000, v86
	v_med3_f32 v86, v3, s2, v236
	v_mov_b32_e32 v3, v51
	v_cvt_pk_fp8_f32 v3, v85, v86
	v_med3_f32 v2, v2, s2, v236
	v_readlane_b32 s61, v252, 46
	v_readlane_b32 s62, v252, 47
	v_cvt_pk_fp8_f32 v3, v2, v87 op_sel:[0,0,1]
	v_mul_f32_e32 v2, 0x42800000, v83
	v_med3_f32 v83, v2, s2, v236
	v_mul_f32_e32 v2, 0x42800000, v84
	v_med3_f32 v84, v2, s2, v236
	v_mul_f32_e32 v2, 0x42800000, v81
	v_med3_f32 v81, v2, s2, v236
	v_mul_f32_e32 v2, 0x42800000, v82
	v_med3_f32 v82, v2, s2, v236
	v_mov_b32_e32 v2, v51
	v_cvt_pk_fp8_f32 v2, v81, v82
	v_med3_f32 v81, v9, s2, v236
	v_mul_f32_e32 v9, 0x42800000, v78
	v_med3_f32 v78, v9, s2, v236
	v_mov_b32_e32 v9, v51
	v_cvt_pk_fp8_f32 v9, v81, v78
	v_med3_f32 v78, v8, s2, v236
	v_mul_f32_e32 v8, 0x42800000, v75
	v_med3_f32 v75, v8, s2, v236
	v_mov_b32_e32 v8, v51
	v_cvt_pk_fp8_f32 v8, v78, v75
	v_med3_f32 v75, v7, s2, v236
	v_mul_f32_e32 v7, 0x42800000, v72
	v_med3_f32 v72, v7, s2, v236
	v_mov_b32_e32 v7, v51
	v_cvt_pk_fp8_f32 v7, v75, v72
	v_med3_f32 v72, v6, s2, v236
	v_mul_f32_e32 v6, 0x42800000, v69
	v_med3_f32 v69, v6, s2, v236
	v_mov_b32_e32 v6, v51
	v_cvt_pk_fp8_f32 v6, v72, v69
	v_med3_f32 v69, v13, s2, v236
	v_mul_f32_e32 v13, 0x42800000, v66
	v_med3_f32 v66, v13, s2, v236
	v_mov_b32_e32 v13, v51
	v_cvt_pk_fp8_f32 v13, v69, v66
	v_med3_f32 v66, v12, s2, v236
	v_mul_f32_e32 v12, 0x42800000, v63
	v_med3_f32 v63, v12, s2, v236
	v_mov_b32_e32 v12, v51
	v_cvt_pk_fp8_f32 v12, v66, v63
	v_med3_f32 v63, v11, s2, v236
	v_mul_f32_e32 v11, 0x42800000, v60
	v_med3_f32 v60, v11, s2, v236
	v_mov_b32_e32 v11, v51
	v_cvt_pk_fp8_f32 v11, v63, v60
	v_med3_f32 v60, v10, s2, v236
	v_mul_f32_e32 v10, 0x42800000, v57
	v_med3_f32 v57, v10, s2, v236
	v_mov_b32_e32 v10, v51
	v_cvt_pk_fp8_f32 v10, v60, v57
	v_med3_f32 v57, v55, s2, v236
	v_mul_f32_e32 v55, 0x42800000, v56
	v_med3_f32 v56, v55, s2, v236
	v_mov_b32_e32 v55, v51
	v_cvt_pk_fp8_f32 v55, v53, v54
	v_mov_b32_e32 v54, v51
	v_cvt_pk_fp8_f32 v54, v48, v49
	v_mov_b32_e32 v53, v51
	v_cvt_pk_fp8_f32 v53, v44, v45
	v_cvt_pk_fp8_f32 v55, v57, v56 op_sel:[0,0,1]
	v_cvt_pk_fp8_f32 v54, v50, v52 op_sel:[0,0,1]
	v_mov_b32_e32 v52, v51
	v_cvt_pk_fp8_f32 v52, v18, v19
	v_cvt_pk_fp8_f32 v53, v46, v47 op_sel:[0,0,1]
	v_cvt_pk_fp8_f32 v13, v67, v68 op_sel:[0,0,1]
	v_cvt_pk_fp8_f32 v12, v64, v65 op_sel:[0,0,1]
	v_cvt_pk_fp8_f32 v52, v42, v43 op_sel:[0,0,1]
	v_cvt_pk_fp8_f32 v11, v61, v62 op_sel:[0,0,1]
	v_cvt_pk_fp8_f32 v10, v58, v59 op_sel:[0,0,1]
	v_lshlrev_b32_e32 v50, 10, v17
	v_cvt_pk_fp8_f32 v9, v79, v80 op_sel:[0,0,1]
	v_cvt_pk_fp8_f32 v8, v76, v77 op_sel:[0,0,1]
	v_cvt_pk_fp8_f32 v7, v73, v74 op_sel:[0,0,1]
	v_cvt_pk_fp8_f32 v6, v70, v71 op_sel:[0,0,1]
	v_lshl_add_u64 v[18:19], s[0:1], 0, v[50:51]
	s_mov_b32 s1, s23
	v_readlane_b32 s63, v252, 48
	v_readlane_b32 s68, v252, 53
	v_readlane_b32 s69, v252, 54
	v_readlane_b32 s71, v252, 56
	s_mov_b32 s58, 0x3f6c835e
	v_readlane_b32 s60, v255, 2
	v_cvt_pk_fp8_f32 v2, v83, v84 op_sel:[0,0,1]
	v_writelane_b32 v254, s0, 32
	v_lshl_add_u64 v[18:19], v[18:19], 0, s[22:23]
	v_readlane_b32 s57, v252, 42
	v_readlane_b32 s66, v252, 51
	v_readlane_b32 s67, v252, 52
	s_mov_b32 s63, 0xbf6c835e
	v_readlane_b32 s62, v255, 4
	s_movk_i32 s68, 0x2200
	s_movk_i32 s71, 0x1ff
	s_mov_b32 s69, 0x7f800000
	s_mov_b32 s59, 0xbec3ef15
	v_readlane_b32 s61, v255, 3
	s_movk_i32 s64, 0x440
	v_writelane_b32 v254, s1, 33
	global_store_dwordx4 v[18:19], v[52:55], off
	global_store_dwordx4 v[18:19], v[10:13], off offset:16
	global_store_dwordx4 v[18:19], v[6:9], off offset:32
	global_store_dwordx4 v[18:19], v[2:5], off offset:48
	s_mov_b64 s[0:1], 0
.LBB0_1949:
	s_andn2_b64 vcc, exec, s[0:1]
	s_cbranch_vccnz .LBB0_1951
	s_add_i32 s0, s6, 0xffffea00
	s_lshr_b32 s0, s0, 8
	v_readlane_b32 s22, v254, 32
	v_readlane_b32 s23, v254, 33
	s_add_i32 s22, s0, s7
	v_readlane_b32 s56, v252, 41
	s_lshl_b64 s[2:3], s[22:23], 22
	v_readlane_b32 s62, v252, 47
	v_readlane_b32 s63, v252, 48
	s_add_u32 s17, s62, s2
	s_mov_b32 s1, s23
	s_addc_u32 s3, s63, s3
	s_lshl_b64 s[0:1], s[0:1], 21
	v_readlane_b32 s2, v253, 61
	s_add_u32 s0, s2, s0
	v_readlane_b32 s2, v253, 62
	s_addc_u32 s1, s2, s1
	s_and_b32 s22, s11, 0x3c0
	s_add_i32 s2, s13, 0xa2000
	s_and_b32 s2, s2, 0x3c0
	s_lshl_b32 s21, s22, 12
	v_or_b32_e32 v2, s2, v20
	s_add_u32 s26, s17, s21
	s_addc_u32 s27, s3, 0
	v_lshlrev_b32_e32 v50, 2, v2
	v_lshl_add_u64 v[2:3], s[26:27], 0, v[50:51]
	s_movk_i32 s3, 0x2000
	v_readlane_b32 s70, v252, 55
	v_add_co_u32_e32 v4, vcc, s3, v2
	s_movk_i32 s70, 0x4000
	s_nop 0
	v_addc_co_u32_e32 v5, vcc, 0, v3, vcc
	global_load_dword v17, v50, s[26:27] nt
	global_load_dword v18, v[4:5], off offset:-4096 nt
	global_load_dword v19, v[4:5], off nt
	v_add_co_u32_e32 v4, vcc, s70, v2
	s_movk_i32 s3, 0x6000
	s_nop 0
	v_addc_co_u32_e32 v5, vcc, 0, v3, vcc
	global_load_dword v42, v[4:5], off offset:-4096 nt
	global_load_dword v43, v[4:5], off nt
	v_add_co_u32_e32 v4, vcc, s3, v2
	s_mov_b32 s3, 0x8000
	s_nop 0
	v_addc_co_u32_e32 v5, vcc, 0, v3, vcc
	global_load_dword v44, v[4:5], off offset:-4096 nt
	global_load_dword v45, v[4:5], off nt
	v_add_co_u32_e32 v4, vcc, s3, v2
	s_mov_b32 s3, 0xa000
; __device__ __forceinline__ int rowmap(int mode, int aux, int n) {
;     ...
;     return 256 * (n >> 7) + 128 + (n & 127);
; __device__ __forceinline__ void transpose_item8(const float* W, int N, unsigned char* WT, int ldt, int item, int lane, int mode, int aux) {
;     ...
;     const float* wp = W + (size_t)k0 * N + ncol;
;     float v[64];
; #pragma unroll
;     for (int i = 0; i < 64; ++i) v[i] = wp[(size_t)i * N];
	s_nop 0
	v_addc_co_u32_e32 v5, vcc, 0, v3, vcc
	global_load_dword v46, v[4:5], off offset:-4096 nt
	global_load_dword v47, v[4:5], off nt
	v_add_co_u32_e32 v4, vcc, s3, v2
	s_mov_b32 s3, 0xc000
	s_nop 0
	v_addc_co_u32_e32 v5, vcc, 0, v3, vcc
	global_load_dword v48, v[4:5], off offset:-4096 nt
	global_load_dword v49, v[4:5], off nt
	v_add_co_u32_e32 v4, vcc, s3, v2
	s_mov_b32 s3, 0xe000
	s_nop 0
	v_addc_co_u32_e32 v5, vcc, 0, v3, vcc
	global_load_dword v50, v[4:5], off offset:-4096 nt
	global_load_dword v52, v[4:5], off nt
	v_add_co_u32_e32 v4, vcc, s3, v2
	s_mov_b32 s3, 0x10000
	s_nop 0
	v_addc_co_u32_e32 v5, vcc, 0, v3, vcc
	global_load_dword v53, v[4:5], off offset:-4096 nt
	global_load_dword v54, v[4:5], off nt
	v_add_co_u32_e32 v4, vcc, s3, v2
	s_mov_b32 s3, 0x12000
	s_nop 0
	v_addc_co_u32_e32 v5, vcc, 0, v3, vcc
	global_load_dword v55, v[4:5], off offset:-4096 nt
	global_load_dword v10, v[4:5], off nt
	v_add_co_u32_e32 v4, vcc, s3, v2
	s_mov_b32 s3, 0x14000
	s_nop 0
	v_addc_co_u32_e32 v5, vcc, 0, v3, vcc
	global_load_dword v56, v[4:5], off offset:-4096 nt
	global_load_dword v57, v[4:5], off nt
	v_add_co_u32_e32 v4, vcc, s3, v2
	s_mov_b32 s3, 0x16000
	s_nop 0
	v_addc_co_u32_e32 v5, vcc, 0, v3, vcc
	global_load_dword v58, v[4:5], off offset:-4096 nt
	global_load_dword v11, v[4:5], off nt
	v_add_co_u32_e32 v4, vcc, s3, v2
	s_mov_b32 s3, 0x18000
	s_nop 0
	v_addc_co_u32_e32 v5, vcc, 0, v3, vcc
	global_load_dword v59, v[4:5], off offset:-4096 nt
	global_load_dword v60, v[4:5], off nt
	v_add_co_u32_e32 v4, vcc, s3, v2
	s_mov_b32 s3, 0x1a000
	s_nop 0
	v_addc_co_u32_e32 v5, vcc, 0, v3, vcc
	global_load_dword v61, v[4:5], off offset:-4096 nt
	global_load_dword v12, v[4:5], off nt
	v_add_co_u32_e32 v4, vcc, s3, v2
	s_mov_b32 s3, 0x1c000
	s_nop 0
	v_addc_co_u32_e32 v5, vcc, 0, v3, vcc
	global_load_dword v62, v[4:5], off offset:-4096 nt
	global_load_dword v63, v[4:5], off nt
	v_add_co_u32_e32 v4, vcc, s3, v2
	s_mov_b32 s3, 0x1e000
	s_nop 0
	v_addc_co_u32_e32 v5, vcc, 0, v3, vcc
	global_load_dword v64, v[4:5], off offset:-4096 nt
	global_load_dword v13, v[4:5], off nt
	v_add_co_u32_e32 v4, vcc, s3, v2
	s_mov_b32 s3, 0x20000
	s_nop 0
	v_addc_co_u32_e32 v5, vcc, 0, v3, vcc
	global_load_dword v65, v[4:5], off offset:-4096 nt
	global_load_dword v66, v[4:5], off nt
	v_add_co_u32_e32 v4, vcc, s3, v2
	s_mov_b32 s3, 0x22000
	s_nop 0
	v_addc_co_u32_e32 v5, vcc, 0, v3, vcc
	global_load_dword v67, v[4:5], off offset:-4096 nt
	global_load_dword v6, v[4:5], off nt
	v_add_co_u32_e32 v4, vcc, s3, v2
	s_mov_b32 s3, 0x24000
	s_nop 0
	v_addc_co_u32_e32 v5, vcc, 0, v3, vcc
	global_load_dword v68, v[4:5], off offset:-4096 nt
	global_load_dword v69, v[4:5], off nt
	v_add_co_u32_e32 v4, vcc, s3, v2
	s_mov_b32 s3, 0x26000
	s_nop 0
	v_addc_co_u32_e32 v5, vcc, 0, v3, vcc
	global_load_dword v70, v[4:5], off offset:-4096 nt
	global_load_dword v7, v[4:5], off nt
	v_add_co_u32_e32 v4, vcc, s3, v2
	s_mov_b32 s3, 0x28000
	s_nop 0
	v_addc_co_u32_e32 v5, vcc, 0, v3, vcc
	global_load_dword v71, v[4:5], off offset:-4096 nt
	global_load_dword v72, v[4:5], off nt
	v_add_co_u32_e32 v4, vcc, s3, v2
	s_mov_b32 s3, 0x2a000
	s_nop 0
	v_addc_co_u32_e32 v5, vcc, 0, v3, vcc
	global_load_dword v73, v[4:5], off offset:-4096 nt
	global_load_dword v8, v[4:5], off nt
	v_add_co_u32_e32 v4, vcc, s3, v2
	s_mov_b32 s3, 0x2c000
	s_nop 0
	v_addc_co_u32_e32 v5, vcc, 0, v3, vcc
	global_load_dword v74, v[4:5], off offset:-4096 nt
	global_load_dword v75, v[4:5], off nt
	v_add_co_u32_e32 v4, vcc, s3, v2
	s_mov_b32 s3, 0x2e000
	s_nop 0
	v_addc_co_u32_e32 v5, vcc, 0, v3, vcc
	global_load_dword v76, v[4:5], off offset:-4096 nt
	global_load_dword v9, v[4:5], off nt
	v_add_co_u32_e32 v4, vcc, s3, v2
	s_mov_b32 s3, 0x30000
	s_nop 0
	v_addc_co_u32_e32 v5, vcc, 0, v3, vcc
	global_load_dword v77, v[4:5], off offset:-4096 nt
	global_load_dword v78, v[4:5], off nt
	v_add_co_u32_e32 v4, vcc, s3, v2
	s_mov_b32 s3, 0x32000
	s_nop 0
	v_addc_co_u32_e32 v5, vcc, 0, v3, vcc
	global_load_dword v80, v[4:5], off offset:-4096 nt
	global_load_dword v81, v[4:5], off nt
	v_add_co_u32_e32 v4, vcc, s3, v2
	s_mov_b32 s3, 0x34000
	s_nop 0
	v_addc_co_u32_e32 v5, vcc, 0, v3, vcc
	global_load_dword v82, v[4:5], off offset:-4096 nt
	global_load_dword v83, v[4:5], off nt
	v_add_co_u32_e32 v4, vcc, s3, v2
	s_mov_b32 s3, 0x36000
	s_nop 0
	v_addc_co_u32_e32 v5, vcc, 0, v3, vcc
	global_load_dword v84, v[4:5], off offset:-4096 nt
	global_load_dword v85, v[4:5], off nt
	v_add_co_u32_e32 v4, vcc, s3, v2
	s_mov_b32 s3, 0x38000
	s_nop 0
	v_addc_co_u32_e32 v5, vcc, 0, v3, vcc
	global_load_dword v86, v[4:5], off offset:-4096 nt
	global_load_dword v87, v[4:5], off nt
	v_add_co_u32_e32 v4, vcc, s3, v2
	s_mov_b32 s3, 0x3a000
	s_nop 0
	v_addc_co_u32_e32 v5, vcc, 0, v3, vcc
	global_load_dword v88, v[4:5], off offset:-4096 nt
	global_load_dword v89, v[4:5], off nt
	v_add_co_u32_e32 v4, vcc, s3, v2
	s_mov_b32 s3, 0x3c000
	s_nop 0
	v_addc_co_u32_e32 v5, vcc, 0, v3, vcc
	global_load_dword v90, v[4:5], off offset:-4096 nt
	global_load_dword v91, v[4:5], off nt
	v_add_co_u32_e32 v4, vcc, s3, v2
	s_mov_b32 s3, 0x3e000
	s_nop 0
	v_addc_co_u32_e32 v5, vcc, 0, v3, vcc
	global_load_dword v92, v[4:5], off offset:-4096 nt
	global_load_dword v93, v[4:5], off nt
	v_add_co_u32_e32 v4, vcc, s3, v2
	s_mov_b32 s3, 0x3f000
	s_nop 0
	v_addc_co_u32_e32 v5, vcc, 0, v3, vcc
	global_load_dword v94, v[4:5], off offset:-4096 nt
	s_nop 0
	global_load_dword v4, v[4:5], off nt
	v_add_co_u32_e32 v2, vcc, s3, v2
	s_and_b32 s3, s15, 0x700
	s_nop 0
	v_addc_co_u32_e32 v3, vcc, 0, v3, vcc
	global_load_dword v2, v[2:3], off nt
	v_bitop3_b32 v3, s2, v237, v20 bitop3:0xc8
	v_or_b32_e32 v79, s3, v3
	s_mov_b32 s2, 0xc3e00000
	s_waitcnt vmcnt(27)
; __device__ __forceinline__ unsigned pk4_fp8(float a, float b, float c, float d) { int w = 0; w = __builtin_amdgcn_cvt_pk_fp8_f32(a, b, w, false); w = __builtin_amdgcn_cvt_pk_fp8_f32(c, d, w, true); return (unsigned)w; }
; __device__ __forceinline__ void transpose_item8(const float* W, int N, unsigned char* WT, int ldt, int item, int lane, int mode, int aux) {
;     ...
;     for (int q = 0; q < 16; ++q) o[q] = pk4_fp8(fminf(fmaxf(v[4 * q] * 64.f, -448.f), 448.f), fminf(fmaxf(v[4 * q + 1] * 64.f, -448.f), 448.f), fminf(fmaxf(v[4 * q + 2] * 64.f, -448.f), 448.f), fminf(fmaxf(v[4 * q + 3] * 64.f, -448.f), 448.f));
	v_mul_f32_e32 v7, 0x42800000, v7
	v_mul_f32_e32 v6, 0x42800000, v6
	v_mul_f32_e32 v13, 0x42800000, v13
	v_mul_f32_e32 v12, 0x42800000, v12
	s_waitcnt vmcnt(23)
	v_mul_f32_e32 v8, 0x42800000, v8
	v_mul_f32_e32 v11, 0x42800000, v11
	v_mul_f32_e32 v10, 0x42800000, v10
	v_mul_f32_e32 v55, 0x42800000, v55
	v_mul_f32_e32 v52, 0x42800000, v52
	v_mul_f32_e32 v53, 0x42800000, v53
	v_med3_f32 v52, v52, s2, v236
	v_med3_f32 v53, v53, s2, v236
	v_mul_f32_e32 v54, 0x42800000, v54
	v_med3_f32 v54, v54, s2, v236
	v_mul_f32_e32 v47, 0x42800000, v47
	v_mul_f32_e32 v48, 0x42800000, v48
	s_waitcnt vmcnt(19)
	v_mul_f32_e32 v9, 0x42800000, v9
	v_med3_f32 v47, v47, s2, v236
	v_med3_f32 v48, v48, s2, v236
	v_mul_f32_e32 v17, 0x42800000, v17
	v_mul_f32_e32 v18, 0x42800000, v18
	v_mul_f32_e32 v43, 0x42800000, v43
	v_mul_f32_e32 v44, 0x42800000, v44
	v_med3_f32 v17, v17, s2, v236
	v_med3_f32 v18, v18, s2, v236
	v_med3_f32 v43, v43, s2, v236
	v_med3_f32 v44, v44, s2, v236
	v_mul_f32_e32 v49, 0x42800000, v49
	v_mul_f32_e32 v50, 0x42800000, v50
	v_med3_f32 v49, v49, s2, v236
	v_med3_f32 v50, v50, s2, v236
	v_mul_f32_e32 v19, 0x42800000, v19
	v_mul_f32_e32 v42, 0x42800000, v42
	v_mul_f32_e32 v45, 0x42800000, v45
	v_mul_f32_e32 v46, 0x42800000, v46
	v_med3_f32 v19, v19, s2, v236
	v_med3_f32 v42, v42, s2, v236
	v_mul_f32_e32 v66, 0x42800000, v66
	v_mul_f32_e32 v67, 0x42800000, v67
	v_mul_f32_e32 v63, 0x42800000, v63
	v_mul_f32_e32 v64, 0x42800000, v64
	v_mul_f32_e32 v60, 0x42800000, v60
	v_mul_f32_e32 v61, 0x42800000, v61
	v_mul_f32_e32 v57, 0x42800000, v57
	v_mul_f32_e32 v58, 0x42800000, v58
	v_med3_f32 v45, v45, s2, v236
	v_med3_f32 v46, v46, s2, v236
	s_waitcnt vmcnt(17)
	v_mul_f32_e32 v78, 0x42800000, v78
	s_waitcnt vmcnt(16)
	v_mul_f32_e32 v80, 0x42800000, v80
	v_mul_f32_e32 v75, 0x42800000, v75
	v_mul_f32_e32 v76, 0x42800000, v76
	v_mul_f32_e32 v72, 0x42800000, v72
	v_mul_f32_e32 v73, 0x42800000, v73
	v_mul_f32_e32 v69, 0x42800000, v69
	v_mul_f32_e32 v70, 0x42800000, v70
	v_med3_f32 v66, v66, s2, v236
	v_med3_f32 v67, v67, s2, v236
	v_med3_f32 v63, v63, s2, v236
	v_med3_f32 v64, v64, s2, v236
	v_med3_f32 v60, v60, s2, v236
	v_med3_f32 v61, v61, s2, v236
	v_med3_f32 v57, v57, s2, v236
	v_med3_f32 v58, v58, s2, v236
	v_readlane_b32 s58, v252, 43
	v_readlane_b32 s59, v252, 44
	v_readlane_b32 s60, v252, 45
	v_readlane_b32 s61, v252, 46
	v_med3_f32 v78, v78, s2, v236
	v_med3_f32 v80, v80, s2, v236
	s_waitcnt vmcnt(2)
	v_mul_f32_e32 v5, 0x42800000, v94
	s_waitcnt vmcnt(1)
	v_mul_f32_e32 v3, 0x42800000, v4
	v_mul_f32_e32 v4, 0x42800000, v93
	v_med3_f32 v4, v4, s2, v236
	v_med3_f32 v93, v5, s2, v236
	v_mov_b32_e32 v5, v51
	v_cvt_pk_fp8_f32 v5, v4, v93
	v_mul_f32_e32 v4, 0x42800000, v89
	v_med3_f32 v89, v4, s2, v236
	v_mul_f32_e32 v4, 0x42800000, v90
	v_med3_f32 v90, v4, s2, v236
	v_mov_b32_e32 v4, v51
	s_waitcnt vmcnt(0)
; __device__ __forceinline__ unsigned pk4_fp8(float a, float b, float c, float d) { int w = 0; w = __builtin_amdgcn_cvt_pk_fp8_f32(a, b, w, false); w = __builtin_amdgcn_cvt_pk_fp8_f32(c, d, w, true); return (unsigned)w; }
; __device__ __forceinline__ void transpose_item8(const float* W, int N, unsigned char* WT, int ldt, int item, int lane, int mode, int aux) {
;     ...
;     for (int q = 0; q < 16; ++q) o[q] = pk4_fp8(fminf(fmaxf(v[4 * q] * 64.f, -448.f), 448.f), fminf(fmaxf(v[4 * q + 1] * 64.f, -448.f), 448.f), fminf(fmaxf(v[4 * q + 2] * 64.f, -448.f), 448.f), fminf(fmaxf(v[4 * q + 3] * 64.f, -448.f), 448.f));
;     v4u* dst = (v4u*)(WT + (size_t)rowmap(mode, aux, ncol) * ldt + k0);
; #pragma unroll
;     for (int q = 0; q < 4; ++q) dst[q] = (v4u){o[4 * q], o[4 * q + 1], o[4 * q + 2], o[4 * q + 3]};
	v_mul_f32_e32 v2, 0x42800000, v2
	v_cvt_pk_fp8_f32 v4, v89, v90
	v_med3_f32 v3, v3, s2, v236
	v_med3_f32 v2, v2, s2, v236
	v_cvt_pk_fp8_f32 v5, v3, v2 op_sel:[0,0,1]
	v_mul_f32_e32 v2, 0x42800000, v91
	v_mul_f32_e32 v3, 0x42800000, v92
	v_med3_f32 v2, v2, s2, v236
	v_med3_f32 v3, v3, s2, v236
	v_cvt_pk_fp8_f32 v4, v2, v3 op_sel:[0,0,1]
	v_mul_f32_e32 v3, 0x42800000, v88
	v_mul_f32_e32 v2, 0x42800000, v87
	v_med3_f32 v87, v3, s2, v236
	v_mul_f32_e32 v3, 0x42800000, v85
	v_med3_f32 v85, v3, s2, v236
	v_mul_f32_e32 v3, 0x42800000, v86
	v_med3_f32 v86, v3, s2, v236
	v_mov_b32_e32 v3, v51
	v_cvt_pk_fp8_f32 v3, v85, v86
	v_med3_f32 v2, v2, s2, v236
	v_med3_f32 v75, v75, s2, v236
	v_med3_f32 v76, v76, s2, v236
	v_cvt_pk_fp8_f32 v3, v2, v87 op_sel:[0,0,1]
	v_mul_f32_e32 v2, 0x42800000, v83
	v_med3_f32 v83, v2, s2, v236
	v_mul_f32_e32 v2, 0x42800000, v84
	v_med3_f32 v84, v2, s2, v236
	v_mul_f32_e32 v2, 0x42800000, v81
	v_med3_f32 v81, v2, s2, v236
	v_mul_f32_e32 v2, 0x42800000, v82
	v_med3_f32 v82, v2, s2, v236
	v_mov_b32_e32 v2, v51
	v_cvt_pk_fp8_f32 v2, v81, v82
	v_med3_f32 v81, v9, s2, v236
	v_mul_f32_e32 v9, 0x42800000, v77
	v_med3_f32 v77, v9, s2, v236
	v_mov_b32_e32 v9, v51
	v_cvt_pk_fp8_f32 v9, v81, v77
	v_med3_f32 v77, v8, s2, v236
	v_mul_f32_e32 v8, 0x42800000, v74
	v_med3_f32 v74, v8, s2, v236
	v_mov_b32_e32 v8, v51
	v_cvt_pk_fp8_f32 v8, v77, v74
	v_med3_f32 v74, v7, s2, v236
	v_mul_f32_e32 v7, 0x42800000, v71
	v_med3_f32 v71, v7, s2, v236
	v_mov_b32_e32 v7, v51
	v_cvt_pk_fp8_f32 v7, v74, v71
	v_med3_f32 v71, v6, s2, v236
	v_mul_f32_e32 v6, 0x42800000, v68
	v_med3_f32 v68, v6, s2, v236
	v_mov_b32_e32 v6, v51
	v_cvt_pk_fp8_f32 v6, v71, v68
	v_med3_f32 v68, v13, s2, v236
	v_mul_f32_e32 v13, 0x42800000, v65
	v_med3_f32 v65, v13, s2, v236
	v_mov_b32_e32 v13, v51
	v_cvt_pk_fp8_f32 v13, v68, v65
	v_med3_f32 v65, v12, s2, v236
	v_mul_f32_e32 v12, 0x42800000, v62
	v_med3_f32 v62, v12, s2, v236
	v_mov_b32_e32 v12, v51
	v_cvt_pk_fp8_f32 v12, v65, v62
	v_med3_f32 v62, v11, s2, v236
	v_mul_f32_e32 v11, 0x42800000, v59
	v_med3_f32 v59, v11, s2, v236
	v_mov_b32_e32 v11, v51
	v_cvt_pk_fp8_f32 v11, v62, v59
	v_med3_f32 v59, v10, s2, v236
	v_mul_f32_e32 v10, 0x42800000, v56
	v_med3_f32 v56, v10, s2, v236
	v_mov_b32_e32 v10, v51
	v_cvt_pk_fp8_f32 v10, v59, v56
	v_med3_f32 v56, v55, s2, v236
	v_mov_b32_e32 v55, v51
	v_cvt_pk_fp8_f32 v55, v52, v53
	v_mov_b32_e32 v52, v51
	v_mov_b32_e32 v53, v51
	v_cvt_pk_fp8_f32 v52, v17, v18
	v_cvt_pk_fp8_f32 v55, v54, v56 op_sel:[0,0,1]
	v_mov_b32_e32 v54, v51
	v_cvt_pk_fp8_f32 v54, v47, v48
	v_cvt_pk_fp8_f32 v53, v43, v44
	v_cvt_pk_fp8_f32 v52, v19, v42 op_sel:[0,0,1]
	v_med3_f32 v72, v72, s2, v236
	v_cvt_pk_fp8_f32 v54, v49, v50 op_sel:[0,0,1]
	v_lshlrev_b32_e32 v50, 10, v79
	v_lshl_add_u64 v[18:19], s[0:1], 0, v[50:51]
	s_mov_b32 s1, s23
	v_cvt_pk_fp8_f32 v53, v45, v46 op_sel:[0,0,1]
	v_writelane_b32 v254, s0, 32
	v_med3_f32 v73, v73, s2, v236
	v_med3_f32 v69, v69, s2, v236
	v_med3_f32 v70, v70, s2, v236
	v_cvt_pk_fp8_f32 v13, v66, v67 op_sel:[0,0,1]
	v_cvt_pk_fp8_f32 v12, v63, v64 op_sel:[0,0,1]
	v_cvt_pk_fp8_f32 v11, v60, v61 op_sel:[0,0,1]
	v_cvt_pk_fp8_f32 v10, v57, v58 op_sel:[0,0,1]
	v_writelane_b32 v254, s1, 33
	v_lshl_add_u64 v[18:19], v[18:19], 0, s[22:23]
	s_mov_b64 s[0:1], 0x20000
	v_readlane_b32 s64, v252, 49
	v_readlane_b32 s68, v252, 53
	v_readlane_b32 s69, v252, 54
	v_readlane_b32 s71, v252, 56
	s_mov_b32 s58, 0x3f6c835e
	v_readlane_b32 s60, v255, 2
	v_cvt_pk_fp8_f32 v9, v78, v80 op_sel:[0,0,1]
	v_cvt_pk_fp8_f32 v8, v75, v76 op_sel:[0,0,1]
	v_cvt_pk_fp8_f32 v7, v72, v73 op_sel:[0,0,1]
	v_cvt_pk_fp8_f32 v6, v69, v70 op_sel:[0,0,1]
	v_lshl_add_u64 v[42:43], v[18:19], 0, s[0:1]
	v_add_co_u32_e32 v18, vcc, 0x20000, v18
	s_movk_i32 s64, 0x440
	s_movk_i32 s68, 0x2200
	s_movk_i32 s71, 0x1ff
	s_mov_b32 s69, 0x7f800000
	s_mov_b32 s59, 0xbec3ef15
	v_readlane_b32 s61, v255, 3
	v_readlane_b32 s62, v255, 4
	s_mov_b32 s63, 0xbf6c835e
	v_cvt_pk_fp8_f32 v2, v83, v84 op_sel:[0,0,1]
	v_addc_co_u32_e32 v19, vcc, 0, v19, vcc
	v_readlane_b32 s57, v252, 42
	v_readlane_b32 s65, v252, 50
	v_readlane_b32 s66, v252, 51
	v_readlane_b32 s67, v252, 52
	global_store_dwordx4 v[18:19], v[52:55], off
	global_store_dwordx4 v[42:43], v[10:13], off offset:16
	global_store_dwordx4 v[42:43], v[6:9], off offset:32
	global_store_dwordx4 v[42:43], v[2:5], off offset:48

; __device__ __forceinline__ unsigned pk4_fp8(float a, float b, float c, float d) { int w = 0; w = __builtin_amdgcn_cvt_pk_fp8_f32(a, b, w, false); w = __builtin_amdgcn_cvt_pk_fp8_f32(c, d, w, true); return (unsigned)w; }
; __device__ __forceinline__ void transpose_item8(const float* W, int N, unsigned char* WT, int ldt, int item, int lane, int mode, int aux) {
;     const int nblk = (N + 63) >> 6, kb = item / nblk, nb = item - kb * nblk, k0 = 64 * kb, n0 = 64 * nb;
;     const int ncol = n0 + lane;
;     const float* wp = W + (size_t)k0 * N + ncol;
;     float v[64];
; #pragma unroll
;     for (int i = 0; i < 64; ++i) v[i] = wp[(size_t)i * N];
;     unsigned o[16];
; #pragma unroll
;     for (int q = 0; q < 16; ++q) o[q] = pk4_fp8(fminf(fmaxf(v[4 * q] * 64.f, -448.f), 448.f), fminf(fmaxf(v[4 * q + 1] * 64.f, -448.f), 448.f), fminf(fmaxf(v[4 * q + 2] * 64.f, -448.f), 448.f), fminf(fmaxf(v[4 * q + 3] * 64.f, -448.f), 448.f));
;     v4u* dst = (v4u*)(WT + (size_t)rowmap(mode, aux, ncol) * ldt + k0);
; #pragma unroll
;     for (int q = 0; q < 4; ++q) dst[q] = (v4u){o[4 * q], o[4 * q + 1], o[4 * q + 2], o[4 * q + 3]};
; }
; __device__ __forceinline__ void convert_rest(const Args& a, LAS unsigned char* lds, int wave, int lane, int gw, int ngw, int l, int it0, int it1) {
;     ...
;         if (r < WI_FF) { const int e = r >> 8; transpose_item8(a.in[I_WFFG] + (size_t)(l * 16 + e) * 1024 * 1024, 1024, ws + WS_WGU + (size_t)e * 2048 * 1024, 1024, r & 255, lane, 3, 0); continue; } r -= WI_FF;
.LBB0_1952:
	s_andn2_b64 vcc, exec, s[0:1]
	s_cbranch_vccnz .LBB0_1954
	s_add_i32 s0, s6, 0xfffffa00
	s_lshr_b32 s0, s0, 8
	v_readlane_b32 s22, v254, 32
	v_readlane_b32 s23, v254, 33
	s_add_i32 s22, s0, s7
	v_readlane_b32 s56, v252, 41
	s_lshl_b64 s[2:3], s[22:23], 22
	v_readlane_b32 s60, v252, 45
	v_readlane_b32 s61, v252, 46
	s_add_u32 s17, s60, s2
	s_mov_b32 s1, s23
	s_addc_u32 s3, s61, s3
	s_lshl_b64 s[0:1], s[0:1], 21
	v_readlane_b32 s2, v253, 61
	s_add_u32 s0, s2, s0
	v_readlane_b32 s2, v253, 62
	s_addc_u32 s1, s2, s1
	s_and_b32 s22, s11, 0x3c0
	s_add_i32 s2, s13, 0xa2000
	s_and_b32 s2, s2, 0x3c0
	s_lshl_b32 s21, s22, 12
	v_or_b32_e32 v2, s2, v20
	s_add_u32 s26, s17, s21
	s_addc_u32 s27, s3, 0
	v_lshlrev_b32_e32 v50, 2, v2
	v_lshl_add_u64 v[2:3], s[26:27], 0, v[50:51]
	s_movk_i32 s3, 0x2000
	v_readlane_b32 s70, v252, 55
	v_add_co_u32_e32 v4, vcc, s3, v2
	s_movk_i32 s70, 0x4000
	s_nop 0
	v_addc_co_u32_e32 v5, vcc, 0, v3, vcc
	global_load_dword v17, v50, s[26:27] nt
	global_load_dword v18, v[4:5], off offset:-4096 nt
	global_load_dword v19, v[4:5], off nt
	v_add_co_u32_e32 v4, vcc, s70, v2
	s_movk_i32 s3, 0x6000
	s_nop 0
	v_addc_co_u32_e32 v5, vcc, 0, v3, vcc
	global_load_dword v42, v[4:5], off offset:-4096 nt
	global_load_dword v43, v[4:5], off nt
	v_add_co_u32_e32 v4, vcc, s3, v2
	s_mov_b32 s3, 0x8000
	s_nop 0
	v_addc_co_u32_e32 v5, vcc, 0, v3, vcc
	global_load_dword v44, v[4:5], off offset:-4096 nt
	global_load_dword v45, v[4:5], off nt
	v_add_co_u32_e32 v4, vcc, s3, v2
	s_mov_b32 s3, 0xa000
	s_nop 0
	v_addc_co_u32_e32 v5, vcc, 0, v3, vcc
	global_load_dword v46, v[4:5], off offset:-4096 nt
	global_load_dword v47, v[4:5], off nt
	v_add_co_u32_e32 v4, vcc, s3, v2
	s_mov_b32 s3, 0xc000
	s_nop 0
	v_addc_co_u32_e32 v5, vcc, 0, v3, vcc
	global_load_dword v48, v[4:5], off offset:-4096 nt
	global_load_dword v49, v[4:5], off nt
	v_add_co_u32_e32 v4, vcc, s3, v2
	s_mov_b32 s3, 0xe000
	s_nop 0
	v_addc_co_u32_e32 v5, vcc, 0, v3, vcc
	global_load_dword v50, v[4:5], off offset:-4096 nt
	global_load_dword v52, v[4:5], off nt
	v_add_co_u32_e32 v4, vcc, s3, v2
	s_mov_b32 s3, 0x10000
	s_nop 0
	v_addc_co_u32_e32 v5, vcc, 0, v3, vcc
	global_load_dword v53, v[4:5], off offset:-4096 nt
	global_load_dword v54, v[4:5], off nt
	v_add_co_u32_e32 v4, vcc, s3, v2
	s_mov_b32 s3, 0x12000
	s_nop 0
	v_addc_co_u32_e32 v5, vcc, 0, v3, vcc
	global_load_dword v55, v[4:5], off offset:-4096 nt
	global_load_dword v10, v[4:5], off nt
	v_add_co_u32_e32 v4, vcc, s3, v2
	s_mov_b32 s3, 0x14000
	s_nop 0
	v_addc_co_u32_e32 v5, vcc, 0, v3, vcc
	global_load_dword v56, v[4:5], off offset:-4096 nt
	global_load_dword v57, v[4:5], off nt
	v_add_co_u32_e32 v4, vcc, s3, v2
	s_mov_b32 s3, 0x16000
	s_nop 0
	v_addc_co_u32_e32 v5, vcc, 0, v3, vcc
	global_load_dword v58, v[4:5], off offset:-4096 nt
	global_load_dword v11, v[4:5], off nt
	v_add_co_u32_e32 v4, vcc, s3, v2
	s_mov_b32 s3, 0x18000
	s_nop 0
	v_addc_co_u32_e32 v5, vcc, 0, v3, vcc
	global_load_dword v59, v[4:5], off offset:-4096 nt
	global_load_dword v60, v[4:5], off nt
	v_add_co_u32_e32 v4, vcc, s3, v2
	s_mov_b32 s3, 0x1a000
	s_nop 0
	v_addc_co_u32_e32 v5, vcc, 0, v3, vcc
	global_load_dword v61, v[4:5], off offset:-4096 nt
	global_load_dword v12, v[4:5], off nt
	v_add_co_u32_e32 v4, vcc, s3, v2
	s_mov_b32 s3, 0x1c000
	s_nop 0
	v_addc_co_u32_e32 v5, vcc, 0, v3, vcc
	global_load_dword v62, v[4:5], off offset:-4096 nt
	global_load_dword v63, v[4:5], off nt
	v_add_co_u32_e32 v4, vcc, s3, v2
	s_mov_b32 s3, 0x1e000
	s_nop 0
	v_addc_co_u32_e32 v5, vcc, 0, v3, vcc
	global_load_dword v64, v[4:5], off offset:-4096 nt
	global_load_dword v13, v[4:5], off nt
	v_add_co_u32_e32 v4, vcc, s3, v2
	s_mov_b32 s3, 0x20000
	s_nop 0
	v_addc_co_u32_e32 v5, vcc, 0, v3, vcc
	global_load_dword v65, v[4:5], off offset:-4096 nt
	global_load_dword v66, v[4:5], off nt
	v_add_co_u32_e32 v4, vcc, s3, v2
	s_mov_b32 s3, 0x22000
	s_nop 0
	v_addc_co_u32_e32 v5, vcc, 0, v3, vcc
	global_load_dword v67, v[4:5], off offset:-4096 nt
	global_load_dword v6, v[4:5], off nt
	v_add_co_u32_e32 v4, vcc, s3, v2
	s_mov_b32 s3, 0x24000
	s_nop 0
	v_addc_co_u32_e32 v5, vcc, 0, v3, vcc
	global_load_dword v68, v[4:5], off offset:-4096 nt
	global_load_dword v69, v[4:5], off nt
	v_add_co_u32_e32 v4, vcc, s3, v2
	s_mov_b32 s3, 0x26000
	s_nop 0
	v_addc_co_u32_e32 v5, vcc, 0, v3, vcc
	global_load_dword v70, v[4:5], off offset:-4096 nt
	global_load_dword v7, v[4:5], off nt
	v_add_co_u32_e32 v4, vcc, s3, v2
	s_mov_b32 s3, 0x28000
	s_nop 0
	v_addc_co_u32_e32 v5, vcc, 0, v3, vcc
	global_load_dword v71, v[4:5], off offset:-4096 nt
	global_load_dword v72, v[4:5], off nt
	v_add_co_u32_e32 v4, vcc, s3, v2
	s_mov_b32 s3, 0x2a000
	s_nop 0
	v_addc_co_u32_e32 v5, vcc, 0, v3, vcc
	global_load_dword v73, v[4:5], off offset:-4096 nt
	global_load_dword v8, v[4:5], off nt
	v_add_co_u32_e32 v4, vcc, s3, v2
	s_mov_b32 s3, 0x2c000
	s_nop 0
	v_addc_co_u32_e32 v5, vcc, 0, v3, vcc
	global_load_dword v74, v[4:5], off offset:-4096 nt
	global_load_dword v75, v[4:5], off nt
	v_add_co_u32_e32 v4, vcc, s3, v2
	s_mov_b32 s3, 0x2e000
	s_nop 0
	v_addc_co_u32_e32 v5, vcc, 0, v3, vcc
	global_load_dword v76, v[4:5], off offset:-4096 nt
	global_load_dword v9, v[4:5], off nt
	v_add_co_u32_e32 v4, vcc, s3, v2
	s_mov_b32 s3, 0x30000
	s_nop 0
	v_addc_co_u32_e32 v5, vcc, 0, v3, vcc
	global_load_dword v77, v[4:5], off offset:-4096 nt
	global_load_dword v78, v[4:5], off nt
	v_add_co_u32_e32 v4, vcc, s3, v2
	s_mov_b32 s3, 0x32000
	s_nop 0
	v_addc_co_u32_e32 v5, vcc, 0, v3, vcc
	global_load_dword v80, v[4:5], off offset:-4096 nt
	global_load_dword v81, v[4:5], off nt
	v_add_co_u32_e32 v4, vcc, s3, v2
	s_mov_b32 s3, 0x34000
	s_nop 0
; __device__ __forceinline__ unsigned pk4_fp8(float a, float b, float c, float d) { int w = 0; w = __builtin_amdgcn_cvt_pk_fp8_f32(a, b, w, false); w = __builtin_amdgcn_cvt_pk_fp8_f32(c, d, w, true); return (unsigned)w; }
; __device__ __forceinline__ void transpose_item8(const float* W, int N, unsigned char* WT, int ldt, int item, int lane, int mode, int aux) {
;     ...
;     for (int i = 0; i < 64; ++i) v[i] = wp[(size_t)i * N];
;     unsigned o[16];
; #pragma unroll
;     for (int q = 0; q < 16; ++q) o[q] = pk4_fp8(fminf(fmaxf(v[4 * q] * 64.f, -448.f), 448.f), fminf(fmaxf(v[4 * q + 1] * 64.f, -448.f), 448.f), fminf(fmaxf(v[4 * q + 2] * 64.f, -448.f), 448.f), fminf(fmaxf(v[4 * q + 3] * 64.f, -448.f), 448.f));
	v_addc_co_u32_e32 v5, vcc, 0, v3, vcc
	global_load_dword v82, v[4:5], off offset:-4096 nt
	global_load_dword v83, v[4:5], off nt
	v_add_co_u32_e32 v4, vcc, s3, v2
	s_mov_b32 s3, 0x36000
	s_nop 0
	v_addc_co_u32_e32 v5, vcc, 0, v3, vcc
	global_load_dword v84, v[4:5], off offset:-4096 nt
	global_load_dword v85, v[4:5], off nt
	v_add_co_u32_e32 v4, vcc, s3, v2
	s_mov_b32 s3, 0x38000
	s_nop 0
	v_addc_co_u32_e32 v5, vcc, 0, v3, vcc
	global_load_dword v86, v[4:5], off offset:-4096 nt
	global_load_dword v87, v[4:5], off nt
	v_add_co_u32_e32 v4, vcc, s3, v2
	s_mov_b32 s3, 0x3a000
	s_nop 0
	v_addc_co_u32_e32 v5, vcc, 0, v3, vcc
	global_load_dword v88, v[4:5], off offset:-4096 nt
	global_load_dword v89, v[4:5], off nt
	v_add_co_u32_e32 v4, vcc, s3, v2
	s_mov_b32 s3, 0x3c000
	s_nop 0
	v_addc_co_u32_e32 v5, vcc, 0, v3, vcc
	global_load_dword v90, v[4:5], off offset:-4096 nt
	global_load_dword v91, v[4:5], off nt
	v_add_co_u32_e32 v4, vcc, s3, v2
	s_mov_b32 s3, 0x3e000
	s_nop 0
	v_addc_co_u32_e32 v5, vcc, 0, v3, vcc
	global_load_dword v92, v[4:5], off offset:-4096 nt
	global_load_dword v93, v[4:5], off nt
	v_add_co_u32_e32 v4, vcc, s3, v2
	s_mov_b32 s3, 0x3f000
	s_nop 0
	v_addc_co_u32_e32 v5, vcc, 0, v3, vcc
	global_load_dword v94, v[4:5], off offset:-4096 nt
	s_nop 0
	global_load_dword v4, v[4:5], off nt
	v_add_co_u32_e32 v2, vcc, s3, v2
	s_and_b32 s3, s15, 0x700
	s_nop 0
	v_addc_co_u32_e32 v3, vcc, 0, v3, vcc
	global_load_dword v2, v[2:3], off nt
	v_bitop3_b32 v3, s2, v237, v20 bitop3:0xc8
	v_or_b32_e32 v79, s3, v3
	s_mov_b32 s2, 0xc3e00000
	s_waitcnt vmcnt(27)
	v_mul_f32_e32 v7, 0x42800000, v7
	v_mul_f32_e32 v6, 0x42800000, v6
	v_mul_f32_e32 v13, 0x42800000, v13
	v_mul_f32_e32 v12, 0x42800000, v12
	s_waitcnt vmcnt(23)
	v_mul_f32_e32 v8, 0x42800000, v8
	v_mul_f32_e32 v11, 0x42800000, v11
	v_mul_f32_e32 v10, 0x42800000, v10
	v_mul_f32_e32 v55, 0x42800000, v55
	v_mul_f32_e32 v52, 0x42800000, v52
	v_mul_f32_e32 v53, 0x42800000, v53
	v_med3_f32 v52, v52, s2, v236
	v_med3_f32 v53, v53, s2, v236
	v_mul_f32_e32 v54, 0x42800000, v54
	v_med3_f32 v54, v54, s2, v236
	v_mul_f32_e32 v47, 0x42800000, v47
	v_mul_f32_e32 v48, 0x42800000, v48
	s_waitcnt vmcnt(19)
	v_mul_f32_e32 v9, 0x42800000, v9
	v_mul_f32_e32 v43, 0x42800000, v43
	v_mul_f32_e32 v44, 0x42800000, v44
	v_mul_f32_e32 v17, 0x42800000, v17
	v_mul_f32_e32 v18, 0x42800000, v18
	v_med3_f32 v47, v47, s2, v236
	v_med3_f32 v48, v48, s2, v236
	v_med3_f32 v43, v43, s2, v236
	v_med3_f32 v44, v44, s2, v236
	v_med3_f32 v17, v17, s2, v236
	v_med3_f32 v18, v18, s2, v236
	v_mul_f32_e32 v49, 0x42800000, v49
	v_mul_f32_e32 v50, 0x42800000, v50
	v_mul_f32_e32 v45, 0x42800000, v45
	v_mul_f32_e32 v46, 0x42800000, v46
	v_mul_f32_e32 v19, 0x42800000, v19
	v_mul_f32_e32 v42, 0x42800000, v42
	v_mul_f32_e32 v66, 0x42800000, v66
	v_mul_f32_e32 v67, 0x42800000, v67
	v_mul_f32_e32 v63, 0x42800000, v63
	v_mul_f32_e32 v64, 0x42800000, v64
	v_mul_f32_e32 v60, 0x42800000, v60
	v_mul_f32_e32 v61, 0x42800000, v61
	v_mul_f32_e32 v57, 0x42800000, v57
	v_mul_f32_e32 v58, 0x42800000, v58
	v_med3_f32 v49, v49, s2, v236
	v_med3_f32 v50, v50, s2, v236
	v_med3_f32 v45, v45, s2, v236
	v_med3_f32 v46, v46, s2, v236
	v_med3_f32 v19, v19, s2, v236
	v_med3_f32 v42, v42, s2, v236
	s_waitcnt vmcnt(17)
	v_mul_f32_e32 v78, 0x42800000, v78
	s_waitcnt vmcnt(16)
	v_mul_f32_e32 v80, 0x42800000, v80
	v_mul_f32_e32 v75, 0x42800000, v75
	v_mul_f32_e32 v76, 0x42800000, v76
	v_mul_f32_e32 v72, 0x42800000, v72
	v_mul_f32_e32 v73, 0x42800000, v73
	v_mul_f32_e32 v69, 0x42800000, v69
	v_mul_f32_e32 v70, 0x42800000, v70
	v_med3_f32 v66, v66, s2, v236
	v_med3_f32 v67, v67, s2, v236
	v_med3_f32 v63, v63, s2, v236
	v_med3_f32 v64, v64, s2, v236
	v_med3_f32 v60, v60, s2, v236
	v_med3_f32 v61, v61, s2, v236
	v_med3_f32 v57, v57, s2, v236
	v_med3_f32 v58, v58, s2, v236
	v_readlane_b32 s58, v252, 43
	v_readlane_b32 s59, v252, 44
	v_med3_f32 v78, v78, s2, v236
	v_med3_f32 v80, v80, s2, v236
	v_med3_f32 v75, v75, s2, v236
	v_med3_f32 v76, v76, s2, v236
	s_waitcnt vmcnt(2)
	v_mul_f32_e32 v5, 0x42800000, v94
	s_waitcnt vmcnt(1)
	v_mul_f32_e32 v3, 0x42800000, v4
	v_mul_f32_e32 v4, 0x42800000, v93
	v_med3_f32 v4, v4, s2, v236
	v_med3_f32 v93, v5, s2, v236
	v_mov_b32_e32 v5, v51
	v_cvt_pk_fp8_f32 v5, v4, v93
	v_mul_f32_e32 v4, 0x42800000, v89
	v_med3_f32 v89, v4, s2, v236
	v_mul_f32_e32 v4, 0x42800000, v90
	v_med3_f32 v90, v4, s2, v236
	v_mov_b32_e32 v4, v51
	s_waitcnt vmcnt(0)
; __device__ __forceinline__ unsigned pk4_fp8(float a, float b, float c, float d) { int w = 0; w = __builtin_amdgcn_cvt_pk_fp8_f32(a, b, w, false); w = __builtin_amdgcn_cvt_pk_fp8_f32(c, d, w, true); return (unsigned)w; }
; __device__ __forceinline__ void transpose_item8(const float* W, int N, unsigned char* WT, int ldt, int item, int lane, int mode, int aux) {
;     ...
; #pragma unroll
;     for (int q = 0; q < 16; ++q) o[q] = pk4_fp8(fminf(fmaxf(v[4 * q] * 64.f, -448.f), 448.f), fminf(fmaxf(v[4 * q + 1] * 64.f, -448.f), 448.f), fminf(fmaxf(v[4 * q + 2] * 64.f, -448.f), 448.f), fminf(fmaxf(v[4 * q + 3] * 64.f, -448.f), 448.f));
;     v4u* dst = (v4u*)(WT + (size_t)rowmap(mode, aux, ncol) * ldt + k0);
; #pragma unroll
;     for (int q = 0; q < 4; ++q) dst[q] = (v4u){o[4 * q], o[4 * q + 1], o[4 * q + 2], o[4 * q + 3]};
	v_mul_f32_e32 v2, 0x42800000, v2
	v_cvt_pk_fp8_f32 v4, v89, v90
	v_med3_f32 v3, v3, s2, v236
	v_med3_f32 v2, v2, s2, v236
	v_cvt_pk_fp8_f32 v5, v3, v2 op_sel:[0,0,1]
	v_mul_f32_e32 v2, 0x42800000, v91
	v_mul_f32_e32 v3, 0x42800000, v92
	v_med3_f32 v2, v2, s2, v236
	v_med3_f32 v3, v3, s2, v236
	v_cvt_pk_fp8_f32 v4, v2, v3 op_sel:[0,0,1]
	v_mul_f32_e32 v3, 0x42800000, v88
	v_mul_f32_e32 v2, 0x42800000, v87
	v_med3_f32 v87, v3, s2, v236
	v_mul_f32_e32 v3, 0x42800000, v85
	v_med3_f32 v85, v3, s2, v236
	v_mul_f32_e32 v3, 0x42800000, v86
	v_med3_f32 v86, v3, s2, v236
	v_mov_b32_e32 v3, v51
	v_cvt_pk_fp8_f32 v3, v85, v86
	v_med3_f32 v2, v2, s2, v236
	v_med3_f32 v72, v72, s2, v236
	v_med3_f32 v73, v73, s2, v236
	v_cvt_pk_fp8_f32 v3, v2, v87 op_sel:[0,0,1]
	v_mul_f32_e32 v2, 0x42800000, v83
	v_med3_f32 v83, v2, s2, v236
	v_mul_f32_e32 v2, 0x42800000, v84
	v_med3_f32 v84, v2, s2, v236
	v_mul_f32_e32 v2, 0x42800000, v81
	v_med3_f32 v81, v2, s2, v236
	v_mul_f32_e32 v2, 0x42800000, v82
	v_med3_f32 v82, v2, s2, v236
	v_mov_b32_e32 v2, v51
	v_cvt_pk_fp8_f32 v2, v81, v82
	v_med3_f32 v81, v9, s2, v236
	v_mul_f32_e32 v9, 0x42800000, v77
	v_med3_f32 v77, v9, s2, v236
	v_mov_b32_e32 v9, v51
	v_cvt_pk_fp8_f32 v9, v81, v77
	v_med3_f32 v77, v8, s2, v236
	v_mul_f32_e32 v8, 0x42800000, v74
	v_med3_f32 v74, v8, s2, v236
	v_mov_b32_e32 v8, v51
	v_cvt_pk_fp8_f32 v8, v77, v74
	v_med3_f32 v74, v7, s2, v236
	v_mul_f32_e32 v7, 0x42800000, v71
	v_med3_f32 v71, v7, s2, v236
	v_mov_b32_e32 v7, v51
	v_cvt_pk_fp8_f32 v7, v74, v71
	v_med3_f32 v71, v6, s2, v236
	v_mul_f32_e32 v6, 0x42800000, v68
	v_med3_f32 v68, v6, s2, v236
	v_mov_b32_e32 v6, v51
	v_cvt_pk_fp8_f32 v6, v71, v68
	v_med3_f32 v68, v13, s2, v236
	v_mul_f32_e32 v13, 0x42800000, v65
	v_med3_f32 v65, v13, s2, v236
	v_mov_b32_e32 v13, v51
	v_cvt_pk_fp8_f32 v13, v68, v65
	v_med3_f32 v65, v12, s2, v236
	v_mul_f32_e32 v12, 0x42800000, v62
	v_med3_f32 v62, v12, s2, v236
	v_mov_b32_e32 v12, v51
	v_cvt_pk_fp8_f32 v12, v65, v62
	v_med3_f32 v62, v11, s2, v236
	v_mul_f32_e32 v11, 0x42800000, v59
	v_med3_f32 v59, v11, s2, v236
	v_mov_b32_e32 v11, v51
	v_cvt_pk_fp8_f32 v11, v62, v59
	v_med3_f32 v59, v10, s2, v236
	v_mul_f32_e32 v10, 0x42800000, v56
	v_med3_f32 v56, v10, s2, v236
	v_mov_b32_e32 v10, v51
	v_cvt_pk_fp8_f32 v10, v59, v56
	v_med3_f32 v56, v55, s2, v236
	v_mov_b32_e32 v55, v51
	v_cvt_pk_fp8_f32 v55, v52, v53
	v_mov_b32_e32 v53, v51
	v_mov_b32_e32 v52, v51
	v_cvt_pk_fp8_f32 v53, v43, v44
	v_cvt_pk_fp8_f32 v55, v54, v56 op_sel:[0,0,1]
	v_mov_b32_e32 v54, v51
	v_cvt_pk_fp8_f32 v54, v47, v48
	v_cvt_pk_fp8_f32 v52, v17, v18
	v_cvt_pk_fp8_f32 v53, v45, v46 op_sel:[0,0,1]
	v_med3_f32 v69, v69, s2, v236
	v_cvt_pk_fp8_f32 v54, v49, v50 op_sel:[0,0,1]
	v_cvt_pk_fp8_f32 v52, v19, v42 op_sel:[0,0,1]
	v_lshlrev_b32_e32 v50, 10, v79
	v_med3_f32 v70, v70, s2, v236
	v_cvt_pk_fp8_f32 v13, v66, v67 op_sel:[0,0,1]
	v_cvt_pk_fp8_f32 v12, v63, v64 op_sel:[0,0,1]
	v_cvt_pk_fp8_f32 v11, v60, v61 op_sel:[0,0,1]
	v_cvt_pk_fp8_f32 v10, v57, v58 op_sel:[0,0,1]
	v_lshl_add_u64 v[18:19], s[0:1], 0, v[50:51]
	s_mov_b32 s1, s23
	v_readlane_b32 s62, v252, 47
	v_readlane_b32 s63, v252, 48
	v_readlane_b32 s64, v252, 49
	v_readlane_b32 s68, v252, 53
	v_readlane_b32 s69, v252, 54
	v_readlane_b32 s71, v252, 56
	s_mov_b32 s58, 0x3f6c835e
	v_readlane_b32 s60, v255, 2
	v_cvt_pk_fp8_f32 v9, v78, v80 op_sel:[0,0,1]
	v_cvt_pk_fp8_f32 v8, v75, v76 op_sel:[0,0,1]
	v_cvt_pk_fp8_f32 v7, v72, v73 op_sel:[0,0,1]
	v_cvt_pk_fp8_f32 v6, v69, v70 op_sel:[0,0,1]
	v_writelane_b32 v254, s0, 32
	s_movk_i32 s64, 0x440
	s_mov_b32 s63, 0xbf6c835e
	v_readlane_b32 s62, v255, 4
	s_movk_i32 s68, 0x2200
	s_movk_i32 s71, 0x1ff
	s_mov_b32 s69, 0x7f800000
	s_mov_b32 s59, 0xbec3ef15
	v_readlane_b32 s61, v255, 3
	v_cvt_pk_fp8_f32 v2, v83, v84 op_sel:[0,0,1]
	v_writelane_b32 v254, s1, 33
	v_lshl_add_u64 v[18:19], v[18:19], 0, s[22:23]
	v_readlane_b32 s57, v252, 42
	v_readlane_b32 s65, v252, 50
	v_readlane_b32 s66, v252, 51
	v_readlane_b32 s67, v252, 52
	global_store_dwordx4 v[18:19], v[52:55], off
	global_store_dwordx4 v[18:19], v[10:13], off offset:16
	global_store_dwordx4 v[18:19], v[6:9], off offset:32
	global_store_dwordx4 v[18:19], v[2:5], off offset:48

; #define LAS __attribute__((address_space(3)))
; __device__ __forceinline__ unsigned pk2(float lo, float hi) { return f2bf(lo) | (f2bf(hi) << 16); }
; __device__ __forceinline__ void transpose_item(const float* W, int N, bf16* WT, int ldt, LAS unsigned* scr, int item, int lane, int mode, int aux) {
;     const int nblk = (N + 63) >> 6, kb = item / nblk, nb = item - kb * nblk, k0 = 64 * kb, n0 = 64 * nb;
;     const int ncol = n0 + lane; const bool okc = ncol < N;
;     const float* wp = W + (size_t)k0 * N + (okc ? ncol : 0);
;     float v[64];
; #pragma unroll
;     for (int i = 0; i < 64; ++i) v[i] = wp[(size_t)i * N];
; #pragma unroll
;     for (int i = 0; i < 32; ++i) scr[i * 65 + lane] = okc ? pk2(v[2 * i], v[2 * i + 1]) : 0u;
; __device__ __forceinline__ void convert_rest(const Args& a, LAS unsigned char* lds, int wave, int lane, int gw, int ngw, int l, int it0, int it1) {
;     ...
;         if (r < WI_OUT) { transpose_item(a.in[I_WOUT] + (size_t)l * 1024 * 1024, 1024, (bf16*)(ws + WS_WOUT), 1024, scr, r, lane, 0, 0); continue; } r -= WI_OUT;
.LBB0_1955:
	s_andn2_b64 vcc, exec, s[0:1]
	s_cbranch_vccnz .LBB0_2003
	s_bfe_u32 s17, s6, 0x40004
	s_lshl_b32 s21, s17, 10
	s_sub_i32 s0, s13, s21
	v_add_u32_e32 v90, s0, v41
	s_lshl_b32 s0, s17, 18
	s_add_u32 s2, s9, s0
	s_movk_i32 s0, 0x400
	v_cmp_gt_i32_e64 s[0:1], s0, v90
	s_addc_u32 s3, s10, 0
	s_nop 0
	v_cndmask_b32_e64 v2, 0, v90, s[0:1]
	v_ashrrev_i32_e32 v3, 31, v2
	v_lshl_add_u64 v[2:3], v[2:3], 2, s[2:3]
	s_mov_b32 s2, 0xd000
	v_add_co_u32_e32 v4, vcc, s2, v2
	s_mov_b32 s2, 0xf000
	s_nop 0
	v_addc_co_u32_e32 v5, vcc, 0, v3, vcc
	v_add_co_u32_e32 v6, vcc, s2, v2
	s_mov_b32 s2, 0x11000
	s_nop 0
	v_addc_co_u32_e32 v7, vcc, 0, v3, vcc
	v_add_co_u32_e32 v8, vcc, s2, v2
	s_mov_b32 s2, 0x13000
	s_nop 0
	v_addc_co_u32_e32 v9, vcc, 0, v3, vcc
	v_add_co_u32_e32 v10, vcc, s2, v2
	s_mov_b32 s2, 0x15000
	s_nop 0
	v_addc_co_u32_e32 v11, vcc, 0, v3, vcc
	v_add_co_u32_e32 v12, vcc, s2, v2
	s_mov_b32 s2, 0x17000
	s_nop 0
	v_addc_co_u32_e32 v13, vcc, 0, v3, vcc
	v_add_co_u32_e32 v18, vcc, s2, v2
	s_mov_b32 s2, 0x19000
	s_nop 0
	v_addc_co_u32_e32 v19, vcc, 0, v3, vcc
	global_load_dword v77, v[8:9], off offset:-4096 nt
	global_load_dword v76, v[8:9], off nt
	global_load_dword v75, v[10:11], off offset:-4096 nt
	global_load_dword v74, v[10:11], off nt
	global_load_dword v69, v[12:13], off offset:-4096 nt
	global_load_dword v67, v[12:13], off nt
	global_load_dword v68, v[18:19], off offset:-4096 nt
	global_load_dword v66, v[18:19], off nt
	v_add_co_u32_e32 v8, vcc, s2, v2
	s_mov_b32 s2, 0x1b000
	s_nop 0
	v_addc_co_u32_e32 v9, vcc, 0, v3, vcc
	v_add_co_u32_e32 v10, vcc, s2, v2
	s_mov_b32 s2, 0x1d000
	s_nop 0
	v_addc_co_u32_e32 v11, vcc, 0, v3, vcc
	v_add_co_u32_e32 v12, vcc, s2, v2
	s_mov_b32 s2, 0x1f000
	s_nop 0
	v_addc_co_u32_e32 v13, vcc, 0, v3, vcc
	v_add_co_u32_e32 v18, vcc, s2, v2
	s_mov_b32 s2, 0x21000
	s_nop 0
	v_addc_co_u32_e32 v19, vcc, 0, v3, vcc
	global_load_dword v73, v[8:9], off offset:-4096 nt
	global_load_dword v72, v[8:9], off nt
	global_load_dword v71, v[10:11], off offset:-4096 nt
	global_load_dword v70, v[10:11], off nt
	global_load_dword v61, v[12:13], off offset:-4096 nt
	global_load_dword v59, v[12:13], off nt
	global_load_dword v60, v[18:19], off offset:-4096 nt
	global_load_dword v58, v[18:19], off nt
	v_add_co_u32_e32 v8, vcc, s2, v2
	s_mov_b32 s2, 0x23000
	s_nop 0
	v_addc_co_u32_e32 v9, vcc, 0, v3, vcc
	v_add_co_u32_e32 v10, vcc, s2, v2
	s_mov_b32 s2, 0x25000
	s_nop 0
	v_addc_co_u32_e32 v11, vcc, 0, v3, vcc
	v_add_co_u32_e32 v12, vcc, s2, v2
	s_mov_b32 s2, 0x27000
	s_nop 0
	v_addc_co_u32_e32 v13, vcc, 0, v3, vcc
	v_add_co_u32_e32 v18, vcc, s2, v2
	s_mov_b32 s2, 0x29000
	s_nop 0
	v_addc_co_u32_e32 v19, vcc, 0, v3, vcc
	global_load_dword v65, v[8:9], off offset:-4096 nt
	global_load_dword v64, v[8:9], off nt
	global_load_dword v63, v[10:11], off offset:-4096 nt
	global_load_dword v62, v[10:11], off nt
	global_load_dword v53, v[12:13], off offset:-4096 nt
	global_load_dword v50, v[12:13], off nt
	global_load_dword v52, v[18:19], off offset:-4096 nt
	global_load_dword v49, v[18:19], off nt
	v_add_co_u32_e32 v8, vcc, s2, v2
	s_mov_b32 s2, 0x2b000
	s_nop 0
	v_addc_co_u32_e32 v9, vcc, 0, v3, vcc
	v_add_co_u32_e32 v10, vcc, s2, v2
	s_mov_b32 s2, 0x2d000
	s_nop 0
	v_addc_co_u32_e32 v11, vcc, 0, v3, vcc
	v_add_co_u32_e32 v12, vcc, s2, v2
	s_mov_b32 s2, 0x2f000
	s_nop 0
	v_addc_co_u32_e32 v13, vcc, 0, v3, vcc
	v_add_co_u32_e32 v18, vcc, s2, v2
	s_mov_b32 s2, 0x31000
	s_nop 0
	v_addc_co_u32_e32 v19, vcc, 0, v3, vcc
	global_load_dword v57, v[8:9], off offset:-4096 nt
	global_load_dword v56, v[8:9], off nt
	global_load_dword v55, v[10:11], off offset:-4096 nt
	global_load_dword v54, v[10:11], off nt
	global_load_dword v44, v[12:13], off offset:-4096 nt
	global_load_dword v42, v[12:13], off nt
	global_load_dword v43, v[18:19], off offset:-4096 nt
	s_nop 0
	global_load_dword v19, v[18:19], off nt
	v_add_co_u32_e32 v8, vcc, s2, v2
	s_mov_b32 s2, 0x33000
	s_nop 0
	v_addc_co_u32_e32 v9, vcc, 0, v3, vcc
	v_add_co_u32_e32 v10, vcc, s2, v2
	s_mov_b32 s2, 0x35000
	s_nop 0
	v_addc_co_u32_e32 v11, vcc, 0, v3, vcc
	v_add_co_u32_e32 v12, vcc, s2, v2
	s_mov_b32 s2, 0x37000
	s_nop 0
	v_addc_co_u32_e32 v13, vcc, 0, v3, vcc
	v_add_co_u32_e32 v78, vcc, s2, v2
	s_mov_b32 s2, 0x39000
	s_nop 0
	v_addc_co_u32_e32 v79, vcc, 0, v3, vcc
	global_load_dword v48, v[8:9], off offset:-4096 nt
	global_load_dword v47, v[8:9], off nt
	global_load_dword v46, v[10:11], off offset:-4096 nt
	global_load_dword v45, v[10:11], off nt
	s_nop 0
	global_load_dword v11, v[12:13], off offset:-4096 nt
	global_load_dword v9, v[12:13], off nt
	global_load_dword v10, v[78:79], off offset:-4096 nt
	global_load_dword v8, v[78:79], off nt
	v_add_co_u32_e32 v12, vcc, s2, v2
	s_mov_b32 s2, 0x3b000
	s_nop 0
	v_addc_co_u32_e32 v13, vcc, 0, v3, vcc
	v_add_co_u32_e32 v78, vcc, s2, v2
	s_mov_b32 s2, 0x3c000
	s_nop 0
	v_addc_co_u32_e32 v79, vcc, 0, v3, vcc
	v_add_co_u32_e32 v82, vcc, s2, v2
	global_load_dword v17, v[12:13], off offset:-4096 nt
	s_nop 0
	global_load_dword v13, v[12:13], off nt
	s_nop 0
	global_load_dword v18, v[78:79], off offset:-4096 nt
	global_load_dword v12, v[78:79], off nt
	v_addc_co_u32_e32 v83, vcc, 0, v3, vcc
	v_add_co_u32_e32 v84, vcc, 0x3d000, v2
	s_movk_i32 s2, 0x3ff
	s_nop 0
	v_addc_co_u32_e32 v85, vcc, 0, v3, vcc
	v_add_co_u32_e32 v86, vcc, 0x3e000, v2
	v_cmp_lt_i32_e64 s[36:37], s2, v90
	s_nop 0
	v_addc_co_u32_e32 v87, vcc, 0, v3, vcc
	v_add_co_u32_e32 v88, vcc, 0x3f000, v2
	s_nop 1
	v_addc_co_u32_e32 v89, vcc, 0, v3, vcc
	global_load_dword v81, v[4:5], off offset:-4096 nt
	global_load_dword v80, v[4:5], off nt
	global_load_dword v79, v[6:7], off offset:-4096 nt
	global_load_dword v78, v[6:7], off nt
	s_nop 0
	global_load_dword v7, v[82:83], off nt
	global_load_dword v6, v[84:85], off nt
	global_load_dword v5, v[86:87], off nt
	global_load_dword v4, v[88:89], off nt
	s_and_saveexec_b64 s[2:3], s[36:37]
	s_xor_b64 s[2:3], exec, s[2:3]
	s_cbranch_execz .LBB0_1958
	ds_write2_b32 v21, v51, v51 offset1:65
	ds_write2_b32 v21, v51, v51 offset0:130 offset1:195
; #define LAS __attribute__((address_space(3)))
; __device__ __forceinline__ unsigned pk2(float lo, float hi) { return f2bf(lo) | (f2bf(hi) << 16); }
; __device__ __forceinline__ void transpose_item(const float* W, int N, bf16* WT, int ldt, LAS unsigned* scr, int item, int lane, int mode, int aux) {
;     const int nblk = (N + 63) >> 6, kb = item / nblk, nb = item - kb * nblk, k0 = 64 * kb, n0 = 64 * nb;
;     const int ncol = n0 + lane; const bool okc = ncol < N;
;     const float* wp = W + (size_t)k0 * N + (okc ? ncol : 0);
;     float v[64];
; #pragma unroll
;     for (int i = 0; i < 64; ++i) v[i] = wp[(size_t)i * N];
; #pragma unroll
;     for (int i = 0; i < 32; ++i) scr[i * 65 + lane] = okc ? pk2(v[2 * i], v[2 * i + 1]) : 0u;
.LBB0_1958:
	s_or_saveexec_b64 s[2:3], s[2:3]
	v_mov_b32_e32 v82, 0
	v_mov_b32_e32 v83, 0
	s_xor_b64 exec, exec, s[2:3]
	s_cbranch_execz .LBB0_1960
	v_add_co_u32_e32 v82, vcc, 0xb000, v2
	s_movk_i32 s22, 0x6000
	s_nop 0
	v_addc_co_u32_e32 v83, vcc, 0, v3, vcc
	global_load_dword v84, v[82:83], off nt
	v_add_co_u32_e32 v82, vcc, 0xa000, v2
	s_movk_i32 s23, 0x7fff
	s_nop 0
	v_addc_co_u32_e32 v83, vcc, 0, v3, vcc
	global_load_dword v85, v[82:83], off nt
	v_add_co_u32_e32 v82, vcc, 0x9000, v2
	s_nop 1
	v_addc_co_u32_e32 v83, vcc, 0, v3, vcc
	global_load_dword v86, v[82:83], off nt
	v_add_co_u32_e32 v82, vcc, 0x8000, v2
	s_nop 1
	v_addc_co_u32_e32 v83, vcc, 0, v3, vcc
	global_load_dword v87, v[82:83], off nt
	v_add_co_u32_e32 v82, vcc, 0x7000, v2
	s_nop 1
	v_addc_co_u32_e32 v83, vcc, 0, v3, vcc
	global_load_dword v88, v[82:83], off nt
	v_add_co_u32_e32 v82, vcc, s22, v2
	s_movk_i32 s22, 0x3000
	s_nop 0
	v_addc_co_u32_e32 v83, vcc, 0, v3, vcc
	global_load_dword v89, v[82:83], off nt
	v_add_co_u32_e32 v82, vcc, 0x5000, v2
	s_nop 1
	v_addc_co_u32_e32 v83, vcc, 0, v3, vcc
	global_load_dword v90, v[82:83], off nt
	v_add_co_u32_e32 v82, vcc, s70, v2
	s_nop 1
	v_addc_co_u32_e32 v83, vcc, 0, v3, vcc
	global_load_dword v91, v[82:83], off nt
	v_add_co_u32_e32 v82, vcc, s22, v2
	s_movk_i32 s22, 0x2000
	s_nop 0
	v_addc_co_u32_e32 v83, vcc, 0, v3, vcc
	global_load_dword v92, v[82:83], off nt
	v_add_co_u32_e32 v82, vcc, s22, v2
	s_movk_i32 s22, 0x1000
	s_nop 0
	v_addc_co_u32_e32 v83, vcc, 0, v3, vcc
	global_load_dword v93, v[82:83], off nt
	v_add_co_u32_e32 v82, vcc, s22, v2
	s_mov_b32 s22, 0xffff0000
	s_nop 0
	v_addc_co_u32_e32 v83, vcc, 0, v3, vcc
	global_load_dword v82, v[82:83], off nt
	s_nop 0
	global_load_dword v2, v[2:3], off nt
	s_waitcnt vmcnt(5)
	v_bfe_u32 v83, v90, 16, 1
	v_add3_u32 v83, v90, v83, s23
	s_waitcnt vmcnt(0)
	v_bfe_u32 v3, v2, 16, 1
	v_add3_u32 v2, v2, v3, s23
	v_bfe_u32 v3, v82, 16, 1
	v_lshrrev_b32_e32 v2, 16, v2
	v_add3_u32 v3, v82, v3, s23
	v_and_or_b32 v2, v3, s22, v2
	v_bfe_u32 v3, v93, 16, 1
	v_add3_u32 v3, v93, v3, s23
	v_bfe_u32 v82, v92, 16, 1
	v_lshrrev_b32_e32 v3, 16, v3
	v_add3_u32 v82, v92, v82, s23
	v_and_or_b32 v3, v82, s22, v3
	v_bfe_u32 v82, v91, 16, 1
	v_add3_u32 v82, v91, v82, s23
	v_lshrrev_b32_e32 v82, 16, v82
	v_and_or_b32 v82, v83, s22, v82
	v_bfe_u32 v83, v89, 16, 1
	v_add3_u32 v83, v89, v83, s23
	v_bfe_u32 v89, v88, 16, 1
	v_lshrrev_b32_e32 v83, 16, v83
	v_add3_u32 v88, v88, v89, s23
	v_and_or_b32 v83, v88, s22, v83
	ds_write2_b32 v21, v2, v3 offset1:65
	ds_write2_b32 v21, v82, v83 offset0:130 offset1:195
	v_bfe_u32 v2, v87, 16, 1
	v_add3_u32 v2, v87, v2, s23
	v_bfe_u32 v3, v86, 16, 1
	v_lshrrev_b32_e32 v2, 16, v2
	v_add3_u32 v3, v86, v3, s23
	v_and_or_b32 v82, v3, s22, v2
	v_bfe_u32 v2, v85, 16, 1
	v_add3_u32 v2, v85, v2, s23
	v_bfe_u32 v3, v84, 16, 1
	v_lshrrev_b32_e32 v2, 16, v2
	v_add3_u32 v3, v84, v3, s23
	v_and_or_b32 v83, v3, s22, v2

; #define LAS __attribute__((address_space(3)))
; __device__ __forceinline__ void transpose_item(const float* W, int N, bf16* WT, int ldt, LAS unsigned* scr, int item, int lane, int mode, int aux) {
;     const int nblk = (N + 63) >> 6, kb = item / nblk, nb = item - kb * nblk, k0 = 64 * kb, n0 = 64 * nb;
;     const int ncol = n0 + lane; const bool okc = ncol < N;
;     const float* wp = W + (size_t)k0 * N + (okc ? ncol : 0);
;     float v[64];
; #pragma unroll
;     for (int i = 0; i < 64; ++i) v[i] = wp[(size_t)i * N];
; __device__ __forceinline__ void convert_rest(const Args& a, LAS unsigned char* lds, int wave, int lane, int gw, int ngw, int l, int it0, int it1) {
;     ...
;         if (r < WI_BR) { const int g = r >> 6; transpose_item(a.in[I_WBR] + (size_t)(l * 4 + g) * 256 * 1024, 1024, (bf16*)(ws + WS_WBR) + (size_t)g * 1024 * 256, 256, scr, r & 63, lane, 0, 0); continue; } r -= WI_BR;
.LBB0_2004:
	s_andn2_b64 vcc, exec, s[0:1]
	s_cbranch_vccnz .LBB0_2006
	v_readlane_b32 s2, v254, 32
	s_add_i32 s0, s6, 0xfffffc00
	v_readlane_b32 s3, v254, 33
	s_lshr_b32 s0, s0, 6
	s_mov_b32 s27, s3
	s_add_i32 s26, s0, s8
	s_mov_b32 s1, s27
	s_lshl_b64 s[2:3], s[26:27], 20
	v_writelane_b32 v254, s0, 32
	s_add_u32 s22, s82, s2
	s_addc_u32 s23, s83, s3
	v_writelane_b32 v254, s1, 33
	s_mov_b32 s1, s27
	s_lshl_b64 s[0:1], s[0:1], 19
	v_readlane_b32 s2, v254, 1
	s_add_u32 s3, s2, s0
	v_readlane_b32 s0, v254, 2
	s_addc_u32 s17, s0, s1
	s_and_b32 s21, s11, 0xc0
	s_add_i32 s0, s13, 0xa2000
	s_and_b32 s2, s0, 0x3c0
	s_lshl_b32 s0, s21, 12
	v_or_b32_e32 v2, s2, v20
	s_add_u32 s0, s22, s0
	s_addc_u32 s1, s23, 0
	v_lshlrev_b32_e32 v50, 2, v2
	v_lshl_add_u64 v[2:3], s[0:1], 0, v[50:51]
	s_mov_b32 s22, 0x9000
	v_add_co_u32_e32 v6, vcc, s22, v2
	s_mov_b32 s22, 0xb000
	s_nop 0
	v_addc_co_u32_e32 v7, vcc, 0, v3, vcc
	v_add_co_u32_e32 v8, vcc, s22, v2
	s_mov_b32 s22, 0xd000
	s_nop 0
	v_addc_co_u32_e32 v9, vcc, 0, v3, vcc
	v_add_co_u32_e32 v10, vcc, s22, v2
	s_mov_b32 s22, 0xf000
	s_nop 0
	v_addc_co_u32_e32 v11, vcc, 0, v3, vcc
	global_load_dword v5, v[6:7], off offset:-4096 nt
	global_load_dword v4, v[6:7], off nt
	s_nop 0
	global_load_dword v7, v[8:9], off offset:-4096 nt
	global_load_dword v6, v[8:9], off nt
	s_nop 0
	global_load_dword v9, v[10:11], off offset:-4096 nt
	global_load_dword v8, v[10:11], off nt
	v_add_co_u32_e32 v10, vcc, s22, v2
	s_mov_b32 s22, 0x11000
	s_nop 0
	v_addc_co_u32_e32 v11, vcc, 0, v3, vcc
	v_add_co_u32_e32 v18, vcc, s22, v2
	s_mov_b32 s22, 0x13000
	s_nop 0
	v_addc_co_u32_e32 v19, vcc, 0, v3, vcc
	v_add_co_u32_e32 v42, vcc, s22, v2
	s_mov_b32 s22, 0x15000
	s_nop 0
	v_addc_co_u32_e32 v43, vcc, 0, v3, vcc
	v_add_co_u32_e32 v44, vcc, s22, v2
	s_mov_b32 s22, 0x17000
	s_nop 0
	v_addc_co_u32_e32 v45, vcc, 0, v3, vcc
	global_load_dword v13, v[10:11], off offset:-4096 nt
	s_nop 0
	global_load_dword v11, v[10:11], off nt
	s_nop 0
	global_load_dword v12, v[18:19], off offset:-4096 nt
	global_load_dword v10, v[18:19], off nt
	s_nop 0
	global_load_dword v18, v[42:43], off offset:-4096 nt
	global_load_dword v17, v[42:43], off nt
	s_nop 0
	global_load_dword v42, v[44:45], off offset:-4096 nt
	global_load_dword v19, v[44:45], off nt
	v_add_co_u32_e32 v44, vcc, s22, v2
	s_mov_b32 s22, 0x19000
	s_nop 0
	v_addc_co_u32_e32 v45, vcc, 0, v3, vcc
	v_add_co_u32_e32 v48, vcc, s22, v2
	s_mov_b32 s22, 0x1b000
	s_nop 0
	v_addc_co_u32_e32 v49, vcc, 0, v3, vcc
	v_add_co_u32_e32 v52, vcc, s22, v2
	s_mov_b32 s22, 0x1d000
	s_nop 0
	v_addc_co_u32_e32 v53, vcc, 0, v3, vcc
	v_add_co_u32_e32 v54, vcc, s22, v2
	s_mov_b32 s22, 0x1f000
	s_nop 0
	v_addc_co_u32_e32 v55, vcc, 0, v3, vcc
	global_load_dword v46, v[44:45], off offset:-4096 nt
	s_nop 0
	global_load_dword v44, v[44:45], off nt
	s_nop 0
	global_load_dword v45, v[48:49], off offset:-4096 nt
	global_load_dword v43, v[48:49], off nt
	s_nop 0
	global_load_dword v48, v[52:53], off offset:-4096 nt
	global_load_dword v47, v[52:53], off nt
	s_nop 0
	global_load_dword v52, v[54:55], off offset:-4096 nt
	global_load_dword v49, v[54:55], off nt
	v_add_co_u32_e32 v54, vcc, s22, v2
	s_mov_b32 s22, 0x21000
	s_nop 0
	v_addc_co_u32_e32 v55, vcc, 0, v3, vcc
	global_load_dword v62, v[54:55], off offset:-4096 nt
	global_load_dword v58, v[54:55], off nt
	v_add_co_u32_e32 v54, vcc, s22, v2
	s_mov_b32 s22, 0x23000
	s_nop 0
	v_addc_co_u32_e32 v55, vcc, 0, v3, vcc
	v_add_co_u32_e32 v56, vcc, s22, v2
	s_mov_b32 s22, 0x25000
	s_nop 0
	v_addc_co_u32_e32 v57, vcc, 0, v3, vcc
	global_load_dword v59, v[54:55], off offset:-4096 nt
	s_nop 0
	global_load_dword v55, v[54:55], off nt
	s_nop 0
	global_load_dword v70, v[56:57], off offset:-4096 nt
	global_load_dword v67, v[56:57], off nt
	v_add_co_u32_e32 v56, vcc, s22, v2
	s_mov_b32 s22, 0x27000
	s_nop 0
	v_addc_co_u32_e32 v57, vcc, 0, v3, vcc
	global_load_dword v78, v[56:57], off offset:-4096 nt
	global_load_dword v74, v[56:57], off nt
	v_add_co_u32_e32 v56, vcc, s22, v2
	s_mov_b32 s22, 0x29000
	s_nop 0
	v_addc_co_u32_e32 v57, vcc, 0, v3, vcc
	global_load_dword v86, v[56:57], off offset:-4096 nt
	global_load_dword v84, v[56:57], off nt
	v_add_co_u32_e32 v56, vcc, s22, v2
	s_mov_b32 s22, 0x2b000
	s_nop 0
	v_addc_co_u32_e32 v57, vcc, 0, v3, vcc
	global_load_dword v85, v[56:57], off offset:-4096 nt
	global_load_dword v82, v[56:57], off nt
	v_add_co_u32_e32 v56, vcc, s22, v2
	s_mov_b32 s22, 0x2d000
	s_nop 0
	v_addc_co_u32_e32 v57, vcc, 0, v3, vcc
	global_load_dword v83, v[56:57], off offset:-4096 nt
	global_load_dword v81, v[56:57], off nt
	v_add_co_u32_e32 v56, vcc, s22, v2
	s_mov_b32 s22, 0x2f000
	s_nop 0
	v_addc_co_u32_e32 v57, vcc, 0, v3, vcc
	global_load_dword v80, v[56:57], off offset:-4096 nt
	global_load_dword v77, v[56:57], off nt
	v_add_co_u32_e32 v56, vcc, s22, v2
	s_mov_b32 s22, 0x31000
	s_nop 0
	v_addc_co_u32_e32 v57, vcc, 0, v3, vcc
	global_load_dword v79, v[56:57], off offset:-4096 nt
	global_load_dword v75, v[56:57], off nt
	v_add_co_u32_e32 v56, vcc, s22, v2
	s_mov_b32 s22, 0x33000
	s_nop 0
	v_addc_co_u32_e32 v57, vcc, 0, v3, vcc
	global_load_dword v76, v[56:57], off offset:-4096 nt
	global_load_dword v72, v[56:57], off nt
	v_add_co_u32_e32 v56, vcc, s22, v2
	s_mov_b32 s22, 0x35000
	s_nop 0
	v_addc_co_u32_e32 v57, vcc, 0, v3, vcc
	global_load_dword v73, v[56:57], off offset:-4096 nt
	global_load_dword v71, v[56:57], off nt
	v_add_co_u32_e32 v56, vcc, s22, v2
	s_mov_b32 s22, 0x37000
	s_nop 0
	v_addc_co_u32_e32 v57, vcc, 0, v3, vcc
	global_load_dword v69, v[56:57], off offset:-4096 nt
	global_load_dword v66, v[56:57], off nt
	v_add_co_u32_e32 v56, vcc, s22, v2
	s_mov_b32 s22, 0x39000
; __device__ __forceinline__ unsigned pk2(float lo, float hi) { return f2bf(lo) | (f2bf(hi) << 16); }
; #define LDS_WAIT() asm volatile("s_waitcnt lgkmcnt(0)" ::: "memory")
; __device__ __forceinline__ void transpose_item(const float* W, int N, bf16* WT, int ldt, LAS unsigned* scr, int item, int lane, int mode, int aux) {
;     ...
;     float v[64];
; #pragma unroll
;     for (int i = 0; i < 64; ++i) v[i] = wp[(size_t)i * N];
; #pragma unroll
;     for (int i = 0; i < 32; ++i) scr[i * 65 + lane] = okc ? pk2(v[2 * i], v[2 * i + 1]) : 0u;
;     LDS_WAIT();
	s_nop 0
	v_addc_co_u32_e32 v57, vcc, 0, v3, vcc
	global_load_dword v68, v[56:57], off offset:-4096 nt
	global_load_dword v64, v[56:57], off nt
	v_add_co_u32_e32 v56, vcc, s22, v2
	s_mov_b32 s22, 0x3b000
	s_nop 0
	v_addc_co_u32_e32 v57, vcc, 0, v3, vcc
	global_load_dword v65, v[56:57], off offset:-4096 nt
	global_load_dword v61, v[56:57], off nt
	v_add_co_u32_e32 v56, vcc, s22, v2
	s_mov_b32 s22, 0x3d000
	s_nop 0
	v_addc_co_u32_e32 v57, vcc, 0, v3, vcc
	v_add_co_u32_e32 v88, vcc, s22, v2
	s_mov_b32 s22, 0x3f000
	s_nop 0
	v_addc_co_u32_e32 v89, vcc, 0, v3, vcc
	global_load_dword v63, v[56:57], off offset:-4096 nt
	global_load_dword v60, v[56:57], off nt
	s_nop 0
	global_load_dword v57, v[88:89], off offset:-4096 nt
	global_load_dword v54, v[88:89], off nt
	v_add_co_u32_e32 v88, vcc, s22, v2
	s_movk_i32 s22, 0x7000
	s_nop 0
	v_addc_co_u32_e32 v89, vcc, 0, v3, vcc
	global_load_dword v56, v[88:89], off offset:-4096 nt
	global_load_dword v53, v[88:89], off nt
	v_add_co_u32_e32 v88, vcc, s22, v2
	s_movk_i32 s22, 0x6000
	s_nop 0
	v_addc_co_u32_e32 v89, vcc, 0, v3, vcc
	global_load_dword v87, v[88:89], off nt
	v_add_co_u32_e32 v88, vcc, s22, v2
	s_movk_i32 s22, 0x3000
	s_nop 0
	v_addc_co_u32_e32 v89, vcc, 0, v3, vcc
	global_load_dword v90, v[88:89], off nt
	v_add_co_u32_e32 v88, vcc, s38, v2
	s_nop 1
	v_addc_co_u32_e32 v89, vcc, 0, v3, vcc
	global_load_dword v91, v[88:89], off nt
	v_add_co_u32_e32 v88, vcc, s70, v2
	s_nop 1
	v_addc_co_u32_e32 v89, vcc, 0, v3, vcc
	global_load_dword v92, v[88:89], off nt
	v_add_co_u32_e32 v88, vcc, s22, v2
	s_movk_i32 s22, 0x2000
	s_nop 0
	v_addc_co_u32_e32 v89, vcc, 0, v3, vcc
	global_load_dword v93, v[88:89], off nt
	v_add_co_u32_e32 v88, vcc, s22, v2
	s_movk_i32 s22, 0x1000
	s_nop 0
	v_addc_co_u32_e32 v89, vcc, 0, v3, vcc
	v_add_co_u32_e32 v2, vcc, s22, v2
	global_load_dword v88, v[88:89], off nt
	s_nop 0
	v_addc_co_u32_e32 v3, vcc, 0, v3, vcc
	global_load_dword v2, v[2:3], off nt
	s_nop 0
	global_load_dword v3, v50, s[0:1] nt
	s_movk_i32 s1, 0x7fff
	s_mov_b32 s0, 0xffff0000
	s_waitcnt vmcnt(0)
	v_bfe_u32 v50, v3, 16, 1
	v_add3_u32 v3, v3, v50, s1
	v_bfe_u32 v50, v2, 16, 1
	v_lshrrev_b32_e32 v3, 16, v3
	v_add3_u32 v2, v2, v50, s1
	v_and_or_b32 v2, v2, s0, v3
	v_bfe_u32 v3, v88, 16, 1
	v_add3_u32 v3, v88, v3, s1
	v_bfe_u32 v50, v93, 16, 1
	v_lshrrev_b32_e32 v3, 16, v3
	v_add3_u32 v50, v93, v50, s1
	v_and_or_b32 v3, v50, s0, v3
	ds_write2_b32 v21, v2, v3 offset1:65
	v_bfe_u32 v2, v92, 16, 1
	v_add3_u32 v2, v92, v2, s1
	v_bfe_u32 v3, v91, 16, 1
	v_lshrrev_b32_e32 v2, 16, v2
	v_add3_u32 v3, v91, v3, s1
	v_and_or_b32 v2, v3, s0, v2
	v_bfe_u32 v3, v90, 16, 1
	v_add3_u32 v3, v90, v3, s1
	v_bfe_u32 v50, v87, 16, 1
	v_lshrrev_b32_e32 v3, 16, v3
	v_add3_u32 v50, v87, v50, s1
	v_and_or_b32 v3, v50, s0, v3
	ds_write2_b32 v21, v2, v3 offset0:130 offset1:195
	v_bfe_u32 v2, v5, 16, 1
	v_add3_u32 v2, v5, v2, s1
	v_bfe_u32 v3, v4, 16, 1
	v_lshrrev_b32_e32 v2, 16, v2
	v_add3_u32 v3, v4, v3, s1
	v_and_or_b32 v2, v3, s0, v2
	v_bfe_u32 v3, v7, 16, 1
	v_add3_u32 v3, v7, v3, s1
	v_bfe_u32 v4, v6, 16, 1
	v_lshrrev_b32_e32 v3, 16, v3
	v_add3_u32 v4, v6, v4, s1
	v_and_or_b32 v3, v4, s0, v3
	v_add_u32_e32 v4, 0x400, v21
	ds_write2_b32 v4, v2, v3 offset0:4 offset1:69
	v_bfe_u32 v2, v9, 16, 1
	v_add3_u32 v2, v9, v2, s1
	v_bfe_u32 v3, v8, 16, 1
	v_lshrrev_b32_e32 v2, 16, v2
	v_add3_u32 v3, v8, v3, s1
	v_and_or_b32 v2, v3, s0, v2
	v_bfe_u32 v3, v13, 16, 1
	v_add3_u32 v3, v13, v3, s1
	v_bfe_u32 v5, v11, 16, 1
	v_lshrrev_b32_e32 v3, 16, v3
	v_add3_u32 v5, v11, v5, s1
	v_and_or_b32 v3, v5, s0, v3
	ds_write2_b32 v4, v2, v3 offset0:134 offset1:199
	v_bfe_u32 v2, v12, 16, 1
	v_add3_u32 v2, v12, v2, s1
	v_bfe_u32 v3, v10, 16, 1
	v_lshrrev_b32_e32 v2, 16, v2
	v_add3_u32 v3, v10, v3, s1
	v_and_or_b32 v2, v3, s0, v2
	v_bfe_u32 v3, v18, 16, 1
	v_add3_u32 v3, v18, v3, s1
	v_bfe_u32 v4, v17, 16, 1
	v_lshrrev_b32_e32 v3, 16, v3
	v_add3_u32 v4, v17, v4, s1
	v_and_or_b32 v3, v4, s0, v3
	v_add_u32_e32 v4, 0x800, v21
	ds_write2_b32 v4, v2, v3 offset0:8 offset1:73
	v_bfe_u32 v2, v42, 16, 1
	v_add3_u32 v2, v42, v2, s1
	v_bfe_u32 v3, v19, 16, 1
	v_lshrrev_b32_e32 v2, 16, v2
	v_add3_u32 v3, v19, v3, s1
	v_and_or_b32 v2, v3, s0, v2
	v_bfe_u32 v3, v46, 16, 1
	v_add3_u32 v3, v46, v3, s1
	v_bfe_u32 v5, v44, 16, 1
	v_lshrrev_b32_e32 v3, 16, v3
	v_add3_u32 v5, v44, v5, s1
	v_and_or_b32 v3, v5, s0, v3
	ds_write2_b32 v4, v2, v3 offset0:138 offset1:203
	v_bfe_u32 v2, v45, 16, 1
	v_add3_u32 v2, v45, v2, s1
	v_bfe_u32 v3, v43, 16, 1
	v_lshrrev_b32_e32 v2, 16, v2
	v_add3_u32 v3, v43, v3, s1
	v_and_or_b32 v2, v3, s0, v2
	v_bfe_u32 v3, v48, 16, 1
	v_add3_u32 v3, v48, v3, s1
	v_bfe_u32 v4, v47, 16, 1
	v_lshrrev_b32_e32 v3, 16, v3
	v_add3_u32 v4, v47, v4, s1
	v_and_or_b32 v3, v4, s0, v3
	v_add_u32_e32 v4, 0xc00, v21
	ds_write2_b32 v4, v2, v3 offset0:12 offset1:77
	v_bfe_u32 v2, v52, 16, 1
	v_add3_u32 v2, v52, v2, s1
	v_bfe_u32 v3, v49, 16, 1
	v_lshrrev_b32_e32 v2, 16, v2
	v_add3_u32 v3, v49, v3, s1
	v_and_or_b32 v2, v3, s0, v2
	v_bfe_u32 v3, v62, 16, 1
	v_add3_u32 v3, v62, v3, s1
	v_bfe_u32 v5, v58, 16, 1
	v_lshrrev_b32_e32 v3, 16, v3
	v_add3_u32 v5, v58, v5, s1
	v_and_or_b32 v3, v5, s0, v3
	ds_write2_b32 v4, v2, v3 offset0:142 offset1:207
	v_bfe_u32 v2, v59, 16, 1
	v_add3_u32 v2, v59, v2, s1
	v_bfe_u32 v3, v55, 16, 1
	v_lshrrev_b32_e32 v2, 16, v2
	v_add3_u32 v3, v55, v3, s1
	v_and_or_b32 v2, v3, s0, v2
	v_bfe_u32 v3, v70, 16, 1
	v_add3_u32 v3, v70, v3, s1
	v_bfe_u32 v4, v67, 16, 1
	v_lshrrev_b32_e32 v3, 16, v3
	v_add3_u32 v4, v67, v4, s1
	v_and_or_b32 v3, v4, s0, v3
	v_add_u32_e32 v4, 0x1000, v21
	ds_write2_b32 v4, v2, v3 offset0:16 offset1:81
	v_bfe_u32 v2, v78, 16, 1
; __device__ __forceinline__ unsigned pk2(float lo, float hi) { return f2bf(lo) | (f2bf(hi) << 16); }
; #define LDS_WAIT() asm volatile("s_waitcnt lgkmcnt(0)" ::: "memory")
; __device__ __forceinline__ void transpose_item(const float* W, int N, bf16* WT, int ldt, LAS unsigned* scr, int item, int lane, int mode, int aux) {
;     ...
;     for (int i = 0; i < 32; ++i) scr[i * 65 + lane] = okc ? pk2(v[2 * i], v[2 * i + 1]) : 0u;
;     LDS_WAIT();
;     const int c = lane & 7;
; #pragma unroll
;     for (int j = 0; j < 8; ++j) { const int nn = (lane >> 3) + 8 * j, n = n0 + nn;
;         v4u o; o.x = scr[(4 * c + 0) * 65 + nn]; o.y = scr[(4 * c + 1) * 65 + nn]; o.z = scr[(4 * c + 2) * 65 + nn]; o.w = scr[(4 * c + 3) * 65 + nn];
;         if (n < N) *(v4u*)(WT + (size_t)rowmap(mode, aux, n) * ldt + k0 + 8 * c) = o; }
;     LDS_WAIT();
	v_add3_u32 v2, v78, v2, s1
	v_bfe_u32 v3, v74, 16, 1
	v_lshrrev_b32_e32 v2, 16, v2
	v_add3_u32 v3, v74, v3, s1
	v_and_or_b32 v2, v3, s0, v2
	v_bfe_u32 v3, v86, 16, 1
	v_add3_u32 v3, v86, v3, s1
	v_bfe_u32 v5, v84, 16, 1
	v_lshrrev_b32_e32 v3, 16, v3
	v_add3_u32 v5, v84, v5, s1
	v_and_or_b32 v3, v5, s0, v3
	ds_write2_b32 v4, v2, v3 offset0:146 offset1:211
	v_bfe_u32 v2, v85, 16, 1
	v_add3_u32 v2, v85, v2, s1
	v_bfe_u32 v3, v82, 16, 1
	v_lshrrev_b32_e32 v2, 16, v2
	v_add3_u32 v3, v82, v3, s1
	v_and_or_b32 v2, v3, s0, v2
	v_bfe_u32 v3, v83, 16, 1
	v_add3_u32 v3, v83, v3, s1
	v_bfe_u32 v4, v81, 16, 1
	v_lshrrev_b32_e32 v3, 16, v3
	v_add3_u32 v4, v81, v4, s1
	v_and_or_b32 v3, v4, s0, v3
	v_add_u32_e32 v4, 0x1400, v21
	ds_write2_b32 v4, v2, v3 offset0:20 offset1:85
	v_bfe_u32 v2, v80, 16, 1
	v_add3_u32 v2, v80, v2, s1
	v_bfe_u32 v3, v77, 16, 1
	v_lshrrev_b32_e32 v2, 16, v2
	v_add3_u32 v3, v77, v3, s1
	v_and_or_b32 v2, v3, s0, v2
	v_bfe_u32 v3, v79, 16, 1
	v_add3_u32 v3, v79, v3, s1
	v_bfe_u32 v5, v75, 16, 1
	v_lshrrev_b32_e32 v3, 16, v3
	v_add3_u32 v5, v75, v5, s1
	v_and_or_b32 v3, v5, s0, v3
	ds_write2_b32 v4, v2, v3 offset0:150 offset1:215
	v_bfe_u32 v2, v76, 16, 1
	v_add3_u32 v2, v76, v2, s1
	v_bfe_u32 v3, v72, 16, 1
	v_lshrrev_b32_e32 v2, 16, v2
	v_add3_u32 v3, v72, v3, s1
	v_and_or_b32 v2, v3, s0, v2
	v_bfe_u32 v3, v73, 16, 1
	v_add3_u32 v3, v73, v3, s1
	v_bfe_u32 v4, v71, 16, 1
	v_lshrrev_b32_e32 v3, 16, v3
	v_add3_u32 v4, v71, v4, s1
	v_and_or_b32 v3, v4, s0, v3
	v_add_u32_e32 v4, 0x1800, v21
	ds_write2_b32 v4, v2, v3 offset0:24 offset1:89
	v_bfe_u32 v2, v69, 16, 1
	v_add3_u32 v2, v69, v2, s1
	v_bfe_u32 v3, v66, 16, 1
	v_lshrrev_b32_e32 v2, 16, v2
	v_add3_u32 v3, v66, v3, s1
	v_and_or_b32 v2, v3, s0, v2
	v_bfe_u32 v3, v68, 16, 1
	v_add3_u32 v3, v68, v3, s1
	v_bfe_u32 v5, v64, 16, 1
	v_lshrrev_b32_e32 v3, 16, v3
	v_add3_u32 v5, v64, v5, s1
	v_and_or_b32 v3, v5, s0, v3
	ds_write2_b32 v4, v2, v3 offset0:154 offset1:219
	v_bfe_u32 v2, v65, 16, 1
	v_add3_u32 v2, v65, v2, s1
	v_bfe_u32 v3, v61, 16, 1
	v_lshrrev_b32_e32 v2, 16, v2
	v_add3_u32 v3, v61, v3, s1
	v_and_or_b32 v2, v3, s0, v2
	v_bfe_u32 v3, v63, 16, 1
	v_add3_u32 v3, v63, v3, s1
	v_bfe_u32 v4, v60, 16, 1
	v_lshrrev_b32_e32 v3, 16, v3
	v_add3_u32 v4, v60, v4, s1
	v_and_or_b32 v3, v4, s0, v3
	v_add_u32_e32 v4, 0x1c00, v21
	ds_write2_b32 v4, v2, v3 offset0:28 offset1:93
	v_bfe_u32 v2, v57, 16, 1
	v_add3_u32 v2, v57, v2, s1
	v_bfe_u32 v3, v54, 16, 1
	v_lshrrev_b32_e32 v2, 16, v2
	v_add3_u32 v3, v54, v3, s1
	v_and_or_b32 v2, v3, s0, v2
	v_bfe_u32 v3, v56, 16, 1
	v_add3_u32 v3, v56, v3, s1
	v_bfe_u32 v5, v53, 16, 1
	v_lshrrev_b32_e32 v3, 16, v3
	v_add3_u32 v5, v53, v5, s1
	v_and_or_b32 v3, v5, s0, v3
	ds_write2_b32 v4, v2, v3 offset0:158 offset1:223
	s_waitcnt lgkmcnt(0)
	s_lshl_b32 s0, s21, 1
	ds_read2_b32 v[2:3], v23 offset0:65 offset1:73
	ds_read2_b32 v[12:13], v23 offset0:130 offset1:138
	ds_read2_b32 v[4:5], v23 offset0:195 offset1:203
	ds_read2_b32 v[18:19], v23 offset1:8
	s_add_u32 s0, s3, s0
	s_addc_u32 s1, s17, 0
	v_mov_b32_e32 v17, v51
	v_lshl_add_u64 v[10:11], s[0:1], 0, v[16:17]
	v_or_b32_e32 v17, s2, v22
	v_lshlrev_b32_e32 v50, 9, v17
	s_waitcnt lgkmcnt(0)
	v_mov_b32_e32 v6, v18
	v_mov_b32_e32 v7, v2
	v_mov_b32_e32 v8, v12
	v_mov_b32_e32 v9, v4
	v_lshl_add_u64 v[42:43], v[10:11], 0, v[50:51]
	global_store_dwordx4 v[42:43], v[6:9], off
	v_mov_b32_e32 v2, v19
	v_mov_b32_e32 v4, v13
	v_or_b32_e32 v6, s2, v24
	v_lshlrev_b32_e32 v50, 9, v6
	v_lshl_add_u64 v[6:7], v[10:11], 0, v[50:51]
	global_store_dwordx4 v[6:7], v[2:5], off
	ds_read2_b32 v[12:13], v23 offset0:16 offset1:24
	ds_read2_b32 v[2:3], v23 offset0:81 offset1:89
	ds_read2_b32 v[18:19], v23 offset0:146 offset1:154
	ds_read2_b32 v[4:5], v23 offset0:211 offset1:219
	v_or_b32_e32 v17, s2, v25
	v_lshlrev_b32_e32 v50, 9, v17
	s_waitcnt lgkmcnt(3)
	v_mov_b32_e32 v6, v12
	s_waitcnt lgkmcnt(2)
	v_mov_b32_e32 v7, v2
	s_waitcnt lgkmcnt(1)
	v_mov_b32_e32 v8, v18
	s_waitcnt lgkmcnt(0)
	v_mov_b32_e32 v9, v4
	v_lshl_add_u64 v[42:43], v[10:11], 0, v[50:51]
	global_store_dwordx4 v[42:43], v[6:9], off
	v_mov_b32_e32 v2, v13
	v_mov_b32_e32 v4, v19
	v_or_b32_e32 v6, s2, v26
	v_lshlrev_b32_e32 v50, 9, v6
	v_lshl_add_u64 v[6:7], v[10:11], 0, v[50:51]
	global_store_dwordx4 v[6:7], v[2:5], off
	ds_read2_b32 v[2:3], v23 offset0:97 offset1:105
	ds_read2_b32 v[12:13], v23 offset0:162 offset1:170
	ds_read2_b32 v[4:5], v23 offset0:227 offset1:235
	ds_read2_b32 v[18:19], v23 offset0:32 offset1:40
	v_or_b32_e32 v17, s2, v27
	v_lshlrev_b32_e32 v50, 9, v17
	s_waitcnt lgkmcnt(3)
	v_mov_b32_e32 v7, v2
	s_waitcnt lgkmcnt(2)
	v_mov_b32_e32 v8, v12
	s_waitcnt lgkmcnt(0)
	v_mov_b32_e32 v6, v18
	v_mov_b32_e32 v9, v4
	v_lshl_add_u64 v[42:43], v[10:11], 0, v[50:51]
	global_store_dwordx4 v[42:43], v[6:9], off
	v_mov_b32_e32 v2, v19
	v_mov_b32_e32 v4, v13
	v_or_b32_e32 v6, s2, v28
	v_lshlrev_b32_e32 v50, 9, v6
	v_lshl_add_u64 v[6:7], v[10:11], 0, v[50:51]
	global_store_dwordx4 v[6:7], v[2:5], off
	ds_read2_b32 v[12:13], v23 offset0:48 offset1:56
	ds_read2_b32 v[2:3], v23 offset0:113 offset1:121
	ds_read2_b32 v[18:19], v23 offset0:178 offset1:186
	ds_read2_b32 v[4:5], v23 offset0:243 offset1:251
	v_or_b32_e32 v17, s2, v29
	v_lshlrev_b32_e32 v50, 9, v17
	s_waitcnt lgkmcnt(3)
	v_mov_b32_e32 v6, v12
	s_waitcnt lgkmcnt(2)
	v_mov_b32_e32 v7, v2
	s_waitcnt lgkmcnt(1)
	v_mov_b32_e32 v8, v18
	s_waitcnt lgkmcnt(0)
	v_mov_b32_e32 v9, v4
	v_lshl_add_u64 v[42:43], v[10:11], 0, v[50:51]
	global_store_dwordx4 v[42:43], v[6:9], off
	v_mov_b32_e32 v2, v13
	v_mov_b32_e32 v4, v19
	v_or_b32_e32 v6, s2, v30
	v_lshlrev_b32_e32 v50, 9, v6
	v_lshl_add_u64 v[6:7], v[10:11], 0, v[50:51]
	global_store_dwordx4 v[6:7], v[2:5], off
	s_waitcnt lgkmcnt(0)

; __device__ __forceinline__ void transpose_item8(const float* W, int N, unsigned char* WT, int ldt, int item, int lane, int mode, int aux) {
;     const int nblk = (N + 63) >> 6, kb = item / nblk, nb = item - kb * nblk, k0 = 64 * kb, n0 = 64 * nb;
;     const int ncol = n0 + lane;
;     const float* wp = W + (size_t)k0 * N + ncol;
;     float v[64];
; #pragma unroll
;     for (int i = 0; i < 64; ++i) v[i] = wp[(size_t)i * N];
; __device__ __forceinline__ void convert_rest(const Args& a, LAS unsigned char* lds, int wave, int lane, int gw, int ngw, int l, int it0, int it1) {
;     ...
;         if (r < WI_G) { const int g = r >> 8; transpose_item8(a.in[I_WGATE] + (size_t)(l * 4 + g) * 1024 * 1024, 1024, ws + WS_WG, 1024, r & 255, lane, 2, g); continue; } r -= WI_G;
.LBB0_2007:
	s_andn2_b64 vcc, exec, s[0:1]
	s_cbranch_vccnz .LBB0_1942
	s_ashr_i32 s0, s6, 8
	s_add_i32 s2, s0, s8
	s_ashr_i32 s3, s2, 31
	s_lshl_b64 s[2:3], s[2:3], 22
	s_add_u32 s2, s78, s2
	s_addc_u32 s3, s79, s3
	s_lshl_b32 s1, s6, 2
	v_readlane_b32 s22, v254, 32
	s_and_b32 s22, s1, 0x3c0
	s_lshl_b32 s1, s6, 6
	s_and_b32 s1, s1, 0x3c0
	s_lshl_b32 s17, s22, 12
	v_or_b32_e32 v2, s1, v20
	s_add_u32 s2, s2, s17
	s_addc_u32 s3, s3, 0
	v_lshlrev_b32_e32 v50, 2, v2
	v_lshl_add_u64 v[2:3], s[2:3], 0, v[50:51]
	global_load_dword v17, v50, s[2:3] nt
	s_movk_i32 s2, 0x2000
	v_add_co_u32_e32 v4, vcc, s2, v2
	s_movk_i32 s2, 0x6000
	s_nop 0
	v_addc_co_u32_e32 v5, vcc, 0, v3, vcc
	global_load_dword v19, v[4:5], off offset:-4096 nt
	global_load_dword v42, v[4:5], off nt
	v_add_co_u32_e32 v4, vcc, s70, v2
	s_lshl_b32 s1, s1, 2
	s_nop 0
	v_addc_co_u32_e32 v5, vcc, 0, v3, vcc
	global_load_dword v43, v[4:5], off offset:-4096 nt
	global_load_dword v44, v[4:5], off nt
	v_add_co_u32_e32 v4, vcc, s2, v2
	s_mov_b32 s2, 0x8000
	s_nop 0
	v_addc_co_u32_e32 v5, vcc, 0, v3, vcc
	global_load_dword v45, v[4:5], off offset:-4096 nt
	global_load_dword v46, v[4:5], off nt
	v_add_co_u32_e32 v4, vcc, s2, v2
	s_mov_b32 s2, 0xa000
	s_nop 0
	v_addc_co_u32_e32 v5, vcc, 0, v3, vcc
	global_load_dword v47, v[4:5], off offset:-4096 nt
	global_load_dword v48, v[4:5], off nt
	v_add_co_u32_e32 v4, vcc, s2, v2
	s_mov_b32 s2, 0xc000
	s_nop 0
	v_addc_co_u32_e32 v5, vcc, 0, v3, vcc
	global_load_dword v49, v[4:5], off offset:-4096 nt
	global_load_dword v50, v[4:5], off nt
	v_add_co_u32_e32 v4, vcc, s2, v2
	s_mov_b32 s2, 0xe000
	s_nop 0
	v_addc_co_u32_e32 v5, vcc, 0, v3, vcc
	global_load_dword v52, v[4:5], off offset:-4096 nt
	global_load_dword v53, v[4:5], off nt
	v_add_co_u32_e32 v4, vcc, s2, v2
	s_mov_b32 s2, 0x10000
	s_nop 0
	v_addc_co_u32_e32 v5, vcc, 0, v3, vcc
	global_load_dword v54, v[4:5], off offset:-4096 nt
	global_load_dword v55, v[4:5], off nt
	v_add_co_u32_e32 v4, vcc, s2, v2
	s_mov_b32 s2, 0x12000
	s_nop 0
	v_addc_co_u32_e32 v5, vcc, 0, v3, vcc
	global_load_dword v56, v[4:5], off offset:-4096 nt
	global_load_dword v10, v[4:5], off nt
	v_add_co_u32_e32 v4, vcc, s2, v2
	s_mov_b32 s2, 0x14000
	s_nop 0
	v_addc_co_u32_e32 v5, vcc, 0, v3, vcc
	global_load_dword v57, v[4:5], off offset:-4096 nt
	global_load_dword v58, v[4:5], off nt
	v_add_co_u32_e32 v4, vcc, s2, v2
	s_mov_b32 s2, 0x16000
	s_nop 0
	v_addc_co_u32_e32 v5, vcc, 0, v3, vcc
	global_load_dword v59, v[4:5], off offset:-4096 nt
	global_load_dword v11, v[4:5], off nt
	v_add_co_u32_e32 v4, vcc, s2, v2
	s_mov_b32 s2, 0x18000
	s_nop 0
	v_addc_co_u32_e32 v5, vcc, 0, v3, vcc
	global_load_dword v60, v[4:5], off offset:-4096 nt
	global_load_dword v61, v[4:5], off nt
	v_add_co_u32_e32 v4, vcc, s2, v2
	s_mov_b32 s2, 0x1a000
	s_nop 0
	v_addc_co_u32_e32 v5, vcc, 0, v3, vcc
	global_load_dword v62, v[4:5], off offset:-4096 nt
	global_load_dword v12, v[4:5], off nt
	v_add_co_u32_e32 v4, vcc, s2, v2
	s_mov_b32 s2, 0x1c000
	s_nop 0
	v_addc_co_u32_e32 v5, vcc, 0, v3, vcc
	global_load_dword v63, v[4:5], off offset:-4096 nt
	global_load_dword v64, v[4:5], off nt
	v_add_co_u32_e32 v4, vcc, s2, v2
	s_mov_b32 s2, 0x1e000
	s_nop 0
	v_addc_co_u32_e32 v5, vcc, 0, v3, vcc
	global_load_dword v65, v[4:5], off offset:-4096 nt
	global_load_dword v13, v[4:5], off nt
	v_add_co_u32_e32 v4, vcc, s2, v2
	s_mov_b32 s2, 0x20000
	s_nop 0
	v_addc_co_u32_e32 v5, vcc, 0, v3, vcc
	global_load_dword v66, v[4:5], off offset:-4096 nt
	global_load_dword v67, v[4:5], off nt
	v_add_co_u32_e32 v4, vcc, s2, v2
	s_mov_b32 s2, 0x22000
	s_nop 0
	v_addc_co_u32_e32 v5, vcc, 0, v3, vcc
	global_load_dword v68, v[4:5], off offset:-4096 nt
	global_load_dword v6, v[4:5], off nt
	v_add_co_u32_e32 v4, vcc, s2, v2
	s_mov_b32 s2, 0x24000
	s_nop 0
	v_addc_co_u32_e32 v5, vcc, 0, v3, vcc
	global_load_dword v69, v[4:5], off offset:-4096 nt
	global_load_dword v70, v[4:5], off nt
	v_add_co_u32_e32 v4, vcc, s2, v2
	s_mov_b32 s2, 0x26000
	s_nop 0
	v_addc_co_u32_e32 v5, vcc, 0, v3, vcc
	global_load_dword v71, v[4:5], off offset:-4096 nt
	global_load_dword v7, v[4:5], off nt
	v_add_co_u32_e32 v4, vcc, s2, v2
	s_mov_b32 s2, 0x28000
	s_nop 0
	v_addc_co_u32_e32 v5, vcc, 0, v3, vcc
	global_load_dword v72, v[4:5], off offset:-4096 nt
	global_load_dword v73, v[4:5], off nt
	v_add_co_u32_e32 v4, vcc, s2, v2
	s_mov_b32 s2, 0x2a000
	s_nop 0
	v_addc_co_u32_e32 v5, vcc, 0, v3, vcc
	global_load_dword v74, v[4:5], off offset:-4096 nt
	global_load_dword v8, v[4:5], off nt
	v_add_co_u32_e32 v4, vcc, s2, v2
	s_mov_b32 s2, 0x2c000
	s_nop 0
	v_addc_co_u32_e32 v5, vcc, 0, v3, vcc
	global_load_dword v75, v[4:5], off offset:-4096 nt
	global_load_dword v76, v[4:5], off nt
	v_add_co_u32_e32 v4, vcc, s2, v2
	s_mov_b32 s2, 0x2e000
	s_nop 0
	v_addc_co_u32_e32 v5, vcc, 0, v3, vcc
	global_load_dword v77, v[4:5], off offset:-4096 nt
	global_load_dword v9, v[4:5], off nt
	v_add_co_u32_e32 v4, vcc, s2, v2
	s_mov_b32 s2, 0x30000
	s_nop 0
	v_addc_co_u32_e32 v5, vcc, 0, v3, vcc
	global_load_dword v78, v[4:5], off offset:-4096 nt
	global_load_dword v79, v[4:5], off nt
	v_add_co_u32_e32 v4, vcc, s2, v2
	s_mov_b32 s2, 0x32000
	s_nop 0
	v_addc_co_u32_e32 v5, vcc, 0, v3, vcc
	global_load_dword v80, v[4:5], off offset:-4096 nt
	global_load_dword v81, v[4:5], off nt
	v_add_co_u32_e32 v4, vcc, s2, v2
	s_mov_b32 s2, 0x34000
	s_nop 0
	v_addc_co_u32_e32 v5, vcc, 0, v3, vcc
	global_load_dword v82, v[4:5], off offset:-4096 nt
	global_load_dword v83, v[4:5], off nt
	v_add_co_u32_e32 v4, vcc, s2, v2
	s_mov_b32 s2, 0x36000
	s_nop 0
	v_addc_co_u32_e32 v5, vcc, 0, v3, vcc
	global_load_dword v84, v[4:5], off offset:-4096 nt
	global_load_dword v85, v[4:5], off nt
	v_add_co_u32_e32 v4, vcc, s2, v2
	s_mov_b32 s2, 0x38000
	s_nop 0
	v_addc_co_u32_e32 v5, vcc, 0, v3, vcc
	global_load_dword v86, v[4:5], off offset:-4096 nt
	global_load_dword v87, v[4:5], off nt
	v_add_co_u32_e32 v4, vcc, s2, v2
	s_mov_b32 s2, 0x3a000
	s_nop 0
	v_addc_co_u32_e32 v5, vcc, 0, v3, vcc
	global_load_dword v88, v[4:5], off offset:-4096 nt
	global_load_dword v89, v[4:5], off nt
	v_add_co_u32_e32 v4, vcc, s2, v2
	s_mov_b32 s2, 0x3c000
	s_nop 0
	v_addc_co_u32_e32 v5, vcc, 0, v3, vcc
	global_load_dword v90, v[4:5], off offset:-4096 nt
	global_load_dword v91, v[4:5], off nt
	v_add_co_u32_e32 v4, vcc, s2, v2
	s_mov_b32 s2, 0x3e000
	s_nop 0
	v_addc_co_u32_e32 v5, vcc, 0, v3, vcc
	global_load_dword v92, v[4:5], off offset:-4096 nt
	global_load_dword v93, v[4:5], off nt
	v_add_co_u32_e32 v4, vcc, s2, v2
	s_mov_b32 s2, 0x3f000
	s_nop 0
	v_addc_co_u32_e32 v5, vcc, 0, v3, vcc
	global_load_dword v94, v[4:5], off offset:-4096 nt
	s_nop 0
	global_load_dword v4, v[4:5], off nt
	v_add_co_u32_e32 v2, vcc, s2, v2
	s_lshl_b32 s2, s0, 6
	s_nop 0
	v_addc_co_u32_e32 v3, vcc, 0, v3, vcc
	global_load_dword v2, v[2:3], off nt
	s_and_b32 s2, s2, 0xffffff80
	s_add_i32 s1, s1, s2
	s_lshl_b32 s0, s0, 4
	v_or_b32_e32 v3, s1, v31
	s_and_b32 s0, s0, 16
	v_or3_b32 v18, v3, s0, v32
	s_mov_b32 s0, 0xc3e00000
	s_waitcnt vmcnt(23)
; __device__ __forceinline__ unsigned pk4_fp8(float a, float b, float c, float d) { int w = 0; w = __builtin_amdgcn_cvt_pk_fp8_f32(a, b, w, false); w = __builtin_amdgcn_cvt_pk_fp8_f32(c, d, w, true); return (unsigned)w; }
; __device__ __forceinline__ void transpose_item8(const float* W, int N, unsigned char* WT, int ldt, int item, int lane, int mode, int aux) {
;     ...
; #pragma unroll
;     for (int q = 0; q < 16; ++q) o[q] = pk4_fp8(fminf(fmaxf(v[4 * q] * 64.f, -448.f), 448.f), fminf(fmaxf(v[4 * q + 1] * 64.f, -448.f), 448.f), fminf(fmaxf(v[4 * q + 2] * 64.f, -448.f), 448.f), fminf(fmaxf(v[4 * q + 3] * 64.f, -448.f), 448.f));
;     v4u* dst = (v4u*)(WT + (size_t)rowmap(mode, aux, ncol) * ldt + k0);
; #pragma unroll
;     for (int q = 0; q < 4; ++q) dst[q] = (v4u){o[4 * q], o[4 * q + 1], o[4 * q + 2], o[4 * q + 3]};
	v_mul_f32_e32 v8, 0x42800000, v8
	v_mul_f32_e32 v7, 0x42800000, v7
	v_mul_f32_e32 v6, 0x42800000, v6
	v_mul_f32_e32 v13, 0x42800000, v13
	v_mul_f32_e32 v12, 0x42800000, v12
	v_mul_f32_e32 v11, 0x42800000, v11
	v_mul_f32_e32 v10, 0x42800000, v10
	v_mul_f32_e32 v55, 0x42800000, v55
	v_mul_f32_e32 v53, 0x42800000, v53
	v_mul_f32_e32 v54, 0x42800000, v54
	v_med3_f32 v53, v53, s0, v236
	v_med3_f32 v54, v54, s0, v236
	s_waitcnt vmcnt(19)
	v_mul_f32_e32 v9, 0x42800000, v9
	v_mul_f32_e32 v48, 0x42800000, v48
	v_mul_f32_e32 v49, 0x42800000, v49
	v_med3_f32 v48, v48, s0, v236
	v_med3_f32 v49, v49, s0, v236
	v_mul_f32_e32 v50, 0x42800000, v50
	v_mul_f32_e32 v52, 0x42800000, v52
	v_med3_f32 v50, v50, s0, v236
	v_med3_f32 v52, v52, s0, v236
	v_mul_f32_e32 v44, 0x42800000, v44
	v_mul_f32_e32 v45, 0x42800000, v45
	v_mul_f32_e32 v17, 0x42800000, v17
	v_mul_f32_e32 v19, 0x42800000, v19
	v_med3_f32 v44, v44, s0, v236
	v_med3_f32 v45, v45, s0, v236
	v_med3_f32 v17, v17, s0, v236
	v_med3_f32 v19, v19, s0, v236
	s_waitcnt vmcnt(17)
	v_mul_f32_e32 v79, 0x42800000, v79
	s_waitcnt vmcnt(16)
	v_mul_f32_e32 v80, 0x42800000, v80
	v_mul_f32_e32 v76, 0x42800000, v76
	v_mul_f32_e32 v77, 0x42800000, v77
	v_mul_f32_e32 v73, 0x42800000, v73
	v_mul_f32_e32 v74, 0x42800000, v74
	v_mul_f32_e32 v70, 0x42800000, v70
	v_mul_f32_e32 v71, 0x42800000, v71
	v_mul_f32_e32 v67, 0x42800000, v67
	v_mul_f32_e32 v68, 0x42800000, v68
	v_mul_f32_e32 v64, 0x42800000, v64
	v_mul_f32_e32 v65, 0x42800000, v65
	v_mul_f32_e32 v61, 0x42800000, v61
	v_mul_f32_e32 v62, 0x42800000, v62
	v_mul_f32_e32 v58, 0x42800000, v58
	v_mul_f32_e32 v59, 0x42800000, v59
	v_mul_f32_e32 v46, 0x42800000, v46
	v_mul_f32_e32 v47, 0x42800000, v47
	v_mul_f32_e32 v42, 0x42800000, v42
	v_mul_f32_e32 v43, 0x42800000, v43
	v_med3_f32 v79, v79, s0, v236
	v_med3_f32 v80, v80, s0, v236
	v_med3_f32 v76, v76, s0, v236
	v_med3_f32 v77, v77, s0, v236
	v_med3_f32 v73, v73, s0, v236
	v_med3_f32 v74, v74, s0, v236
	v_med3_f32 v70, v70, s0, v236
	v_med3_f32 v71, v71, s0, v236
	v_med3_f32 v67, v67, s0, v236
	v_med3_f32 v68, v68, s0, v236
	v_med3_f32 v64, v64, s0, v236
	v_med3_f32 v65, v65, s0, v236
	v_med3_f32 v61, v61, s0, v236
	v_med3_f32 v62, v62, s0, v236
	v_med3_f32 v58, v58, s0, v236
	v_med3_f32 v59, v59, s0, v236
	s_waitcnt vmcnt(2)
	v_mul_f32_e32 v5, 0x42800000, v94
	s_waitcnt vmcnt(1)
	v_mul_f32_e32 v3, 0x42800000, v4
	v_mul_f32_e32 v4, 0x42800000, v93
	v_med3_f32 v4, v4, s0, v236
	v_med3_f32 v93, v5, s0, v236
	v_mov_b32_e32 v5, v51
	v_cvt_pk_fp8_f32 v5, v4, v93
	v_mul_f32_e32 v4, 0x42800000, v89
	v_med3_f32 v89, v4, s0, v236
	v_mul_f32_e32 v4, 0x42800000, v90
	v_med3_f32 v90, v4, s0, v236
	v_mov_b32_e32 v4, v51
	s_waitcnt vmcnt(0)
	v_mul_f32_e32 v2, 0x42800000, v2
	v_cvt_pk_fp8_f32 v4, v89, v90
	v_med3_f32 v3, v3, s0, v236
	v_med3_f32 v2, v2, s0, v236
	v_cvt_pk_fp8_f32 v5, v3, v2 op_sel:[0,0,1]
	v_mul_f32_e32 v2, 0x42800000, v91
	v_mul_f32_e32 v3, 0x42800000, v92
	v_med3_f32 v2, v2, s0, v236
	v_med3_f32 v3, v3, s0, v236
	v_cvt_pk_fp8_f32 v4, v2, v3 op_sel:[0,0,1]
	v_mul_f32_e32 v3, 0x42800000, v88
	v_mul_f32_e32 v2, 0x42800000, v87
	v_med3_f32 v87, v3, s0, v236
	v_mul_f32_e32 v3, 0x42800000, v85
	v_med3_f32 v85, v3, s0, v236
	v_mul_f32_e32 v3, 0x42800000, v86
	v_med3_f32 v86, v3, s0, v236
	v_mov_b32_e32 v3, v51
	v_cvt_pk_fp8_f32 v3, v85, v86
	v_med3_f32 v2, v2, s0, v236
	v_med3_f32 v46, v46, s0, v236
	v_med3_f32 v47, v47, s0, v236
	v_cvt_pk_fp8_f32 v3, v2, v87 op_sel:[0,0,1]
	v_mul_f32_e32 v2, 0x42800000, v83
	v_med3_f32 v83, v2, s0, v236
	v_mul_f32_e32 v2, 0x42800000, v84
	v_med3_f32 v84, v2, s0, v236
	v_mul_f32_e32 v2, 0x42800000, v81
	v_med3_f32 v81, v2, s0, v236
	v_mul_f32_e32 v2, 0x42800000, v82
	v_med3_f32 v82, v2, s0, v236
	v_mov_b32_e32 v2, v51
	v_cvt_pk_fp8_f32 v2, v81, v82
	v_med3_f32 v81, v9, s0, v236
	v_mul_f32_e32 v9, 0x42800000, v78
	v_med3_f32 v78, v9, s0, v236
	v_mov_b32_e32 v9, v51
	v_cvt_pk_fp8_f32 v9, v81, v78
	v_med3_f32 v78, v8, s0, v236
	v_mul_f32_e32 v8, 0x42800000, v75
	v_med3_f32 v75, v8, s0, v236
	v_mov_b32_e32 v8, v51
	v_cvt_pk_fp8_f32 v8, v78, v75
	v_med3_f32 v75, v7, s0, v236
	v_mul_f32_e32 v7, 0x42800000, v72
	v_med3_f32 v72, v7, s0, v236
	v_mov_b32_e32 v7, v51
	v_cvt_pk_fp8_f32 v7, v75, v72
	v_med3_f32 v72, v6, s0, v236
	v_mul_f32_e32 v6, 0x42800000, v69
	v_med3_f32 v69, v6, s0, v236
	v_mov_b32_e32 v6, v51
	v_cvt_pk_fp8_f32 v6, v72, v69
	v_med3_f32 v69, v13, s0, v236
	v_mul_f32_e32 v13, 0x42800000, v66
	v_med3_f32 v66, v13, s0, v236
	v_mov_b32_e32 v13, v51
	v_cvt_pk_fp8_f32 v13, v69, v66
	v_med3_f32 v66, v12, s0, v236
	v_mul_f32_e32 v12, 0x42800000, v63
	v_med3_f32 v63, v12, s0, v236
	v_mov_b32_e32 v12, v51
	v_cvt_pk_fp8_f32 v12, v66, v63
	v_med3_f32 v63, v11, s0, v236
	v_mul_f32_e32 v11, 0x42800000, v60
	v_med3_f32 v60, v11, s0, v236
	v_mov_b32_e32 v11, v51
	v_cvt_pk_fp8_f32 v11, v63, v60
	v_med3_f32 v60, v10, s0, v236
	v_mul_f32_e32 v10, 0x42800000, v57
	v_med3_f32 v57, v10, s0, v236
	v_mov_b32_e32 v10, v51
	v_cvt_pk_fp8_f32 v10, v60, v57
	v_med3_f32 v57, v55, s0, v236
	v_mul_f32_e32 v55, 0x42800000, v56
	v_med3_f32 v56, v55, s0, v236
	v_mov_b32_e32 v55, v51
	v_cvt_pk_fp8_f32 v55, v53, v54
	v_mov_b32_e32 v54, v51
	v_cvt_pk_fp8_f32 v54, v48, v49
	v_mov_b32_e32 v53, v51
	v_cvt_pk_fp8_f32 v53, v44, v45
	v_med3_f32 v42, v42, s0, v236
	v_cvt_pk_fp8_f32 v54, v50, v52 op_sel:[0,0,1]
	v_mov_b32_e32 v52, v51
	v_cvt_pk_fp8_f32 v52, v17, v19
	v_med3_f32 v43, v43, s0, v236
	v_ashrrev_i32_e32 v19, 31, v18
	v_readlane_b32 s0, v254, 3
	v_readlane_b32 s23, v254, 33
	v_cvt_pk_fp8_f32 v55, v57, v56 op_sel:[0,0,1]
	v_cvt_pk_fp8_f32 v53, v46, v47 op_sel:[0,0,1]
	v_cvt_pk_fp8_f32 v52, v42, v43 op_sel:[0,0,1]
	v_lshlrev_b64 v[18:19], 10, v[18:19]
	v_readlane_b32 s1, v254, 4
	v_cvt_pk_fp8_f32 v13, v67, v68 op_sel:[0,0,1]
	v_cvt_pk_fp8_f32 v12, v64, v65 op_sel:[0,0,1]
	v_cvt_pk_fp8_f32 v11, v61, v62 op_sel:[0,0,1]
	v_cvt_pk_fp8_f32 v10, v58, v59 op_sel:[0,0,1]
	v_lshl_add_u64 v[18:19], s[0:1], 0, v[18:19]
	s_mov_b32 s1, s23
	v_cvt_pk_fp8_f32 v9, v79, v80 op_sel:[0,0,1]
	v_cvt_pk_fp8_f32 v8, v76, v77 op_sel:[0,0,1]
	v_cvt_pk_fp8_f32 v7, v73, v74 op_sel:[0,0,1]
	v_cvt_pk_fp8_f32 v6, v70, v71 op_sel:[0,0,1]
	v_writelane_b32 v254, s0, 32
	v_cvt_pk_fp8_f32 v2, v83, v84 op_sel:[0,0,1]
	v_lshl_add_u64 v[18:19], v[18:19], 0, s[22:23]
	v_writelane_b32 v254, s1, 33
	global_store_dwordx4 v[18:19], v[52:55], off
	global_store_dwordx4 v[18:19], v[10:13], off offset:16
	global_store_dwordx4 v[18:19], v[6:9], off offset:32
	global_store_dwordx4 v[18:19], v[2:5], off offset:48
	s_branch .LBB0_1942

; __device__ __forceinline__ void transpose_item8(const float* W, int N, unsigned char* WT, int ldt, int item, int lane, int mode, int aux) {
;     const int nblk = (N + 63) >> 6, kb = item / nblk, nb = item - kb * nblk, k0 = 64 * kb, n0 = 64 * nb;
;     const int ncol = n0 + lane;
;     const float* wp = W + (size_t)k0 * N + ncol;
;     float v[64];
; #pragma unroll
;     for (int i = 0; i < 64; ++i) v[i] = wp[(size_t)i * N];
; __device__ __forceinline__ void convert_rest(const Args& a, LAS unsigned char* lds, int wave, int lane, int gw, int ngw, int l, int it0, int it1) {
;     ...
;     for (int it = it0 + gw; it < it1; it += ngw) {
;         int r = it;
;         if (r < WI_G) { const int g = r >> 8; transpose_item8(a.in[I_WGATE] + (size_t)(l * 4 + g) * 1024 * 1024, 1024, ws + WS_WG, 1024, r & 255, lane, 2, g); continue; } r -= WI_G;
;         if (r < WI_BR) { const int g = r >> 6; transpose_item(a.in[I_WBR] + (size_t)(l * 4 + g) * 256 * 1024, 1024, (bf16*)(ws + WS_WBR) + (size_t)g * 1024 * 256, 256, scr, r & 63, lane, 0, 0); continue; } r -= WI_BR;
;         if (r < WI_OUT) { transpose_item(a.in[I_WOUT] + (size_t)l * 1024 * 1024, 1024, (bf16*)(ws + WS_WOUT), 1024, scr, r, lane, 0, 0); continue; } r -= WI_OUT;
;         if (r < WI_FF) { const int e = r >> 8; transpose_item8(a.in[I_WFFG] + (size_t)(l * 16 + e) * 1024 * 1024, 1024, ws + WS_WGU + (size_t)e * 2048 * 1024, 1024, r & 255, lane, 3, 0); continue; } r -= WI_FF;
;         if (r < WI_FF) { const int e = r >> 8; transpose_item8(a.in[I_WFFU] + (size_t)(l * 16 + e) * 1024 * 1024, 1024, ws + WS_WGU + (size_t)e * 2048 * 1024, 1024, r & 255, lane, 4, 0); continue; } r -= WI_FF;
;         { const int e = r >> 8; transpose_item8(a.in[I_WFFD] + (size_t)(l * 16 + e) * 1024 * 1024, 1024, ws + WS_WDN + (size_t)e * 1024 * 1024, 1024, r & 255, lane, 0, 0); }
.LBB0_2014:
	s_cmpk_gt_i32 s6, 0x3ff
	s_mov_b64 s[0:1], -1
	s_cbranch_scc0 .LBB0_2078
	s_cmpk_gt_u32 s6, 0x4ff
	s_cbranch_scc0 .LBB0_2075
	s_cmpk_gt_u32 s6, 0x5ff
	s_cbranch_scc0 .LBB0_2026
	s_cmpk_gt_u32 s6, 0x15ff
	s_cbranch_scc0 .LBB0_2023
	s_cmpk_gt_u32 s6, 0x25ff
	s_cbranch_scc0 .LBB0_2020
	s_add_i32 s0, s6, 0xffffda00
	s_lshr_b32 s0, s0, 8
	v_readlane_b32 s22, v254, 32
	v_readlane_b32 s23, v254, 33
	s_add_i32 s22, s0, s7
	v_readlane_b32 s56, v252, 41
	s_lshl_b64 s[2:3], s[22:23], 22
	v_readlane_b32 s64, v252, 49
	v_readlane_b32 s65, v252, 50
	s_add_u32 s2, s64, s2
	s_mov_b32 s1, s23
	s_addc_u32 s3, s65, s3
	s_lshl_b64 s[0:1], s[0:1], 20
	v_readlane_b32 s16, v253, 59
	s_add_u32 s0, s16, s0
	v_readlane_b32 s16, v253, 60
	s_addc_u32 s1, s16, s1
	s_lshl_b32 s16, s6, 2
	s_and_b32 s22, s16, 0x3c0
	s_lshl_b32 s16, s6, 6
	s_and_b32 s16, s16, 0x3c0
	v_or_b32_e32 v17, s16, v20
	s_lshl_b32 s16, s22, 12
	s_add_u32 s2, s2, s16
	s_addc_u32 s3, s3, 0
	v_lshlrev_b32_e32 v4, 2, v17
	v_mov_b32_e32 v5, v51
	v_lshl_add_u64 v[2:3], s[2:3], 0, v[4:5]
	global_load_dword v18, v4, s[2:3] nt
	s_movk_i32 s2, 0x2000
	v_readlane_b32 s70, v252, 55
	v_add_co_u32_e32 v4, vcc, s2, v2
	s_movk_i32 s70, 0x4000
	s_nop 0
	v_addc_co_u32_e32 v5, vcc, 0, v3, vcc
	global_load_dword v19, v[4:5], off offset:-4096 nt
	global_load_dword v42, v[4:5], off nt
	v_add_co_u32_e32 v4, vcc, s70, v2
	s_movk_i32 s2, 0x6000
	s_nop 0
	v_addc_co_u32_e32 v5, vcc, 0, v3, vcc
	global_load_dword v43, v[4:5], off offset:-4096 nt
	global_load_dword v44, v[4:5], off nt
	v_add_co_u32_e32 v4, vcc, s2, v2
	s_mov_b32 s2, 0x8000
	s_nop 0
	v_addc_co_u32_e32 v5, vcc, 0, v3, vcc
	global_load_dword v45, v[4:5], off offset:-4096 nt
	global_load_dword v46, v[4:5], off nt
	v_add_co_u32_e32 v4, vcc, s2, v2
	s_mov_b32 s2, 0xa000
	s_nop 0
	v_addc_co_u32_e32 v5, vcc, 0, v3, vcc
	global_load_dword v47, v[4:5], off offset:-4096 nt
	global_load_dword v48, v[4:5], off nt
	v_add_co_u32_e32 v4, vcc, s2, v2
	s_mov_b32 s2, 0xc000
	s_nop 0
	v_addc_co_u32_e32 v5, vcc, 0, v3, vcc
	global_load_dword v49, v[4:5], off offset:-4096 nt
	global_load_dword v50, v[4:5], off nt
	v_add_co_u32_e32 v4, vcc, s2, v2
	s_mov_b32 s2, 0xe000
	s_nop 0
	v_addc_co_u32_e32 v5, vcc, 0, v3, vcc
	global_load_dword v52, v[4:5], off offset:-4096 nt
	global_load_dword v53, v[4:5], off nt
	v_add_co_u32_e32 v4, vcc, s2, v2
	s_mov_b32 s2, 0x10000
	s_nop 0
	v_addc_co_u32_e32 v5, vcc, 0, v3, vcc
	global_load_dword v54, v[4:5], off offset:-4096 nt
	global_load_dword v55, v[4:5], off nt
	v_add_co_u32_e32 v4, vcc, s2, v2
	s_mov_b32 s2, 0x12000
	s_nop 0
	v_addc_co_u32_e32 v5, vcc, 0, v3, vcc
	global_load_dword v56, v[4:5], off offset:-4096 nt
	global_load_dword v10, v[4:5], off nt
	v_add_co_u32_e32 v4, vcc, s2, v2
	s_mov_b32 s2, 0x14000
	s_nop 0
	v_addc_co_u32_e32 v5, vcc, 0, v3, vcc
	global_load_dword v57, v[4:5], off offset:-4096 nt
	global_load_dword v58, v[4:5], off nt
	v_add_co_u32_e32 v4, vcc, s2, v2
	s_mov_b32 s2, 0x16000
	s_nop 0
	v_addc_co_u32_e32 v5, vcc, 0, v3, vcc
	global_load_dword v59, v[4:5], off offset:-4096 nt
	global_load_dword v11, v[4:5], off nt
	v_add_co_u32_e32 v4, vcc, s2, v2
	s_mov_b32 s2, 0x18000
	s_nop 0
	v_addc_co_u32_e32 v5, vcc, 0, v3, vcc
	global_load_dword v60, v[4:5], off offset:-4096 nt
	global_load_dword v61, v[4:5], off nt
	v_add_co_u32_e32 v4, vcc, s2, v2
	s_mov_b32 s2, 0x1a000
	s_nop 0
	v_addc_co_u32_e32 v5, vcc, 0, v3, vcc
	global_load_dword v62, v[4:5], off offset:-4096 nt
	global_load_dword v12, v[4:5], off nt
	v_add_co_u32_e32 v4, vcc, s2, v2
	s_mov_b32 s2, 0x1c000
	s_nop 0
	v_addc_co_u32_e32 v5, vcc, 0, v3, vcc
	global_load_dword v63, v[4:5], off offset:-4096 nt
	global_load_dword v64, v[4:5], off nt
	v_add_co_u32_e32 v4, vcc, s2, v2
	s_mov_b32 s2, 0x1e000
	s_nop 0
	v_addc_co_u32_e32 v5, vcc, 0, v3, vcc
	global_load_dword v65, v[4:5], off offset:-4096 nt
	global_load_dword v13, v[4:5], off nt
	v_add_co_u32_e32 v4, vcc, s2, v2
	s_mov_b32 s2, 0x20000
	s_nop 0
	v_addc_co_u32_e32 v5, vcc, 0, v3, vcc
	global_load_dword v66, v[4:5], off offset:-4096 nt
	global_load_dword v67, v[4:5], off nt
	v_add_co_u32_e32 v4, vcc, s2, v2
	s_mov_b32 s2, 0x22000
	s_nop 0
	v_addc_co_u32_e32 v5, vcc, 0, v3, vcc
	global_load_dword v68, v[4:5], off offset:-4096 nt
	global_load_dword v6, v[4:5], off nt
	v_add_co_u32_e32 v4, vcc, s2, v2
	s_mov_b32 s2, 0x24000
	s_nop 0
	v_addc_co_u32_e32 v5, vcc, 0, v3, vcc
	global_load_dword v69, v[4:5], off offset:-4096 nt
	global_load_dword v70, v[4:5], off nt
	v_add_co_u32_e32 v4, vcc, s2, v2
	s_mov_b32 s2, 0x26000
	s_nop 0
	v_addc_co_u32_e32 v5, vcc, 0, v3, vcc
	global_load_dword v71, v[4:5], off offset:-4096 nt
	global_load_dword v7, v[4:5], off nt
	v_add_co_u32_e32 v4, vcc, s2, v2
	s_mov_b32 s2, 0x28000
	s_nop 0
	v_addc_co_u32_e32 v5, vcc, 0, v3, vcc
	global_load_dword v72, v[4:5], off offset:-4096 nt
	global_load_dword v73, v[4:5], off nt
	v_add_co_u32_e32 v4, vcc, s2, v2
	s_mov_b32 s2, 0x2a000
	s_nop 0
	v_addc_co_u32_e32 v5, vcc, 0, v3, vcc
	global_load_dword v74, v[4:5], off offset:-4096 nt
	global_load_dword v8, v[4:5], off nt
	v_add_co_u32_e32 v4, vcc, s2, v2
	s_mov_b32 s2, 0x2c000
	s_nop 0
	v_addc_co_u32_e32 v5, vcc, 0, v3, vcc
	global_load_dword v75, v[4:5], off offset:-4096 nt
	global_load_dword v76, v[4:5], off nt
	v_add_co_u32_e32 v4, vcc, s2, v2
	s_mov_b32 s2, 0x2e000
	s_nop 0
	v_addc_co_u32_e32 v5, vcc, 0, v3, vcc
	global_load_dword v77, v[4:5], off offset:-4096 nt
	global_load_dword v9, v[4:5], off nt
	v_add_co_u32_e32 v4, vcc, s2, v2
	s_mov_b32 s2, 0x30000
	s_nop 0
	v_addc_co_u32_e32 v5, vcc, 0, v3, vcc
	global_load_dword v78, v[4:5], off offset:-4096 nt
	global_load_dword v79, v[4:5], off nt
; __device__ __forceinline__ unsigned pk4_fp8(float a, float b, float c, float d) { int w = 0; w = __builtin_amdgcn_cvt_pk_fp8_f32(a, b, w, false); w = __builtin_amdgcn_cvt_pk_fp8_f32(c, d, w, true); return (unsigned)w; }
; __device__ __forceinline__ void transpose_item8(const float* W, int N, unsigned char* WT, int ldt, int item, int lane, int mode, int aux) {
;     ...
;     for (int i = 0; i < 64; ++i) v[i] = wp[(size_t)i * N];
;     unsigned o[16];
; #pragma unroll
;     for (int q = 0; q < 16; ++q) o[q] = pk4_fp8(fminf(fmaxf(v[4 * q] * 64.f, -448.f), 448.f), fminf(fmaxf(v[4 * q + 1] * 64.f, -448.f), 448.f), fminf(fmaxf(v[4 * q + 2] * 64.f, -448.f), 448.f), fminf(fmaxf(v[4 * q + 3] * 64.f, -448.f), 448.f));
	v_add_co_u32_e32 v4, vcc, s2, v2
	s_mov_b32 s2, 0x32000
	s_nop 0
	v_addc_co_u32_e32 v5, vcc, 0, v3, vcc
	global_load_dword v80, v[4:5], off offset:-4096 nt
	global_load_dword v81, v[4:5], off nt
	v_add_co_u32_e32 v4, vcc, s2, v2
	s_mov_b32 s2, 0x34000
	s_nop 0
	v_addc_co_u32_e32 v5, vcc, 0, v3, vcc
	global_load_dword v82, v[4:5], off offset:-4096 nt
	global_load_dword v83, v[4:5], off nt
	v_add_co_u32_e32 v4, vcc, s2, v2
	s_mov_b32 s2, 0x36000
	s_nop 0
	v_addc_co_u32_e32 v5, vcc, 0, v3, vcc
	global_load_dword v84, v[4:5], off offset:-4096 nt
	global_load_dword v85, v[4:5], off nt
	v_add_co_u32_e32 v4, vcc, s2, v2
	s_mov_b32 s2, 0x38000
	s_nop 0
	v_addc_co_u32_e32 v5, vcc, 0, v3, vcc
	global_load_dword v86, v[4:5], off offset:-4096 nt
	global_load_dword v87, v[4:5], off nt
	v_add_co_u32_e32 v4, vcc, s2, v2
	s_mov_b32 s2, 0x3a000
	s_nop 0
	v_addc_co_u32_e32 v5, vcc, 0, v3, vcc
	global_load_dword v88, v[4:5], off offset:-4096 nt
	global_load_dword v89, v[4:5], off nt
	v_add_co_u32_e32 v4, vcc, s2, v2
	s_mov_b32 s2, 0x3c000
	s_nop 0
	v_addc_co_u32_e32 v5, vcc, 0, v3, vcc
	global_load_dword v90, v[4:5], off offset:-4096 nt
	global_load_dword v91, v[4:5], off nt
	v_add_co_u32_e32 v4, vcc, s2, v2
	s_mov_b32 s2, 0x3e000
	s_nop 0
	v_addc_co_u32_e32 v5, vcc, 0, v3, vcc
	global_load_dword v92, v[4:5], off offset:-4096 nt
	global_load_dword v93, v[4:5], off nt
	v_add_co_u32_e32 v4, vcc, s2, v2
	s_mov_b32 s2, 0x3f000
	s_nop 0
	v_addc_co_u32_e32 v5, vcc, 0, v3, vcc
	global_load_dword v94, v[4:5], off offset:-4096 nt
	s_nop 0
	global_load_dword v4, v[4:5], off nt
	v_add_co_u32_e32 v2, vcc, s2, v2
	s_mov_b32 s2, 0xc3e00000
	s_nop 0
	v_addc_co_u32_e32 v3, vcc, 0, v3, vcc
	global_load_dword v2, v[2:3], off nt
	s_waitcnt vmcnt(27)
	v_mul_f32_e32 v7, 0x42800000, v7
	v_mul_f32_e32 v6, 0x42800000, v6
	v_mul_f32_e32 v13, 0x42800000, v13
	v_mul_f32_e32 v12, 0x42800000, v12
	v_mul_f32_e32 v11, 0x42800000, v11
	v_mul_f32_e32 v10, 0x42800000, v10
	v_mul_f32_e32 v55, 0x42800000, v55
	s_waitcnt vmcnt(23)
	v_mul_f32_e32 v8, 0x42800000, v8
	v_mul_f32_e32 v53, 0x42800000, v53
	v_mul_f32_e32 v54, 0x42800000, v54
	v_med3_f32 v53, v53, s2, v236
	v_med3_f32 v54, v54, s2, v236
	v_mul_f32_e32 v48, 0x42800000, v48
	v_mul_f32_e32 v49, 0x42800000, v49
	v_med3_f32 v48, v48, s2, v236
	v_med3_f32 v49, v49, s2, v236
	v_mul_f32_e32 v50, 0x42800000, v50
	v_mul_f32_e32 v52, 0x42800000, v52
	v_med3_f32 v50, v50, s2, v236
	s_waitcnt vmcnt(19)
	v_mul_f32_e32 v9, 0x42800000, v9
	v_med3_f32 v52, v52, s2, v236
	v_mul_f32_e32 v44, 0x42800000, v44
	v_mul_f32_e32 v45, 0x42800000, v45
	v_mul_f32_e32 v18, 0x42800000, v18
	v_mul_f32_e32 v19, 0x42800000, v19
	v_med3_f32 v44, v44, s2, v236
	v_med3_f32 v45, v45, s2, v236
	v_med3_f32 v18, v18, s2, v236
	v_med3_f32 v19, v19, s2, v236
	v_mul_f32_e32 v46, 0x42800000, v46
	v_mul_f32_e32 v47, 0x42800000, v47
	v_mul_f32_e32 v42, 0x42800000, v42
	v_mul_f32_e32 v43, 0x42800000, v43
	v_mul_f32_e32 v67, 0x42800000, v67
	v_mul_f32_e32 v68, 0x42800000, v68
	v_mul_f32_e32 v64, 0x42800000, v64
	v_mul_f32_e32 v65, 0x42800000, v65
	v_mul_f32_e32 v61, 0x42800000, v61
	v_mul_f32_e32 v62, 0x42800000, v62
	v_mul_f32_e32 v58, 0x42800000, v58
	v_mul_f32_e32 v59, 0x42800000, v59
	v_med3_f32 v46, v46, s2, v236
	v_med3_f32 v47, v47, s2, v236
	v_med3_f32 v42, v42, s2, v236
	v_med3_f32 v43, v43, s2, v236
	s_waitcnt vmcnt(17)
	v_mul_f32_e32 v79, 0x42800000, v79
	s_waitcnt vmcnt(16)
	v_mul_f32_e32 v80, 0x42800000, v80
	v_mul_f32_e32 v76, 0x42800000, v76
	v_mul_f32_e32 v77, 0x42800000, v77
	v_mul_f32_e32 v73, 0x42800000, v73
	v_mul_f32_e32 v74, 0x42800000, v74
	v_mul_f32_e32 v70, 0x42800000, v70
	v_mul_f32_e32 v71, 0x42800000, v71
	v_med3_f32 v67, v67, s2, v236
	v_med3_f32 v68, v68, s2, v236
	v_med3_f32 v64, v64, s2, v236
	v_med3_f32 v65, v65, s2, v236
	v_med3_f32 v61, v61, s2, v236
	v_med3_f32 v62, v62, s2, v236
	v_med3_f32 v58, v58, s2, v236
	v_med3_f32 v59, v59, s2, v236
	v_med3_f32 v79, v79, s2, v236
	v_med3_f32 v80, v80, s2, v236
	v_med3_f32 v76, v76, s2, v236
	v_med3_f32 v77, v77, s2, v236
	v_med3_f32 v73, v73, s2, v236
	v_med3_f32 v74, v74, s2, v236
	v_med3_f32 v70, v70, s2, v236
	v_med3_f32 v71, v71, s2, v236
	v_readlane_b32 s58, v252, 43
	v_readlane_b32 s59, v252, 44
	v_readlane_b32 s60, v252, 45
	s_waitcnt vmcnt(2)
	v_mul_f32_e32 v5, 0x42800000, v94
	s_waitcnt vmcnt(1)
	v_mul_f32_e32 v3, 0x42800000, v4
	v_mul_f32_e32 v4, 0x42800000, v93
	v_med3_f32 v4, v4, s2, v236
	v_med3_f32 v93, v5, s2, v236
	v_mov_b32_e32 v5, v51
	v_cvt_pk_fp8_f32 v5, v4, v93
	v_mul_f32_e32 v4, 0x42800000, v89
	v_med3_f32 v89, v4, s2, v236
	v_mul_f32_e32 v4, 0x42800000, v90
	v_med3_f32 v90, v4, s2, v236
	v_mov_b32_e32 v4, v51
	s_waitcnt vmcnt(0)
; __device__ __forceinline__ unsigned pk4_fp8(float a, float b, float c, float d) { int w = 0; w = __builtin_amdgcn_cvt_pk_fp8_f32(a, b, w, false); w = __builtin_amdgcn_cvt_pk_fp8_f32(c, d, w, true); return (unsigned)w; }
; __device__ __forceinline__ void transpose_item8(const float* W, int N, unsigned char* WT, int ldt, int item, int lane, int mode, int aux) {
;     ...
;     for (int q = 0; q < 16; ++q) o[q] = pk4_fp8(fminf(fmaxf(v[4 * q] * 64.f, -448.f), 448.f), fminf(fmaxf(v[4 * q + 1] * 64.f, -448.f), 448.f), fminf(fmaxf(v[4 * q + 2] * 64.f, -448.f), 448.f), fminf(fmaxf(v[4 * q + 3] * 64.f, -448.f), 448.f));
;     v4u* dst = (v4u*)(WT + (size_t)rowmap(mode, aux, ncol) * ldt + k0);
; #pragma unroll
;     for (int q = 0; q < 4; ++q) dst[q] = (v4u){o[4 * q], o[4 * q + 1], o[4 * q + 2], o[4 * q + 3]};
; __device__ __forceinline__ void convert_rest(const Args& a, LAS unsigned char* lds, int wave, int lane, int gw, int ngw, int l, int it0, int it1) {
;     ...
;         if (r < WI_FF) { const int e = r >> 8; transpose_item8(a.in[I_WFFU] + (size_t)(l * 16 + e) * 1024 * 1024, 1024, ws + WS_WGU + (size_t)e * 2048 * 1024, 1024, r & 255, lane, 4, 0); continue; } r -= WI_FF;
	v_mul_f32_e32 v2, 0x42800000, v2
	v_cvt_pk_fp8_f32 v4, v89, v90
	v_med3_f32 v3, v3, s2, v236
	v_med3_f32 v2, v2, s2, v236
	v_cvt_pk_fp8_f32 v5, v3, v2 op_sel:[0,0,1]
	v_mul_f32_e32 v2, 0x42800000, v91
	v_mul_f32_e32 v3, 0x42800000, v92
	v_med3_f32 v2, v2, s2, v236
	v_med3_f32 v3, v3, s2, v236
	v_cvt_pk_fp8_f32 v4, v2, v3 op_sel:[0,0,1]
	v_mul_f32_e32 v3, 0x42800000, v88
	v_mul_f32_e32 v2, 0x42800000, v87
	v_med3_f32 v87, v3, s2, v236
	v_mul_f32_e32 v3, 0x42800000, v85
	v_med3_f32 v85, v3, s2, v236
	v_mul_f32_e32 v3, 0x42800000, v86
	v_med3_f32 v86, v3, s2, v236
	v_mov_b32_e32 v3, v51
	v_cvt_pk_fp8_f32 v3, v85, v86
	v_med3_f32 v2, v2, s2, v236
	v_readlane_b32 s61, v252, 46
	v_readlane_b32 s62, v252, 47
	v_cvt_pk_fp8_f32 v3, v2, v87 op_sel:[0,0,1]
	v_mul_f32_e32 v2, 0x42800000, v83
	v_med3_f32 v83, v2, s2, v236
	v_mul_f32_e32 v2, 0x42800000, v84
	v_med3_f32 v84, v2, s2, v236
	v_mul_f32_e32 v2, 0x42800000, v81
	v_med3_f32 v81, v2, s2, v236
	v_mul_f32_e32 v2, 0x42800000, v82
	v_med3_f32 v82, v2, s2, v236
	v_mov_b32_e32 v2, v51
	v_cvt_pk_fp8_f32 v2, v81, v82
	v_med3_f32 v81, v9, s2, v236
	v_mul_f32_e32 v9, 0x42800000, v78
	v_med3_f32 v78, v9, s2, v236
	v_mov_b32_e32 v9, v51
	v_cvt_pk_fp8_f32 v9, v81, v78
	v_med3_f32 v78, v8, s2, v236
	v_mul_f32_e32 v8, 0x42800000, v75
	v_med3_f32 v75, v8, s2, v236
	v_mov_b32_e32 v8, v51
	v_cvt_pk_fp8_f32 v8, v78, v75
	v_med3_f32 v75, v7, s2, v236
	v_mul_f32_e32 v7, 0x42800000, v72
	v_med3_f32 v72, v7, s2, v236
	v_mov_b32_e32 v7, v51
	v_cvt_pk_fp8_f32 v7, v75, v72
	v_med3_f32 v72, v6, s2, v236
	v_mul_f32_e32 v6, 0x42800000, v69
	v_med3_f32 v69, v6, s2, v236
	v_mov_b32_e32 v6, v51
	v_cvt_pk_fp8_f32 v6, v72, v69
	v_med3_f32 v69, v13, s2, v236
	v_mul_f32_e32 v13, 0x42800000, v66
	v_med3_f32 v66, v13, s2, v236
	v_mov_b32_e32 v13, v51
	v_cvt_pk_fp8_f32 v13, v69, v66
	v_med3_f32 v66, v12, s2, v236
	v_mul_f32_e32 v12, 0x42800000, v63
	v_med3_f32 v63, v12, s2, v236
	v_mov_b32_e32 v12, v51
	v_cvt_pk_fp8_f32 v12, v66, v63
	v_med3_f32 v63, v11, s2, v236
	v_mul_f32_e32 v11, 0x42800000, v60
	v_med3_f32 v60, v11, s2, v236
	v_mov_b32_e32 v11, v51
	v_cvt_pk_fp8_f32 v11, v63, v60
	v_med3_f32 v60, v10, s2, v236
	v_mul_f32_e32 v10, 0x42800000, v57
	v_med3_f32 v57, v10, s2, v236
	v_mov_b32_e32 v10, v51
	v_cvt_pk_fp8_f32 v10, v60, v57
	v_med3_f32 v57, v55, s2, v236
	v_mul_f32_e32 v55, 0x42800000, v56
	v_med3_f32 v56, v55, s2, v236
	v_mov_b32_e32 v55, v51
	v_cvt_pk_fp8_f32 v55, v53, v54
	v_mov_b32_e32 v54, v51
	v_cvt_pk_fp8_f32 v54, v48, v49
	v_mov_b32_e32 v53, v51
	v_cvt_pk_fp8_f32 v53, v44, v45
	v_cvt_pk_fp8_f32 v55, v57, v56 op_sel:[0,0,1]
	v_cvt_pk_fp8_f32 v54, v50, v52 op_sel:[0,0,1]
	v_mov_b32_e32 v52, v51
	v_cvt_pk_fp8_f32 v52, v18, v19
	v_cvt_pk_fp8_f32 v53, v46, v47 op_sel:[0,0,1]
	v_cvt_pk_fp8_f32 v13, v67, v68 op_sel:[0,0,1]
	v_cvt_pk_fp8_f32 v12, v64, v65 op_sel:[0,0,1]
	v_cvt_pk_fp8_f32 v52, v42, v43 op_sel:[0,0,1]
	v_cvt_pk_fp8_f32 v11, v61, v62 op_sel:[0,0,1]
	v_cvt_pk_fp8_f32 v10, v58, v59 op_sel:[0,0,1]
	v_lshlrev_b32_e32 v18, 10, v17
	v_mov_b32_e32 v19, v51
	v_cvt_pk_fp8_f32 v9, v79, v80 op_sel:[0,0,1]
	v_cvt_pk_fp8_f32 v8, v76, v77 op_sel:[0,0,1]
	v_cvt_pk_fp8_f32 v7, v73, v74 op_sel:[0,0,1]
	v_cvt_pk_fp8_f32 v6, v70, v71 op_sel:[0,0,1]
	v_lshl_add_u64 v[18:19], s[0:1], 0, v[18:19]
	s_mov_b32 s1, s23
	v_readlane_b32 s63, v252, 48
	v_readlane_b32 s68, v252, 53
	v_readlane_b32 s69, v252, 54
	v_readlane_b32 s71, v252, 56
	s_mov_b32 s58, 0x3f6c835e
	v_readlane_b32 s60, v255, 2
	v_cvt_pk_fp8_f32 v2, v83, v84 op_sel:[0,0,1]
	v_writelane_b32 v254, s0, 32
	v_lshl_add_u64 v[18:19], v[18:19], 0, s[22:23]
	v_readlane_b32 s57, v252, 42
	v_readlane_b32 s66, v252, 51
	v_readlane_b32 s67, v252, 52
	s_mov_b32 s63, 0xbf6c835e
	v_readlane_b32 s62, v255, 4
	s_movk_i32 s68, 0x2200
	s_movk_i32 s71, 0x1ff
	s_mov_b32 s69, 0x7f800000
	s_mov_b32 s59, 0xbec3ef15
	v_readlane_b32 s61, v255, 3
	s_movk_i32 s64, 0x440
	v_writelane_b32 v254, s1, 33
	global_store_dwordx4 v[18:19], v[52:55], off
	global_store_dwordx4 v[18:19], v[10:13], off offset:16
	global_store_dwordx4 v[18:19], v[6:9], off offset:32
	global_store_dwordx4 v[18:19], v[2:5], off offset:48
	s_mov_b64 s[0:1], 0
.LBB0_2020:
	s_andn2_b64 vcc, exec, s[0:1]
	s_cbranch_vccnz .LBB0_2022
	s_add_i32 s0, s6, 0xffffea00
	s_lshr_b32 s0, s0, 8
	v_readlane_b32 s22, v254, 32
	v_readlane_b32 s23, v254, 33
	s_add_i32 s22, s0, s7
	v_readlane_b32 s56, v252, 41
	s_lshl_b64 s[2:3], s[22:23], 22
	v_readlane_b32 s62, v252, 47
	v_readlane_b32 s63, v252, 48
	s_add_u32 s16, s62, s2
	s_mov_b32 s1, s23
	s_addc_u32 s3, s63, s3
	s_lshl_b64 s[0:1], s[0:1], 21
	v_readlane_b32 s2, v253, 61
	s_add_u32 s0, s2, s0
	v_readlane_b32 s2, v253, 62
	s_addc_u32 s1, s2, s1
	s_and_b32 s22, s11, 0x3c0
	s_add_i32 s2, s4, 0xa2000
	s_and_b32 s2, s2, 0x3c0
	s_lshl_b32 s17, s22, 12
	v_or_b32_e32 v2, s2, v20
	s_add_u32 s16, s16, s17
	s_addc_u32 s17, s3, 0
	v_lshlrev_b32_e32 v4, 2, v2
	v_mov_b32_e32 v5, v51
	v_lshl_add_u64 v[2:3], s[16:17], 0, v[4:5]
	s_movk_i32 s3, 0x2000
	v_readlane_b32 s70, v252, 55
	global_load_dword v17, v4, s[16:17] nt
	v_add_co_u32_e32 v4, vcc, s3, v2
	s_movk_i32 s70, 0x4000
	s_nop 0
	v_addc_co_u32_e32 v5, vcc, 0, v3, vcc
	global_load_dword v18, v[4:5], off offset:-4096 nt
	global_load_dword v19, v[4:5], off nt
	v_add_co_u32_e32 v4, vcc, s70, v2
	s_movk_i32 s3, 0x6000
	s_nop 0
	v_addc_co_u32_e32 v5, vcc, 0, v3, vcc
	global_load_dword v42, v[4:5], off offset:-4096 nt
	global_load_dword v43, v[4:5], off nt
	v_add_co_u32_e32 v4, vcc, s3, v2
	s_mov_b32 s3, 0x8000
	s_nop 0
	v_addc_co_u32_e32 v5, vcc, 0, v3, vcc
	global_load_dword v44, v[4:5], off offset:-4096 nt
	global_load_dword v45, v[4:5], off nt
; __device__ __forceinline__ void transpose_item8(const float* W, int N, unsigned char* WT, int ldt, int item, int lane, int mode, int aux) {
;     ...
;     for (int i = 0; i < 64; ++i) v[i] = wp[(size_t)i * N];
	v_add_co_u32_e32 v4, vcc, s3, v2
	s_mov_b32 s3, 0xa000
	s_nop 0
	v_addc_co_u32_e32 v5, vcc, 0, v3, vcc
	global_load_dword v46, v[4:5], off offset:-4096 nt
	global_load_dword v47, v[4:5], off nt
	v_add_co_u32_e32 v4, vcc, s3, v2
	s_mov_b32 s3, 0xc000
	s_nop 0
	v_addc_co_u32_e32 v5, vcc, 0, v3, vcc
	global_load_dword v48, v[4:5], off offset:-4096 nt
	global_load_dword v49, v[4:5], off nt
	v_add_co_u32_e32 v4, vcc, s3, v2
	s_mov_b32 s3, 0xe000
	s_nop 0
	v_addc_co_u32_e32 v5, vcc, 0, v3, vcc
	global_load_dword v50, v[4:5], off offset:-4096 nt
	global_load_dword v52, v[4:5], off nt
	v_add_co_u32_e32 v4, vcc, s3, v2
	s_mov_b32 s3, 0x10000
	s_nop 0
	v_addc_co_u32_e32 v5, vcc, 0, v3, vcc
	global_load_dword v53, v[4:5], off offset:-4096 nt
	global_load_dword v54, v[4:5], off nt
	v_add_co_u32_e32 v4, vcc, s3, v2
	s_mov_b32 s3, 0x12000
	s_nop 0
	v_addc_co_u32_e32 v5, vcc, 0, v3, vcc
	global_load_dword v55, v[4:5], off offset:-4096 nt
	global_load_dword v10, v[4:5], off nt
	v_add_co_u32_e32 v4, vcc, s3, v2
	s_mov_b32 s3, 0x14000
	s_nop 0
	v_addc_co_u32_e32 v5, vcc, 0, v3, vcc
	global_load_dword v56, v[4:5], off offset:-4096 nt
	global_load_dword v57, v[4:5], off nt
	v_add_co_u32_e32 v4, vcc, s3, v2
	s_mov_b32 s3, 0x16000
	s_nop 0
	v_addc_co_u32_e32 v5, vcc, 0, v3, vcc
	global_load_dword v58, v[4:5], off offset:-4096 nt
	global_load_dword v11, v[4:5], off nt
	v_add_co_u32_e32 v4, vcc, s3, v2
	s_mov_b32 s3, 0x18000
	s_nop 0
	v_addc_co_u32_e32 v5, vcc, 0, v3, vcc
	global_load_dword v59, v[4:5], off offset:-4096 nt
	global_load_dword v60, v[4:5], off nt
	v_add_co_u32_e32 v4, vcc, s3, v2
	s_mov_b32 s3, 0x1a000
	s_nop 0
	v_addc_co_u32_e32 v5, vcc, 0, v3, vcc
	global_load_dword v61, v[4:5], off offset:-4096 nt
	global_load_dword v12, v[4:5], off nt
	v_add_co_u32_e32 v4, vcc, s3, v2
	s_mov_b32 s3, 0x1c000
	s_nop 0
	v_addc_co_u32_e32 v5, vcc, 0, v3, vcc
	global_load_dword v62, v[4:5], off offset:-4096 nt
	global_load_dword v63, v[4:5], off nt
	v_add_co_u32_e32 v4, vcc, s3, v2
	s_mov_b32 s3, 0x1e000
	s_nop 0
	v_addc_co_u32_e32 v5, vcc, 0, v3, vcc
	global_load_dword v64, v[4:5], off offset:-4096 nt
	global_load_dword v13, v[4:5], off nt
	v_add_co_u32_e32 v4, vcc, s3, v2
	s_mov_b32 s3, 0x20000
	s_nop 0
	v_addc_co_u32_e32 v5, vcc, 0, v3, vcc
	global_load_dword v65, v[4:5], off offset:-4096 nt
	global_load_dword v66, v[4:5], off nt
	v_add_co_u32_e32 v4, vcc, s3, v2
	s_mov_b32 s3, 0x22000
	s_nop 0
	v_addc_co_u32_e32 v5, vcc, 0, v3, vcc
	global_load_dword v67, v[4:5], off offset:-4096 nt
	global_load_dword v6, v[4:5], off nt
	v_add_co_u32_e32 v4, vcc, s3, v2
	s_mov_b32 s3, 0x24000
	s_nop 0
	v_addc_co_u32_e32 v5, vcc, 0, v3, vcc
	global_load_dword v68, v[4:5], off offset:-4096 nt
	global_load_dword v69, v[4:5], off nt
	v_add_co_u32_e32 v4, vcc, s3, v2
	s_mov_b32 s3, 0x26000
	s_nop 0
	v_addc_co_u32_e32 v5, vcc, 0, v3, vcc
	global_load_dword v70, v[4:5], off offset:-4096 nt
	global_load_dword v7, v[4:5], off nt
	v_add_co_u32_e32 v4, vcc, s3, v2
	s_mov_b32 s3, 0x28000
	s_nop 0
	v_addc_co_u32_e32 v5, vcc, 0, v3, vcc
	global_load_dword v71, v[4:5], off offset:-4096 nt
	global_load_dword v72, v[4:5], off nt
	v_add_co_u32_e32 v4, vcc, s3, v2
	s_mov_b32 s3, 0x2a000
	s_nop 0
	v_addc_co_u32_e32 v5, vcc, 0, v3, vcc
	global_load_dword v73, v[4:5], off offset:-4096 nt
	global_load_dword v8, v[4:5], off nt
	v_add_co_u32_e32 v4, vcc, s3, v2
	s_mov_b32 s3, 0x2c000
	s_nop 0
	v_addc_co_u32_e32 v5, vcc, 0, v3, vcc
	global_load_dword v74, v[4:5], off offset:-4096 nt
	global_load_dword v75, v[4:5], off nt
	v_add_co_u32_e32 v4, vcc, s3, v2
	s_mov_b32 s3, 0x2e000
	s_nop 0
	v_addc_co_u32_e32 v5, vcc, 0, v3, vcc
	global_load_dword v76, v[4:5], off offset:-4096 nt
	global_load_dword v9, v[4:5], off nt
	v_add_co_u32_e32 v4, vcc, s3, v2
	s_mov_b32 s3, 0x30000
	s_nop 0
	v_addc_co_u32_e32 v5, vcc, 0, v3, vcc
	global_load_dword v77, v[4:5], off offset:-4096 nt
	global_load_dword v78, v[4:5], off nt
	v_add_co_u32_e32 v4, vcc, s3, v2
	s_mov_b32 s3, 0x32000
	s_nop 0
	v_addc_co_u32_e32 v5, vcc, 0, v3, vcc
	global_load_dword v80, v[4:5], off offset:-4096 nt
	global_load_dword v81, v[4:5], off nt
	v_add_co_u32_e32 v4, vcc, s3, v2
	s_mov_b32 s3, 0x34000
	s_nop 0
	v_addc_co_u32_e32 v5, vcc, 0, v3, vcc
	global_load_dword v82, v[4:5], off offset:-4096 nt
	global_load_dword v83, v[4:5], off nt
	v_add_co_u32_e32 v4, vcc, s3, v2
	s_mov_b32 s3, 0x36000
	s_nop 0
	v_addc_co_u32_e32 v5, vcc, 0, v3, vcc
	global_load_dword v84, v[4:5], off offset:-4096 nt
	global_load_dword v85, v[4:5], off nt
	v_add_co_u32_e32 v4, vcc, s3, v2
	s_mov_b32 s3, 0x38000
	s_nop 0
	v_addc_co_u32_e32 v5, vcc, 0, v3, vcc
	global_load_dword v86, v[4:5], off offset:-4096 nt
	global_load_dword v87, v[4:5], off nt
	v_add_co_u32_e32 v4, vcc, s3, v2
	s_mov_b32 s3, 0x3a000
	s_nop 0
	v_addc_co_u32_e32 v5, vcc, 0, v3, vcc
	global_load_dword v88, v[4:5], off offset:-4096 nt
	global_load_dword v89, v[4:5], off nt
	v_add_co_u32_e32 v4, vcc, s3, v2
	s_mov_b32 s3, 0x3c000
	s_nop 0
	v_addc_co_u32_e32 v5, vcc, 0, v3, vcc
	global_load_dword v90, v[4:5], off offset:-4096 nt
	global_load_dword v91, v[4:5], off nt
	v_add_co_u32_e32 v4, vcc, s3, v2
	s_mov_b32 s3, 0x3e000
	s_nop 0
	v_addc_co_u32_e32 v5, vcc, 0, v3, vcc
	global_load_dword v92, v[4:5], off offset:-4096 nt
	global_load_dword v93, v[4:5], off nt
	v_add_co_u32_e32 v4, vcc, s3, v2
	s_mov_b32 s3, 0x3f000
	s_nop 0
	v_addc_co_u32_e32 v5, vcc, 0, v3, vcc
	global_load_dword v94, v[4:5], off offset:-4096 nt
	s_nop 0
	global_load_dword v4, v[4:5], off nt
	v_add_co_u32_e32 v2, vcc, s3, v2
	s_and_b32 s3, s14, 0x700
	s_nop 0
	v_addc_co_u32_e32 v3, vcc, 0, v3, vcc
	global_load_dword v2, v[2:3], off nt
	v_bitop3_b32 v3, s2, v237, v20 bitop3:0xc8
	v_or_b32_e32 v79, s3, v3
	s_mov_b32 s2, 0xc3e00000
	s_waitcnt vmcnt(27)
; __device__ __forceinline__ unsigned pk4_fp8(float a, float b, float c, float d) { int w = 0; w = __builtin_amdgcn_cvt_pk_fp8_f32(a, b, w, false); w = __builtin_amdgcn_cvt_pk_fp8_f32(c, d, w, true); return (unsigned)w; }
; __device__ __forceinline__ void transpose_item8(const float* W, int N, unsigned char* WT, int ldt, int item, int lane, int mode, int aux) {
;     ...
;     for (int q = 0; q < 16; ++q) o[q] = pk4_fp8(fminf(fmaxf(v[4 * q] * 64.f, -448.f), 448.f), fminf(fmaxf(v[4 * q + 1] * 64.f, -448.f), 448.f), fminf(fmaxf(v[4 * q + 2] * 64.f, -448.f), 448.f), fminf(fmaxf(v[4 * q + 3] * 64.f, -448.f), 448.f));
	v_mul_f32_e32 v7, 0x42800000, v7
	v_mul_f32_e32 v6, 0x42800000, v6
	v_mul_f32_e32 v13, 0x42800000, v13
	v_mul_f32_e32 v12, 0x42800000, v12
	s_waitcnt vmcnt(23)
	v_mul_f32_e32 v8, 0x42800000, v8
	v_mul_f32_e32 v11, 0x42800000, v11
	v_mul_f32_e32 v10, 0x42800000, v10
	v_mul_f32_e32 v55, 0x42800000, v55
	v_mul_f32_e32 v52, 0x42800000, v52
	v_mul_f32_e32 v53, 0x42800000, v53
	v_med3_f32 v52, v52, s2, v236
	v_med3_f32 v53, v53, s2, v236
	v_mul_f32_e32 v17, 0x42800000, v17
	v_mul_f32_e32 v18, 0x42800000, v18
	v_mul_f32_e32 v54, 0x42800000, v54
	v_med3_f32 v17, v17, s2, v236
	s_waitcnt vmcnt(19)
	v_mul_f32_e32 v9, 0x42800000, v9
	v_med3_f32 v18, v18, s2, v236
	v_med3_f32 v54, v54, s2, v236
	v_mul_f32_e32 v47, 0x42800000, v47
	v_mul_f32_e32 v48, 0x42800000, v48
	v_mul_f32_e32 v43, 0x42800000, v43
	v_mul_f32_e32 v44, 0x42800000, v44
	v_med3_f32 v47, v47, s2, v236
	v_med3_f32 v48, v48, s2, v236
	v_med3_f32 v43, v43, s2, v236
	v_med3_f32 v44, v44, s2, v236
	v_mul_f32_e32 v19, 0x42800000, v19
	v_mul_f32_e32 v42, 0x42800000, v42
	v_med3_f32 v19, v19, s2, v236
	v_med3_f32 v42, v42, s2, v236
	v_mul_f32_e32 v49, 0x42800000, v49
	v_mul_f32_e32 v50, 0x42800000, v50
	v_mul_f32_e32 v45, 0x42800000, v45
	v_mul_f32_e32 v46, 0x42800000, v46
	v_mul_f32_e32 v66, 0x42800000, v66
	v_mul_f32_e32 v67, 0x42800000, v67
	v_mul_f32_e32 v63, 0x42800000, v63
	v_mul_f32_e32 v64, 0x42800000, v64
	v_mul_f32_e32 v60, 0x42800000, v60
	v_mul_f32_e32 v61, 0x42800000, v61
	v_mul_f32_e32 v57, 0x42800000, v57
	v_mul_f32_e32 v58, 0x42800000, v58
	v_med3_f32 v49, v49, s2, v236
	v_med3_f32 v50, v50, s2, v236
	v_med3_f32 v45, v45, s2, v236
	v_med3_f32 v46, v46, s2, v236
	s_waitcnt vmcnt(17)
	v_mul_f32_e32 v78, 0x42800000, v78
	s_waitcnt vmcnt(16)
	v_mul_f32_e32 v80, 0x42800000, v80
	v_mul_f32_e32 v75, 0x42800000, v75
	v_mul_f32_e32 v76, 0x42800000, v76
	v_mul_f32_e32 v72, 0x42800000, v72
	v_mul_f32_e32 v73, 0x42800000, v73
	v_mul_f32_e32 v69, 0x42800000, v69
	v_mul_f32_e32 v70, 0x42800000, v70
	v_med3_f32 v66, v66, s2, v236
	v_med3_f32 v67, v67, s2, v236
	v_med3_f32 v63, v63, s2, v236
	v_med3_f32 v64, v64, s2, v236
	v_med3_f32 v60, v60, s2, v236
	v_med3_f32 v61, v61, s2, v236
	v_med3_f32 v57, v57, s2, v236
	v_med3_f32 v58, v58, s2, v236
	v_readlane_b32 s58, v252, 43
	v_readlane_b32 s59, v252, 44
	v_readlane_b32 s60, v252, 45
	v_readlane_b32 s61, v252, 46
	v_med3_f32 v78, v78, s2, v236
	v_med3_f32 v80, v80, s2, v236
	s_waitcnt vmcnt(2)
	v_mul_f32_e32 v5, 0x42800000, v94
	s_waitcnt vmcnt(1)
	v_mul_f32_e32 v3, 0x42800000, v4
	v_mul_f32_e32 v4, 0x42800000, v93
	v_med3_f32 v4, v4, s2, v236
	v_med3_f32 v93, v5, s2, v236
	v_mov_b32_e32 v5, v51
	v_cvt_pk_fp8_f32 v5, v4, v93
	v_mul_f32_e32 v4, 0x42800000, v89
	v_med3_f32 v89, v4, s2, v236
	v_mul_f32_e32 v4, 0x42800000, v90
	v_med3_f32 v90, v4, s2, v236
	v_mov_b32_e32 v4, v51
	s_waitcnt vmcnt(0)
; __device__ __forceinline__ unsigned pk4_fp8(float a, float b, float c, float d) { int w = 0; w = __builtin_amdgcn_cvt_pk_fp8_f32(a, b, w, false); w = __builtin_amdgcn_cvt_pk_fp8_f32(c, d, w, true); return (unsigned)w; }
; __device__ __forceinline__ int rowmap(int mode, int aux, int n) {
;     ...
;     return 256 * (n >> 7) + 128 + (n & 127);
; __device__ __forceinline__ void transpose_item8(const float* W, int N, unsigned char* WT, int ldt, int item, int lane, int mode, int aux) {
;     ...
;     for (int q = 0; q < 16; ++q) o[q] = pk4_fp8(fminf(fmaxf(v[4 * q] * 64.f, -448.f), 448.f), fminf(fmaxf(v[4 * q + 1] * 64.f, -448.f), 448.f), fminf(fmaxf(v[4 * q + 2] * 64.f, -448.f), 448.f), fminf(fmaxf(v[4 * q + 3] * 64.f, -448.f), 448.f));
;     v4u* dst = (v4u*)(WT + (size_t)rowmap(mode, aux, ncol) * ldt + k0);
; #pragma unroll
;     for (int q = 0; q < 4; ++q) dst[q] = (v4u){o[4 * q], o[4 * q + 1], o[4 * q + 2], o[4 * q + 3]};
	v_mul_f32_e32 v2, 0x42800000, v2
	v_cvt_pk_fp8_f32 v4, v89, v90
	v_med3_f32 v3, v3, s2, v236
	v_med3_f32 v2, v2, s2, v236
	v_cvt_pk_fp8_f32 v5, v3, v2 op_sel:[0,0,1]
	v_mul_f32_e32 v2, 0x42800000, v91
	v_mul_f32_e32 v3, 0x42800000, v92
	v_med3_f32 v2, v2, s2, v236
	v_med3_f32 v3, v3, s2, v236
	v_cvt_pk_fp8_f32 v4, v2, v3 op_sel:[0,0,1]
	v_mul_f32_e32 v3, 0x42800000, v88
	v_mul_f32_e32 v2, 0x42800000, v87
	v_med3_f32 v87, v3, s2, v236
	v_mul_f32_e32 v3, 0x42800000, v85
	v_med3_f32 v85, v3, s2, v236
	v_mul_f32_e32 v3, 0x42800000, v86
	v_med3_f32 v86, v3, s2, v236
	v_mov_b32_e32 v3, v51
	v_cvt_pk_fp8_f32 v3, v85, v86
	v_med3_f32 v2, v2, s2, v236
	v_med3_f32 v75, v75, s2, v236
	v_med3_f32 v76, v76, s2, v236
	v_cvt_pk_fp8_f32 v3, v2, v87 op_sel:[0,0,1]
	v_mul_f32_e32 v2, 0x42800000, v83
	v_med3_f32 v83, v2, s2, v236
	v_mul_f32_e32 v2, 0x42800000, v84
	v_med3_f32 v84, v2, s2, v236
	v_mul_f32_e32 v2, 0x42800000, v81
	v_med3_f32 v81, v2, s2, v236
	v_mul_f32_e32 v2, 0x42800000, v82
	v_med3_f32 v82, v2, s2, v236
	v_mov_b32_e32 v2, v51
	v_cvt_pk_fp8_f32 v2, v81, v82
	v_med3_f32 v81, v9, s2, v236
	v_mul_f32_e32 v9, 0x42800000, v77
	v_med3_f32 v77, v9, s2, v236
	v_mov_b32_e32 v9, v51
	v_cvt_pk_fp8_f32 v9, v81, v77
	v_med3_f32 v77, v8, s2, v236
	v_mul_f32_e32 v8, 0x42800000, v74
	v_med3_f32 v74, v8, s2, v236
	v_mov_b32_e32 v8, v51
	v_cvt_pk_fp8_f32 v8, v77, v74
	v_med3_f32 v74, v7, s2, v236
	v_mul_f32_e32 v7, 0x42800000, v71
	v_med3_f32 v71, v7, s2, v236
	v_mov_b32_e32 v7, v51
	v_cvt_pk_fp8_f32 v7, v74, v71
	v_med3_f32 v71, v6, s2, v236
	v_mul_f32_e32 v6, 0x42800000, v68
	v_med3_f32 v68, v6, s2, v236
	v_mov_b32_e32 v6, v51
	v_cvt_pk_fp8_f32 v6, v71, v68
	v_med3_f32 v68, v13, s2, v236
	v_mul_f32_e32 v13, 0x42800000, v65
	v_med3_f32 v65, v13, s2, v236
	v_mov_b32_e32 v13, v51
	v_cvt_pk_fp8_f32 v13, v68, v65
	v_med3_f32 v65, v12, s2, v236
	v_mul_f32_e32 v12, 0x42800000, v62
	v_med3_f32 v62, v12, s2, v236
	v_mov_b32_e32 v12, v51
	v_cvt_pk_fp8_f32 v12, v65, v62
	v_med3_f32 v62, v11, s2, v236
	v_mul_f32_e32 v11, 0x42800000, v59
	v_med3_f32 v59, v11, s2, v236
	v_mov_b32_e32 v11, v51
	v_cvt_pk_fp8_f32 v11, v62, v59
	v_med3_f32 v59, v10, s2, v236
	v_mul_f32_e32 v10, 0x42800000, v56
	v_med3_f32 v56, v10, s2, v236
	v_mov_b32_e32 v10, v51
	v_cvt_pk_fp8_f32 v10, v59, v56
	v_med3_f32 v56, v55, s2, v236
	v_mov_b32_e32 v55, v51
	v_cvt_pk_fp8_f32 v55, v52, v53
	v_mov_b32_e32 v52, v51
	v_cvt_pk_fp8_f32 v52, v17, v18
	v_mov_b32_e32 v53, v51
	v_cvt_pk_fp8_f32 v55, v54, v56 op_sel:[0,0,1]
	v_mov_b32_e32 v54, v51
	v_cvt_pk_fp8_f32 v54, v47, v48
	v_cvt_pk_fp8_f32 v53, v43, v44
	v_cvt_pk_fp8_f32 v52, v19, v42 op_sel:[0,0,1]
	v_lshlrev_b32_e32 v18, 10, v79
	v_mov_b32_e32 v19, v51
	v_lshl_add_u64 v[18:19], s[0:1], 0, v[18:19]
	s_mov_b32 s1, s23
	v_cvt_pk_fp8_f32 v54, v49, v50 op_sel:[0,0,1]
	v_cvt_pk_fp8_f32 v53, v45, v46 op_sel:[0,0,1]
	v_writelane_b32 v254, s0, 32
	v_med3_f32 v72, v72, s2, v236
	v_med3_f32 v73, v73, s2, v236
	v_med3_f32 v69, v69, s2, v236
	v_med3_f32 v70, v70, s2, v236
	v_cvt_pk_fp8_f32 v13, v66, v67 op_sel:[0,0,1]
	v_cvt_pk_fp8_f32 v12, v63, v64 op_sel:[0,0,1]
	v_cvt_pk_fp8_f32 v11, v60, v61 op_sel:[0,0,1]
	v_cvt_pk_fp8_f32 v10, v57, v58 op_sel:[0,0,1]
	v_writelane_b32 v254, s1, 33
	v_lshl_add_u64 v[18:19], v[18:19], 0, s[22:23]
	s_mov_b64 s[0:1], 0x20000
	v_readlane_b32 s64, v252, 49
	v_readlane_b32 s68, v252, 53
	v_readlane_b32 s69, v252, 54
	v_readlane_b32 s71, v252, 56
	s_mov_b32 s58, 0x3f6c835e
	v_readlane_b32 s60, v255, 2
	v_cvt_pk_fp8_f32 v9, v78, v80 op_sel:[0,0,1]
	v_cvt_pk_fp8_f32 v8, v75, v76 op_sel:[0,0,1]
	v_cvt_pk_fp8_f32 v7, v72, v73 op_sel:[0,0,1]
	v_cvt_pk_fp8_f32 v6, v69, v70 op_sel:[0,0,1]
	v_lshl_add_u64 v[42:43], v[18:19], 0, s[0:1]
	v_add_co_u32_e32 v18, vcc, 0x20000, v18
	s_movk_i32 s64, 0x440
	s_movk_i32 s68, 0x2200
	s_movk_i32 s71, 0x1ff
	s_mov_b32 s69, 0x7f800000
	s_mov_b32 s59, 0xbec3ef15
	v_readlane_b32 s61, v255, 3
	v_readlane_b32 s62, v255, 4
	s_mov_b32 s63, 0xbf6c835e
	v_cvt_pk_fp8_f32 v2, v83, v84 op_sel:[0,0,1]
	v_addc_co_u32_e32 v19, vcc, 0, v19, vcc
	v_readlane_b32 s57, v252, 42
	v_readlane_b32 s65, v252, 50
	v_readlane_b32 s66, v252, 51
	v_readlane_b32 s67, v252, 52
	global_store_dwordx4 v[18:19], v[52:55], off
	global_store_dwordx4 v[42:43], v[10:13], off offset:16
	global_store_dwordx4 v[42:43], v[6:9], off offset:32
	global_store_dwordx4 v[42:43], v[2:5], off offset:48

; __device__ __forceinline__ unsigned pk4_fp8(float a, float b, float c, float d) { int w = 0; w = __builtin_amdgcn_cvt_pk_fp8_f32(a, b, w, false); w = __builtin_amdgcn_cvt_pk_fp8_f32(c, d, w, true); return (unsigned)w; }
; __device__ __forceinline__ void transpose_item8(const float* W, int N, unsigned char* WT, int ldt, int item, int lane, int mode, int aux) {
;     const int nblk = (N + 63) >> 6, kb = item / nblk, nb = item - kb * nblk, k0 = 64 * kb, n0 = 64 * nb;
;     const int ncol = n0 + lane;
;     const float* wp = W + (size_t)k0 * N + ncol;
;     float v[64];
; #pragma unroll
;     for (int i = 0; i < 64; ++i) v[i] = wp[(size_t)i * N];
;     unsigned o[16];
; #pragma unroll
;     for (int q = 0; q < 16; ++q) o[q] = pk4_fp8(fminf(fmaxf(v[4 * q] * 64.f, -448.f), 448.f), fminf(fmaxf(v[4 * q + 1] * 64.f, -448.f), 448.f), fminf(fmaxf(v[4 * q + 2] * 64.f, -448.f), 448.f), fminf(fmaxf(v[4 * q + 3] * 64.f, -448.f), 448.f));
;     v4u* dst = (v4u*)(WT + (size_t)rowmap(mode, aux, ncol) * ldt + k0);
; #pragma unroll
;     for (int q = 0; q < 4; ++q) dst[q] = (v4u){o[4 * q], o[4 * q + 1], o[4 * q + 2], o[4 * q + 3]};
; }
; __device__ __forceinline__ void convert_rest(const Args& a, LAS unsigned char* lds, int wave, int lane, int gw, int ngw, int l, int it0, int it1) {
;     ...
;         if (r < WI_FF) { const int e = r >> 8; transpose_item8(a.in[I_WFFG] + (size_t)(l * 16 + e) * 1024 * 1024, 1024, ws + WS_WGU + (size_t)e * 2048 * 1024, 1024, r & 255, lane, 3, 0); continue; } r -= WI_FF;
.LBB0_2023:
	s_andn2_b64 vcc, exec, s[0:1]
	s_cbranch_vccnz .LBB0_2025
	s_add_i32 s0, s6, 0xfffffa00
	s_lshr_b32 s0, s0, 8
	v_readlane_b32 s22, v254, 32
	v_readlane_b32 s23, v254, 33
	s_add_i32 s22, s0, s7
	v_readlane_b32 s56, v252, 41
	s_lshl_b64 s[2:3], s[22:23], 22
	v_readlane_b32 s60, v252, 45
	v_readlane_b32 s61, v252, 46
	s_add_u32 s16, s60, s2
	s_mov_b32 s1, s23
	s_addc_u32 s3, s61, s3
	s_lshl_b64 s[0:1], s[0:1], 21
	v_readlane_b32 s2, v253, 61
	s_add_u32 s0, s2, s0
	v_readlane_b32 s2, v253, 62
	s_addc_u32 s1, s2, s1
	s_and_b32 s22, s11, 0x3c0
	s_add_i32 s2, s4, 0xa2000
	s_and_b32 s2, s2, 0x3c0
	s_lshl_b32 s17, s22, 12
	v_or_b32_e32 v2, s2, v20
	s_add_u32 s16, s16, s17
	s_addc_u32 s17, s3, 0
	v_lshlrev_b32_e32 v50, 2, v2
	v_lshl_add_u64 v[2:3], s[16:17], 0, v[50:51]
	s_movk_i32 s3, 0x2000
	v_readlane_b32 s70, v252, 55
	v_add_co_u32_e32 v4, vcc, s3, v2
	s_movk_i32 s70, 0x4000
	s_nop 0
	v_addc_co_u32_e32 v5, vcc, 0, v3, vcc
	global_load_dword v17, v50, s[16:17] nt
	global_load_dword v18, v[4:5], off offset:-4096 nt
	global_load_dword v19, v[4:5], off nt
	v_add_co_u32_e32 v4, vcc, s70, v2
	s_movk_i32 s3, 0x6000
	s_nop 0
	v_addc_co_u32_e32 v5, vcc, 0, v3, vcc
	global_load_dword v42, v[4:5], off offset:-4096 nt
	global_load_dword v43, v[4:5], off nt
	v_add_co_u32_e32 v4, vcc, s3, v2
	s_mov_b32 s3, 0x8000
	s_nop 0
	v_addc_co_u32_e32 v5, vcc, 0, v3, vcc
	global_load_dword v44, v[4:5], off offset:-4096 nt
	global_load_dword v45, v[4:5], off nt
	v_add_co_u32_e32 v4, vcc, s3, v2
	s_mov_b32 s3, 0xa000
	s_nop 0
	v_addc_co_u32_e32 v5, vcc, 0, v3, vcc
	global_load_dword v46, v[4:5], off offset:-4096 nt
	global_load_dword v47, v[4:5], off nt
	v_add_co_u32_e32 v4, vcc, s3, v2
	s_mov_b32 s3, 0xc000
	s_nop 0
	v_addc_co_u32_e32 v5, vcc, 0, v3, vcc
	global_load_dword v48, v[4:5], off offset:-4096 nt
	global_load_dword v49, v[4:5], off nt
	v_add_co_u32_e32 v4, vcc, s3, v2
	s_mov_b32 s3, 0xe000
	s_nop 0
	v_addc_co_u32_e32 v5, vcc, 0, v3, vcc
	global_load_dword v50, v[4:5], off offset:-4096 nt
	global_load_dword v52, v[4:5], off nt
	v_add_co_u32_e32 v4, vcc, s3, v2
	s_mov_b32 s3, 0x10000
	s_nop 0
	v_addc_co_u32_e32 v5, vcc, 0, v3, vcc
	global_load_dword v53, v[4:5], off offset:-4096 nt
	global_load_dword v54, v[4:5], off nt
	v_add_co_u32_e32 v4, vcc, s3, v2
	s_mov_b32 s3, 0x12000
	s_nop 0
	v_addc_co_u32_e32 v5, vcc, 0, v3, vcc
	global_load_dword v55, v[4:5], off offset:-4096 nt
	global_load_dword v10, v[4:5], off nt
	v_add_co_u32_e32 v4, vcc, s3, v2
	s_mov_b32 s3, 0x14000
	s_nop 0
	v_addc_co_u32_e32 v5, vcc, 0, v3, vcc
	global_load_dword v56, v[4:5], off offset:-4096 nt
	global_load_dword v57, v[4:5], off nt
	v_add_co_u32_e32 v4, vcc, s3, v2
	s_mov_b32 s3, 0x16000
	s_nop 0
	v_addc_co_u32_e32 v5, vcc, 0, v3, vcc
	global_load_dword v58, v[4:5], off offset:-4096 nt
	global_load_dword v11, v[4:5], off nt
	v_add_co_u32_e32 v4, vcc, s3, v2
	s_mov_b32 s3, 0x18000
	s_nop 0
	v_addc_co_u32_e32 v5, vcc, 0, v3, vcc
	global_load_dword v59, v[4:5], off offset:-4096 nt
	global_load_dword v60, v[4:5], off nt
	v_add_co_u32_e32 v4, vcc, s3, v2
	s_mov_b32 s3, 0x1a000
	s_nop 0
	v_addc_co_u32_e32 v5, vcc, 0, v3, vcc
	global_load_dword v61, v[4:5], off offset:-4096 nt
	global_load_dword v12, v[4:5], off nt
	v_add_co_u32_e32 v4, vcc, s3, v2
	s_mov_b32 s3, 0x1c000
	s_nop 0
	v_addc_co_u32_e32 v5, vcc, 0, v3, vcc
	global_load_dword v62, v[4:5], off offset:-4096 nt
	global_load_dword v63, v[4:5], off nt
	v_add_co_u32_e32 v4, vcc, s3, v2
	s_mov_b32 s3, 0x1e000
	s_nop 0
	v_addc_co_u32_e32 v5, vcc, 0, v3, vcc
	global_load_dword v64, v[4:5], off offset:-4096 nt
	global_load_dword v13, v[4:5], off nt
	v_add_co_u32_e32 v4, vcc, s3, v2
	s_mov_b32 s3, 0x20000
	s_nop 0
	v_addc_co_u32_e32 v5, vcc, 0, v3, vcc
	global_load_dword v65, v[4:5], off offset:-4096 nt
	global_load_dword v66, v[4:5], off nt
	v_add_co_u32_e32 v4, vcc, s3, v2
	s_mov_b32 s3, 0x22000
	s_nop 0
	v_addc_co_u32_e32 v5, vcc, 0, v3, vcc
	global_load_dword v67, v[4:5], off offset:-4096 nt
	global_load_dword v6, v[4:5], off nt
	v_add_co_u32_e32 v4, vcc, s3, v2
	s_mov_b32 s3, 0x24000
	s_nop 0
	v_addc_co_u32_e32 v5, vcc, 0, v3, vcc
	global_load_dword v68, v[4:5], off offset:-4096 nt
	global_load_dword v69, v[4:5], off nt
	v_add_co_u32_e32 v4, vcc, s3, v2
	s_mov_b32 s3, 0x26000
	s_nop 0
	v_addc_co_u32_e32 v5, vcc, 0, v3, vcc
	global_load_dword v70, v[4:5], off offset:-4096 nt
	global_load_dword v7, v[4:5], off nt
	v_add_co_u32_e32 v4, vcc, s3, v2
	s_mov_b32 s3, 0x28000
	s_nop 0
	v_addc_co_u32_e32 v5, vcc, 0, v3, vcc
	global_load_dword v71, v[4:5], off offset:-4096 nt
	global_load_dword v72, v[4:5], off nt
	v_add_co_u32_e32 v4, vcc, s3, v2
	s_mov_b32 s3, 0x2a000
	s_nop 0
	v_addc_co_u32_e32 v5, vcc, 0, v3, vcc
	global_load_dword v73, v[4:5], off offset:-4096 nt
	global_load_dword v8, v[4:5], off nt
	v_add_co_u32_e32 v4, vcc, s3, v2
	s_mov_b32 s3, 0x2c000
	s_nop 0
	v_addc_co_u32_e32 v5, vcc, 0, v3, vcc
	global_load_dword v74, v[4:5], off offset:-4096 nt
	global_load_dword v75, v[4:5], off nt
	v_add_co_u32_e32 v4, vcc, s3, v2
	s_mov_b32 s3, 0x2e000
	s_nop 0
	v_addc_co_u32_e32 v5, vcc, 0, v3, vcc
	global_load_dword v76, v[4:5], off offset:-4096 nt
	global_load_dword v9, v[4:5], off nt
	v_add_co_u32_e32 v4, vcc, s3, v2
	s_mov_b32 s3, 0x30000
	s_nop 0
	v_addc_co_u32_e32 v5, vcc, 0, v3, vcc
	global_load_dword v77, v[4:5], off offset:-4096 nt
	global_load_dword v78, v[4:5], off nt
	v_add_co_u32_e32 v4, vcc, s3, v2
	s_mov_b32 s3, 0x32000
	s_nop 0
	v_addc_co_u32_e32 v5, vcc, 0, v3, vcc
	global_load_dword v80, v[4:5], off offset:-4096 nt
	global_load_dword v81, v[4:5], off nt
	v_add_co_u32_e32 v4, vcc, s3, v2
	s_mov_b32 s3, 0x34000
	s_nop 0
; __device__ __forceinline__ unsigned pk4_fp8(float a, float b, float c, float d) { int w = 0; w = __builtin_amdgcn_cvt_pk_fp8_f32(a, b, w, false); w = __builtin_amdgcn_cvt_pk_fp8_f32(c, d, w, true); return (unsigned)w; }
; __device__ __forceinline__ void transpose_item8(const float* W, int N, unsigned char* WT, int ldt, int item, int lane, int mode, int aux) {
;     ...
;     for (int i = 0; i < 64; ++i) v[i] = wp[(size_t)i * N];
;     unsigned o[16];
; #pragma unroll
;     for (int q = 0; q < 16; ++q) o[q] = pk4_fp8(fminf(fmaxf(v[4 * q] * 64.f, -448.f), 448.f), fminf(fmaxf(v[4 * q + 1] * 64.f, -448.f), 448.f), fminf(fmaxf(v[4 * q + 2] * 64.f, -448.f), 448.f), fminf(fmaxf(v[4 * q + 3] * 64.f, -448.f), 448.f));
	v_addc_co_u32_e32 v5, vcc, 0, v3, vcc
	global_load_dword v82, v[4:5], off offset:-4096 nt
	global_load_dword v83, v[4:5], off nt
	v_add_co_u32_e32 v4, vcc, s3, v2
	s_mov_b32 s3, 0x36000
	s_nop 0
	v_addc_co_u32_e32 v5, vcc, 0, v3, vcc
	global_load_dword v84, v[4:5], off offset:-4096 nt
	global_load_dword v85, v[4:5], off nt
	v_add_co_u32_e32 v4, vcc, s3, v2
	s_mov_b32 s3, 0x38000
	s_nop 0
	v_addc_co_u32_e32 v5, vcc, 0, v3, vcc
	global_load_dword v86, v[4:5], off offset:-4096 nt
	global_load_dword v87, v[4:5], off nt
	v_add_co_u32_e32 v4, vcc, s3, v2
	s_mov_b32 s3, 0x3a000
	s_nop 0
	v_addc_co_u32_e32 v5, vcc, 0, v3, vcc
	global_load_dword v88, v[4:5], off offset:-4096 nt
	global_load_dword v89, v[4:5], off nt
	v_add_co_u32_e32 v4, vcc, s3, v2
	s_mov_b32 s3, 0x3c000
	s_nop 0
	v_addc_co_u32_e32 v5, vcc, 0, v3, vcc
	global_load_dword v90, v[4:5], off offset:-4096 nt
	global_load_dword v91, v[4:5], off nt
	v_add_co_u32_e32 v4, vcc, s3, v2
	s_mov_b32 s3, 0x3e000
	s_nop 0
	v_addc_co_u32_e32 v5, vcc, 0, v3, vcc
	global_load_dword v92, v[4:5], off offset:-4096 nt
	global_load_dword v93, v[4:5], off nt
	v_add_co_u32_e32 v4, vcc, s3, v2
	s_mov_b32 s3, 0x3f000
	s_nop 0
	v_addc_co_u32_e32 v5, vcc, 0, v3, vcc
	global_load_dword v94, v[4:5], off offset:-4096 nt
	s_nop 0
	global_load_dword v4, v[4:5], off nt
	v_add_co_u32_e32 v2, vcc, s3, v2
	s_and_b32 s3, s14, 0x700
	s_nop 0
	v_addc_co_u32_e32 v3, vcc, 0, v3, vcc
	global_load_dword v2, v[2:3], off nt
	v_bitop3_b32 v3, s2, v237, v20 bitop3:0xc8
	v_or_b32_e32 v79, s3, v3
	s_mov_b32 s2, 0xc3e00000
	s_waitcnt vmcnt(27)
	v_mul_f32_e32 v7, 0x42800000, v7
	v_mul_f32_e32 v6, 0x42800000, v6
	v_mul_f32_e32 v13, 0x42800000, v13
	v_mul_f32_e32 v12, 0x42800000, v12
	s_waitcnt vmcnt(23)
	v_mul_f32_e32 v8, 0x42800000, v8
	v_mul_f32_e32 v11, 0x42800000, v11
	v_mul_f32_e32 v10, 0x42800000, v10
	v_mul_f32_e32 v55, 0x42800000, v55
	v_mul_f32_e32 v52, 0x42800000, v52
	v_mul_f32_e32 v53, 0x42800000, v53
	v_med3_f32 v52, v52, s2, v236
	v_med3_f32 v53, v53, s2, v236
	v_mul_f32_e32 v54, 0x42800000, v54
	v_med3_f32 v54, v54, s2, v236
	v_mul_f32_e32 v47, 0x42800000, v47
	v_mul_f32_e32 v48, 0x42800000, v48
	s_waitcnt vmcnt(19)
	v_mul_f32_e32 v9, 0x42800000, v9
	v_mul_f32_e32 v43, 0x42800000, v43
	v_mul_f32_e32 v44, 0x42800000, v44
	v_mul_f32_e32 v17, 0x42800000, v17
	v_mul_f32_e32 v18, 0x42800000, v18
	v_med3_f32 v47, v47, s2, v236
	v_med3_f32 v48, v48, s2, v236
	v_med3_f32 v43, v43, s2, v236
	v_med3_f32 v44, v44, s2, v236
	v_med3_f32 v17, v17, s2, v236
	v_med3_f32 v18, v18, s2, v236
	v_mul_f32_e32 v49, 0x42800000, v49
	v_mul_f32_e32 v50, 0x42800000, v50
	v_mul_f32_e32 v45, 0x42800000, v45
	v_mul_f32_e32 v46, 0x42800000, v46
	v_mul_f32_e32 v19, 0x42800000, v19
	v_mul_f32_e32 v42, 0x42800000, v42
	v_mul_f32_e32 v66, 0x42800000, v66
	v_mul_f32_e32 v67, 0x42800000, v67
	v_mul_f32_e32 v63, 0x42800000, v63
	v_mul_f32_e32 v64, 0x42800000, v64
	v_mul_f32_e32 v60, 0x42800000, v60
	v_mul_f32_e32 v61, 0x42800000, v61
	v_mul_f32_e32 v57, 0x42800000, v57
	v_mul_f32_e32 v58, 0x42800000, v58
	v_med3_f32 v49, v49, s2, v236
	v_med3_f32 v50, v50, s2, v236
	v_med3_f32 v45, v45, s2, v236
	v_med3_f32 v46, v46, s2, v236
	v_med3_f32 v19, v19, s2, v236
	v_med3_f32 v42, v42, s2, v236
	s_waitcnt vmcnt(17)
	v_mul_f32_e32 v78, 0x42800000, v78
	s_waitcnt vmcnt(16)
	v_mul_f32_e32 v80, 0x42800000, v80
	v_mul_f32_e32 v75, 0x42800000, v75
	v_mul_f32_e32 v76, 0x42800000, v76
	v_mul_f32_e32 v72, 0x42800000, v72
	v_mul_f32_e32 v73, 0x42800000, v73
	v_mul_f32_e32 v69, 0x42800000, v69
	v_mul_f32_e32 v70, 0x42800000, v70
	v_med3_f32 v66, v66, s2, v236
	v_med3_f32 v67, v67, s2, v236
	v_med3_f32 v63, v63, s2, v236
	v_med3_f32 v64, v64, s2, v236
	v_med3_f32 v60, v60, s2, v236
	v_med3_f32 v61, v61, s2, v236
	v_med3_f32 v57, v57, s2, v236
	v_med3_f32 v58, v58, s2, v236
	v_readlane_b32 s58, v252, 43
	v_readlane_b32 s59, v252, 44
	v_med3_f32 v78, v78, s2, v236
	v_med3_f32 v80, v80, s2, v236
	v_med3_f32 v75, v75, s2, v236
	v_med3_f32 v76, v76, s2, v236
	s_waitcnt vmcnt(2)
	v_mul_f32_e32 v5, 0x42800000, v94
	s_waitcnt vmcnt(1)
	v_mul_f32_e32 v3, 0x42800000, v4
	v_mul_f32_e32 v4, 0x42800000, v93
	v_med3_f32 v4, v4, s2, v236
	v_med3_f32 v93, v5, s2, v236
	v_mov_b32_e32 v5, v51
	v_cvt_pk_fp8_f32 v5, v4, v93
	v_mul_f32_e32 v4, 0x42800000, v89
	v_med3_f32 v89, v4, s2, v236
	v_mul_f32_e32 v4, 0x42800000, v90
	v_med3_f32 v90, v4, s2, v236
	v_mov_b32_e32 v4, v51
	s_waitcnt vmcnt(0)
; __device__ __forceinline__ unsigned pk4_fp8(float a, float b, float c, float d) { int w = 0; w = __builtin_amdgcn_cvt_pk_fp8_f32(a, b, w, false); w = __builtin_amdgcn_cvt_pk_fp8_f32(c, d, w, true); return (unsigned)w; }
; __device__ __forceinline__ void transpose_item8(const float* W, int N, unsigned char* WT, int ldt, int item, int lane, int mode, int aux) {
;     ...
;     for (int q = 0; q < 16; ++q) o[q] = pk4_fp8(fminf(fmaxf(v[4 * q] * 64.f, -448.f), 448.f), fminf(fmaxf(v[4 * q + 1] * 64.f, -448.f), 448.f), fminf(fmaxf(v[4 * q + 2] * 64.f, -448.f), 448.f), fminf(fmaxf(v[4 * q + 3] * 64.f, -448.f), 448.f));
;     v4u* dst = (v4u*)(WT + (size_t)rowmap(mode, aux, ncol) * ldt + k0);
; #pragma unroll
;     for (int q = 0; q < 4; ++q) dst[q] = (v4u){o[4 * q], o[4 * q + 1], o[4 * q + 2], o[4 * q + 3]};
	v_mul_f32_e32 v2, 0x42800000, v2
	v_cvt_pk_fp8_f32 v4, v89, v90
	v_med3_f32 v3, v3, s2, v236
	v_med3_f32 v2, v2, s2, v236
	v_cvt_pk_fp8_f32 v5, v3, v2 op_sel:[0,0,1]
	v_mul_f32_e32 v2, 0x42800000, v91
	v_mul_f32_e32 v3, 0x42800000, v92
	v_med3_f32 v2, v2, s2, v236
	v_med3_f32 v3, v3, s2, v236
	v_cvt_pk_fp8_f32 v4, v2, v3 op_sel:[0,0,1]
	v_mul_f32_e32 v3, 0x42800000, v88
	v_mul_f32_e32 v2, 0x42800000, v87
	v_med3_f32 v87, v3, s2, v236
	v_mul_f32_e32 v3, 0x42800000, v85
	v_med3_f32 v85, v3, s2, v236
	v_mul_f32_e32 v3, 0x42800000, v86
	v_med3_f32 v86, v3, s2, v236
	v_mov_b32_e32 v3, v51
	v_cvt_pk_fp8_f32 v3, v85, v86
	v_med3_f32 v2, v2, s2, v236
	v_med3_f32 v72, v72, s2, v236
	v_med3_f32 v73, v73, s2, v236
	v_cvt_pk_fp8_f32 v3, v2, v87 op_sel:[0,0,1]
	v_mul_f32_e32 v2, 0x42800000, v83
	v_med3_f32 v83, v2, s2, v236
	v_mul_f32_e32 v2, 0x42800000, v84
	v_med3_f32 v84, v2, s2, v236
	v_mul_f32_e32 v2, 0x42800000, v81
	v_med3_f32 v81, v2, s2, v236
	v_mul_f32_e32 v2, 0x42800000, v82
	v_med3_f32 v82, v2, s2, v236
	v_mov_b32_e32 v2, v51
	v_cvt_pk_fp8_f32 v2, v81, v82
	v_med3_f32 v81, v9, s2, v236
	v_mul_f32_e32 v9, 0x42800000, v77
	v_med3_f32 v77, v9, s2, v236
	v_mov_b32_e32 v9, v51
	v_cvt_pk_fp8_f32 v9, v81, v77
	v_med3_f32 v77, v8, s2, v236
	v_mul_f32_e32 v8, 0x42800000, v74
	v_med3_f32 v74, v8, s2, v236
	v_mov_b32_e32 v8, v51
	v_cvt_pk_fp8_f32 v8, v77, v74
	v_med3_f32 v74, v7, s2, v236
	v_mul_f32_e32 v7, 0x42800000, v71
	v_med3_f32 v71, v7, s2, v236
	v_mov_b32_e32 v7, v51
	v_cvt_pk_fp8_f32 v7, v74, v71
	v_med3_f32 v71, v6, s2, v236
	v_mul_f32_e32 v6, 0x42800000, v68
	v_med3_f32 v68, v6, s2, v236
	v_mov_b32_e32 v6, v51
	v_cvt_pk_fp8_f32 v6, v71, v68
	v_med3_f32 v68, v13, s2, v236
	v_mul_f32_e32 v13, 0x42800000, v65
	v_med3_f32 v65, v13, s2, v236
	v_mov_b32_e32 v13, v51
	v_cvt_pk_fp8_f32 v13, v68, v65
	v_med3_f32 v65, v12, s2, v236
	v_mul_f32_e32 v12, 0x42800000, v62
	v_med3_f32 v62, v12, s2, v236
	v_mov_b32_e32 v12, v51
	v_cvt_pk_fp8_f32 v12, v65, v62
	v_med3_f32 v62, v11, s2, v236
	v_mul_f32_e32 v11, 0x42800000, v59
	v_med3_f32 v59, v11, s2, v236
	v_mov_b32_e32 v11, v51
	v_cvt_pk_fp8_f32 v11, v62, v59
	v_med3_f32 v59, v10, s2, v236
	v_mul_f32_e32 v10, 0x42800000, v56
	v_med3_f32 v56, v10, s2, v236
	v_mov_b32_e32 v10, v51
	v_cvt_pk_fp8_f32 v10, v59, v56
	v_med3_f32 v56, v55, s2, v236
	v_mov_b32_e32 v55, v51
	v_cvt_pk_fp8_f32 v55, v52, v53
	v_mov_b32_e32 v53, v51
	v_mov_b32_e32 v52, v51
	v_cvt_pk_fp8_f32 v53, v43, v44
	v_cvt_pk_fp8_f32 v55, v54, v56 op_sel:[0,0,1]
	v_mov_b32_e32 v54, v51
	v_cvt_pk_fp8_f32 v54, v47, v48
	v_cvt_pk_fp8_f32 v52, v17, v18
	v_cvt_pk_fp8_f32 v53, v45, v46 op_sel:[0,0,1]
	v_lshlrev_b32_e32 v18, 10, v79
	v_cvt_pk_fp8_f32 v54, v49, v50 op_sel:[0,0,1]
	v_cvt_pk_fp8_f32 v52, v19, v42 op_sel:[0,0,1]
	v_mov_b32_e32 v19, v51
	v_med3_f32 v69, v69, s2, v236
	v_med3_f32 v70, v70, s2, v236
	v_cvt_pk_fp8_f32 v13, v66, v67 op_sel:[0,0,1]
	v_cvt_pk_fp8_f32 v12, v63, v64 op_sel:[0,0,1]
	v_cvt_pk_fp8_f32 v11, v60, v61 op_sel:[0,0,1]
	v_cvt_pk_fp8_f32 v10, v57, v58 op_sel:[0,0,1]
	v_lshl_add_u64 v[18:19], s[0:1], 0, v[18:19]
	s_mov_b32 s1, s23
	v_readlane_b32 s62, v252, 47
	v_readlane_b32 s63, v252, 48
	v_readlane_b32 s64, v252, 49
	v_readlane_b32 s68, v252, 53
	v_readlane_b32 s69, v252, 54
	v_readlane_b32 s71, v252, 56
	s_mov_b32 s58, 0x3f6c835e
	v_readlane_b32 s60, v255, 2
	v_cvt_pk_fp8_f32 v9, v78, v80 op_sel:[0,0,1]
	v_cvt_pk_fp8_f32 v8, v75, v76 op_sel:[0,0,1]
	v_cvt_pk_fp8_f32 v7, v72, v73 op_sel:[0,0,1]
	v_cvt_pk_fp8_f32 v6, v69, v70 op_sel:[0,0,1]
	v_writelane_b32 v254, s0, 32
	s_movk_i32 s64, 0x440
	s_mov_b32 s63, 0xbf6c835e
	v_readlane_b32 s62, v255, 4
	s_movk_i32 s68, 0x2200
	s_movk_i32 s71, 0x1ff
	s_mov_b32 s69, 0x7f800000
	s_mov_b32 s59, 0xbec3ef15
	v_readlane_b32 s61, v255, 3
	v_cvt_pk_fp8_f32 v2, v83, v84 op_sel:[0,0,1]
	v_writelane_b32 v254, s1, 33
	v_lshl_add_u64 v[18:19], v[18:19], 0, s[22:23]
	v_readlane_b32 s57, v252, 42
	v_readlane_b32 s65, v252, 50
	v_readlane_b32 s66, v252, 51
	v_readlane_b32 s67, v252, 52
	global_store_dwordx4 v[18:19], v[52:55], off
	global_store_dwordx4 v[18:19], v[10:13], off offset:16
	global_store_dwordx4 v[18:19], v[6:9], off offset:32
	global_store_dwordx4 v[18:19], v[2:5], off offset:48

; #define LAS __attribute__((address_space(3)))
; __device__ __forceinline__ unsigned pk2(float lo, float hi) { return f2bf(lo) | (f2bf(hi) << 16); }
; __device__ __forceinline__ void transpose_item(const float* W, int N, bf16* WT, int ldt, LAS unsigned* scr, int item, int lane, int mode, int aux) {
;     const int nblk = (N + 63) >> 6, kb = item / nblk, nb = item - kb * nblk, k0 = 64 * kb, n0 = 64 * nb;
;     const int ncol = n0 + lane; const bool okc = ncol < N;
;     const float* wp = W + (size_t)k0 * N + (okc ? ncol : 0);
;     float v[64];
; #pragma unroll
;     for (int i = 0; i < 64; ++i) v[i] = wp[(size_t)i * N];
; #pragma unroll
;     for (int i = 0; i < 32; ++i) scr[i * 65 + lane] = okc ? pk2(v[2 * i], v[2 * i + 1]) : 0u;
; __device__ __forceinline__ void convert_rest(const Args& a, LAS unsigned char* lds, int wave, int lane, int gw, int ngw, int l, int it0, int it1) {
;     ...
;         if (r < WI_BR) { const int g = r >> 6; transpose_item(a.in[I_WBR] + (size_t)(l * 4 + g) * 256 * 1024, 1024, (bf16*)(ws + WS_WBR) + (size_t)g * 1024 * 256, 256, scr, r & 63, lane, 0, 0); continue; } r -= WI_BR;
;         if (r < WI_OUT) { transpose_item(a.in[I_WOUT] + (size_t)l * 1024 * 1024, 1024, (bf16*)(ws + WS_WOUT), 1024, scr, r, lane, 0, 0); continue; } r -= WI_OUT;
.LBB0_2026:
	s_andn2_b64 vcc, exec, s[0:1]
	s_cbranch_vccnz .LBB0_2074
	s_bfe_u32 s16, s6, 0x40004
	s_lshl_b32 s17, s16, 10
	s_sub_i32 s0, s4, s17
	v_add_u32_e32 v90, s0, v41
	s_lshl_b32 s0, s16, 18
	s_add_u32 s2, s9, s0
	s_movk_i32 s0, 0x400
	v_cmp_gt_i32_e64 s[0:1], s0, v90
	s_addc_u32 s3, s10, 0
	s_nop 0
	v_cndmask_b32_e64 v2, 0, v90, s[0:1]
	v_ashrrev_i32_e32 v3, 31, v2
	v_lshl_add_u64 v[2:3], v[2:3], 2, s[2:3]
	s_mov_b32 s2, 0xd000
	v_add_co_u32_e32 v4, vcc, s2, v2
	s_mov_b32 s2, 0xf000
	s_nop 0
	v_addc_co_u32_e32 v5, vcc, 0, v3, vcc
	v_add_co_u32_e32 v6, vcc, s2, v2
	s_mov_b32 s2, 0x11000
	s_nop 0
	v_addc_co_u32_e32 v7, vcc, 0, v3, vcc
	v_add_co_u32_e32 v8, vcc, s2, v2
	s_mov_b32 s2, 0x13000
	s_nop 0
	v_addc_co_u32_e32 v9, vcc, 0, v3, vcc
	v_add_co_u32_e32 v10, vcc, s2, v2
	s_mov_b32 s2, 0x15000
	s_nop 0
	v_addc_co_u32_e32 v11, vcc, 0, v3, vcc
	v_add_co_u32_e32 v12, vcc, s2, v2
	s_mov_b32 s2, 0x17000
	s_nop 0
	v_addc_co_u32_e32 v13, vcc, 0, v3, vcc
	v_add_co_u32_e32 v18, vcc, s2, v2
	s_mov_b32 s2, 0x19000
	s_nop 0
	v_addc_co_u32_e32 v19, vcc, 0, v3, vcc
	global_load_dword v77, v[8:9], off offset:-4096 nt
	global_load_dword v76, v[8:9], off nt
	global_load_dword v75, v[10:11], off offset:-4096 nt
	global_load_dword v74, v[10:11], off nt
	global_load_dword v69, v[12:13], off offset:-4096 nt
	global_load_dword v67, v[12:13], off nt
	global_load_dword v68, v[18:19], off offset:-4096 nt
	global_load_dword v66, v[18:19], off nt
	v_add_co_u32_e32 v8, vcc, s2, v2
	s_mov_b32 s2, 0x1b000
	s_nop 0
	v_addc_co_u32_e32 v9, vcc, 0, v3, vcc
	v_add_co_u32_e32 v10, vcc, s2, v2
	s_mov_b32 s2, 0x1d000
	s_nop 0
	v_addc_co_u32_e32 v11, vcc, 0, v3, vcc
	v_add_co_u32_e32 v12, vcc, s2, v2
	s_mov_b32 s2, 0x1f000
	s_nop 0
	v_addc_co_u32_e32 v13, vcc, 0, v3, vcc
	v_add_co_u32_e32 v18, vcc, s2, v2
	s_mov_b32 s2, 0x21000
	s_nop 0
	v_addc_co_u32_e32 v19, vcc, 0, v3, vcc
	global_load_dword v73, v[8:9], off offset:-4096 nt
	global_load_dword v72, v[8:9], off nt
	global_load_dword v71, v[10:11], off offset:-4096 nt
	global_load_dword v70, v[10:11], off nt
	global_load_dword v61, v[12:13], off offset:-4096 nt
	global_load_dword v59, v[12:13], off nt
	global_load_dword v60, v[18:19], off offset:-4096 nt
	global_load_dword v58, v[18:19], off nt
	v_add_co_u32_e32 v8, vcc, s2, v2
	s_mov_b32 s2, 0x23000
	s_nop 0
	v_addc_co_u32_e32 v9, vcc, 0, v3, vcc
	v_add_co_u32_e32 v10, vcc, s2, v2
	s_mov_b32 s2, 0x25000
	s_nop 0
	v_addc_co_u32_e32 v11, vcc, 0, v3, vcc
	v_add_co_u32_e32 v12, vcc, s2, v2
	s_mov_b32 s2, 0x27000
	s_nop 0
	v_addc_co_u32_e32 v13, vcc, 0, v3, vcc
	v_add_co_u32_e32 v18, vcc, s2, v2
	s_mov_b32 s2, 0x29000
	s_nop 0
	v_addc_co_u32_e32 v19, vcc, 0, v3, vcc
	global_load_dword v65, v[8:9], off offset:-4096 nt
	global_load_dword v64, v[8:9], off nt
	global_load_dword v63, v[10:11], off offset:-4096 nt
	global_load_dword v62, v[10:11], off nt
	global_load_dword v53, v[12:13], off offset:-4096 nt
	global_load_dword v50, v[12:13], off nt
	global_load_dword v52, v[18:19], off offset:-4096 nt
	global_load_dword v49, v[18:19], off nt
	v_add_co_u32_e32 v8, vcc, s2, v2
	s_mov_b32 s2, 0x2b000
	s_nop 0
	v_addc_co_u32_e32 v9, vcc, 0, v3, vcc
	v_add_co_u32_e32 v10, vcc, s2, v2
	s_mov_b32 s2, 0x2d000
	s_nop 0
	v_addc_co_u32_e32 v11, vcc, 0, v3, vcc
	v_add_co_u32_e32 v12, vcc, s2, v2
	s_mov_b32 s2, 0x2f000
	s_nop 0
	v_addc_co_u32_e32 v13, vcc, 0, v3, vcc
	v_add_co_u32_e32 v18, vcc, s2, v2
	s_mov_b32 s2, 0x31000
	s_nop 0
	v_addc_co_u32_e32 v19, vcc, 0, v3, vcc
	global_load_dword v57, v[8:9], off offset:-4096 nt
	global_load_dword v56, v[8:9], off nt
	global_load_dword v55, v[10:11], off offset:-4096 nt
	global_load_dword v54, v[10:11], off nt
	global_load_dword v44, v[12:13], off offset:-4096 nt
	global_load_dword v42, v[12:13], off nt
	global_load_dword v43, v[18:19], off offset:-4096 nt
	s_nop 0
	global_load_dword v19, v[18:19], off nt
	v_add_co_u32_e32 v8, vcc, s2, v2
	s_mov_b32 s2, 0x33000
	s_nop 0
	v_addc_co_u32_e32 v9, vcc, 0, v3, vcc
	v_add_co_u32_e32 v10, vcc, s2, v2
	s_mov_b32 s2, 0x35000
	s_nop 0
	v_addc_co_u32_e32 v11, vcc, 0, v3, vcc
	v_add_co_u32_e32 v12, vcc, s2, v2
	s_mov_b32 s2, 0x37000
	s_nop 0
	v_addc_co_u32_e32 v13, vcc, 0, v3, vcc
	v_add_co_u32_e32 v78, vcc, s2, v2
	s_mov_b32 s2, 0x39000
	s_nop 0
	v_addc_co_u32_e32 v79, vcc, 0, v3, vcc
	global_load_dword v48, v[8:9], off offset:-4096 nt
	global_load_dword v47, v[8:9], off nt
	global_load_dword v46, v[10:11], off offset:-4096 nt
	global_load_dword v45, v[10:11], off nt
	s_nop 0
	global_load_dword v11, v[12:13], off offset:-4096 nt
	global_load_dword v9, v[12:13], off nt
	global_load_dword v10, v[78:79], off offset:-4096 nt
	global_load_dword v8, v[78:79], off nt
	v_add_co_u32_e32 v12, vcc, s2, v2
	s_mov_b32 s2, 0x3b000
	s_nop 0
	v_addc_co_u32_e32 v13, vcc, 0, v3, vcc
	v_add_co_u32_e32 v78, vcc, s2, v2
	s_mov_b32 s2, 0x3c000
	s_nop 0
	v_addc_co_u32_e32 v79, vcc, 0, v3, vcc
	v_add_co_u32_e32 v82, vcc, s2, v2
	global_load_dword v17, v[12:13], off offset:-4096 nt
	s_nop 0
	global_load_dword v13, v[12:13], off nt
	s_nop 0
	global_load_dword v18, v[78:79], off offset:-4096 nt
	global_load_dword v12, v[78:79], off nt
	v_addc_co_u32_e32 v83, vcc, 0, v3, vcc
	v_add_co_u32_e32 v84, vcc, 0x3d000, v2
	s_movk_i32 s2, 0x3ff
	s_nop 0
	v_addc_co_u32_e32 v85, vcc, 0, v3, vcc
	v_add_co_u32_e32 v86, vcc, 0x3e000, v2
	v_cmp_lt_i32_e64 s[36:37], s2, v90
	s_nop 0
	v_addc_co_u32_e32 v87, vcc, 0, v3, vcc
	v_add_co_u32_e32 v88, vcc, 0x3f000, v2
	s_nop 1
	v_addc_co_u32_e32 v89, vcc, 0, v3, vcc
	global_load_dword v81, v[4:5], off offset:-4096 nt
	global_load_dword v80, v[4:5], off nt
	global_load_dword v79, v[6:7], off offset:-4096 nt
	global_load_dword v78, v[6:7], off nt
	s_nop 0
	global_load_dword v7, v[82:83], off nt
	global_load_dword v6, v[84:85], off nt
	global_load_dword v5, v[86:87], off nt
	global_load_dword v4, v[88:89], off nt
	s_and_saveexec_b64 s[2:3], s[36:37]
	s_xor_b64 s[2:3], exec, s[2:3]
	s_cbranch_execz .LBB0_2029
	ds_write2_b32 v21, v51, v51 offset1:65
	ds_write2_b32 v21, v51, v51 offset0:130 offset1:195
; #define LAS __attribute__((address_space(3)))
; __device__ __forceinline__ unsigned pk2(float lo, float hi) { return f2bf(lo) | (f2bf(hi) << 16); }
; __device__ __forceinline__ void transpose_item(const float* W, int N, bf16* WT, int ldt, LAS unsigned* scr, int item, int lane, int mode, int aux) {
;     const int nblk = (N + 63) >> 6, kb = item / nblk, nb = item - kb * nblk, k0 = 64 * kb, n0 = 64 * nb;
;     const int ncol = n0 + lane; const bool okc = ncol < N;
;     const float* wp = W + (size_t)k0 * N + (okc ? ncol : 0);
;     float v[64];
; #pragma unroll
;     for (int i = 0; i < 64; ++i) v[i] = wp[(size_t)i * N];
; #pragma unroll
;     for (int i = 0; i < 32; ++i) scr[i * 65 + lane] = okc ? pk2(v[2 * i], v[2 * i + 1]) : 0u;
.LBB0_2029:
	s_or_saveexec_b64 s[2:3], s[2:3]
	v_mov_b32_e32 v82, 0
	v_mov_b32_e32 v83, 0
	s_xor_b64 exec, exec, s[2:3]
	s_cbranch_execz .LBB0_2031
	v_add_co_u32_e32 v82, vcc, 0xb000, v2
	s_movk_i32 s21, 0x6000
	s_nop 0
	v_addc_co_u32_e32 v83, vcc, 0, v3, vcc
	global_load_dword v84, v[82:83], off nt
	v_add_co_u32_e32 v82, vcc, 0xa000, v2
	s_movk_i32 s22, 0x7fff
	s_nop 0
	v_addc_co_u32_e32 v83, vcc, 0, v3, vcc
	global_load_dword v85, v[82:83], off nt
	v_add_co_u32_e32 v82, vcc, 0x9000, v2
	s_nop 1
	v_addc_co_u32_e32 v83, vcc, 0, v3, vcc
	global_load_dword v86, v[82:83], off nt
	v_add_co_u32_e32 v82, vcc, 0x8000, v2
	s_nop 1
	v_addc_co_u32_e32 v83, vcc, 0, v3, vcc
	global_load_dword v87, v[82:83], off nt
	v_add_co_u32_e32 v82, vcc, 0x7000, v2
	s_nop 1
	v_addc_co_u32_e32 v83, vcc, 0, v3, vcc
	global_load_dword v88, v[82:83], off nt
	v_add_co_u32_e32 v82, vcc, s21, v2
	s_movk_i32 s21, 0x3000
	s_nop 0
	v_addc_co_u32_e32 v83, vcc, 0, v3, vcc
	global_load_dword v89, v[82:83], off nt
	v_add_co_u32_e32 v82, vcc, 0x5000, v2
	s_nop 1
	v_addc_co_u32_e32 v83, vcc, 0, v3, vcc
	global_load_dword v90, v[82:83], off nt
	v_add_co_u32_e32 v82, vcc, s70, v2
	s_nop 1
	v_addc_co_u32_e32 v83, vcc, 0, v3, vcc
	global_load_dword v91, v[82:83], off nt
	v_add_co_u32_e32 v82, vcc, s21, v2
	s_movk_i32 s21, 0x2000
	s_nop 0
	v_addc_co_u32_e32 v83, vcc, 0, v3, vcc
	global_load_dword v92, v[82:83], off nt
	v_add_co_u32_e32 v82, vcc, s21, v2
	s_movk_i32 s21, 0x1000
	s_nop 0
	v_addc_co_u32_e32 v83, vcc, 0, v3, vcc
	global_load_dword v93, v[82:83], off nt
	v_add_co_u32_e32 v82, vcc, s21, v2
	s_mov_b32 s21, 0xffff0000
	s_nop 0
	v_addc_co_u32_e32 v83, vcc, 0, v3, vcc
	global_load_dword v82, v[82:83], off nt
	s_nop 0
	global_load_dword v2, v[2:3], off nt
	s_waitcnt vmcnt(5)
	v_bfe_u32 v83, v90, 16, 1
	v_add3_u32 v83, v90, v83, s22
	s_waitcnt vmcnt(0)
	v_bfe_u32 v3, v2, 16, 1
	v_add3_u32 v2, v2, v3, s22
	v_bfe_u32 v3, v82, 16, 1
	v_lshrrev_b32_e32 v2, 16, v2
	v_add3_u32 v3, v82, v3, s22
	v_and_or_b32 v2, v3, s21, v2
	v_bfe_u32 v3, v93, 16, 1
	v_add3_u32 v3, v93, v3, s22
	v_bfe_u32 v82, v92, 16, 1
	v_lshrrev_b32_e32 v3, 16, v3
	v_add3_u32 v82, v92, v82, s22
	v_and_or_b32 v3, v82, s21, v3
	v_bfe_u32 v82, v91, 16, 1
	v_add3_u32 v82, v91, v82, s22
	v_lshrrev_b32_e32 v82, 16, v82
	v_and_or_b32 v82, v83, s21, v82
	v_bfe_u32 v83, v89, 16, 1
	v_add3_u32 v83, v89, v83, s22
	v_bfe_u32 v89, v88, 16, 1
	v_lshrrev_b32_e32 v83, 16, v83
	v_add3_u32 v88, v88, v89, s22
	v_and_or_b32 v83, v88, s21, v83
	ds_write2_b32 v21, v2, v3 offset1:65
	ds_write2_b32 v21, v82, v83 offset0:130 offset1:195
	v_bfe_u32 v2, v87, 16, 1
	v_add3_u32 v2, v87, v2, s22
	v_bfe_u32 v3, v86, 16, 1
	v_lshrrev_b32_e32 v2, 16, v2
	v_add3_u32 v3, v86, v3, s22
	v_and_or_b32 v82, v3, s21, v2
	v_bfe_u32 v2, v85, 16, 1
	v_add3_u32 v2, v85, v2, s22
	v_bfe_u32 v3, v84, 16, 1
	v_lshrrev_b32_e32 v2, 16, v2
	v_add3_u32 v3, v84, v3, s22
	v_and_or_b32 v83, v3, s21, v2

; #define LAS __attribute__((address_space(3)))
; __device__ __forceinline__ unsigned pk2(float lo, float hi) { return f2bf(lo) | (f2bf(hi) << 16); }
; __device__ __forceinline__ void transpose_item(const float* W, int N, bf16* WT, int ldt, LAS unsigned* scr, int item, int lane, int mode, int aux) {
;     const int nblk = (N + 63) >> 6, kb = item / nblk, nb = item - kb * nblk, k0 = 64 * kb, n0 = 64 * nb;
;     const int ncol = n0 + lane; const bool okc = ncol < N;
;     const float* wp = W + (size_t)k0 * N + (okc ? ncol : 0);
;     float v[64];
; #pragma unroll
;     for (int i = 0; i < 64; ++i) v[i] = wp[(size_t)i * N];
; #pragma unroll
;     for (int i = 0; i < 32; ++i) scr[i * 65 + lane] = okc ? pk2(v[2 * i], v[2 * i + 1]) : 0u;
; __device__ __forceinline__ void convert_rest(const Args& a, LAS unsigned char* lds, int wave, int lane, int gw, int ngw, int l, int it0, int it1) {
;     ...
;         if (r < WI_BR) { const int g = r >> 6; transpose_item(a.in[I_WBR] + (size_t)(l * 4 + g) * 256 * 1024, 1024, (bf16*)(ws + WS_WBR) + (size_t)g * 1024 * 256, 256, scr, r & 63, lane, 0, 0); continue; } r -= WI_BR;
.LBB0_2075:
	s_andn2_b64 vcc, exec, s[0:1]
	s_cbranch_vccnz .LBB0_2077
	v_readlane_b32 s2, v254, 32
	s_add_i32 s0, s6, 0xfffffc00
	v_readlane_b32 s3, v254, 33
	s_lshr_b32 s0, s0, 6
	s_mov_b32 s17, s3
	s_add_i32 s16, s0, s8
	s_mov_b32 s1, s17
	s_lshl_b64 s[2:3], s[16:17], 20
	v_writelane_b32 v254, s0, 32
	s_add_u32 s21, s82, s2
	s_addc_u32 s22, s83, s3
	v_writelane_b32 v254, s1, 33
	s_mov_b32 s1, s17
	s_lshl_b64 s[0:1], s[0:1], 19
	v_readlane_b32 s2, v254, 1
	s_add_u32 s3, s2, s0
	v_readlane_b32 s0, v254, 2
	s_addc_u32 s16, s0, s1
	s_and_b32 s17, s11, 0xc0
	s_add_i32 s0, s4, 0xa2000
	s_and_b32 s2, s0, 0x3c0
	s_lshl_b32 s0, s17, 12
	v_or_b32_e32 v2, s2, v20
	s_add_u32 s0, s21, s0
	s_addc_u32 s1, s22, 0
	v_lshlrev_b32_e32 v50, 2, v2
	v_lshl_add_u64 v[2:3], s[0:1], 0, v[50:51]
	s_mov_b32 s21, 0x9000
	v_add_co_u32_e32 v6, vcc, s21, v2
	s_mov_b32 s21, 0xb000
	s_nop 0
	v_addc_co_u32_e32 v7, vcc, 0, v3, vcc
	v_add_co_u32_e32 v8, vcc, s21, v2
	s_mov_b32 s21, 0xd000
	s_nop 0
	v_addc_co_u32_e32 v9, vcc, 0, v3, vcc
	v_add_co_u32_e32 v10, vcc, s21, v2
	s_mov_b32 s21, 0xf000
	s_nop 0
	v_addc_co_u32_e32 v11, vcc, 0, v3, vcc
	global_load_dword v5, v[6:7], off offset:-4096 nt
	global_load_dword v4, v[6:7], off nt
	s_nop 0
	global_load_dword v7, v[8:9], off offset:-4096 nt
	global_load_dword v6, v[8:9], off nt
	s_nop 0
	global_load_dword v9, v[10:11], off offset:-4096 nt
	global_load_dword v8, v[10:11], off nt
	v_add_co_u32_e32 v10, vcc, s21, v2
	s_mov_b32 s21, 0x11000
	s_nop 0
	v_addc_co_u32_e32 v11, vcc, 0, v3, vcc
	v_add_co_u32_e32 v18, vcc, s21, v2
	s_mov_b32 s21, 0x13000
	s_nop 0
	v_addc_co_u32_e32 v19, vcc, 0, v3, vcc
	v_add_co_u32_e32 v42, vcc, s21, v2
	s_mov_b32 s21, 0x15000
	s_nop 0
	v_addc_co_u32_e32 v43, vcc, 0, v3, vcc
	v_add_co_u32_e32 v44, vcc, s21, v2
	s_mov_b32 s21, 0x17000
	s_nop 0
	v_addc_co_u32_e32 v45, vcc, 0, v3, vcc
	global_load_dword v13, v[10:11], off offset:-4096 nt
	s_nop 0
	global_load_dword v11, v[10:11], off nt
	s_nop 0
	global_load_dword v12, v[18:19], off offset:-4096 nt
	global_load_dword v10, v[18:19], off nt
	s_nop 0
	global_load_dword v18, v[42:43], off offset:-4096 nt
	global_load_dword v17, v[42:43], off nt
	s_nop 0
	global_load_dword v42, v[44:45], off offset:-4096 nt
	global_load_dword v19, v[44:45], off nt
	v_add_co_u32_e32 v44, vcc, s21, v2
	s_mov_b32 s21, 0x19000
	s_nop 0
	v_addc_co_u32_e32 v45, vcc, 0, v3, vcc
	v_add_co_u32_e32 v48, vcc, s21, v2
	s_mov_b32 s21, 0x1b000
	s_nop 0
	v_addc_co_u32_e32 v49, vcc, 0, v3, vcc
	v_add_co_u32_e32 v52, vcc, s21, v2
	s_mov_b32 s21, 0x1d000
	s_nop 0
	v_addc_co_u32_e32 v53, vcc, 0, v3, vcc
	v_add_co_u32_e32 v54, vcc, s21, v2
	s_mov_b32 s21, 0x1f000
	s_nop 0
	v_addc_co_u32_e32 v55, vcc, 0, v3, vcc
	global_load_dword v46, v[44:45], off offset:-4096 nt
	s_nop 0
	global_load_dword v44, v[44:45], off nt
	s_nop 0
	global_load_dword v45, v[48:49], off offset:-4096 nt
	global_load_dword v43, v[48:49], off nt
	s_nop 0
	global_load_dword v48, v[52:53], off offset:-4096 nt
	global_load_dword v47, v[52:53], off nt
	s_nop 0
	global_load_dword v52, v[54:55], off offset:-4096 nt
	global_load_dword v49, v[54:55], off nt
	v_add_co_u32_e32 v54, vcc, s21, v2
	s_mov_b32 s21, 0x21000
	s_nop 0
	v_addc_co_u32_e32 v55, vcc, 0, v3, vcc
	global_load_dword v62, v[54:55], off offset:-4096 nt
	global_load_dword v58, v[54:55], off nt
	v_add_co_u32_e32 v54, vcc, s21, v2
	s_mov_b32 s21, 0x23000
	s_nop 0
	v_addc_co_u32_e32 v55, vcc, 0, v3, vcc
	v_add_co_u32_e32 v56, vcc, s21, v2
	s_mov_b32 s21, 0x25000
	s_nop 0
	v_addc_co_u32_e32 v57, vcc, 0, v3, vcc
	global_load_dword v59, v[54:55], off offset:-4096 nt
	s_nop 0
	global_load_dword v55, v[54:55], off nt
	s_nop 0
	global_load_dword v70, v[56:57], off offset:-4096 nt
	global_load_dword v67, v[56:57], off nt
	v_add_co_u32_e32 v56, vcc, s21, v2
	s_mov_b32 s21, 0x27000
	s_nop 0
	v_addc_co_u32_e32 v57, vcc, 0, v3, vcc
	global_load_dword v78, v[56:57], off offset:-4096 nt
	global_load_dword v74, v[56:57], off nt
	v_add_co_u32_e32 v56, vcc, s21, v2
	s_mov_b32 s21, 0x29000
	s_nop 0
	v_addc_co_u32_e32 v57, vcc, 0, v3, vcc
	global_load_dword v86, v[56:57], off offset:-4096 nt
	global_load_dword v84, v[56:57], off nt
	v_add_co_u32_e32 v56, vcc, s21, v2
	s_mov_b32 s21, 0x2b000
	s_nop 0
	v_addc_co_u32_e32 v57, vcc, 0, v3, vcc
	global_load_dword v85, v[56:57], off offset:-4096 nt
	global_load_dword v82, v[56:57], off nt
	v_add_co_u32_e32 v56, vcc, s21, v2
	s_mov_b32 s21, 0x2d000
	s_nop 0
	v_addc_co_u32_e32 v57, vcc, 0, v3, vcc
	global_load_dword v83, v[56:57], off offset:-4096 nt
	global_load_dword v81, v[56:57], off nt
	v_add_co_u32_e32 v56, vcc, s21, v2
	s_mov_b32 s21, 0x2f000
	s_nop 0
	v_addc_co_u32_e32 v57, vcc, 0, v3, vcc
	global_load_dword v80, v[56:57], off offset:-4096 nt
	global_load_dword v77, v[56:57], off nt
	v_add_co_u32_e32 v56, vcc, s21, v2
	s_mov_b32 s21, 0x31000
	s_nop 0
	v_addc_co_u32_e32 v57, vcc, 0, v3, vcc
	global_load_dword v79, v[56:57], off offset:-4096 nt
	global_load_dword v75, v[56:57], off nt
	v_add_co_u32_e32 v56, vcc, s21, v2
	s_mov_b32 s21, 0x33000
	s_nop 0
	v_addc_co_u32_e32 v57, vcc, 0, v3, vcc
	global_load_dword v76, v[56:57], off offset:-4096 nt
	global_load_dword v72, v[56:57], off nt
	v_add_co_u32_e32 v56, vcc, s21, v2
	s_mov_b32 s21, 0x35000
	s_nop 0
	v_addc_co_u32_e32 v57, vcc, 0, v3, vcc
	global_load_dword v73, v[56:57], off offset:-4096 nt
	global_load_dword v71, v[56:57], off nt
	v_add_co_u32_e32 v56, vcc, s21, v2
	s_mov_b32 s21, 0x37000
	s_nop 0
	v_addc_co_u32_e32 v57, vcc, 0, v3, vcc
	global_load_dword v69, v[56:57], off offset:-4096 nt
	global_load_dword v66, v[56:57], off nt
	v_add_co_u32_e32 v56, vcc, s21, v2
	s_mov_b32 s21, 0x39000
; __device__ __forceinline__ unsigned pk2(float lo, float hi) { return f2bf(lo) | (f2bf(hi) << 16); }
; #define LDS_WAIT() asm volatile("s_waitcnt lgkmcnt(0)" ::: "memory")
; __device__ __forceinline__ void transpose_item(const float* W, int N, bf16* WT, int ldt, LAS unsigned* scr, int item, int lane, int mode, int aux) {
;     ...
; #pragma unroll
;     for (int i = 0; i < 64; ++i) v[i] = wp[(size_t)i * N];
; #pragma unroll
;     for (int i = 0; i < 32; ++i) scr[i * 65 + lane] = okc ? pk2(v[2 * i], v[2 * i + 1]) : 0u;
;     LDS_WAIT();
;     const int c = lane & 7;
; #pragma unroll
;     for (int j = 0; j < 8; ++j) { const int nn = (lane >> 3) + 8 * j, n = n0 + nn;
;         v4u o; o.x = scr[(4 * c + 0) * 65 + nn]; o.y = scr[(4 * c + 1) * 65 + nn]; o.z = scr[(4 * c + 2) * 65 + nn]; o.w = scr[(4 * c + 3) * 65 + nn];
;         if (n < N) *(v4u*)(WT + (size_t)rowmap(mode, aux, n) * ldt + k0 + 8 * c) = o; }
	s_nop 0
	v_addc_co_u32_e32 v57, vcc, 0, v3, vcc
	global_load_dword v68, v[56:57], off offset:-4096 nt
	global_load_dword v64, v[56:57], off nt
	v_add_co_u32_e32 v56, vcc, s21, v2
	s_mov_b32 s21, 0x3b000
	s_nop 0
	v_addc_co_u32_e32 v57, vcc, 0, v3, vcc
	global_load_dword v65, v[56:57], off offset:-4096 nt
	global_load_dword v61, v[56:57], off nt
	v_add_co_u32_e32 v56, vcc, s21, v2
	s_mov_b32 s21, 0x3d000
	s_nop 0
	v_addc_co_u32_e32 v57, vcc, 0, v3, vcc
	v_add_co_u32_e32 v88, vcc, s21, v2
	s_mov_b32 s21, 0x3f000
	s_nop 0
	v_addc_co_u32_e32 v89, vcc, 0, v3, vcc
	global_load_dword v63, v[56:57], off offset:-4096 nt
	global_load_dword v60, v[56:57], off nt
	s_nop 0
	global_load_dword v57, v[88:89], off offset:-4096 nt
	global_load_dword v54, v[88:89], off nt
	v_add_co_u32_e32 v88, vcc, s21, v2
	s_movk_i32 s21, 0x7000
	s_nop 0
	v_addc_co_u32_e32 v89, vcc, 0, v3, vcc
	global_load_dword v56, v[88:89], off offset:-4096 nt
	global_load_dword v53, v[88:89], off nt
	v_add_co_u32_e32 v88, vcc, s21, v2
	s_movk_i32 s21, 0x6000
	s_nop 0
	v_addc_co_u32_e32 v89, vcc, 0, v3, vcc
	global_load_dword v87, v[88:89], off nt
	v_add_co_u32_e32 v88, vcc, s21, v2
	s_movk_i32 s21, 0x3000
	s_nop 0
	v_addc_co_u32_e32 v89, vcc, 0, v3, vcc
	global_load_dword v90, v[88:89], off nt
	v_add_co_u32_e32 v88, vcc, s38, v2
	s_nop 1
	v_addc_co_u32_e32 v89, vcc, 0, v3, vcc
	global_load_dword v91, v[88:89], off nt
	v_add_co_u32_e32 v88, vcc, s70, v2
	s_nop 1
	v_addc_co_u32_e32 v89, vcc, 0, v3, vcc
	global_load_dword v92, v[88:89], off nt
	v_add_co_u32_e32 v88, vcc, s21, v2
	s_movk_i32 s21, 0x2000
	s_nop 0
	v_addc_co_u32_e32 v89, vcc, 0, v3, vcc
	global_load_dword v93, v[88:89], off nt
	v_add_co_u32_e32 v88, vcc, s21, v2
	s_movk_i32 s21, 0x1000
	s_nop 0
	v_addc_co_u32_e32 v89, vcc, 0, v3, vcc
	v_add_co_u32_e32 v2, vcc, s21, v2
	global_load_dword v88, v[88:89], off nt
	s_nop 0
	v_addc_co_u32_e32 v3, vcc, 0, v3, vcc
	global_load_dword v2, v[2:3], off nt
	s_nop 0
	global_load_dword v3, v50, s[0:1] nt
	s_movk_i32 s1, 0x7fff
	s_mov_b32 s0, 0xffff0000
	s_waitcnt vmcnt(0)
	v_bfe_u32 v50, v3, 16, 1
	v_add3_u32 v3, v3, v50, s1
	v_bfe_u32 v50, v2, 16, 1
	v_lshrrev_b32_e32 v3, 16, v3
	v_add3_u32 v2, v2, v50, s1
	v_and_or_b32 v2, v2, s0, v3
	v_bfe_u32 v3, v88, 16, 1
	v_add3_u32 v3, v88, v3, s1
	v_bfe_u32 v50, v93, 16, 1
	v_lshrrev_b32_e32 v3, 16, v3
	v_add3_u32 v50, v93, v50, s1
	v_and_or_b32 v3, v50, s0, v3
	ds_write2_b32 v21, v2, v3 offset1:65
	v_bfe_u32 v2, v92, 16, 1
	v_add3_u32 v2, v92, v2, s1
	v_bfe_u32 v3, v91, 16, 1
	v_lshrrev_b32_e32 v2, 16, v2
	v_add3_u32 v3, v91, v3, s1
	v_and_or_b32 v2, v3, s0, v2
	v_bfe_u32 v3, v90, 16, 1
	v_add3_u32 v3, v90, v3, s1
	v_bfe_u32 v50, v87, 16, 1
	v_lshrrev_b32_e32 v3, 16, v3
	v_add3_u32 v50, v87, v50, s1
	v_and_or_b32 v3, v50, s0, v3
	ds_write2_b32 v21, v2, v3 offset0:130 offset1:195
	v_bfe_u32 v2, v5, 16, 1
	v_add3_u32 v2, v5, v2, s1
	v_bfe_u32 v3, v4, 16, 1
	v_lshrrev_b32_e32 v2, 16, v2
	v_add3_u32 v3, v4, v3, s1
	v_and_or_b32 v2, v3, s0, v2
	v_bfe_u32 v3, v7, 16, 1
	v_add3_u32 v3, v7, v3, s1
	v_bfe_u32 v4, v6, 16, 1
	v_lshrrev_b32_e32 v3, 16, v3
	v_add3_u32 v4, v6, v4, s1
	v_and_or_b32 v3, v4, s0, v3
	v_add_u32_e32 v4, 0x400, v21
	ds_write2_b32 v4, v2, v3 offset0:4 offset1:69
	v_bfe_u32 v2, v9, 16, 1
	v_add3_u32 v2, v9, v2, s1
	v_bfe_u32 v3, v8, 16, 1
	v_lshrrev_b32_e32 v2, 16, v2
	v_add3_u32 v3, v8, v3, s1
	v_and_or_b32 v2, v3, s0, v2
	v_bfe_u32 v3, v13, 16, 1
	v_add3_u32 v3, v13, v3, s1
	v_bfe_u32 v5, v11, 16, 1
	v_lshrrev_b32_e32 v3, 16, v3
	v_add3_u32 v5, v11, v5, s1
	v_and_or_b32 v3, v5, s0, v3
	ds_write2_b32 v4, v2, v3 offset0:134 offset1:199
	v_bfe_u32 v2, v12, 16, 1
	v_add3_u32 v2, v12, v2, s1
	v_bfe_u32 v3, v10, 16, 1
	v_lshrrev_b32_e32 v2, 16, v2
	v_add3_u32 v3, v10, v3, s1
	v_and_or_b32 v2, v3, s0, v2
	v_bfe_u32 v3, v18, 16, 1
	v_add3_u32 v3, v18, v3, s1
	v_bfe_u32 v4, v17, 16, 1
	v_lshrrev_b32_e32 v3, 16, v3
	v_add3_u32 v4, v17, v4, s1
	v_and_or_b32 v3, v4, s0, v3
	v_add_u32_e32 v4, 0x800, v21
	ds_write2_b32 v4, v2, v3 offset0:8 offset1:73
	v_bfe_u32 v2, v42, 16, 1
	v_add3_u32 v2, v42, v2, s1
	v_bfe_u32 v3, v19, 16, 1
	v_lshrrev_b32_e32 v2, 16, v2
	v_add3_u32 v3, v19, v3, s1
	v_and_or_b32 v2, v3, s0, v2
	v_bfe_u32 v3, v46, 16, 1
	v_add3_u32 v3, v46, v3, s1
	v_bfe_u32 v5, v44, 16, 1
	v_lshrrev_b32_e32 v3, 16, v3
	v_add3_u32 v5, v44, v5, s1
	v_and_or_b32 v3, v5, s0, v3
	ds_write2_b32 v4, v2, v3 offset0:138 offset1:203
	v_bfe_u32 v2, v45, 16, 1
	v_add3_u32 v2, v45, v2, s1
	v_bfe_u32 v3, v43, 16, 1
	v_lshrrev_b32_e32 v2, 16, v2
	v_add3_u32 v3, v43, v3, s1
	v_and_or_b32 v2, v3, s0, v2
	v_bfe_u32 v3, v48, 16, 1
	v_add3_u32 v3, v48, v3, s1
	v_bfe_u32 v4, v47, 16, 1
	v_lshrrev_b32_e32 v3, 16, v3
	v_add3_u32 v4, v47, v4, s1
	v_and_or_b32 v3, v4, s0, v3
	v_add_u32_e32 v4, 0xc00, v21
	ds_write2_b32 v4, v2, v3 offset0:12 offset1:77
	v_bfe_u32 v2, v52, 16, 1
	v_add3_u32 v2, v52, v2, s1
	v_bfe_u32 v3, v49, 16, 1
	v_lshrrev_b32_e32 v2, 16, v2
	v_add3_u32 v3, v49, v3, s1
	v_and_or_b32 v2, v3, s0, v2
	v_bfe_u32 v3, v62, 16, 1
	v_add3_u32 v3, v62, v3, s1
	v_bfe_u32 v5, v58, 16, 1
	v_lshrrev_b32_e32 v3, 16, v3
	v_add3_u32 v5, v58, v5, s1
	v_and_or_b32 v3, v5, s0, v3
	ds_write2_b32 v4, v2, v3 offset0:142 offset1:207
	v_bfe_u32 v2, v59, 16, 1
	v_add3_u32 v2, v59, v2, s1
	v_bfe_u32 v3, v55, 16, 1
	v_lshrrev_b32_e32 v2, 16, v2
	v_add3_u32 v3, v55, v3, s1
	v_and_or_b32 v2, v3, s0, v2
	v_bfe_u32 v3, v70, 16, 1
	v_add3_u32 v3, v70, v3, s1
	v_bfe_u32 v4, v67, 16, 1
	v_lshrrev_b32_e32 v3, 16, v3
	v_add3_u32 v4, v67, v4, s1
	v_and_or_b32 v3, v4, s0, v3
	v_add_u32_e32 v4, 0x1000, v21
	ds_write2_b32 v4, v2, v3 offset0:16 offset1:81
	v_bfe_u32 v2, v78, 16, 1
; __device__ __forceinline__ unsigned pk2(float lo, float hi) { return f2bf(lo) | (f2bf(hi) << 16); }
; #define LDS_WAIT() asm volatile("s_waitcnt lgkmcnt(0)" ::: "memory")
; __device__ __forceinline__ void transpose_item(const float* W, int N, bf16* WT, int ldt, LAS unsigned* scr, int item, int lane, int mode, int aux) {
;     ...
;     for (int i = 0; i < 32; ++i) scr[i * 65 + lane] = okc ? pk2(v[2 * i], v[2 * i + 1]) : 0u;
;     LDS_WAIT();
;     const int c = lane & 7;
; #pragma unroll
;     for (int j = 0; j < 8; ++j) { const int nn = (lane >> 3) + 8 * j, n = n0 + nn;
;         v4u o; o.x = scr[(4 * c + 0) * 65 + nn]; o.y = scr[(4 * c + 1) * 65 + nn]; o.z = scr[(4 * c + 2) * 65 + nn]; o.w = scr[(4 * c + 3) * 65 + nn];
;         if (n < N) *(v4u*)(WT + (size_t)rowmap(mode, aux, n) * ldt + k0 + 8 * c) = o; }
;     LDS_WAIT();
	v_add3_u32 v2, v78, v2, s1
	v_bfe_u32 v3, v74, 16, 1
	v_lshrrev_b32_e32 v2, 16, v2
	v_add3_u32 v3, v74, v3, s1
	v_and_or_b32 v2, v3, s0, v2
	v_bfe_u32 v3, v86, 16, 1
	v_add3_u32 v3, v86, v3, s1
	v_bfe_u32 v5, v84, 16, 1
	v_lshrrev_b32_e32 v3, 16, v3
	v_add3_u32 v5, v84, v5, s1
	v_and_or_b32 v3, v5, s0, v3
	ds_write2_b32 v4, v2, v3 offset0:146 offset1:211
	v_bfe_u32 v2, v85, 16, 1
	v_add3_u32 v2, v85, v2, s1
	v_bfe_u32 v3, v82, 16, 1
	v_lshrrev_b32_e32 v2, 16, v2
	v_add3_u32 v3, v82, v3, s1
	v_and_or_b32 v2, v3, s0, v2
	v_bfe_u32 v3, v83, 16, 1
	v_add3_u32 v3, v83, v3, s1
	v_bfe_u32 v4, v81, 16, 1
	v_lshrrev_b32_e32 v3, 16, v3
	v_add3_u32 v4, v81, v4, s1
	v_and_or_b32 v3, v4, s0, v3
	v_add_u32_e32 v4, 0x1400, v21
	ds_write2_b32 v4, v2, v3 offset0:20 offset1:85
	v_bfe_u32 v2, v80, 16, 1
	v_add3_u32 v2, v80, v2, s1
	v_bfe_u32 v3, v77, 16, 1
	v_lshrrev_b32_e32 v2, 16, v2
	v_add3_u32 v3, v77, v3, s1
	v_and_or_b32 v2, v3, s0, v2
	v_bfe_u32 v3, v79, 16, 1
	v_add3_u32 v3, v79, v3, s1
	v_bfe_u32 v5, v75, 16, 1
	v_lshrrev_b32_e32 v3, 16, v3
	v_add3_u32 v5, v75, v5, s1
	v_and_or_b32 v3, v5, s0, v3
	ds_write2_b32 v4, v2, v3 offset0:150 offset1:215
	v_bfe_u32 v2, v76, 16, 1
	v_add3_u32 v2, v76, v2, s1
	v_bfe_u32 v3, v72, 16, 1
	v_lshrrev_b32_e32 v2, 16, v2
	v_add3_u32 v3, v72, v3, s1
	v_and_or_b32 v2, v3, s0, v2
	v_bfe_u32 v3, v73, 16, 1
	v_add3_u32 v3, v73, v3, s1
	v_bfe_u32 v4, v71, 16, 1
	v_lshrrev_b32_e32 v3, 16, v3
	v_add3_u32 v4, v71, v4, s1
	v_and_or_b32 v3, v4, s0, v3
	v_add_u32_e32 v4, 0x1800, v21
	ds_write2_b32 v4, v2, v3 offset0:24 offset1:89
	v_bfe_u32 v2, v69, 16, 1
	v_add3_u32 v2, v69, v2, s1
	v_bfe_u32 v3, v66, 16, 1
	v_lshrrev_b32_e32 v2, 16, v2
	v_add3_u32 v3, v66, v3, s1
	v_and_or_b32 v2, v3, s0, v2
	v_bfe_u32 v3, v68, 16, 1
	v_add3_u32 v3, v68, v3, s1
	v_bfe_u32 v5, v64, 16, 1
	v_lshrrev_b32_e32 v3, 16, v3
	v_add3_u32 v5, v64, v5, s1
	v_and_or_b32 v3, v5, s0, v3
	ds_write2_b32 v4, v2, v3 offset0:154 offset1:219
	v_bfe_u32 v2, v65, 16, 1
	v_add3_u32 v2, v65, v2, s1
	v_bfe_u32 v3, v61, 16, 1
	v_lshrrev_b32_e32 v2, 16, v2
	v_add3_u32 v3, v61, v3, s1
	v_and_or_b32 v2, v3, s0, v2
	v_bfe_u32 v3, v63, 16, 1
	v_add3_u32 v3, v63, v3, s1
	v_bfe_u32 v4, v60, 16, 1
	v_lshrrev_b32_e32 v3, 16, v3
	v_add3_u32 v4, v60, v4, s1
	v_and_or_b32 v3, v4, s0, v3
	v_add_u32_e32 v4, 0x1c00, v21
	ds_write2_b32 v4, v2, v3 offset0:28 offset1:93
	v_bfe_u32 v2, v57, 16, 1
	v_add3_u32 v2, v57, v2, s1
	v_bfe_u32 v3, v54, 16, 1
	v_lshrrev_b32_e32 v2, 16, v2
	v_add3_u32 v3, v54, v3, s1
	v_and_or_b32 v2, v3, s0, v2
	v_bfe_u32 v3, v56, 16, 1
	v_add3_u32 v3, v56, v3, s1
	v_bfe_u32 v5, v53, 16, 1
	v_lshrrev_b32_e32 v3, 16, v3
	v_add3_u32 v5, v53, v5, s1
	v_and_or_b32 v3, v5, s0, v3
	ds_write2_b32 v4, v2, v3 offset0:158 offset1:223
	s_waitcnt lgkmcnt(0)
	s_lshl_b32 s0, s17, 1
	ds_read2_b32 v[2:3], v23 offset0:65 offset1:73
	ds_read2_b32 v[12:13], v23 offset0:130 offset1:138
	ds_read2_b32 v[4:5], v23 offset0:195 offset1:203
	ds_read2_b32 v[18:19], v23 offset1:8
	s_add_u32 s0, s3, s0
	s_addc_u32 s1, s16, 0
	v_mov_b32_e32 v17, v51
	v_lshl_add_u64 v[10:11], s[0:1], 0, v[16:17]
	v_or_b32_e32 v17, s2, v22
	v_lshlrev_b32_e32 v50, 9, v17
	s_waitcnt lgkmcnt(0)
	v_mov_b32_e32 v6, v18
	v_mov_b32_e32 v7, v2
	v_mov_b32_e32 v8, v12
	v_mov_b32_e32 v9, v4
	v_lshl_add_u64 v[42:43], v[10:11], 0, v[50:51]
	global_store_dwordx4 v[42:43], v[6:9], off
	v_mov_b32_e32 v2, v19
	v_mov_b32_e32 v4, v13
	v_or_b32_e32 v6, s2, v24
	v_lshlrev_b32_e32 v50, 9, v6
	v_lshl_add_u64 v[6:7], v[10:11], 0, v[50:51]
	global_store_dwordx4 v[6:7], v[2:5], off
	ds_read2_b32 v[12:13], v23 offset0:16 offset1:24
	ds_read2_b32 v[2:3], v23 offset0:81 offset1:89
	ds_read2_b32 v[18:19], v23 offset0:146 offset1:154
	ds_read2_b32 v[4:5], v23 offset0:211 offset1:219
	v_or_b32_e32 v17, s2, v25
	v_lshlrev_b32_e32 v50, 9, v17
	s_waitcnt lgkmcnt(3)
	v_mov_b32_e32 v6, v12
	s_waitcnt lgkmcnt(2)
	v_mov_b32_e32 v7, v2
	s_waitcnt lgkmcnt(1)
	v_mov_b32_e32 v8, v18
	s_waitcnt lgkmcnt(0)
	v_mov_b32_e32 v9, v4
	v_lshl_add_u64 v[42:43], v[10:11], 0, v[50:51]
	global_store_dwordx4 v[42:43], v[6:9], off
	v_mov_b32_e32 v2, v13
	v_mov_b32_e32 v4, v19
	v_or_b32_e32 v6, s2, v26
	v_lshlrev_b32_e32 v50, 9, v6
	v_lshl_add_u64 v[6:7], v[10:11], 0, v[50:51]
	global_store_dwordx4 v[6:7], v[2:5], off
	ds_read2_b32 v[2:3], v23 offset0:97 offset1:105
	ds_read2_b32 v[12:13], v23 offset0:162 offset1:170
	ds_read2_b32 v[4:5], v23 offset0:227 offset1:235
	ds_read2_b32 v[18:19], v23 offset0:32 offset1:40
	v_or_b32_e32 v17, s2, v27
	v_lshlrev_b32_e32 v50, 9, v17
	s_waitcnt lgkmcnt(3)
	v_mov_b32_e32 v7, v2
	s_waitcnt lgkmcnt(2)
	v_mov_b32_e32 v8, v12
	s_waitcnt lgkmcnt(0)
	v_mov_b32_e32 v6, v18
	v_mov_b32_e32 v9, v4
	v_lshl_add_u64 v[42:43], v[10:11], 0, v[50:51]
	global_store_dwordx4 v[42:43], v[6:9], off
	v_mov_b32_e32 v2, v19
	v_mov_b32_e32 v4, v13
	v_or_b32_e32 v6, s2, v28
	v_lshlrev_b32_e32 v50, 9, v6
	v_lshl_add_u64 v[6:7], v[10:11], 0, v[50:51]
	global_store_dwordx4 v[6:7], v[2:5], off
	ds_read2_b32 v[12:13], v23 offset0:48 offset1:56
	ds_read2_b32 v[2:3], v23 offset0:113 offset1:121
	ds_read2_b32 v[18:19], v23 offset0:178 offset1:186
	ds_read2_b32 v[4:5], v23 offset0:243 offset1:251
	v_or_b32_e32 v17, s2, v29
	v_lshlrev_b32_e32 v50, 9, v17
	s_waitcnt lgkmcnt(3)
	v_mov_b32_e32 v6, v12
	s_waitcnt lgkmcnt(2)
	v_mov_b32_e32 v7, v2
	s_waitcnt lgkmcnt(1)
	v_mov_b32_e32 v8, v18
	s_waitcnt lgkmcnt(0)
	v_mov_b32_e32 v9, v4
	v_lshl_add_u64 v[42:43], v[10:11], 0, v[50:51]
	global_store_dwordx4 v[42:43], v[6:9], off
	v_mov_b32_e32 v2, v13
	v_mov_b32_e32 v4, v19
	v_or_b32_e32 v6, s2, v30
	v_lshlrev_b32_e32 v50, 9, v6
	v_lshl_add_u64 v[6:7], v[10:11], 0, v[50:51]
	global_store_dwordx4 v[6:7], v[2:5], off
	s_waitcnt lgkmcnt(0)

; __device__ __forceinline__ unsigned pk4_fp8(float a, float b, float c, float d) { int w = 0; w = __builtin_amdgcn_cvt_pk_fp8_f32(a, b, w, false); w = __builtin_amdgcn_cvt_pk_fp8_f32(c, d, w, true); return (unsigned)w; }
; __device__ __forceinline__ void transpose_item8(const float* W, int N, unsigned char* WT, int ldt, int item, int lane, int mode, int aux) {
;     const int nblk = (N + 63) >> 6, kb = item / nblk, nb = item - kb * nblk, k0 = 64 * kb, n0 = 64 * nb;
;     const int ncol = n0 + lane;
;     const float* wp = W + (size_t)k0 * N + ncol;
;     float v[64];
; #pragma unroll
;     for (int i = 0; i < 64; ++i) v[i] = wp[(size_t)i * N];
;     unsigned o[16];
; #pragma unroll
;     for (int q = 0; q < 16; ++q) o[q] = pk4_fp8(fminf(fmaxf(v[4 * q] * 64.f, -448.f), 448.f), fminf(fmaxf(v[4 * q + 1] * 64.f, -448.f), 448.f), fminf(fmaxf(v[4 * q + 2] * 64.f, -448.f), 448.f), fminf(fmaxf(v[4 * q + 3] * 64.f, -448.f), 448.f));
;     v4u* dst = (v4u*)(WT + (size_t)rowmap(mode, aux, ncol) * ldt + k0);
; #pragma unroll
;     for (int q = 0; q < 4; ++q) dst[q] = (v4u){o[4 * q], o[4 * q + 1], o[4 * q + 2], o[4 * q + 3]};
; __device__ __forceinline__ void convert_rest(const Args& a, LAS unsigned char* lds, int wave, int lane, int gw, int ngw, int l, int it0, int it1) {
;     ...
;         if (r < WI_FF) { const int e = r >> 8; transpose_item8(a.in[I_WFFG] + (size_t)(l * 16 + e) * 1024 * 1024, 1024, ws + WS_WGU + (size_t)e * 2048 * 1024, 1024, r & 255, lane, 3, 0); continue; } r -= WI_FF;
;         if (r < WI_FF) { const int e = r >> 8; transpose_item8(a.in[I_WFFU] + (size_t)(l * 16 + e) * 1024 * 1024, 1024, ws + WS_WGU + (size_t)e * 2048 * 1024, 1024, r & 255, lane, 4, 0); continue; } r -= WI_FF;
;         { const int e = r >> 8; transpose_item8(a.in[I_WFFD] + (size_t)(l * 16 + e) * 1024 * 1024, 1024, ws + WS_WDN + (size_t)e * 1024 * 1024, 1024, r & 255, lane, 0, 0); }
.LBB0_2078:
	s_andn2_b64 vcc, exec, s[0:1]
	s_cbranch_vccnz .LBB0_2013
	s_ashr_i32 s0, s6, 8
	s_add_i32 s2, s0, s8
	s_ashr_i32 s3, s2, 31
	s_lshl_b64 s[2:3], s[2:3], 22
	s_add_u32 s2, s78, s2
	s_addc_u32 s3, s79, s3
	s_lshl_b32 s1, s6, 2
	v_readlane_b32 s22, v254, 32
	s_and_b32 s22, s1, 0x3c0
	s_lshl_b32 s1, s6, 6
	s_and_b32 s1, s1, 0x3c0
	s_lshl_b32 s16, s22, 12
	v_or_b32_e32 v2, s1, v20
	s_add_u32 s2, s2, s16
	s_addc_u32 s3, s3, 0
	v_lshlrev_b32_e32 v50, 2, v2
	v_lshl_add_u64 v[2:3], s[2:3], 0, v[50:51]
	global_load_dword v17, v50, s[2:3] nt
	s_movk_i32 s2, 0x2000
	v_add_co_u32_e32 v4, vcc, s2, v2
	s_movk_i32 s2, 0x6000
	s_nop 0
	v_addc_co_u32_e32 v5, vcc, 0, v3, vcc
	global_load_dword v19, v[4:5], off offset:-4096 nt
	global_load_dword v42, v[4:5], off nt
	v_add_co_u32_e32 v4, vcc, s70, v2
	s_lshl_b32 s1, s1, 2
	s_nop 0
	v_addc_co_u32_e32 v5, vcc, 0, v3, vcc
	global_load_dword v43, v[4:5], off offset:-4096 nt
	global_load_dword v44, v[4:5], off nt
	v_add_co_u32_e32 v4, vcc, s2, v2
	s_mov_b32 s2, 0x8000
	s_nop 0
	v_addc_co_u32_e32 v5, vcc, 0, v3, vcc
	global_load_dword v45, v[4:5], off offset:-4096 nt
	global_load_dword v46, v[4:5], off nt
	v_add_co_u32_e32 v4, vcc, s2, v2
	s_mov_b32 s2, 0xa000
	s_nop 0
	v_addc_co_u32_e32 v5, vcc, 0, v3, vcc
	global_load_dword v47, v[4:5], off offset:-4096 nt
	global_load_dword v48, v[4:5], off nt
	v_add_co_u32_e32 v4, vcc, s2, v2
	s_mov_b32 s2, 0xc000
	s_nop 0
	v_addc_co_u32_e32 v5, vcc, 0, v3, vcc
	global_load_dword v49, v[4:5], off offset:-4096 nt
	global_load_dword v50, v[4:5], off nt
	v_add_co_u32_e32 v4, vcc, s2, v2
	s_mov_b32 s2, 0xe000
	s_nop 0
	v_addc_co_u32_e32 v5, vcc, 0, v3, vcc
	global_load_dword v52, v[4:5], off offset:-4096 nt
	global_load_dword v53, v[4:5], off nt
	v_add_co_u32_e32 v4, vcc, s2, v2
	s_mov_b32 s2, 0x10000
	s_nop 0
	v_addc_co_u32_e32 v5, vcc, 0, v3, vcc
	global_load_dword v54, v[4:5], off offset:-4096 nt
	global_load_dword v55, v[4:5], off nt
	v_add_co_u32_e32 v4, vcc, s2, v2
	s_mov_b32 s2, 0x12000
	s_nop 0
	v_addc_co_u32_e32 v5, vcc, 0, v3, vcc
	global_load_dword v56, v[4:5], off offset:-4096 nt
	global_load_dword v10, v[4:5], off nt
	v_add_co_u32_e32 v4, vcc, s2, v2
	s_mov_b32 s2, 0x14000
	s_nop 0
	v_addc_co_u32_e32 v5, vcc, 0, v3, vcc
	global_load_dword v57, v[4:5], off offset:-4096 nt
	global_load_dword v58, v[4:5], off nt
	v_add_co_u32_e32 v4, vcc, s2, v2
	s_mov_b32 s2, 0x16000
	s_nop 0
	v_addc_co_u32_e32 v5, vcc, 0, v3, vcc
	global_load_dword v59, v[4:5], off offset:-4096 nt
	global_load_dword v11, v[4:5], off nt
	v_add_co_u32_e32 v4, vcc, s2, v2
	s_mov_b32 s2, 0x18000
	s_nop 0
	v_addc_co_u32_e32 v5, vcc, 0, v3, vcc
	global_load_dword v60, v[4:5], off offset:-4096 nt
	global_load_dword v61, v[4:5], off nt
	v_add_co_u32_e32 v4, vcc, s2, v2
	s_mov_b32 s2, 0x1a000
	s_nop 0
	v_addc_co_u32_e32 v5, vcc, 0, v3, vcc
	global_load_dword v62, v[4:5], off offset:-4096 nt
	global_load_dword v12, v[4:5], off nt
	v_add_co_u32_e32 v4, vcc, s2, v2
	s_mov_b32 s2, 0x1c000
	s_nop 0
	v_addc_co_u32_e32 v5, vcc, 0, v3, vcc
	global_load_dword v63, v[4:5], off offset:-4096 nt
	global_load_dword v64, v[4:5], off nt
	v_add_co_u32_e32 v4, vcc, s2, v2
	s_mov_b32 s2, 0x1e000
	s_nop 0
	v_addc_co_u32_e32 v5, vcc, 0, v3, vcc
	global_load_dword v65, v[4:5], off offset:-4096 nt
	global_load_dword v13, v[4:5], off nt
	v_add_co_u32_e32 v4, vcc, s2, v2
	s_mov_b32 s2, 0x20000
	s_nop 0
	v_addc_co_u32_e32 v5, vcc, 0, v3, vcc
	global_load_dword v66, v[4:5], off offset:-4096 nt
	global_load_dword v67, v[4:5], off nt
	v_add_co_u32_e32 v4, vcc, s2, v2
	s_mov_b32 s2, 0x22000
	s_nop 0
	v_addc_co_u32_e32 v5, vcc, 0, v3, vcc
	global_load_dword v68, v[4:5], off offset:-4096 nt
	global_load_dword v6, v[4:5], off nt
	v_add_co_u32_e32 v4, vcc, s2, v2
	s_mov_b32 s2, 0x24000
	s_nop 0
	v_addc_co_u32_e32 v5, vcc, 0, v3, vcc
	global_load_dword v69, v[4:5], off offset:-4096 nt
	global_load_dword v70, v[4:5], off nt
	v_add_co_u32_e32 v4, vcc, s2, v2
	s_mov_b32 s2, 0x26000
	s_nop 0
	v_addc_co_u32_e32 v5, vcc, 0, v3, vcc
	global_load_dword v71, v[4:5], off offset:-4096 nt
	global_load_dword v7, v[4:5], off nt
	v_add_co_u32_e32 v4, vcc, s2, v2
	s_mov_b32 s2, 0x28000
	s_nop 0
	v_addc_co_u32_e32 v5, vcc, 0, v3, vcc
	global_load_dword v72, v[4:5], off offset:-4096 nt
	global_load_dword v73, v[4:5], off nt
	v_add_co_u32_e32 v4, vcc, s2, v2
	s_mov_b32 s2, 0x2a000
	s_nop 0
	v_addc_co_u32_e32 v5, vcc, 0, v3, vcc
	global_load_dword v74, v[4:5], off offset:-4096 nt
	global_load_dword v8, v[4:5], off nt
	v_add_co_u32_e32 v4, vcc, s2, v2
	s_mov_b32 s2, 0x2c000
	s_nop 0
	v_addc_co_u32_e32 v5, vcc, 0, v3, vcc
	global_load_dword v75, v[4:5], off offset:-4096 nt
	global_load_dword v76, v[4:5], off nt
	v_add_co_u32_e32 v4, vcc, s2, v2
	s_mov_b32 s2, 0x2e000
	s_nop 0
	v_addc_co_u32_e32 v5, vcc, 0, v3, vcc
	global_load_dword v77, v[4:5], off offset:-4096 nt
	global_load_dword v9, v[4:5], off nt
	v_add_co_u32_e32 v4, vcc, s2, v2
	s_mov_b32 s2, 0x30000
	s_nop 0
	v_addc_co_u32_e32 v5, vcc, 0, v3, vcc
	global_load_dword v78, v[4:5], off offset:-4096 nt
	global_load_dword v79, v[4:5], off nt
	v_add_co_u32_e32 v4, vcc, s2, v2
	s_mov_b32 s2, 0x32000
	s_nop 0
	v_addc_co_u32_e32 v5, vcc, 0, v3, vcc
	global_load_dword v80, v[4:5], off offset:-4096 nt
	global_load_dword v81, v[4:5], off nt
	v_add_co_u32_e32 v4, vcc, s2, v2
	s_mov_b32 s2, 0x34000
	s_nop 0
	v_addc_co_u32_e32 v5, vcc, 0, v3, vcc
	global_load_dword v82, v[4:5], off offset:-4096 nt
	global_load_dword v83, v[4:5], off nt
	v_add_co_u32_e32 v4, vcc, s2, v2
	s_mov_b32 s2, 0x36000
	s_nop 0
	v_addc_co_u32_e32 v5, vcc, 0, v3, vcc
	global_load_dword v84, v[4:5], off offset:-4096 nt
	global_load_dword v85, v[4:5], off nt
	v_add_co_u32_e32 v4, vcc, s2, v2
	s_mov_b32 s2, 0x38000
	s_nop 0
	v_addc_co_u32_e32 v5, vcc, 0, v3, vcc
	global_load_dword v86, v[4:5], off offset:-4096 nt
	global_load_dword v87, v[4:5], off nt
	v_add_co_u32_e32 v4, vcc, s2, v2
	s_mov_b32 s2, 0x3a000
	s_nop 0
	v_addc_co_u32_e32 v5, vcc, 0, v3, vcc
	global_load_dword v88, v[4:5], off offset:-4096 nt
	global_load_dword v89, v[4:5], off nt
	v_add_co_u32_e32 v4, vcc, s2, v2
	s_mov_b32 s2, 0x3c000
	s_nop 0
	v_addc_co_u32_e32 v5, vcc, 0, v3, vcc
	global_load_dword v90, v[4:5], off offset:-4096 nt
	global_load_dword v91, v[4:5], off nt
	v_add_co_u32_e32 v4, vcc, s2, v2
	s_mov_b32 s2, 0x3e000
	s_nop 0
	v_addc_co_u32_e32 v5, vcc, 0, v3, vcc
	global_load_dword v92, v[4:5], off offset:-4096 nt
	global_load_dword v93, v[4:5], off nt
	v_add_co_u32_e32 v4, vcc, s2, v2
	s_mov_b32 s2, 0x3f000
	s_nop 0
	v_addc_co_u32_e32 v5, vcc, 0, v3, vcc
	global_load_dword v94, v[4:5], off offset:-4096 nt
	s_nop 0
	global_load_dword v4, v[4:5], off nt
	v_add_co_u32_e32 v2, vcc, s2, v2
	s_lshl_b32 s2, s0, 6
	s_nop 0
	v_addc_co_u32_e32 v3, vcc, 0, v3, vcc
	global_load_dword v2, v[2:3], off nt
	s_and_b32 s2, s2, 0xffffff80
	s_add_i32 s1, s1, s2
	s_lshl_b32 s0, s0, 4
	v_or_b32_e32 v3, s1, v31
	s_and_b32 s0, s0, 16
	v_or3_b32 v18, v3, s0, v32
	s_mov_b32 s0, 0xc3e00000
	s_waitcnt vmcnt(23)
; __device__ __forceinline__ unsigned pk4_fp8(float a, float b, float c, float d) { int w = 0; w = __builtin_amdgcn_cvt_pk_fp8_f32(a, b, w, false); w = __builtin_amdgcn_cvt_pk_fp8_f32(c, d, w, true); return (unsigned)w; }
; __device__ __forceinline__ void transpose_item8(const float* W, int N, unsigned char* WT, int ldt, int item, int lane, int mode, int aux) {
;     ...
;     for (int i = 0; i < 64; ++i) v[i] = wp[(size_t)i * N];
;     unsigned o[16];
; #pragma unroll
;     for (int q = 0; q < 16; ++q) o[q] = pk4_fp8(fminf(fmaxf(v[4 * q] * 64.f, -448.f), 448.f), fminf(fmaxf(v[4 * q + 1] * 64.f, -448.f), 448.f), fminf(fmaxf(v[4 * q + 2] * 64.f, -448.f), 448.f), fminf(fmaxf(v[4 * q + 3] * 64.f, -448.f), 448.f));
;     v4u* dst = (v4u*)(WT + (size_t)rowmap(mode, aux, ncol) * ldt + k0);
; #pragma unroll
;     for (int q = 0; q < 4; ++q) dst[q] = (v4u){o[4 * q], o[4 * q + 1], o[4 * q + 2], o[4 * q + 3]};
	v_mul_f32_e32 v8, 0x42800000, v8
	v_mul_f32_e32 v7, 0x42800000, v7
	v_mul_f32_e32 v6, 0x42800000, v6
	v_mul_f32_e32 v13, 0x42800000, v13
	v_mul_f32_e32 v12, 0x42800000, v12
	v_mul_f32_e32 v11, 0x42800000, v11
	v_mul_f32_e32 v10, 0x42800000, v10
	v_mul_f32_e32 v55, 0x42800000, v55
	v_mul_f32_e32 v53, 0x42800000, v53
	v_mul_f32_e32 v54, 0x42800000, v54
	v_med3_f32 v53, v53, s0, v236
	v_med3_f32 v54, v54, s0, v236
	s_waitcnt vmcnt(19)
	v_mul_f32_e32 v9, 0x42800000, v9
	v_mul_f32_e32 v48, 0x42800000, v48
	v_mul_f32_e32 v49, 0x42800000, v49
	v_med3_f32 v48, v48, s0, v236
	v_med3_f32 v49, v49, s0, v236
	v_mul_f32_e32 v50, 0x42800000, v50
	v_mul_f32_e32 v52, 0x42800000, v52
	v_med3_f32 v50, v50, s0, v236
	v_med3_f32 v52, v52, s0, v236
	v_mul_f32_e32 v44, 0x42800000, v44
	v_mul_f32_e32 v45, 0x42800000, v45
	v_mul_f32_e32 v17, 0x42800000, v17
	v_mul_f32_e32 v19, 0x42800000, v19
	v_med3_f32 v44, v44, s0, v236
	v_med3_f32 v45, v45, s0, v236
	v_med3_f32 v17, v17, s0, v236
	v_med3_f32 v19, v19, s0, v236
	s_waitcnt vmcnt(17)
	v_mul_f32_e32 v79, 0x42800000, v79
	s_waitcnt vmcnt(16)
	v_mul_f32_e32 v80, 0x42800000, v80
	v_mul_f32_e32 v76, 0x42800000, v76
	v_mul_f32_e32 v77, 0x42800000, v77
	v_mul_f32_e32 v73, 0x42800000, v73
	v_mul_f32_e32 v74, 0x42800000, v74
	v_mul_f32_e32 v70, 0x42800000, v70
	v_mul_f32_e32 v71, 0x42800000, v71
	v_mul_f32_e32 v67, 0x42800000, v67
	v_mul_f32_e32 v68, 0x42800000, v68
	v_mul_f32_e32 v64, 0x42800000, v64
	v_mul_f32_e32 v65, 0x42800000, v65
	v_mul_f32_e32 v61, 0x42800000, v61
	v_mul_f32_e32 v62, 0x42800000, v62
	v_mul_f32_e32 v58, 0x42800000, v58
	v_mul_f32_e32 v59, 0x42800000, v59
	v_mul_f32_e32 v46, 0x42800000, v46
	v_mul_f32_e32 v47, 0x42800000, v47
	v_mul_f32_e32 v42, 0x42800000, v42
	v_mul_f32_e32 v43, 0x42800000, v43
	v_med3_f32 v79, v79, s0, v236
	v_med3_f32 v80, v80, s0, v236
	v_med3_f32 v76, v76, s0, v236
	v_med3_f32 v77, v77, s0, v236
	v_med3_f32 v73, v73, s0, v236
	v_med3_f32 v74, v74, s0, v236
	v_med3_f32 v70, v70, s0, v236
	v_med3_f32 v71, v71, s0, v236
	v_med3_f32 v67, v67, s0, v236
	v_med3_f32 v68, v68, s0, v236
	v_med3_f32 v64, v64, s0, v236
	v_med3_f32 v65, v65, s0, v236
	v_med3_f32 v61, v61, s0, v236
	v_med3_f32 v62, v62, s0, v236
	v_med3_f32 v58, v58, s0, v236
	v_med3_f32 v59, v59, s0, v236
	s_waitcnt vmcnt(2)
	v_mul_f32_e32 v5, 0x42800000, v94
	s_waitcnt vmcnt(1)
	v_mul_f32_e32 v3, 0x42800000, v4
	v_mul_f32_e32 v4, 0x42800000, v93
	v_med3_f32 v4, v4, s0, v236
	v_med3_f32 v93, v5, s0, v236
	v_mov_b32_e32 v5, v51
	v_cvt_pk_fp8_f32 v5, v4, v93
	v_mul_f32_e32 v4, 0x42800000, v89
	v_med3_f32 v89, v4, s0, v236
	v_mul_f32_e32 v4, 0x42800000, v90
	v_med3_f32 v90, v4, s0, v236
	v_mov_b32_e32 v4, v51
	s_waitcnt vmcnt(0)
	v_mul_f32_e32 v2, 0x42800000, v2
	v_cvt_pk_fp8_f32 v4, v89, v90
	v_med3_f32 v3, v3, s0, v236
	v_med3_f32 v2, v2, s0, v236
	v_cvt_pk_fp8_f32 v5, v3, v2 op_sel:[0,0,1]
	v_mul_f32_e32 v2, 0x42800000, v91
	v_mul_f32_e32 v3, 0x42800000, v92
	v_med3_f32 v2, v2, s0, v236
	v_med3_f32 v3, v3, s0, v236
	v_cvt_pk_fp8_f32 v4, v2, v3 op_sel:[0,0,1]
	v_mul_f32_e32 v3, 0x42800000, v88
	v_mul_f32_e32 v2, 0x42800000, v87
	v_med3_f32 v87, v3, s0, v236
	v_mul_f32_e32 v3, 0x42800000, v85
	v_med3_f32 v85, v3, s0, v236
	v_mul_f32_e32 v3, 0x42800000, v86
	v_med3_f32 v86, v3, s0, v236
	v_mov_b32_e32 v3, v51
	v_cvt_pk_fp8_f32 v3, v85, v86
	v_med3_f32 v2, v2, s0, v236
	v_med3_f32 v46, v46, s0, v236
	v_med3_f32 v47, v47, s0, v236
	v_cvt_pk_fp8_f32 v3, v2, v87 op_sel:[0,0,1]
	v_mul_f32_e32 v2, 0x42800000, v83
	v_med3_f32 v83, v2, s0, v236
	v_mul_f32_e32 v2, 0x42800000, v84
	v_med3_f32 v84, v2, s0, v236
	v_mul_f32_e32 v2, 0x42800000, v81
	v_med3_f32 v81, v2, s0, v236
	v_mul_f32_e32 v2, 0x42800000, v82
	v_med3_f32 v82, v2, s0, v236
	v_mov_b32_e32 v2, v51
	v_cvt_pk_fp8_f32 v2, v81, v82
	v_med3_f32 v81, v9, s0, v236
	v_mul_f32_e32 v9, 0x42800000, v78
	v_med3_f32 v78, v9, s0, v236
	v_mov_b32_e32 v9, v51
	v_cvt_pk_fp8_f32 v9, v81, v78
	v_med3_f32 v78, v8, s0, v236
	v_mul_f32_e32 v8, 0x42800000, v75
	v_med3_f32 v75, v8, s0, v236
	v_mov_b32_e32 v8, v51
	v_cvt_pk_fp8_f32 v8, v78, v75
	v_med3_f32 v75, v7, s0, v236
	v_mul_f32_e32 v7, 0x42800000, v72
	v_med3_f32 v72, v7, s0, v236
	v_mov_b32_e32 v7, v51
	v_cvt_pk_fp8_f32 v7, v75, v72
	v_med3_f32 v72, v6, s0, v236
	v_mul_f32_e32 v6, 0x42800000, v69
	v_med3_f32 v69, v6, s0, v236
	v_mov_b32_e32 v6, v51
	v_cvt_pk_fp8_f32 v6, v72, v69
	v_med3_f32 v69, v13, s0, v236
	v_mul_f32_e32 v13, 0x42800000, v66
	v_med3_f32 v66, v13, s0, v236
	v_mov_b32_e32 v13, v51
	v_cvt_pk_fp8_f32 v13, v69, v66
	v_med3_f32 v66, v12, s0, v236
	v_mul_f32_e32 v12, 0x42800000, v63
	v_med3_f32 v63, v12, s0, v236
	v_mov_b32_e32 v12, v51
	v_cvt_pk_fp8_f32 v12, v66, v63
	v_med3_f32 v63, v11, s0, v236
	v_mul_f32_e32 v11, 0x42800000, v60
	v_med3_f32 v60, v11, s0, v236
	v_mov_b32_e32 v11, v51
	v_cvt_pk_fp8_f32 v11, v63, v60
	v_med3_f32 v60, v10, s0, v236
	v_mul_f32_e32 v10, 0x42800000, v57
	v_med3_f32 v57, v10, s0, v236
	v_mov_b32_e32 v10, v51
	v_cvt_pk_fp8_f32 v10, v60, v57
	v_med3_f32 v57, v55, s0, v236
	v_mul_f32_e32 v55, 0x42800000, v56
	v_med3_f32 v56, v55, s0, v236
	v_mov_b32_e32 v55, v51
	v_cvt_pk_fp8_f32 v55, v53, v54
	v_mov_b32_e32 v54, v51
	v_cvt_pk_fp8_f32 v54, v48, v49
	v_mov_b32_e32 v53, v51
	v_cvt_pk_fp8_f32 v53, v44, v45
	v_med3_f32 v42, v42, s0, v236
	v_cvt_pk_fp8_f32 v54, v50, v52 op_sel:[0,0,1]
	v_mov_b32_e32 v52, v51
	v_cvt_pk_fp8_f32 v52, v17, v19
	v_med3_f32 v43, v43, s0, v236
	v_ashrrev_i32_e32 v19, 31, v18
	v_readlane_b32 s0, v254, 3
	v_readlane_b32 s23, v254, 33
	v_cvt_pk_fp8_f32 v55, v57, v56 op_sel:[0,0,1]
	v_cvt_pk_fp8_f32 v53, v46, v47 op_sel:[0,0,1]
	v_cvt_pk_fp8_f32 v52, v42, v43 op_sel:[0,0,1]
	v_lshlrev_b64 v[18:19], 10, v[18:19]
	v_readlane_b32 s1, v254, 4
	v_cvt_pk_fp8_f32 v13, v67, v68 op_sel:[0,0,1]
	v_cvt_pk_fp8_f32 v12, v64, v65 op_sel:[0,0,1]
	v_cvt_pk_fp8_f32 v11, v61, v62 op_sel:[0,0,1]
	v_cvt_pk_fp8_f32 v10, v58, v59 op_sel:[0,0,1]
	v_lshl_add_u64 v[18:19], s[0:1], 0, v[18:19]
	s_mov_b32 s1, s23
	v_cvt_pk_fp8_f32 v9, v79, v80 op_sel:[0,0,1]
	v_cvt_pk_fp8_f32 v8, v76, v77 op_sel:[0,0,1]
	v_cvt_pk_fp8_f32 v7, v73, v74 op_sel:[0,0,1]
	v_cvt_pk_fp8_f32 v6, v70, v71 op_sel:[0,0,1]
	v_writelane_b32 v254, s0, 32
	v_cvt_pk_fp8_f32 v2, v83, v84 op_sel:[0,0,1]
	v_lshl_add_u64 v[18:19], v[18:19], 0, s[22:23]
	v_writelane_b32 v254, s1, 33
	global_store_dwordx4 v[18:19], v[52:55], off
	global_store_dwordx4 v[18:19], v[10:13], off offset:16
	global_store_dwordx4 v[18:19], v[6:9], off offset:32
	global_store_dwordx4 v[18:19], v[2:5], off offset:48
	s_branch .LBB0_2013

; #define LAS __attribute__((address_space(3)))
; __device__ __forceinline__ void phase_ln1(const Args& a, LAS unsigned char* lds, const WCtx& w, int l, int nrows) {
;     ...
;     float* X = (float*)(a.ws + WS_X); const bf16* Y = (const bf16*)(a.ws + WS_Y); bf16* H = (bf16*)(a.ws + WS_H); float* AFF = (float*)(a.ws + WS_AFF);
;     int row = r0 + w.wave;
;     f32x4 x[4]; v2u yb[4];
; #pragma unroll
;     for (int j = 0; j < 4; ++j) { x[j] = (f32x4){0.f, 0.f, 0.f, 0.f}; yb[j] = (v2u){0u, 0u}; }
;     if (row < r1) { row_load(X + (size_t)row * 1024, w.lane, x);
; #pragma unroll
;         for (int j = 0; j < 4; ++j) yb[j] = *((const v2u*)(Y + (size_t)row * 1024) + w.lane + 64 * j); }
;     f32x4 wr[10][4];
; #pragma unroll
;     for (int e = 0; e < 10; ++e)
; #pragma unroll
;         for (int j = 0; j < 4; ++j) wr[e][j] = *(const LAS f32x4*)(WRT + e * 1024 + 256 * j + 4 * w.lane);
.LBB0_2160:
	s_or_b64 exec, exec, s[2:3]
	s_ashr_i32 s0, s16, 6
	s_add_i32 s2, s17, s0
	s_cmp_lt_i32 s2, s14
	s_waitcnt vmcnt(0) lgkmcnt(0)
	s_barrier
	s_cbranch_scc0 .LBB0_2168
	s_ashr_i32 s3, s2, 31
	s_lshl_b64 s[4:5], s[2:3], 10
	s_lshl_b64 s[6:7], s[2:3], 12
	v_readlane_b32 s0, v254, 7
	v_and_b32_e32 v50, 63, v164
	v_readlane_b32 s1, v254, 8
	s_add_u32 s0, s0, s6
	s_addc_u32 s1, s1, s7
	v_lshlrev_b32_e32 v165, 4, v50
	s_nop 1
	global_load_dwordx4 v[192:195], v165, s[0:1] nt
	global_load_dwordx4 v[188:191], v165, s[0:1] offset:1024 nt
	global_load_dwordx4 v[184:187], v165, s[0:1] offset:2048 nt
	global_load_dwordx4 v[180:183], v165, s[0:1] offset:3072 nt
	s_lshl_b64 s[8:9], s[2:3], 11
	v_readlane_b32 s0, v254, 11
	s_add_u32 s0, s0, s8
	v_readlane_b32 s1, v254, 12
	s_addc_u32 s1, s1, s9
	v_lshlrev_b32_e32 v166, 3, v50
	s_nop 2
	global_load_dwordx2 v[224:225], v166, s[0:1] nt
	global_load_dwordx2 v[222:223], v166, s[0:1] offset:512 nt
	global_load_dwordx2 v[220:221], v166, s[0:1] offset:1024 nt
	global_load_dwordx2 v[218:219], v166, s[0:1] offset:1536 nt
	v_add_u32_e32 v197, 0, v165
	ds_read_b128 v[2:5], v197 offset:39936
	ds_read_b128 v[6:9], v197 offset:38912
	ds_read_b128 v[10:13], v197 offset:37888
	ds_read_b128 v[14:17], v197 offset:36864
	ds_read_b128 v[18:21], v197 offset:35840
	ds_read_b128 v[22:25], v197 offset:34816
	ds_read_b128 v[26:29], v197 offset:33792
	ds_read_b128 v[30:33], v197 offset:32768
	ds_read_b128 v[34:37], v197 offset:31744
	ds_read_b128 v[38:41], v197 offset:30720
	ds_read_b128 v[42:45], v197 offset:29696
	ds_read_b128 v[46:49], v197 offset:28672
	ds_read_b128 v[52:55], v197 offset:27648
	ds_read_b128 v[56:59], v197 offset:26624
	ds_read_b128 v[60:63], v197 offset:25600
	ds_read_b128 v[64:67], v197 offset:24576
	ds_read_b128 v[68:71], v197 offset:23552
	ds_read_b128 v[72:75], v197 offset:22528
	ds_read_b128 v[76:79], v197 offset:21504
	ds_read_b128 v[80:83], v197 offset:20480
	ds_read_b128 v[84:87], v197 offset:19456
	ds_read_b128 v[88:91], v197 offset:18432
	ds_read_b128 v[92:95], v197 offset:17408
	ds_read_b128 v[96:99], v197 offset:16384
	ds_read_b128 v[100:103], v197 offset:15360
	ds_read_b128 v[104:107], v197 offset:14336
	ds_read_b128 v[108:111], v197 offset:13312
	ds_read_b128 v[112:115], v197 offset:12288
	ds_read_b128 v[116:119], v197 offset:11264
	ds_read_b128 v[120:123], v197 offset:10240
	ds_read_b128 v[124:127], v197 offset:9216
	ds_read_b128 v[128:131], v197 offset:8192
	ds_read_b128 v[132:135], v197 offset:7168
	ds_read_b128 v[136:139], v197 offset:6144
	ds_read_b128 v[140:143], v197 offset:5120
	ds_read_b128 v[144:147], v197 offset:4096
	ds_read_b128 v[148:151], v197 offset:3072
	ds_read_b128 v[152:155], v197 offset:2048
	ds_read_b128 v[156:159], v197 offset:1024
	ds_read_b128 v[160:163], v197
	s_add_i32 s10, 0, 0x12000
	s_add_i32 s0, 0, 0x10000
	v_and_b32_e32 v167, 8, v164
	v_add_u32_e32 v242, s10, v165
	s_lshl_b64 s[10:11], s[2:3], 6
	v_add_u32_e32 v199, s0, v165
	v_cmp_eq_u32_e64 s[0:1], 0, v167
	v_and_b32_e32 v167, 4, v164
	s_add_u32 s3, s10, 0x1600000
	v_cmp_eq_u32_e64 s[36:37], 0, v167
	v_and_b32_e32 v167, 3, v164
	s_addc_u32 s10, s11, 0
	v_add_u32_e32 v241, s62, v165
	v_cmp_eq_u32_e64 s[40:41], 0, v167
	v_and_or_b32 v200, v164, 60, s3
	v_mov_b32_e32 v201, s10
	v_or_b32_e32 v202, s6, v165
	v_mov_b32_e32 v203, s7
	v_lshl_or_b32 v204, v50, 2, s4
	v_mov_b32_e32 v205, s5
	v_or_b32_e32 v206, s8, v166
	v_mov_b32_e32 v207, s9
	s_mov_b64 s[10:11], 0x4000
	s_branch .LBB0_2163

; __device__ __forceinline__ void phase_ln1(const Args& a, LAS unsigned char* lds, const WCtx& w, int l, int nrows) {
;     ...
;     while (row < r1) {
;         const int nrow = row + NWAVES; f32x4 xn[4]; v2u ybn[4];
; #pragma unroll
;         for (int j = 0; j < 4; ++j) { xn[j] = (f32x4){0.f, 0.f, 0.f, 0.f}; ybn[j] = (v2u){0u, 0u}; }
;         if (nrow < r1) { row_load(X + (size_t)nrow * 1024, w.lane, xn);
; #pragma unroll
;             for (int j = 0; j < 4; ++j) ybn[j] = *((const v2u*)(Y + (size_t)nrow * 1024) + w.lane + 64 * j); }
.LBB0_2163:
	s_add_i32 s8, s2, 8
	s_cmp_ge_i32 s8, s14
	s_cselect_b64 s[6:7], -1, 0
	s_and_b64 vcc, exec, s[6:7]
	v_lshl_add_u64 v[216:217], s[52:53], 0, v[202:203]
	s_cbranch_vccnz .LBB0_2165
	v_add_co_u32_e32 v176, vcc, 0x9308000, v216
	v_lshl_add_u64 v[208:209], s[52:53], 0, v[206:207]
	s_nop 0
	v_addc_co_u32_e32 v177, vcc, 0, v217, vcc
	v_add_co_u32_e32 v214, vcc, 0x2d404000, v208
	global_load_dwordx4 v[164:167], v[176:177], off nt
	global_load_dwordx4 v[168:171], v[176:177], off offset:1024 nt
	global_load_dwordx4 v[172:175], v[176:177], off offset:2048 nt
	s_nop 0
	global_load_dwordx4 v[176:179], v[176:177], off offset:3072 nt
	v_addc_co_u32_e32 v215, vcc, 0, v209, vcc
	global_load_dwordx2 v[208:209], v[214:215], off nt
	global_load_dwordx2 v[210:211], v[214:215], off offset:512 nt
	global_load_dwordx2 v[212:213], v[214:215], off offset:1024 nt
	s_nop 0
	global_load_dwordx2 v[214:215], v[214:215], off offset:1536 nt
	s_branch .LBB0_2166

; __device__ __forceinline__ void phase_ln2(const Args& a, LAS unsigned char* lds, const WCtx& w, int l, int nrows) {
;     ...
;     float* X = (float*)(a.ws + WS_X); bf16* H = (bf16*)(a.ws + WS_H); const unsigned char* YE = (const unsigned char*)(a.ws + WS_YE);   const int* SLOT = (const int*)(a.ws + WS_SLOT);
;     int row = r0 + w.wave;
;     f32x4 x[4]; int myslot = -1;
; #pragma unroll
;     for (int j = 0; j < 4; ++j) x[j] = (f32x4){0.f, 0.f, 0.f, 0.f};
;     if (row < r1) { row_load(X + (size_t)row * 1024, w.lane, x); myslot = SLOT[(size_t)row * 16 + (w.lane & 15)]; }
.LBB0_2551:
	s_or_b64 exec, exec, s[2:3]
	s_ashr_i32 s10, s23, 6
	s_add_i32 s4, s27, s10
	v_and_b32_e32 v35, 63, v34
	s_cmp_lt_i32 s4, s26
	s_waitcnt vmcnt(0) lgkmcnt(0)
	s_barrier
	s_cbranch_scc0 .LBB0_2572
	s_ashr_i32 s5, s4, 31
	s_lshl_b64 s[0:1], s[4:5], 12
	v_readlane_b32 s2, v254, 7
	v_readlane_b32 s3, v254, 8
	s_add_u32 s0, s2, s0
	s_addc_u32 s1, s3, s1
	v_lshlrev_b32_e32 v2, 4, v35
	global_load_dwordx4 v[30:33], v2, s[0:1] nt
	global_load_dwordx4 v[26:29], v2, s[0:1] offset:1024 nt
	global_load_dwordx4 v[22:25], v2, s[0:1] offset:2048 nt
	global_load_dwordx4 v[18:21], v2, s[0:1] offset:3072 nt
	s_lshl_b64 s[0:1], s[4:5], 6
	v_readlane_b32 s6, v254, 15
	v_and_b32_e32 v4, 15, v34
	v_readlane_b32 s7, v254, 16
	s_add_u32 s0, s6, s0
	s_addc_u32 s1, s7, s1
	v_lshlrev_b32_e32 v4, 2, v4
	global_load_dword v69, v4, s[0:1] nt
	v_mov_b32_e32 v5, v51
	v_readlane_b32 s0, v254, 9
	v_lshl_add_u64 v[38:39], s[6:7], 0, v[4:5]
	v_lshlrev_b32_e32 v4, 3, v35
	v_readlane_b32 s1, v254, 10
	v_readlane_b32 s56, v252, 41
	v_mov_b32_e32 v3, v51
	v_lshl_add_u64 v[40:41], s[0:1], 0, v[4:5]
	v_readlane_b32 s0, v254, 19
	v_lshlrev_b32_e32 v4, 2, v35
	v_readlane_b32 s1, v254, 20
	v_readlane_b32 s70, v252, 55
	v_readlane_b32 s71, v252, 56
	v_lshl_add_u64 v[46:47], s[0:1], 0, v[4:5]
	v_readlane_b32 s0, v254, 21
	v_readlane_b32 s1, v254, 22
	v_lshl_add_u64 v[36:37], s[2:3], 0, v[2:3]
	v_lshl_add_u64 v[42:43], s[52:53], 0, v[4:5]
	v_lshl_add_u64 v[44:45], s[70:71], 0, v[2:3]
	v_add_u32_e32 v68, 0, v2
	v_lshl_add_u64 v[48:49], s[0:1], 0, v[4:5]
	v_readlane_b32 s57, v252, 42
	v_readlane_b32 s58, v252, 43
	v_readlane_b32 s59, v252, 44
	v_readlane_b32 s60, v252, 45
	v_readlane_b32 s61, v252, 46
	v_readlane_b32 s62, v252, 47
	v_readlane_b32 s63, v252, 48
	v_readlane_b32 s64, v252, 49
	v_readlane_b32 s65, v252, 50
	v_readlane_b32 s66, v252, 51
	v_readlane_b32 s67, v252, 52
	v_readlane_b32 s68, v252, 53
	v_readlane_b32 s69, v252, 54
	s_branch .LBB0_2554

; __device__ __forceinline__ void phase_ln2(const Args& a, LAS unsigned char* lds, const WCtx& w, int l, int nrows) {
;     ...
;         unsigned m = (unsigned)(__ballot(myslot >= 0) & 0xFFFFull);
;         while (m) {
;             unsigned t[4][4];
; #pragma unroll
;             for (int k = 0; k < 4; ++k) {
; #pragma unroll
;                 for (int j = 0; j < 4; ++j) t[k][j] = 0u;
;                 if (m) { const int e = __builtin_ctz(m); m &= m - 1u; const int s = __builtin_amdgcn_readlane(myslot, e);
;                     const size_t xr = row < ML ? (size_t)(e * 4096 + b * 256 + s) : (size_t)(65536 + e * 512 + b * 32 + s); const unsigned* yr = (const unsigned*)(YE + xr * 1024) + w.lane;
; #pragma unroll
;                     for (int j = 0; j < 4; ++j) t[k][j] = yr[64 * j]; } }
; #pragma unroll
;             for (int k = 0; k < 4; ++k)
; #pragma unroll
;                 for (int j = 0; j < 4; ++j) { const f32x2 lo = __builtin_amdgcn_cvt_pk_f32_fp8((int)t[k][j], false), hi = __builtin_amdgcn_cvt_pk_f32_fp8((int)t[k][j], true); mo[j][0] += lo[0]; mo[j][1] += lo[1]; mo[j][2] += hi[0]; mo[j][3] += hi[1]; }
.LBB0_2557:
	s_ff1_i32_b32 s6, s5
	s_add_i32 s7, s5, -1
	s_and_b32 s7, s7, s5
	v_readlane_b32 s5, v69, s6
	s_lshl_b32 s8, s6, 12
	s_lshl_b32 s6, s6, 9
	s_add_i32 s11, s8, s3
	s_add_i32 s6, s6, s2
	s_and_b64 s[8:9], s[0:1], exec
	s_cselect_b32 s6, s11, s6
	s_add_i32 s8, s6, s5
	s_ashr_i32 s9, s8, 31
	s_lshl_b64 s[8:9], s[8:9], 10
	v_lshl_add_u64 v[6:7], v[46:47], 0, s[8:9]
	global_load_dword v5, v[6:7], off nt
	global_load_dword v4, v[6:7], off offset:256 nt
	global_load_dword v3, v[6:7], off offset:512 nt
	global_load_dword v2, v[6:7], off offset:768 nt
	s_cmp_eq_u32 s7, 0
	s_mov_b32 s6, 0
	v_mov_b32_e32 v6, 0
	v_mov_b32_e32 v7, 0
	v_mov_b32_e32 v8, 0
	v_mov_b32_e32 v9, 0
	s_mov_b32 s5, 0
	s_cbranch_scc1 .LBB0_2559
	s_ff1_i32_b32 s8, s7
	s_add_i32 s5, s7, -1
	s_and_b32 s5, s5, s7
	v_readlane_b32 s7, v69, s8
	s_lshl_b32 s9, s8, 12
	s_lshl_b32 s8, s8, 9
	s_add_i32 s11, s9, s3
	s_add_i32 s12, s8, s2
	s_and_b64 s[8:9], s[0:1], exec
	s_cselect_b32 s8, s11, s12
	s_add_i32 s8, s7, s8
	s_ashr_i32 s9, s8, 31
	s_lshl_b64 s[8:9], s[8:9], 10
	v_lshl_add_u64 v[10:11], v[46:47], 0, s[8:9]
	global_load_dword v9, v[10:11], off nt
	global_load_dword v8, v[10:11], off offset:256 nt
	global_load_dword v7, v[10:11], off offset:512 nt
	global_load_dword v6, v[10:11], off offset:768 nt
.LBB0_2559:
	v_mov_b32_e32 v10, 0
	s_cmp_eq_u32 s5, 0
	v_mov_b32_e32 v11, 0
	v_mov_b32_e32 v12, 0
	v_mov_b32_e32 v13, 0
	v_mov_b32_e32 v14, 0
	s_cbranch_scc1 .LBB0_2561
	s_ff1_i32_b32 s7, s5
	s_add_i32 s6, s5, -1
	s_and_b32 s6, s6, s5
	v_readlane_b32 s5, v69, s7
	s_lshl_b32 s8, s7, 12
	s_lshl_b32 s7, s7, 9
	s_add_i32 s11, s8, s3
	s_add_i32 s7, s7, s2
	s_and_b64 s[8:9], s[0:1], exec
	s_cselect_b32 s7, s11, s7
	s_add_i32 s8, s5, s7
	s_ashr_i32 s9, s8, 31
	s_lshl_b64 s[8:9], s[8:9], 10
	v_lshl_add_u64 v[16:17], v[46:47], 0, s[8:9]
	global_load_dword v14, v[16:17], off nt
	global_load_dword v13, v[16:17], off offset:256 nt
	global_load_dword v12, v[16:17], off offset:512 nt
	global_load_dword v11, v[16:17], off offset:768 nt
.LBB0_2561:
	s_cmp_eq_u32 s6, 0
	s_mov_b32 s5, 0
	v_mov_b32_e32 v15, 0
	v_mov_b32_e32 v16, 0
	v_mov_b32_e32 v17, 0
	s_cbranch_scc1 .LBB0_2556
	s_ff1_i32_b32 s7, s6
	s_add_i32 s5, s6, -1
	s_and_b32 s5, s5, s6
	s_lshl_b32 s6, s7, 12
	s_add_i32 s9, s6, s3
	s_lshl_b32 s6, s7, 9
	s_add_i32 s11, s6, s2
	v_readlane_b32 s8, v69, s7
	s_and_b64 s[6:7], s[0:1], exec
	s_cselect_b32 s6, s9, s11
	s_add_i32 s6, s8, s6
	s_ashr_i32 s7, s6, 31
	s_lshl_b64 s[6:7], s[6:7], 10
	v_lshl_add_u64 v[70:71], v[46:47], 0, s[6:7]
	global_load_dword v17, v[70:71], off nt
	global_load_dword v16, v[70:71], off offset:256 nt
	global_load_dword v15, v[70:71], off offset:512 nt
	global_load_dword v10, v[70:71], off offset:768 nt
	s_branch .LBB0_2556

; __device__ __forceinline__ void phase_ln2(const Args& a, LAS unsigned char* lds, const WCtx& w, int l, int nrows) {
;     ...
;         if (nrow < r1) { row_load(X + (size_t)nrow * 1024, w.lane, xn); nslot = SLOT[(size_t)nrow * 16 + (w.lane & 15)]; }
.LBB0_2564:
	s_add_i32 s2, s4, 8
	s_cmp_ge_i32 s2, s26
	s_cselect_b64 s[6:7], -1, 0
	s_cmp_lt_i32 s2, s26
	s_cbranch_scc0 .LBB0_2566
	s_ashr_i32 s3, s2, 31
	s_lshl_b64 s[0:1], s[2:3], 12
	v_lshl_add_u64 v[2:3], v[36:37], 0, s[0:1]
	global_load_dwordx4 v[14:17], v[2:3], off nt
	global_load_dwordx4 v[10:13], v[2:3], off offset:1024 nt
	global_load_dwordx4 v[6:9], v[2:3], off offset:2048 nt
	s_nop 0
	global_load_dwordx4 v[2:5], v[2:3], off offset:3072 nt
	s_lshl_b64 s[0:1], s[2:3], 6
	v_lshl_add_u64 v[70:71], v[38:39], 0, s[0:1]
	global_load_dword v69, v[70:71], off nt
	s_branch .LBB0_2567

; #define LAS __attribute__((address_space(3)))
; __device__ __forceinline__ unsigned pk2(float lo, float hi) { return f2bf(lo) | (f2bf(hi) << 16); }
; __device__ __forceinline__ void transpose_item(const float* W, int N, bf16* WT, int ldt, LAS unsigned* scr, int item, int lane, int mode, int aux) {
;     const int nblk = (N + 63) >> 6, kb = item / nblk, nb = item - kb * nblk, k0 = 64 * kb, n0 = 64 * nb;
;     const int ncol = n0 + lane; const bool okc = ncol < N;
;     const float* wp = W + (size_t)k0 * N + (okc ? ncol : 0);
;     float v[64];
; #pragma unroll
;     for (int i = 0; i < 64; ++i) v[i] = wp[(size_t)i * N];
; #pragma unroll
;     for (int i = 0; i < 32; ++i) scr[i * 65 + lane] = okc ? pk2(v[2 * i], v[2 * i + 1]) : 0u;
; __device__ __forceinline__ void convert_win(const Args& a, LAS unsigned char* lds, int wave, int lane, int gw, int ngw, int l) {
;     ...
;     for (int it = gw; it < WI_IN; it += ngw) transpose_item(a.in[I_WIN] + (size_t)l * 1024 * IN_COLS, IN_COLS, (bf16*)(a.ws + WS_WIN), 1024, scr, it, lane, 1, 0);
.LBB0_2578:
	s_mul_hi_i32 s0, s12, 0x4d4873ed
	s_lshr_b32 s1, s0, 31
	s_ashr_i32 s6, s0, 4
	s_add_i32 s6, s6, s1
	s_mul_i32 s21, s6, 0xfffff2c0
	s_lshl_b32 s4, s6, 6
	s_add_i32 s21, s21, s16
	s_mul_i32 s0, s6, 0xd1800
	v_add_u32_e32 v78, s21, v35
	s_mul_hi_i32 s1, s4, 0x3460
	s_add_u32 s2, s14, s0
	s_movk_i32 s0, 0xd18
	s_addc_u32 s3, s15, s1
	v_cmp_gt_i32_e64 s[0:1], s0, v78
	s_nop 1
	v_cndmask_b32_e64 v2, 0, v78, s[0:1]
	v_ashrrev_i32_e32 v3, 31, v2
	v_lshl_add_u64 v[2:3], v[2:3], 2, s[2:3]
	s_mov_b32 s2, 0x27000
	s_waitcnt vmcnt(0)
	v_add_co_u32_e32 v4, vcc, s2, v2
	s_mov_b32 s2, 0x2a000
	s_nop 0
	v_addc_co_u32_e32 v5, vcc, 0, v3, vcc
	v_add_co_u32_e32 v8, vcc, s2, v2
	s_mov_b32 s2, 0x2d000
	s_nop 0
	v_addc_co_u32_e32 v9, vcc, 0, v3, vcc
	v_add_co_u32_e32 v10, vcc, s2, v2
	s_mov_b32 s2, 0x31000
	s_nop 0
	v_addc_co_u32_e32 v11, vcc, 0, v3, vcc
	v_add_co_u32_e32 v22, vcc, s2, v2
	s_mov_b32 s2, 0x34000
	s_nop 0
	v_addc_co_u32_e32 v23, vcc, 0, v3, vcc
	v_add_co_u32_e32 v24, vcc, s2, v2
	s_mov_b32 s2, 0x37000
	s_nop 0
	v_addc_co_u32_e32 v25, vcc, 0, v3, vcc
	v_add_co_u32_e32 v26, vcc, s2, v2
	s_mov_b32 s2, 0x3a000
	s_nop 0
	v_addc_co_u32_e32 v27, vcc, 0, v3, vcc
	v_add_co_u32_e32 v28, vcc, s2, v2
	s_mov_b32 s2, 0x3e000
	s_nop 0
	v_addc_co_u32_e32 v29, vcc, 0, v3, vcc
	v_add_co_u32_e32 v30, vcc, s2, v2
	s_mov_b32 s2, 0x41000
	s_nop 0
	v_addc_co_u32_e32 v31, vcc, 0, v3, vcc
	global_load_dword v69, v[4:5], off offset:1152 nt
	global_load_dword v68, v[8:9], off offset:2272 nt
	global_load_dword v67, v[10:11], off offset:3392 nt
	global_load_dword v66, v[22:23], off offset:416 nt
	global_load_dword v65, v[24:25], off offset:1536 nt
	global_load_dword v64, v[26:27], off offset:2656 nt
	global_load_dword v62, v[28:29], off offset:3776 nt
	global_load_dword v63, v[30:31], off offset:800 nt
	v_add_co_u32_e32 v4, vcc, s2, v2
	s_mov_b32 s2, 0x44000
	s_nop 0
	v_addc_co_u32_e32 v5, vcc, 0, v3, vcc
	v_add_co_u32_e32 v8, vcc, s2, v2
	s_mov_b32 s2, 0x48000
	s_nop 0
	v_addc_co_u32_e32 v9, vcc, 0, v3, vcc
	v_add_co_u32_e32 v10, vcc, s2, v2
	s_mov_b32 s2, 0x4b000
	s_nop 0
	v_addc_co_u32_e32 v11, vcc, 0, v3, vcc
	v_add_co_u32_e32 v22, vcc, s2, v2
	s_mov_b32 s2, 0x4e000
	s_nop 0
	v_addc_co_u32_e32 v23, vcc, 0, v3, vcc
	v_add_co_u32_e32 v24, vcc, s2, v2
	s_mov_b32 s2, 0x51000
	s_nop 0
	v_addc_co_u32_e32 v25, vcc, 0, v3, vcc
	v_add_co_u32_e32 v26, vcc, s2, v2
	s_mov_b32 s2, 0x55000
	s_nop 0
	v_addc_co_u32_e32 v27, vcc, 0, v3, vcc
	v_add_co_u32_e32 v28, vcc, s2, v2
	s_mov_b32 s2, 0x58000
	s_nop 0
	v_addc_co_u32_e32 v29, vcc, 0, v3, vcc
	v_add_co_u32_e32 v30, vcc, s2, v2
	s_mov_b32 s2, 0x5b000
	s_nop 0
	v_addc_co_u32_e32 v31, vcc, 0, v3, vcc
	global_load_dword v61, v[4:5], off offset:1920 nt
	global_load_dword v60, v[8:9], off offset:3040 nt
	global_load_dword v59, v[10:11], off offset:64 nt
	global_load_dword v58, v[22:23], off offset:1184 nt
	global_load_dword v57, v[24:25], off offset:2304 nt
	global_load_dword v56, v[26:27], off offset:3424 nt
	global_load_dword v54, v[28:29], off offset:448 nt
	global_load_dword v55, v[30:31], off offset:1568 nt
	v_add_co_u32_e32 v4, vcc, s2, v2
	s_mov_b32 s2, 0x5e000
	s_nop 0
	v_addc_co_u32_e32 v5, vcc, 0, v3, vcc
	v_add_co_u32_e32 v8, vcc, s2, v2
	s_mov_b32 s2, 0x62000
	s_nop 0
	v_addc_co_u32_e32 v9, vcc, 0, v3, vcc
	v_add_co_u32_e32 v10, vcc, s2, v2
	s_mov_b32 s2, 0x65000
	s_nop 0
	v_addc_co_u32_e32 v11, vcc, 0, v3, vcc
	v_add_co_u32_e32 v22, vcc, s2, v2
	s_mov_b32 s2, 0x68000
	s_nop 0
	v_addc_co_u32_e32 v23, vcc, 0, v3, vcc
	v_add_co_u32_e32 v24, vcc, s2, v2
	s_mov_b32 s2, 0x6c000
	s_nop 0
	v_addc_co_u32_e32 v25, vcc, 0, v3, vcc
	v_add_co_u32_e32 v26, vcc, s2, v2
	s_mov_b32 s2, 0x6f000
	s_nop 0
	v_addc_co_u32_e32 v27, vcc, 0, v3, vcc
	v_add_co_u32_e32 v28, vcc, s2, v2
	s_mov_b32 s2, 0x72000
	s_nop 0
	v_addc_co_u32_e32 v29, vcc, 0, v3, vcc
	v_add_co_u32_e32 v30, vcc, s2, v2
	s_mov_b32 s2, 0x75000
	s_nop 0
	v_addc_co_u32_e32 v31, vcc, 0, v3, vcc
	global_load_dword v53, v[4:5], off offset:2688 nt
	global_load_dword v52, v[8:9], off offset:3808 nt
	global_load_dword v50, v[10:11], off offset:832 nt
	global_load_dword v49, v[22:23], off offset:1952 nt
	global_load_dword v48, v[24:25], off offset:3072 nt
	global_load_dword v47, v[26:27], off offset:96 nt
	global_load_dword v45, v[28:29], off offset:1216 nt
	global_load_dword v46, v[30:31], off offset:2336 nt
	v_add_co_u32_e32 v4, vcc, s2, v2
	s_mov_b32 s2, 0x79000
	s_nop 0
	v_addc_co_u32_e32 v5, vcc, 0, v3, vcc
	v_add_co_u32_e32 v8, vcc, s2, v2
	s_mov_b32 s2, 0x7c000
	s_nop 0
	v_addc_co_u32_e32 v9, vcc, 0, v3, vcc
	v_add_co_u32_e32 v10, vcc, s2, v2
	s_mov_b32 s2, 0x7f000
	s_nop 0
	v_addc_co_u32_e32 v11, vcc, 0, v3, vcc
	v_add_co_u32_e32 v22, vcc, s2, v2
	s_mov_b32 s2, 0x82000
	s_nop 0
	v_addc_co_u32_e32 v23, vcc, 0, v3, vcc
	v_add_co_u32_e32 v24, vcc, s2, v2
	s_mov_b32 s2, 0x86000
	s_nop 0
	v_addc_co_u32_e32 v25, vcc, 0, v3, vcc
	v_add_co_u32_e32 v26, vcc, s2, v2
	s_mov_b32 s2, 0x89000
	s_nop 0
	v_addc_co_u32_e32 v27, vcc, 0, v3, vcc
	v_add_co_u32_e32 v28, vcc, s2, v2
	s_mov_b32 s2, 0x8c000
	s_nop 0
	v_addc_co_u32_e32 v29, vcc, 0, v3, vcc
	v_add_co_u32_e32 v30, vcc, s2, v2
	s_mov_b32 s2, 0x90000
	s_nop 0
	v_addc_co_u32_e32 v31, vcc, 0, v3, vcc
	global_load_dword v44, v[4:5], off offset:3456 nt
	global_load_dword v43, v[8:9], off offset:480 nt
	global_load_dword v42, v[10:11], off offset:1600 nt
	global_load_dword v41, v[22:23], off offset:2720 nt
	global_load_dword v40, v[24:25], off offset:3840 nt
	global_load_dword v39, v[26:27], off offset:864 nt
	global_load_dword v37, v[28:29], off offset:1984 nt
	global_load_dword v38, v[30:31], off offset:3104 nt
	v_add_co_u32_e32 v4, vcc, s2, v2
; #define LAS __attribute__((address_space(3)))
; __device__ __forceinline__ unsigned pk2(float lo, float hi) { return f2bf(lo) | (f2bf(hi) << 16); }
; __device__ __forceinline__ void transpose_item(const float* W, int N, bf16* WT, int ldt, LAS unsigned* scr, int item, int lane, int mode, int aux) {
;     const int nblk = (N + 63) >> 6, kb = item / nblk, nb = item - kb * nblk, k0 = 64 * kb, n0 = 64 * nb;
;     const int ncol = n0 + lane; const bool okc = ncol < N;
;     const float* wp = W + (size_t)k0 * N + (okc ? ncol : 0);
;     float v[64];
; #pragma unroll
;     for (int i = 0; i < 64; ++i) v[i] = wp[(size_t)i * N];
; #pragma unroll
;     for (int i = 0; i < 32; ++i) scr[i * 65 + lane] = okc ? pk2(v[2 * i], v[2 * i + 1]) : 0u;
	s_mov_b32 s2, 0x93000
	s_nop 0
	v_addc_co_u32_e32 v5, vcc, 0, v3, vcc
	v_add_co_u32_e32 v8, vcc, s2, v2
	s_mov_b32 s2, 0x96000
	s_nop 0
	v_addc_co_u32_e32 v9, vcc, 0, v3, vcc
	v_add_co_u32_e32 v10, vcc, s2, v2
	s_mov_b32 s2, 0x99000
	s_nop 0
	v_addc_co_u32_e32 v11, vcc, 0, v3, vcc
	v_add_co_u32_e32 v22, vcc, s2, v2
	s_mov_b32 s2, 0x9d000
	s_nop 0
	v_addc_co_u32_e32 v23, vcc, 0, v3, vcc
	v_add_co_u32_e32 v24, vcc, s2, v2
	s_mov_b32 s2, 0xa0000
	s_nop 0
	v_addc_co_u32_e32 v25, vcc, 0, v3, vcc
	v_add_co_u32_e32 v26, vcc, s2, v2
	s_mov_b32 s2, 0xa3000
	s_nop 0
	v_addc_co_u32_e32 v27, vcc, 0, v3, vcc
	v_add_co_u32_e32 v28, vcc, s2, v2
	s_mov_b32 s2, 0xa6000
	s_nop 0
	v_addc_co_u32_e32 v29, vcc, 0, v3, vcc
	v_add_co_u32_e32 v70, vcc, s2, v2
	s_mov_b32 s2, 0xaa000
	s_nop 0
	v_addc_co_u32_e32 v71, vcc, 0, v3, vcc
	global_load_dword v36, v[4:5], off offset:128 nt
	global_load_dword v34, v[8:9], off offset:1248 nt
	global_load_dword v33, v[10:11], off offset:2368 nt
	global_load_dword v32, v[22:23], off offset:3488 nt
	global_load_dword v31, v[24:25], off offset:512 nt
	global_load_dword v30, v[26:27], off offset:1632 nt
	s_nop 0
	global_load_dword v28, v[28:29], off offset:2752 nt
	s_nop 0
	global_load_dword v29, v[70:71], off offset:3872 nt
	v_add_co_u32_e32 v4, vcc, s2, v2
	s_mov_b32 s2, 0xad000
	s_nop 0
	v_addc_co_u32_e32 v5, vcc, 0, v3, vcc
	v_add_co_u32_e32 v8, vcc, s2, v2
	s_mov_b32 s2, 0xb0000
	s_nop 0
	v_addc_co_u32_e32 v9, vcc, 0, v3, vcc
	v_add_co_u32_e32 v10, vcc, s2, v2
	s_mov_b32 s2, 0xb4000
	s_nop 0
	v_addc_co_u32_e32 v11, vcc, 0, v3, vcc
	v_add_co_u32_e32 v22, vcc, s2, v2
	s_mov_b32 s2, 0xb7000
	s_nop 0
	v_addc_co_u32_e32 v23, vcc, 0, v3, vcc
	v_add_co_u32_e32 v70, vcc, s2, v2
	s_mov_b32 s2, 0xba000
	s_nop 0
	v_addc_co_u32_e32 v71, vcc, 0, v3, vcc
	v_add_co_u32_e32 v72, vcc, s2, v2
	s_mov_b32 s2, 0xbd000
	s_nop 0
	v_addc_co_u32_e32 v73, vcc, 0, v3, vcc
	v_add_co_u32_e32 v74, vcc, s2, v2
	s_mov_b32 s2, 0xc1000
	s_nop 0
	v_addc_co_u32_e32 v75, vcc, 0, v3, vcc
	v_add_co_u32_e32 v76, vcc, s2, v2
	s_mov_b32 s2, 0xc4000
	s_nop 0
	v_addc_co_u32_e32 v77, vcc, 0, v3, vcc
	global_load_dword v27, v[4:5], off offset:896 nt
	global_load_dword v26, v[8:9], off offset:2016 nt
	global_load_dword v25, v[10:11], off offset:3136 nt
	global_load_dword v24, v[22:23], off offset:160 nt
	s_nop 0
	global_load_dword v23, v[70:71], off offset:1280 nt
	global_load_dword v22, v[72:73], off offset:2400 nt
	global_load_dword v10, v[74:75], off offset:3520 nt
	global_load_dword v11, v[76:77], off offset:544 nt
	v_add_co_u32_e32 v4, vcc, s2, v2
	s_movk_i32 s2, 0xd17
	s_nop 0
	v_addc_co_u32_e32 v5, vcc, 0, v3, vcc
	v_add_co_u32_e32 v70, vcc, 0xc7000, v2
	v_cmp_lt_i32_e64 s[36:37], s2, v78
	s_nop 0
	v_addc_co_u32_e32 v71, vcc, 0, v3, vcc
	v_add_co_u32_e32 v72, vcc, 0xca000, v2
	s_nop 1
	v_addc_co_u32_e32 v73, vcc, 0, v3, vcc
	v_add_co_u32_e32 v74, vcc, 0xce000, v2
	s_nop 1
	v_addc_co_u32_e32 v75, vcc, 0, v3, vcc
	global_load_dword v9, v[4:5], off offset:1664 nt
	global_load_dword v8, v[70:71], off offset:2784 nt
	s_nop 0
	global_load_dword v5, v[72:73], off offset:3904 nt
	global_load_dword v4, v[74:75], off offset:928 nt
	s_and_saveexec_b64 s[2:3], s[36:37]
	s_xor_b64 s[2:3], exec, s[2:3]
	s_cbranch_execz .LBB0_2580
	ds_write2_b32 v12, v51, v51 offset1:65
	ds_write2_b32 v12, v51, v51 offset0:130 offset1:195
.LBB0_2580:
	s_or_saveexec_b64 s[2:3], s[2:3]
	v_mov_b32_e32 v70, 0
	v_mov_b32_e32 v71, 0
	s_xor_b64 exec, exec, s[2:3]
	s_cbranch_execz .LBB0_2582
	v_add_co_u32_e32 v70, vcc, 0x24000, v2
	s_mov_b32 s5, 0x16000
	s_nop 0
	v_addc_co_u32_e32 v71, vcc, 0, v3, vcc
	global_load_dword v72, v[70:71], off offset:32 nt
	v_add_co_u32_e32 v70, vcc, 0x20000, v2
	s_movk_i32 s7, 0x7fff
	s_nop 0
	v_addc_co_u32_e32 v71, vcc, 0, v3, vcc
	global_load_dword v73, v[70:71], off offset:3008 nt
	v_add_co_u32_e32 v70, vcc, 0x1d000, v2
	s_nop 1
	v_addc_co_u32_e32 v71, vcc, 0, v3, vcc
	global_load_dword v74, v[70:71], off offset:1888 nt
	v_add_co_u32_e32 v70, vcc, 0x1a000, v2
	s_nop 1
	v_addc_co_u32_e32 v71, vcc, 0, v3, vcc
	global_load_dword v75, v[70:71], off offset:768 nt
	v_add_co_u32_e32 v70, vcc, s5, v2
	s_mov_b32 s5, 0x10000
	s_nop 0
	v_addc_co_u32_e32 v71, vcc, 0, v3, vcc
	global_load_dword v76, v[70:71], off offset:3744 nt
	v_add_co_u32_e32 v70, vcc, 0x13000, v2
	s_nop 1
	v_addc_co_u32_e32 v71, vcc, 0, v3, vcc
	global_load_dword v77, v[70:71], off offset:2624 nt
	v_add_co_u32_e32 v70, vcc, s5, v2
	s_mov_b32 s5, 0xd000
	s_nop 0
	v_addc_co_u32_e32 v71, vcc, 0, v3, vcc
	global_load_dword v78, v[70:71], off offset:1504 nt
	v_add_co_u32_e32 v70, vcc, s5, v2
	s_mov_b32 s5, 0x9000
	s_nop 0
	v_addc_co_u32_e32 v71, vcc, 0, v3, vcc
	global_load_dword v79, v[70:71], off offset:384 nt
	v_add_co_u32_e32 v70, vcc, s5, v2
	s_movk_i32 s5, 0x6000
	s_nop 0
	v_addc_co_u32_e32 v71, vcc, 0, v3, vcc
	global_load_dword v80, v[70:71], off offset:3360 nt
	v_add_co_u32_e32 v70, vcc, s5, v2
	s_mov_b32 s5, 0xffff0000
	s_nop 0
	v_addc_co_u32_e32 v71, vcc, 0, v3, vcc
	global_load_dword v81, v[70:71], off offset:2240 nt
	v_add_co_u32_e32 v70, vcc, s10, v2
	s_nop 1
	v_addc_co_u32_e32 v71, vcc, 0, v3, vcc
	global_load_dword v70, v[70:71], off offset:1120 nt
	s_nop 0
	global_load_dword v2, v[2:3], off nt
	s_waitcnt vmcnt(5)
	v_bfe_u32 v71, v78, 16, 1
	v_add3_u32 v71, v78, v71, s7
	s_waitcnt vmcnt(0)
	v_bfe_u32 v3, v2, 16, 1
	v_add3_u32 v2, v2, v3, s7
	v_bfe_u32 v3, v70, 16, 1
	v_lshrrev_b32_e32 v2, 16, v2
	v_add3_u32 v3, v70, v3, s7
	v_and_or_b32 v2, v3, s5, v2
	v_bfe_u32 v3, v81, 16, 1
	v_add3_u32 v3, v81, v3, s7
	v_bfe_u32 v70, v80, 16, 1
	v_lshrrev_b32_e32 v3, 16, v3
	v_add3_u32 v70, v80, v70, s7
	v_and_or_b32 v3, v70, s5, v3
	v_bfe_u32 v70, v79, 16, 1
	v_add3_u32 v70, v79, v70, s7
	v_lshrrev_b32_e32 v70, 16, v70
	v_and_or_b32 v70, v71, s5, v70
	v_bfe_u32 v71, v77, 16, 1
	v_add3_u32 v71, v77, v71, s7
	v_bfe_u32 v77, v76, 16, 1
	v_lshrrev_b32_e32 v71, 16, v71
	v_add3_u32 v76, v76, v77, s7
	v_and_or_b32 v71, v76, s5, v71
	ds_write2_b32 v12, v2, v3 offset1:65
	ds_write2_b32 v12, v70, v71 offset0:130 offset1:195
	v_bfe_u32 v2, v75, 16, 1
	v_add3_u32 v2, v75, v2, s7
	v_bfe_u32 v3, v74, 16, 1
	v_lshrrev_b32_e32 v2, 16, v2
	v_add3_u32 v3, v74, v3, s7
	v_and_or_b32 v70, v3, s5, v2
	v_bfe_u32 v2, v73, 16, 1
	v_add3_u32 v2, v73, v2, s7
	v_bfe_u32 v3, v72, 16, 1
	v_lshrrev_b32_e32 v2, 16, v2
	v_add3_u32 v3, v72, v3, s7
	v_and_or_b32 v71, v3, s5, v2
